# scan compute path rewritten (2 rows x 4 keys per lane, half the LDS reads); IEEE 1/x sequences replaced by v_rcp_f32 (f32, 1ulp)
# speedup vs baseline: 1.0370x; 1.0370x over previous
; #define LAS __attribute__((address_space(3)))
; __device__ __forceinline__ void phase_scan(CParams& p, LAS unsigned char* lds) {
;     ...
;             const int j = lane & 7, row = hf * 32 + wid * 8 + (lane >> 3);
;             f32x2 S[4];
; #pragma unroll
;             for (int i = 0; i < 4; ++i) S[i] = (f32x2){0.f, 0.f};
;             if (!prompt) { const float* sp = p.in[I_SWKV] + ((size_t)chain * 64 + row) * 64; const f32x4 a = *(const f32x4*)(sp + 4 * j), bq = *(const f32x4*)(sp + 32 + 4 * j);
;                 S[0] = a.lo; S[1] = a.hi; S[2] = bq.lo; S[3] = bq.hi; }
;             __syncthreads();
;             for (int c = 0; c < nch; ++c) {
;                 const LAS float* base = (const LAS float*)(lds + (c & 1) * SBUF) + 4 * j;
;                 const LAS float* vb = (const LAS float*)(lds + (c & 1) * SBUF) + 320 + row;
;                 const int nst = (T - c * SCH) < SCH ? (T - c * SCH) : SCH;
;                 ScanOps cur, nxt;
;                 scan_ld(cur, base, vb);
;                 for (int g16 = 0; g16 < nst; g16 += 16) {
;                     unsigned ywb = (unsigned)(YP_OFF + (g16 >> 4) * YP_BYTES + (wid * 64 + lane) * 4);
;                     asm volatile("" : "+v"(ywb));
;                     LAS float* yw = (LAS float*)(lds + ywb);
; #pragma unroll
;                     for (int s16 = 0; s16 < 16; ++s16) {
;                         scan_ld(nxt, base + (g16 + s16 + 1) * 384, vb + (g16 + s16 + 1) * 384);
;                         f32x2 d = S[0] * cur.n0.lo; d = S[1] * cur.n0.hi + d; d = S[2] * cur.n1.lo + d; d = S[3] * cur.n1.hi + d;
;                         const float sa = reduce8(d.x + d.y);
;                         const f32x2 sa2 = (f32x2){sa, sa}, v2 = (f32x2){cur.v, cur.v};
;                         S[0] = S[0] * cur.w0.lo + (cur.b0.lo * sa2 + cur.k0.lo * v2);
;                         S[1] = S[1] * cur.w0.hi + (cur.b0.hi * sa2 + cur.k0.hi * v2);
;                         S[2] = S[2] * cur.w1.lo + (cur.b1.lo * sa2 + cur.k1.lo * v2);
;                         S[3] = S[3] * cur.w1.hi + (cur.b1.hi * sa2 + cur.k1.hi * v2);
;                         f32x2 e = S[0] * cur.r0.lo; e = S[1] * cur.r0.hi + e; e = S[2] * cur.r1.lo + e; e = S[3] * cur.r1.hi + e;
;                         yw[s16 * 256] = e.x + e.y;
;                         cur = nxt;
;                     }
;                     __syncthreads();
;                 }
.LBB0_137:
	s_ashr_i32 s12, s1, 1
	s_and_b32 s33, s1, 1
	s_and_b64 s[2:3], s[50:51], exec
	s_cselect_b32 s1, 16, 0x1000
	s_add_i32 s2, s1, 31
	s_lshr_b32 s3, s2, 5
	s_mov_b64 s[54:55], -1
	s_and_b64 vcc, exec, s[4:5]
	s_cbranch_vccz .LBB0_147
	v_and_b32_e32 v112, 63, v192
	v_lshrrev_b32_e32 v113, 6, v192
	v_and_b32_e32 v114, 15, v112
	v_lshrrev_b32_e32 v115, 4, v112
	v_lshlrev_b32_e32 v116, 3, v113
	v_lshl_add_u32 v116, v115, 1, v116
	v_lshlrev_b32_e32 v100, 4, v114
	s_lshl_b32 s13, s33, 5
	v_add_u32_e32 v103, s13, v116
	v_lshlrev_b32_e32 v101, 2, v103
	v_add_u32_e32 v101, 0x500, v101
	v_lshlrev_b32_e32 v103, 8, v103
	v_add_u32_e32 v103, v103, v100
	v_and_b32_e32 v117, 1, v112
	v_add_u32_e32 v102, v116, v117
	v_lshrrev_b32_e32 v114, 1, v114
	v_lshl_add_u32 v102, v102, 3, v114
	v_lshlrev_b32_e32 v102, 2, v102
	v_add_u32_e32 v102, 0x18600, v102
	v_cmp_eq_u32_e32 vcc, 1, v117
	s_mov_b32 s13, 0
	s_lshl_b64 s[54:55], s[12:13], 14
	s_cmp_eq_u64 s[50:51], 0
	s_cbranch_scc1 .Lsc_zero
	s_add_u32 s54, s18, s54
	s_addc_u32 s55, s19, s55
	s_nop 4
	global_load_dwordx4 v[104:107], v103, s[54:55]
	global_load_dwordx4 v[108:111], v103, s[54:55] offset:256
	s_waitcnt vmcnt(0)
	v_mov_b32_e32 v32, v104
	v_mov_b32_e32 v33, v108
	v_mov_b32_e32 v34, v105
	v_mov_b32_e32 v35, v109
	v_mov_b32_e32 v36, v106
	v_mov_b32_e32 v37, v110
	v_mov_b32_e32 v38, v107
	v_mov_b32_e32 v39, v111
	s_branch .Lsc_go
.Lsc_zero:
	v_mov_b32_e32 v32, 0
	v_mov_b32_e32 v33, 0
	v_mov_b32_e32 v34, 0
	v_mov_b32_e32 v35, 0
	v_mov_b32_e32 v36, 0
	v_mov_b32_e32 v37, 0
	v_mov_b32_e32 v38, 0
	v_mov_b32_e32 v39, 0
.Lsc_go:
	s_waitcnt lgkmcnt(0)
	s_barrier
	s_mov_b32 s13, 0
.Lsc_chunk:
	s_lshl_b32 s15, s13, 5
	s_sub_i32 s54, s1, s15
	s_min_i32 s54, s54, 32
	s_bitcmp1_b32 s13, 0
	s_cselect_b32 s55, 0xc000, 0
	v_add_u32_e32 v97, s55, v100
	v_add_u32_e32 v98, s55, v101
	v_mov_b32_e32 v99, v102
	s_mov_b32 s15, 0
	s_nop 0
	ds_read_b128 v[40:43], v97 offset:768
	ds_read_b128 v[44:47], v97 offset:1024
	ds_read_b64 v[56:57], v98 offset:0
	ds_read_b128 v[48:51], v97 offset:512
	ds_read_b128 v[52:55], v97 offset:256
	ds_read_b128 v[60:63], v97 offset:0
.Lsc_grp:
	ds_read_b128 v[64:67], v97 offset:2304
	s_waitcnt lgkmcnt(2)
	v_pk_mul_f32 v[84:85], v[32:33], v[40:41] op_sel_hi:[1,0]
	ds_read_b128 v[68:71], v97 offset:2560
	v_pk_fma_f32 v[84:85], v[34:35], v[40:41], v[84:85] op_sel:[0,1,0] op_sel_hi:[1,1,1]
	ds_read_b64 v[58:59], v98 offset:1536
	v_pk_fma_f32 v[84:85], v[36:37], v[42:43], v[84:85] op_sel_hi:[1,0,1]
	ds_read_b128 v[72:75], v97 offset:2048
	v_pk_fma_f32 v[84:85], v[38:39], v[42:43], v[84:85] op_sel:[0,1,0] op_sel_hi:[1,1,1]
	ds_read_b128 v[76:79], v97 offset:1792
	s_nop 0
	v_add_f32_dpp v84, v84, v84 quad_perm:[1,0,3,2] row_mask:0xf bank_mask:0xf bound_ctrl:1
	v_add_f32_dpp v85, v85, v85 quad_perm:[1,0,3,2] row_mask:0xf bank_mask:0xf bound_ctrl:1
	s_nop 0
	v_add_f32_dpp v84, v84, v84 quad_perm:[2,3,0,1] row_mask:0xf bank_mask:0xf bound_ctrl:1
	v_add_f32_dpp v85, v85, v85 quad_perm:[2,3,0,1] row_mask:0xf bank_mask:0xf bound_ctrl:1
	s_nop 0
	v_add_f32_dpp v84, v84, v84 row_half_mirror row_mask:0xf bank_mask:0xf bound_ctrl:1
	v_add_f32_dpp v85, v85, v85 row_half_mirror row_mask:0xf bank_mask:0xf bound_ctrl:1
	s_nop 0
	v_add_f32_dpp v84, v84, v84 row_mirror row_mask:0xf bank_mask:0xf bound_ctrl:1
	v_add_f32_dpp v85, v85, v85 row_mirror row_mask:0xf bank_mask:0xf bound_ctrl:1
	ds_read_b128 v[80:83], v97 offset:1536
	v_pk_mul_f32 v[86:87], v[84:85], v[44:45] op_sel_hi:[1,0]
	v_pk_mul_f32 v[88:89], v[84:85], v[44:45] op_sel:[0,1] op_sel_hi:[1,1]
	v_pk_mul_f32 v[90:91], v[84:85], v[46:47] op_sel_hi:[1,0]
	v_pk_mul_f32 v[92:93], v[84:85], v[46:47] op_sel:[0,1] op_sel_hi:[1,1]
	v_pk_fma_f32 v[86:87], v[56:57], v[48:49], v[86:87] op_sel_hi:[1,0,1]
	v_pk_fma_f32 v[88:89], v[56:57], v[48:49], v[88:89] op_sel:[0,1,0] op_sel_hi:[1,1,1]
	v_pk_fma_f32 v[90:91], v[56:57], v[50:51], v[90:91] op_sel_hi:[1,0,1]
	v_pk_fma_f32 v[92:93], v[56:57], v[50:51], v[92:93] op_sel:[0,1,0] op_sel_hi:[1,1,1]
	v_pk_fma_f32 v[32:33], v[32:33], v[52:53], v[86:87] op_sel_hi:[1,0,1]
	v_pk_fma_f32 v[34:35], v[34:35], v[52:53], v[88:89] op_sel:[0,1,0] op_sel_hi:[1,1,1]
	v_pk_fma_f32 v[36:37], v[36:37], v[54:55], v[90:91] op_sel_hi:[1,0,1]
	v_pk_fma_f32 v[38:39], v[38:39], v[54:55], v[92:93] op_sel:[0,1,0] op_sel_hi:[1,1,1]
	ds_read_b128 v[40:43], v97 offset:3840
	s_waitcnt lgkmcnt(2)
; __device__ __forceinline__ float reduce8(float x) { x += dppf<0xB1>(x); x += dppf<0x4E>(x); x += dppf<0x141>(x); return x; }
; __device__ __forceinline__ void phase_scan(CParams& p, LAS unsigned char* lds) {
;     ...
;                     for (int s16 = 0; s16 < 16; ++s16) {
;                         scan_ld(nxt, base + (g16 + s16 + 1) * 384, vb + (g16 + s16 + 1) * 384);
;                         f32x2 d = S[0] * cur.n0.lo; d = S[1] * cur.n0.hi + d; d = S[2] * cur.n1.lo + d; d = S[3] * cur.n1.hi + d;
;                         const float sa = reduce8(d.x + d.y);
;                         const f32x2 sa2 = (f32x2){sa, sa}, v2 = (f32x2){cur.v, cur.v};
;                         S[0] = S[0] * cur.w0.lo + (cur.b0.lo * sa2 + cur.k0.lo * v2);
;                         S[1] = S[1] * cur.w0.hi + (cur.b0.hi * sa2 + cur.k0.hi * v2);
;                         S[2] = S[2] * cur.w1.lo + (cur.b1.lo * sa2 + cur.k1.lo * v2);
;                         S[3] = S[3] * cur.w1.hi + (cur.b1.hi * sa2 + cur.k1.hi * v2);
;                         f32x2 e = S[0] * cur.r0.lo; e = S[1] * cur.r0.hi + e; e = S[2] * cur.r1.lo + e; e = S[3] * cur.r1.hi + e;
;                         yw[s16 * 256] = e.x + e.y;
;                         cur = nxt;
;                     }
	v_pk_mul_f32 v[84:85], v[32:33], v[64:65] op_sel_hi:[1,0]
	ds_read_b128 v[44:47], v97 offset:4096
	v_pk_fma_f32 v[84:85], v[34:35], v[64:65], v[84:85] op_sel:[0,1,0] op_sel_hi:[1,1,1]
	ds_read_b64 v[56:57], v98 offset:3072
	v_pk_fma_f32 v[84:85], v[36:37], v[66:67], v[84:85] op_sel_hi:[1,0,1]
	ds_read_b128 v[48:51], v97 offset:3584
	v_pk_fma_f32 v[84:85], v[38:39], v[66:67], v[84:85] op_sel:[0,1,0] op_sel_hi:[1,1,1]
	ds_read_b128 v[52:55], v97 offset:3328
	v_pk_mul_f32 v[94:95], v[32:33], v[60:61] op_sel_hi:[1,0]
	v_add_f32_dpp v84, v84, v84 quad_perm:[1,0,3,2] row_mask:0xf bank_mask:0xf bound_ctrl:1
	v_add_f32_dpp v85, v85, v85 quad_perm:[1,0,3,2] row_mask:0xf bank_mask:0xf bound_ctrl:1
	v_pk_fma_f32 v[94:95], v[34:35], v[60:61], v[94:95] op_sel:[0,1,0] op_sel_hi:[1,1,1]
	v_add_f32_dpp v84, v84, v84 quad_perm:[2,3,0,1] row_mask:0xf bank_mask:0xf bound_ctrl:1
	v_add_f32_dpp v85, v85, v85 quad_perm:[2,3,0,1] row_mask:0xf bank_mask:0xf bound_ctrl:1
	v_pk_fma_f32 v[94:95], v[36:37], v[62:63], v[94:95] op_sel_hi:[1,0,1]
	v_add_f32_dpp v84, v84, v84 row_half_mirror row_mask:0xf bank_mask:0xf bound_ctrl:1
	v_add_f32_dpp v85, v85, v85 row_half_mirror row_mask:0xf bank_mask:0xf bound_ctrl:1
	v_pk_fma_f32 v[94:95], v[38:39], v[62:63], v[94:95] op_sel:[0,1,0] op_sel_hi:[1,1,1]
	v_add_f32_dpp v84, v84, v84 row_mirror row_mask:0xf bank_mask:0xf bound_ctrl:1
	v_add_f32_dpp v85, v85, v85 row_mirror row_mask:0xf bank_mask:0xf bound_ctrl:1
	ds_read_b128 v[60:63], v97 offset:3072
	v_pk_mul_f32 v[86:87], v[84:85], v[68:69] op_sel_hi:[1,0]
	v_pk_mul_f32 v[88:89], v[84:85], v[68:69] op_sel:[0,1] op_sel_hi:[1,1]
	v_pk_mul_f32 v[90:91], v[84:85], v[70:71] op_sel_hi:[1,0]
	v_pk_mul_f32 v[92:93], v[84:85], v[70:71] op_sel:[0,1] op_sel_hi:[1,1]
	v_pk_fma_f32 v[86:87], v[58:59], v[72:73], v[86:87] op_sel_hi:[1,0,1]
	v_pk_fma_f32 v[88:89], v[58:59], v[72:73], v[88:89] op_sel:[0,1,0] op_sel_hi:[1,1,1]
	v_pk_fma_f32 v[90:91], v[58:59], v[74:75], v[90:91] op_sel_hi:[1,0,1]
	v_pk_fma_f32 v[92:93], v[58:59], v[74:75], v[92:93] op_sel:[0,1,0] op_sel_hi:[1,1,1]
	v_pk_fma_f32 v[32:33], v[32:33], v[76:77], v[86:87] op_sel_hi:[1,0,1]
	v_pk_fma_f32 v[34:35], v[34:35], v[76:77], v[88:89] op_sel:[0,1,0] op_sel_hi:[1,1,1]
	v_pk_fma_f32 v[36:37], v[36:37], v[78:79], v[90:91] op_sel_hi:[1,0,1]
	v_pk_fma_f32 v[38:39], v[38:39], v[78:79], v[92:93] op_sel:[0,1,0] op_sel_hi:[1,1,1]
	v_add_f32_dpp v94, v94, v94 quad_perm:[1,0,3,2] row_mask:0xf bank_mask:0xf bound_ctrl:1
	v_add_f32_dpp v95, v95, v95 quad_perm:[1,0,3,2] row_mask:0xf bank_mask:0xf bound_ctrl:1
	v_cndmask_b32_e32 v96, v94, v95, vcc
	ds_write_b32 v99, v96 offset:0
	ds_read_b128 v[64:67], v97 offset:5376
	s_waitcnt lgkmcnt(3)
	v_pk_mul_f32 v[84:85], v[32:33], v[40:41] op_sel_hi:[1,0]
	ds_read_b128 v[68:71], v97 offset:5632
	v_pk_fma_f32 v[84:85], v[34:35], v[40:41], v[84:85] op_sel:[0,1,0] op_sel_hi:[1,1,1]
	ds_read_b64 v[58:59], v98 offset:4608
	v_pk_fma_f32 v[84:85], v[36:37], v[42:43], v[84:85] op_sel_hi:[1,0,1]
	ds_read_b128 v[72:75], v97 offset:5120
	v_pk_fma_f32 v[84:85], v[38:39], v[42:43], v[84:85] op_sel:[0,1,0] op_sel_hi:[1,1,1]
	ds_read_b128 v[76:79], v97 offset:4864
	v_pk_mul_f32 v[94:95], v[32:33], v[80:81] op_sel_hi:[1,0]
	v_add_f32_dpp v84, v84, v84 quad_perm:[1,0,3,2] row_mask:0xf bank_mask:0xf bound_ctrl:1
	v_add_f32_dpp v85, v85, v85 quad_perm:[1,0,3,2] row_mask:0xf bank_mask:0xf bound_ctrl:1
	v_pk_fma_f32 v[94:95], v[34:35], v[80:81], v[94:95] op_sel:[0,1,0] op_sel_hi:[1,1,1]
	v_add_f32_dpp v84, v84, v84 quad_perm:[2,3,0,1] row_mask:0xf bank_mask:0xf bound_ctrl:1
	v_add_f32_dpp v85, v85, v85 quad_perm:[2,3,0,1] row_mask:0xf bank_mask:0xf bound_ctrl:1
	v_pk_fma_f32 v[94:95], v[36:37], v[82:83], v[94:95] op_sel_hi:[1,0,1]
	v_add_f32_dpp v84, v84, v84 row_half_mirror row_mask:0xf bank_mask:0xf bound_ctrl:1
	v_add_f32_dpp v85, v85, v85 row_half_mirror row_mask:0xf bank_mask:0xf bound_ctrl:1
	v_pk_fma_f32 v[94:95], v[38:39], v[82:83], v[94:95] op_sel:[0,1,0] op_sel_hi:[1,1,1]
	v_add_f32_dpp v84, v84, v84 row_mirror row_mask:0xf bank_mask:0xf bound_ctrl:1
	v_add_f32_dpp v85, v85, v85 row_mirror row_mask:0xf bank_mask:0xf bound_ctrl:1
	ds_read_b128 v[80:83], v97 offset:4608
	v_pk_mul_f32 v[86:87], v[84:85], v[44:45] op_sel_hi:[1,0]
	v_pk_mul_f32 v[88:89], v[84:85], v[44:45] op_sel:[0,1] op_sel_hi:[1,1]
	v_pk_mul_f32 v[90:91], v[84:85], v[46:47] op_sel_hi:[1,0]
	v_pk_mul_f32 v[92:93], v[84:85], v[46:47] op_sel:[0,1] op_sel_hi:[1,1]
	v_pk_fma_f32 v[86:87], v[56:57], v[48:49], v[86:87] op_sel_hi:[1,0,1]
	v_pk_fma_f32 v[88:89], v[56:57], v[48:49], v[88:89] op_sel:[0,1,0] op_sel_hi:[1,1,1]
	v_pk_fma_f32 v[90:91], v[56:57], v[50:51], v[90:91] op_sel_hi:[1,0,1]
	v_pk_fma_f32 v[92:93], v[56:57], v[50:51], v[92:93] op_sel:[0,1,0] op_sel_hi:[1,1,1]
	v_pk_fma_f32 v[32:33], v[32:33], v[52:53], v[86:87] op_sel_hi:[1,0,1]
	v_pk_fma_f32 v[34:35], v[34:35], v[52:53], v[88:89] op_sel:[0,1,0] op_sel_hi:[1,1,1]
	v_pk_fma_f32 v[36:37], v[36:37], v[54:55], v[90:91] op_sel_hi:[1,0,1]
	v_pk_fma_f32 v[38:39], v[38:39], v[54:55], v[92:93] op_sel:[0,1,0] op_sel_hi:[1,1,1]
	v_add_f32_dpp v94, v94, v94 quad_perm:[1,0,3,2] row_mask:0xf bank_mask:0xf bound_ctrl:1
	v_add_f32_dpp v95, v95, v95 quad_perm:[1,0,3,2] row_mask:0xf bank_mask:0xf bound_ctrl:1
	v_cndmask_b32_e32 v96, v94, v95, vcc
	ds_write_b32 v99, v96 offset:1024
	ds_read_b128 v[40:43], v97 offset:6912
	s_waitcnt lgkmcnt(3)
; __device__ __forceinline__ float reduce8(float x) { x += dppf<0xB1>(x); x += dppf<0x4E>(x); x += dppf<0x141>(x); return x; }
; __device__ __forceinline__ void phase_scan(CParams& p, LAS unsigned char* lds) {
;     ...
;                     for (int s16 = 0; s16 < 16; ++s16) {
;                         scan_ld(nxt, base + (g16 + s16 + 1) * 384, vb + (g16 + s16 + 1) * 384);
;                         f32x2 d = S[0] * cur.n0.lo; d = S[1] * cur.n0.hi + d; d = S[2] * cur.n1.lo + d; d = S[3] * cur.n1.hi + d;
;                         const float sa = reduce8(d.x + d.y);
;                         const f32x2 sa2 = (f32x2){sa, sa}, v2 = (f32x2){cur.v, cur.v};
;                         S[0] = S[0] * cur.w0.lo + (cur.b0.lo * sa2 + cur.k0.lo * v2);
;                         S[1] = S[1] * cur.w0.hi + (cur.b0.hi * sa2 + cur.k0.hi * v2);
;                         S[2] = S[2] * cur.w1.lo + (cur.b1.lo * sa2 + cur.k1.lo * v2);
;                         S[3] = S[3] * cur.w1.hi + (cur.b1.hi * sa2 + cur.k1.hi * v2);
;                         f32x2 e = S[0] * cur.r0.lo; e = S[1] * cur.r0.hi + e; e = S[2] * cur.r1.lo + e; e = S[3] * cur.r1.hi + e;
;                         yw[s16 * 256] = e.x + e.y;
;                         cur = nxt;
;                     }
	v_pk_mul_f32 v[84:85], v[32:33], v[64:65] op_sel_hi:[1,0]
	ds_read_b128 v[44:47], v97 offset:7168
	v_pk_fma_f32 v[84:85], v[34:35], v[64:65], v[84:85] op_sel:[0,1,0] op_sel_hi:[1,1,1]
	ds_read_b64 v[56:57], v98 offset:6144
	v_pk_fma_f32 v[84:85], v[36:37], v[66:67], v[84:85] op_sel_hi:[1,0,1]
	ds_read_b128 v[48:51], v97 offset:6656
	v_pk_fma_f32 v[84:85], v[38:39], v[66:67], v[84:85] op_sel:[0,1,0] op_sel_hi:[1,1,1]
	ds_read_b128 v[52:55], v97 offset:6400
	v_pk_mul_f32 v[94:95], v[32:33], v[60:61] op_sel_hi:[1,0]
	v_add_f32_dpp v84, v84, v84 quad_perm:[1,0,3,2] row_mask:0xf bank_mask:0xf bound_ctrl:1
	v_add_f32_dpp v85, v85, v85 quad_perm:[1,0,3,2] row_mask:0xf bank_mask:0xf bound_ctrl:1
	v_pk_fma_f32 v[94:95], v[34:35], v[60:61], v[94:95] op_sel:[0,1,0] op_sel_hi:[1,1,1]
	v_add_f32_dpp v84, v84, v84 quad_perm:[2,3,0,1] row_mask:0xf bank_mask:0xf bound_ctrl:1
	v_add_f32_dpp v85, v85, v85 quad_perm:[2,3,0,1] row_mask:0xf bank_mask:0xf bound_ctrl:1
	v_pk_fma_f32 v[94:95], v[36:37], v[62:63], v[94:95] op_sel_hi:[1,0,1]
	v_add_f32_dpp v84, v84, v84 row_half_mirror row_mask:0xf bank_mask:0xf bound_ctrl:1
	v_add_f32_dpp v85, v85, v85 row_half_mirror row_mask:0xf bank_mask:0xf bound_ctrl:1
	v_pk_fma_f32 v[94:95], v[38:39], v[62:63], v[94:95] op_sel:[0,1,0] op_sel_hi:[1,1,1]
	v_add_f32_dpp v84, v84, v84 row_mirror row_mask:0xf bank_mask:0xf bound_ctrl:1
	v_add_f32_dpp v85, v85, v85 row_mirror row_mask:0xf bank_mask:0xf bound_ctrl:1
	ds_read_b128 v[60:63], v97 offset:6144
	v_pk_mul_f32 v[86:87], v[84:85], v[68:69] op_sel_hi:[1,0]
	v_pk_mul_f32 v[88:89], v[84:85], v[68:69] op_sel:[0,1] op_sel_hi:[1,1]
	v_pk_mul_f32 v[90:91], v[84:85], v[70:71] op_sel_hi:[1,0]
	v_pk_mul_f32 v[92:93], v[84:85], v[70:71] op_sel:[0,1] op_sel_hi:[1,1]
	v_pk_fma_f32 v[86:87], v[58:59], v[72:73], v[86:87] op_sel_hi:[1,0,1]
	v_pk_fma_f32 v[88:89], v[58:59], v[72:73], v[88:89] op_sel:[0,1,0] op_sel_hi:[1,1,1]
	v_pk_fma_f32 v[90:91], v[58:59], v[74:75], v[90:91] op_sel_hi:[1,0,1]
	v_pk_fma_f32 v[92:93], v[58:59], v[74:75], v[92:93] op_sel:[0,1,0] op_sel_hi:[1,1,1]
	v_pk_fma_f32 v[32:33], v[32:33], v[76:77], v[86:87] op_sel_hi:[1,0,1]
	v_pk_fma_f32 v[34:35], v[34:35], v[76:77], v[88:89] op_sel:[0,1,0] op_sel_hi:[1,1,1]
	v_pk_fma_f32 v[36:37], v[36:37], v[78:79], v[90:91] op_sel_hi:[1,0,1]
	v_pk_fma_f32 v[38:39], v[38:39], v[78:79], v[92:93] op_sel:[0,1,0] op_sel_hi:[1,1,1]
	v_add_f32_dpp v94, v94, v94 quad_perm:[1,0,3,2] row_mask:0xf bank_mask:0xf bound_ctrl:1
	v_add_f32_dpp v95, v95, v95 quad_perm:[1,0,3,2] row_mask:0xf bank_mask:0xf bound_ctrl:1
	v_cndmask_b32_e32 v96, v94, v95, vcc
	ds_write_b32 v99, v96 offset:2048
	ds_read_b128 v[64:67], v97 offset:8448
	s_waitcnt lgkmcnt(3)
	v_pk_mul_f32 v[84:85], v[32:33], v[40:41] op_sel_hi:[1,0]
	ds_read_b128 v[68:71], v97 offset:8704
	v_pk_fma_f32 v[84:85], v[34:35], v[40:41], v[84:85] op_sel:[0,1,0] op_sel_hi:[1,1,1]
	ds_read_b64 v[58:59], v98 offset:7680
	v_pk_fma_f32 v[84:85], v[36:37], v[42:43], v[84:85] op_sel_hi:[1,0,1]
	ds_read_b128 v[72:75], v97 offset:8192
	v_pk_fma_f32 v[84:85], v[38:39], v[42:43], v[84:85] op_sel:[0,1,0] op_sel_hi:[1,1,1]
	ds_read_b128 v[76:79], v97 offset:7936
	v_pk_mul_f32 v[94:95], v[32:33], v[80:81] op_sel_hi:[1,0]
	v_add_f32_dpp v84, v84, v84 quad_perm:[1,0,3,2] row_mask:0xf bank_mask:0xf bound_ctrl:1
	v_add_f32_dpp v85, v85, v85 quad_perm:[1,0,3,2] row_mask:0xf bank_mask:0xf bound_ctrl:1
	v_pk_fma_f32 v[94:95], v[34:35], v[80:81], v[94:95] op_sel:[0,1,0] op_sel_hi:[1,1,1]
	v_add_f32_dpp v84, v84, v84 quad_perm:[2,3,0,1] row_mask:0xf bank_mask:0xf bound_ctrl:1
	v_add_f32_dpp v85, v85, v85 quad_perm:[2,3,0,1] row_mask:0xf bank_mask:0xf bound_ctrl:1
	v_pk_fma_f32 v[94:95], v[36:37], v[82:83], v[94:95] op_sel_hi:[1,0,1]
	v_add_f32_dpp v84, v84, v84 row_half_mirror row_mask:0xf bank_mask:0xf bound_ctrl:1
	v_add_f32_dpp v85, v85, v85 row_half_mirror row_mask:0xf bank_mask:0xf bound_ctrl:1
	v_pk_fma_f32 v[94:95], v[38:39], v[82:83], v[94:95] op_sel:[0,1,0] op_sel_hi:[1,1,1]
	v_add_f32_dpp v84, v84, v84 row_mirror row_mask:0xf bank_mask:0xf bound_ctrl:1
	v_add_f32_dpp v85, v85, v85 row_mirror row_mask:0xf bank_mask:0xf bound_ctrl:1
	ds_read_b128 v[80:83], v97 offset:7680
	v_pk_mul_f32 v[86:87], v[84:85], v[44:45] op_sel_hi:[1,0]
	v_pk_mul_f32 v[88:89], v[84:85], v[44:45] op_sel:[0,1] op_sel_hi:[1,1]
	v_pk_mul_f32 v[90:91], v[84:85], v[46:47] op_sel_hi:[1,0]
	v_pk_mul_f32 v[92:93], v[84:85], v[46:47] op_sel:[0,1] op_sel_hi:[1,1]
	v_pk_fma_f32 v[86:87], v[56:57], v[48:49], v[86:87] op_sel_hi:[1,0,1]
	v_pk_fma_f32 v[88:89], v[56:57], v[48:49], v[88:89] op_sel:[0,1,0] op_sel_hi:[1,1,1]
	v_pk_fma_f32 v[90:91], v[56:57], v[50:51], v[90:91] op_sel_hi:[1,0,1]
	v_pk_fma_f32 v[92:93], v[56:57], v[50:51], v[92:93] op_sel:[0,1,0] op_sel_hi:[1,1,1]
	v_pk_fma_f32 v[32:33], v[32:33], v[52:53], v[86:87] op_sel_hi:[1,0,1]
	v_pk_fma_f32 v[34:35], v[34:35], v[52:53], v[88:89] op_sel:[0,1,0] op_sel_hi:[1,1,1]
	v_pk_fma_f32 v[36:37], v[36:37], v[54:55], v[90:91] op_sel_hi:[1,0,1]
	v_pk_fma_f32 v[38:39], v[38:39], v[54:55], v[92:93] op_sel:[0,1,0] op_sel_hi:[1,1,1]
	v_add_f32_dpp v94, v94, v94 quad_perm:[1,0,3,2] row_mask:0xf bank_mask:0xf bound_ctrl:1
	v_add_f32_dpp v95, v95, v95 quad_perm:[1,0,3,2] row_mask:0xf bank_mask:0xf bound_ctrl:1
	v_cndmask_b32_e32 v96, v94, v95, vcc
	ds_write_b32 v99, v96 offset:3072
	ds_read_b128 v[40:43], v97 offset:9984
	s_waitcnt lgkmcnt(3)
; __device__ __forceinline__ float reduce8(float x) { x += dppf<0xB1>(x); x += dppf<0x4E>(x); x += dppf<0x141>(x); return x; }
; __device__ __forceinline__ void phase_scan(CParams& p, LAS unsigned char* lds) {
;     ...
;                     for (int s16 = 0; s16 < 16; ++s16) {
;                         scan_ld(nxt, base + (g16 + s16 + 1) * 384, vb + (g16 + s16 + 1) * 384);
;                         f32x2 d = S[0] * cur.n0.lo; d = S[1] * cur.n0.hi + d; d = S[2] * cur.n1.lo + d; d = S[3] * cur.n1.hi + d;
;                         const float sa = reduce8(d.x + d.y);
;                         const f32x2 sa2 = (f32x2){sa, sa}, v2 = (f32x2){cur.v, cur.v};
;                         S[0] = S[0] * cur.w0.lo + (cur.b0.lo * sa2 + cur.k0.lo * v2);
;                         S[1] = S[1] * cur.w0.hi + (cur.b0.hi * sa2 + cur.k0.hi * v2);
;                         S[2] = S[2] * cur.w1.lo + (cur.b1.lo * sa2 + cur.k1.lo * v2);
;                         S[3] = S[3] * cur.w1.hi + (cur.b1.hi * sa2 + cur.k1.hi * v2);
;                         f32x2 e = S[0] * cur.r0.lo; e = S[1] * cur.r0.hi + e; e = S[2] * cur.r1.lo + e; e = S[3] * cur.r1.hi + e;
;                         yw[s16 * 256] = e.x + e.y;
;                         cur = nxt;
;                     }
	v_pk_mul_f32 v[84:85], v[32:33], v[64:65] op_sel_hi:[1,0]
	ds_read_b128 v[44:47], v97 offset:10240
	v_pk_fma_f32 v[84:85], v[34:35], v[64:65], v[84:85] op_sel:[0,1,0] op_sel_hi:[1,1,1]
	ds_read_b64 v[56:57], v98 offset:9216
	v_pk_fma_f32 v[84:85], v[36:37], v[66:67], v[84:85] op_sel_hi:[1,0,1]
	ds_read_b128 v[48:51], v97 offset:9728
	v_pk_fma_f32 v[84:85], v[38:39], v[66:67], v[84:85] op_sel:[0,1,0] op_sel_hi:[1,1,1]
	ds_read_b128 v[52:55], v97 offset:9472
	v_pk_mul_f32 v[94:95], v[32:33], v[60:61] op_sel_hi:[1,0]
	v_add_f32_dpp v84, v84, v84 quad_perm:[1,0,3,2] row_mask:0xf bank_mask:0xf bound_ctrl:1
	v_add_f32_dpp v85, v85, v85 quad_perm:[1,0,3,2] row_mask:0xf bank_mask:0xf bound_ctrl:1
	v_pk_fma_f32 v[94:95], v[34:35], v[60:61], v[94:95] op_sel:[0,1,0] op_sel_hi:[1,1,1]
	v_add_f32_dpp v84, v84, v84 quad_perm:[2,3,0,1] row_mask:0xf bank_mask:0xf bound_ctrl:1
	v_add_f32_dpp v85, v85, v85 quad_perm:[2,3,0,1] row_mask:0xf bank_mask:0xf bound_ctrl:1
	v_pk_fma_f32 v[94:95], v[36:37], v[62:63], v[94:95] op_sel_hi:[1,0,1]
	v_add_f32_dpp v84, v84, v84 row_half_mirror row_mask:0xf bank_mask:0xf bound_ctrl:1
	v_add_f32_dpp v85, v85, v85 row_half_mirror row_mask:0xf bank_mask:0xf bound_ctrl:1
	v_pk_fma_f32 v[94:95], v[38:39], v[62:63], v[94:95] op_sel:[0,1,0] op_sel_hi:[1,1,1]
	v_add_f32_dpp v84, v84, v84 row_mirror row_mask:0xf bank_mask:0xf bound_ctrl:1
	v_add_f32_dpp v85, v85, v85 row_mirror row_mask:0xf bank_mask:0xf bound_ctrl:1
	ds_read_b128 v[60:63], v97 offset:9216
	v_pk_mul_f32 v[86:87], v[84:85], v[68:69] op_sel_hi:[1,0]
	v_pk_mul_f32 v[88:89], v[84:85], v[68:69] op_sel:[0,1] op_sel_hi:[1,1]
	v_pk_mul_f32 v[90:91], v[84:85], v[70:71] op_sel_hi:[1,0]
	v_pk_mul_f32 v[92:93], v[84:85], v[70:71] op_sel:[0,1] op_sel_hi:[1,1]
	v_pk_fma_f32 v[86:87], v[58:59], v[72:73], v[86:87] op_sel_hi:[1,0,1]
	v_pk_fma_f32 v[88:89], v[58:59], v[72:73], v[88:89] op_sel:[0,1,0] op_sel_hi:[1,1,1]
	v_pk_fma_f32 v[90:91], v[58:59], v[74:75], v[90:91] op_sel_hi:[1,0,1]
	v_pk_fma_f32 v[92:93], v[58:59], v[74:75], v[92:93] op_sel:[0,1,0] op_sel_hi:[1,1,1]
	v_pk_fma_f32 v[32:33], v[32:33], v[76:77], v[86:87] op_sel_hi:[1,0,1]
	v_pk_fma_f32 v[34:35], v[34:35], v[76:77], v[88:89] op_sel:[0,1,0] op_sel_hi:[1,1,1]
	v_pk_fma_f32 v[36:37], v[36:37], v[78:79], v[90:91] op_sel_hi:[1,0,1]
	v_pk_fma_f32 v[38:39], v[38:39], v[78:79], v[92:93] op_sel:[0,1,0] op_sel_hi:[1,1,1]
	v_add_f32_dpp v94, v94, v94 quad_perm:[1,0,3,2] row_mask:0xf bank_mask:0xf bound_ctrl:1
	v_add_f32_dpp v95, v95, v95 quad_perm:[1,0,3,2] row_mask:0xf bank_mask:0xf bound_ctrl:1
	v_cndmask_b32_e32 v96, v94, v95, vcc
	ds_write_b32 v99, v96 offset:4096
	ds_read_b128 v[64:67], v97 offset:11520
	s_waitcnt lgkmcnt(3)
	v_pk_mul_f32 v[84:85], v[32:33], v[40:41] op_sel_hi:[1,0]
	ds_read_b128 v[68:71], v97 offset:11776
	v_pk_fma_f32 v[84:85], v[34:35], v[40:41], v[84:85] op_sel:[0,1,0] op_sel_hi:[1,1,1]
	ds_read_b64 v[58:59], v98 offset:10752
	v_pk_fma_f32 v[84:85], v[36:37], v[42:43], v[84:85] op_sel_hi:[1,0,1]
	ds_read_b128 v[72:75], v97 offset:11264
	v_pk_fma_f32 v[84:85], v[38:39], v[42:43], v[84:85] op_sel:[0,1,0] op_sel_hi:[1,1,1]
	ds_read_b128 v[76:79], v97 offset:11008
	v_pk_mul_f32 v[94:95], v[32:33], v[80:81] op_sel_hi:[1,0]
	v_add_f32_dpp v84, v84, v84 quad_perm:[1,0,3,2] row_mask:0xf bank_mask:0xf bound_ctrl:1
	v_add_f32_dpp v85, v85, v85 quad_perm:[1,0,3,2] row_mask:0xf bank_mask:0xf bound_ctrl:1
	v_pk_fma_f32 v[94:95], v[34:35], v[80:81], v[94:95] op_sel:[0,1,0] op_sel_hi:[1,1,1]
	v_add_f32_dpp v84, v84, v84 quad_perm:[2,3,0,1] row_mask:0xf bank_mask:0xf bound_ctrl:1
	v_add_f32_dpp v85, v85, v85 quad_perm:[2,3,0,1] row_mask:0xf bank_mask:0xf bound_ctrl:1
	v_pk_fma_f32 v[94:95], v[36:37], v[82:83], v[94:95] op_sel_hi:[1,0,1]
	v_add_f32_dpp v84, v84, v84 row_half_mirror row_mask:0xf bank_mask:0xf bound_ctrl:1
	v_add_f32_dpp v85, v85, v85 row_half_mirror row_mask:0xf bank_mask:0xf bound_ctrl:1
	v_pk_fma_f32 v[94:95], v[38:39], v[82:83], v[94:95] op_sel:[0,1,0] op_sel_hi:[1,1,1]
	v_add_f32_dpp v84, v84, v84 row_mirror row_mask:0xf bank_mask:0xf bound_ctrl:1
	v_add_f32_dpp v85, v85, v85 row_mirror row_mask:0xf bank_mask:0xf bound_ctrl:1
	ds_read_b128 v[80:83], v97 offset:10752
	v_pk_mul_f32 v[86:87], v[84:85], v[44:45] op_sel_hi:[1,0]
	v_pk_mul_f32 v[88:89], v[84:85], v[44:45] op_sel:[0,1] op_sel_hi:[1,1]
	v_pk_mul_f32 v[90:91], v[84:85], v[46:47] op_sel_hi:[1,0]
	v_pk_mul_f32 v[92:93], v[84:85], v[46:47] op_sel:[0,1] op_sel_hi:[1,1]
	v_pk_fma_f32 v[86:87], v[56:57], v[48:49], v[86:87] op_sel_hi:[1,0,1]
	v_pk_fma_f32 v[88:89], v[56:57], v[48:49], v[88:89] op_sel:[0,1,0] op_sel_hi:[1,1,1]
	v_pk_fma_f32 v[90:91], v[56:57], v[50:51], v[90:91] op_sel_hi:[1,0,1]
	v_pk_fma_f32 v[92:93], v[56:57], v[50:51], v[92:93] op_sel:[0,1,0] op_sel_hi:[1,1,1]
	v_pk_fma_f32 v[32:33], v[32:33], v[52:53], v[86:87] op_sel_hi:[1,0,1]
	v_pk_fma_f32 v[34:35], v[34:35], v[52:53], v[88:89] op_sel:[0,1,0] op_sel_hi:[1,1,1]
	v_pk_fma_f32 v[36:37], v[36:37], v[54:55], v[90:91] op_sel_hi:[1,0,1]
	v_pk_fma_f32 v[38:39], v[38:39], v[54:55], v[92:93] op_sel:[0,1,0] op_sel_hi:[1,1,1]
	v_add_f32_dpp v94, v94, v94 quad_perm:[1,0,3,2] row_mask:0xf bank_mask:0xf bound_ctrl:1
	v_add_f32_dpp v95, v95, v95 quad_perm:[1,0,3,2] row_mask:0xf bank_mask:0xf bound_ctrl:1
	v_cndmask_b32_e32 v96, v94, v95, vcc
	ds_write_b32 v99, v96 offset:5120
	ds_read_b128 v[40:43], v97 offset:13056
	s_waitcnt lgkmcnt(3)
; __device__ __forceinline__ float reduce8(float x) { x += dppf<0xB1>(x); x += dppf<0x4E>(x); x += dppf<0x141>(x); return x; }
; __device__ __forceinline__ void phase_scan(CParams& p, LAS unsigned char* lds) {
;     ...
;                     for (int s16 = 0; s16 < 16; ++s16) {
;                         scan_ld(nxt, base + (g16 + s16 + 1) * 384, vb + (g16 + s16 + 1) * 384);
;                         f32x2 d = S[0] * cur.n0.lo; d = S[1] * cur.n0.hi + d; d = S[2] * cur.n1.lo + d; d = S[3] * cur.n1.hi + d;
;                         const float sa = reduce8(d.x + d.y);
;                         const f32x2 sa2 = (f32x2){sa, sa}, v2 = (f32x2){cur.v, cur.v};
;                         S[0] = S[0] * cur.w0.lo + (cur.b0.lo * sa2 + cur.k0.lo * v2);
;                         S[1] = S[1] * cur.w0.hi + (cur.b0.hi * sa2 + cur.k0.hi * v2);
;                         S[2] = S[2] * cur.w1.lo + (cur.b1.lo * sa2 + cur.k1.lo * v2);
;                         S[3] = S[3] * cur.w1.hi + (cur.b1.hi * sa2 + cur.k1.hi * v2);
;                         f32x2 e = S[0] * cur.r0.lo; e = S[1] * cur.r0.hi + e; e = S[2] * cur.r1.lo + e; e = S[3] * cur.r1.hi + e;
;                         yw[s16 * 256] = e.x + e.y;
;                         cur = nxt;
;                     }
	v_pk_mul_f32 v[84:85], v[32:33], v[64:65] op_sel_hi:[1,0]
	ds_read_b128 v[44:47], v97 offset:13312
	v_pk_fma_f32 v[84:85], v[34:35], v[64:65], v[84:85] op_sel:[0,1,0] op_sel_hi:[1,1,1]
	ds_read_b64 v[56:57], v98 offset:12288
	v_pk_fma_f32 v[84:85], v[36:37], v[66:67], v[84:85] op_sel_hi:[1,0,1]
	ds_read_b128 v[48:51], v97 offset:12800
	v_pk_fma_f32 v[84:85], v[38:39], v[66:67], v[84:85] op_sel:[0,1,0] op_sel_hi:[1,1,1]
	ds_read_b128 v[52:55], v97 offset:12544
	v_pk_mul_f32 v[94:95], v[32:33], v[60:61] op_sel_hi:[1,0]
	v_add_f32_dpp v84, v84, v84 quad_perm:[1,0,3,2] row_mask:0xf bank_mask:0xf bound_ctrl:1
	v_add_f32_dpp v85, v85, v85 quad_perm:[1,0,3,2] row_mask:0xf bank_mask:0xf bound_ctrl:1
	v_pk_fma_f32 v[94:95], v[34:35], v[60:61], v[94:95] op_sel:[0,1,0] op_sel_hi:[1,1,1]
	v_add_f32_dpp v84, v84, v84 quad_perm:[2,3,0,1] row_mask:0xf bank_mask:0xf bound_ctrl:1
	v_add_f32_dpp v85, v85, v85 quad_perm:[2,3,0,1] row_mask:0xf bank_mask:0xf bound_ctrl:1
	v_pk_fma_f32 v[94:95], v[36:37], v[62:63], v[94:95] op_sel_hi:[1,0,1]
	v_add_f32_dpp v84, v84, v84 row_half_mirror row_mask:0xf bank_mask:0xf bound_ctrl:1
	v_add_f32_dpp v85, v85, v85 row_half_mirror row_mask:0xf bank_mask:0xf bound_ctrl:1
	v_pk_fma_f32 v[94:95], v[38:39], v[62:63], v[94:95] op_sel:[0,1,0] op_sel_hi:[1,1,1]
	v_add_f32_dpp v84, v84, v84 row_mirror row_mask:0xf bank_mask:0xf bound_ctrl:1
	v_add_f32_dpp v85, v85, v85 row_mirror row_mask:0xf bank_mask:0xf bound_ctrl:1
	ds_read_b128 v[60:63], v97 offset:12288
	v_pk_mul_f32 v[86:87], v[84:85], v[68:69] op_sel_hi:[1,0]
	v_pk_mul_f32 v[88:89], v[84:85], v[68:69] op_sel:[0,1] op_sel_hi:[1,1]
	v_pk_mul_f32 v[90:91], v[84:85], v[70:71] op_sel_hi:[1,0]
	v_pk_mul_f32 v[92:93], v[84:85], v[70:71] op_sel:[0,1] op_sel_hi:[1,1]
	v_pk_fma_f32 v[86:87], v[58:59], v[72:73], v[86:87] op_sel_hi:[1,0,1]
	v_pk_fma_f32 v[88:89], v[58:59], v[72:73], v[88:89] op_sel:[0,1,0] op_sel_hi:[1,1,1]
	v_pk_fma_f32 v[90:91], v[58:59], v[74:75], v[90:91] op_sel_hi:[1,0,1]
	v_pk_fma_f32 v[92:93], v[58:59], v[74:75], v[92:93] op_sel:[0,1,0] op_sel_hi:[1,1,1]
	v_pk_fma_f32 v[32:33], v[32:33], v[76:77], v[86:87] op_sel_hi:[1,0,1]
	v_pk_fma_f32 v[34:35], v[34:35], v[76:77], v[88:89] op_sel:[0,1,0] op_sel_hi:[1,1,1]
	v_pk_fma_f32 v[36:37], v[36:37], v[78:79], v[90:91] op_sel_hi:[1,0,1]
	v_pk_fma_f32 v[38:39], v[38:39], v[78:79], v[92:93] op_sel:[0,1,0] op_sel_hi:[1,1,1]
	v_add_f32_dpp v94, v94, v94 quad_perm:[1,0,3,2] row_mask:0xf bank_mask:0xf bound_ctrl:1
	v_add_f32_dpp v95, v95, v95 quad_perm:[1,0,3,2] row_mask:0xf bank_mask:0xf bound_ctrl:1
	v_cndmask_b32_e32 v96, v94, v95, vcc
	ds_write_b32 v99, v96 offset:6144
	ds_read_b128 v[64:67], v97 offset:14592
	s_waitcnt lgkmcnt(3)
	v_pk_mul_f32 v[84:85], v[32:33], v[40:41] op_sel_hi:[1,0]
	ds_read_b128 v[68:71], v97 offset:14848
	v_pk_fma_f32 v[84:85], v[34:35], v[40:41], v[84:85] op_sel:[0,1,0] op_sel_hi:[1,1,1]
	ds_read_b64 v[58:59], v98 offset:13824
	v_pk_fma_f32 v[84:85], v[36:37], v[42:43], v[84:85] op_sel_hi:[1,0,1]
	ds_read_b128 v[72:75], v97 offset:14336
	v_pk_fma_f32 v[84:85], v[38:39], v[42:43], v[84:85] op_sel:[0,1,0] op_sel_hi:[1,1,1]
	ds_read_b128 v[76:79], v97 offset:14080
	v_pk_mul_f32 v[94:95], v[32:33], v[80:81] op_sel_hi:[1,0]
	v_add_f32_dpp v84, v84, v84 quad_perm:[1,0,3,2] row_mask:0xf bank_mask:0xf bound_ctrl:1
	v_add_f32_dpp v85, v85, v85 quad_perm:[1,0,3,2] row_mask:0xf bank_mask:0xf bound_ctrl:1
	v_pk_fma_f32 v[94:95], v[34:35], v[80:81], v[94:95] op_sel:[0,1,0] op_sel_hi:[1,1,1]
	v_add_f32_dpp v84, v84, v84 quad_perm:[2,3,0,1] row_mask:0xf bank_mask:0xf bound_ctrl:1
	v_add_f32_dpp v85, v85, v85 quad_perm:[2,3,0,1] row_mask:0xf bank_mask:0xf bound_ctrl:1
	v_pk_fma_f32 v[94:95], v[36:37], v[82:83], v[94:95] op_sel_hi:[1,0,1]
	v_add_f32_dpp v84, v84, v84 row_half_mirror row_mask:0xf bank_mask:0xf bound_ctrl:1
	v_add_f32_dpp v85, v85, v85 row_half_mirror row_mask:0xf bank_mask:0xf bound_ctrl:1
	v_pk_fma_f32 v[94:95], v[38:39], v[82:83], v[94:95] op_sel:[0,1,0] op_sel_hi:[1,1,1]
	v_add_f32_dpp v84, v84, v84 row_mirror row_mask:0xf bank_mask:0xf bound_ctrl:1
	v_add_f32_dpp v85, v85, v85 row_mirror row_mask:0xf bank_mask:0xf bound_ctrl:1
	ds_read_b128 v[80:83], v97 offset:13824
	v_pk_mul_f32 v[86:87], v[84:85], v[44:45] op_sel_hi:[1,0]
	v_pk_mul_f32 v[88:89], v[84:85], v[44:45] op_sel:[0,1] op_sel_hi:[1,1]
	v_pk_mul_f32 v[90:91], v[84:85], v[46:47] op_sel_hi:[1,0]
	v_pk_mul_f32 v[92:93], v[84:85], v[46:47] op_sel:[0,1] op_sel_hi:[1,1]
	v_pk_fma_f32 v[86:87], v[56:57], v[48:49], v[86:87] op_sel_hi:[1,0,1]
	v_pk_fma_f32 v[88:89], v[56:57], v[48:49], v[88:89] op_sel:[0,1,0] op_sel_hi:[1,1,1]
	v_pk_fma_f32 v[90:91], v[56:57], v[50:51], v[90:91] op_sel_hi:[1,0,1]
	v_pk_fma_f32 v[92:93], v[56:57], v[50:51], v[92:93] op_sel:[0,1,0] op_sel_hi:[1,1,1]
	v_pk_fma_f32 v[32:33], v[32:33], v[52:53], v[86:87] op_sel_hi:[1,0,1]
	v_pk_fma_f32 v[34:35], v[34:35], v[52:53], v[88:89] op_sel:[0,1,0] op_sel_hi:[1,1,1]
	v_pk_fma_f32 v[36:37], v[36:37], v[54:55], v[90:91] op_sel_hi:[1,0,1]
	v_pk_fma_f32 v[38:39], v[38:39], v[54:55], v[92:93] op_sel:[0,1,0] op_sel_hi:[1,1,1]
	v_add_f32_dpp v94, v94, v94 quad_perm:[1,0,3,2] row_mask:0xf bank_mask:0xf bound_ctrl:1
	v_add_f32_dpp v95, v95, v95 quad_perm:[1,0,3,2] row_mask:0xf bank_mask:0xf bound_ctrl:1
	v_cndmask_b32_e32 v96, v94, v95, vcc
	ds_write_b32 v99, v96 offset:7168
	ds_read_b128 v[40:43], v97 offset:16128
	s_waitcnt lgkmcnt(3)
; __device__ __forceinline__ float reduce8(float x) { x += dppf<0xB1>(x); x += dppf<0x4E>(x); x += dppf<0x141>(x); return x; }
; __device__ __forceinline__ void phase_scan(CParams& p, LAS unsigned char* lds) {
;     ...
;                     for (int s16 = 0; s16 < 16; ++s16) {
;                         scan_ld(nxt, base + (g16 + s16 + 1) * 384, vb + (g16 + s16 + 1) * 384);
;                         f32x2 d = S[0] * cur.n0.lo; d = S[1] * cur.n0.hi + d; d = S[2] * cur.n1.lo + d; d = S[3] * cur.n1.hi + d;
;                         const float sa = reduce8(d.x + d.y);
;                         const f32x2 sa2 = (f32x2){sa, sa}, v2 = (f32x2){cur.v, cur.v};
;                         S[0] = S[0] * cur.w0.lo + (cur.b0.lo * sa2 + cur.k0.lo * v2);
;                         S[1] = S[1] * cur.w0.hi + (cur.b0.hi * sa2 + cur.k0.hi * v2);
;                         S[2] = S[2] * cur.w1.lo + (cur.b1.lo * sa2 + cur.k1.lo * v2);
;                         S[3] = S[3] * cur.w1.hi + (cur.b1.hi * sa2 + cur.k1.hi * v2);
;                         f32x2 e = S[0] * cur.r0.lo; e = S[1] * cur.r0.hi + e; e = S[2] * cur.r1.lo + e; e = S[3] * cur.r1.hi + e;
;                         yw[s16 * 256] = e.x + e.y;
;                         cur = nxt;
;                     }
	v_pk_mul_f32 v[84:85], v[32:33], v[64:65] op_sel_hi:[1,0]
	ds_read_b128 v[44:47], v97 offset:16384
	v_pk_fma_f32 v[84:85], v[34:35], v[64:65], v[84:85] op_sel:[0,1,0] op_sel_hi:[1,1,1]
	ds_read_b64 v[56:57], v98 offset:15360
	v_pk_fma_f32 v[84:85], v[36:37], v[66:67], v[84:85] op_sel_hi:[1,0,1]
	ds_read_b128 v[48:51], v97 offset:15872
	v_pk_fma_f32 v[84:85], v[38:39], v[66:67], v[84:85] op_sel:[0,1,0] op_sel_hi:[1,1,1]
	ds_read_b128 v[52:55], v97 offset:15616
	v_pk_mul_f32 v[94:95], v[32:33], v[60:61] op_sel_hi:[1,0]
	v_add_f32_dpp v84, v84, v84 quad_perm:[1,0,3,2] row_mask:0xf bank_mask:0xf bound_ctrl:1
	v_add_f32_dpp v85, v85, v85 quad_perm:[1,0,3,2] row_mask:0xf bank_mask:0xf bound_ctrl:1
	v_pk_fma_f32 v[94:95], v[34:35], v[60:61], v[94:95] op_sel:[0,1,0] op_sel_hi:[1,1,1]
	v_add_f32_dpp v84, v84, v84 quad_perm:[2,3,0,1] row_mask:0xf bank_mask:0xf bound_ctrl:1
	v_add_f32_dpp v85, v85, v85 quad_perm:[2,3,0,1] row_mask:0xf bank_mask:0xf bound_ctrl:1
	v_pk_fma_f32 v[94:95], v[36:37], v[62:63], v[94:95] op_sel_hi:[1,0,1]
	v_add_f32_dpp v84, v84, v84 row_half_mirror row_mask:0xf bank_mask:0xf bound_ctrl:1
	v_add_f32_dpp v85, v85, v85 row_half_mirror row_mask:0xf bank_mask:0xf bound_ctrl:1
	v_pk_fma_f32 v[94:95], v[38:39], v[62:63], v[94:95] op_sel:[0,1,0] op_sel_hi:[1,1,1]
	v_add_f32_dpp v84, v84, v84 row_mirror row_mask:0xf bank_mask:0xf bound_ctrl:1
	v_add_f32_dpp v85, v85, v85 row_mirror row_mask:0xf bank_mask:0xf bound_ctrl:1
	ds_read_b128 v[60:63], v97 offset:15360
	v_pk_mul_f32 v[86:87], v[84:85], v[68:69] op_sel_hi:[1,0]
	v_pk_mul_f32 v[88:89], v[84:85], v[68:69] op_sel:[0,1] op_sel_hi:[1,1]
	v_pk_mul_f32 v[90:91], v[84:85], v[70:71] op_sel_hi:[1,0]
	v_pk_mul_f32 v[92:93], v[84:85], v[70:71] op_sel:[0,1] op_sel_hi:[1,1]
	v_pk_fma_f32 v[86:87], v[58:59], v[72:73], v[86:87] op_sel_hi:[1,0,1]
	v_pk_fma_f32 v[88:89], v[58:59], v[72:73], v[88:89] op_sel:[0,1,0] op_sel_hi:[1,1,1]
	v_pk_fma_f32 v[90:91], v[58:59], v[74:75], v[90:91] op_sel_hi:[1,0,1]
	v_pk_fma_f32 v[92:93], v[58:59], v[74:75], v[92:93] op_sel:[0,1,0] op_sel_hi:[1,1,1]
	v_pk_fma_f32 v[32:33], v[32:33], v[76:77], v[86:87] op_sel_hi:[1,0,1]
	v_pk_fma_f32 v[34:35], v[34:35], v[76:77], v[88:89] op_sel:[0,1,0] op_sel_hi:[1,1,1]
	v_pk_fma_f32 v[36:37], v[36:37], v[78:79], v[90:91] op_sel_hi:[1,0,1]
	v_pk_fma_f32 v[38:39], v[38:39], v[78:79], v[92:93] op_sel:[0,1,0] op_sel_hi:[1,1,1]
	v_add_f32_dpp v94, v94, v94 quad_perm:[1,0,3,2] row_mask:0xf bank_mask:0xf bound_ctrl:1
	v_add_f32_dpp v95, v95, v95 quad_perm:[1,0,3,2] row_mask:0xf bank_mask:0xf bound_ctrl:1
	v_cndmask_b32_e32 v96, v94, v95, vcc
	ds_write_b32 v99, v96 offset:8192
	ds_read_b128 v[64:67], v97 offset:17664
	s_waitcnt lgkmcnt(3)
	v_pk_mul_f32 v[84:85], v[32:33], v[40:41] op_sel_hi:[1,0]
	ds_read_b128 v[68:71], v97 offset:17920
	v_pk_fma_f32 v[84:85], v[34:35], v[40:41], v[84:85] op_sel:[0,1,0] op_sel_hi:[1,1,1]
	ds_read_b64 v[58:59], v98 offset:16896
	v_pk_fma_f32 v[84:85], v[36:37], v[42:43], v[84:85] op_sel_hi:[1,0,1]
	ds_read_b128 v[72:75], v97 offset:17408
	v_pk_fma_f32 v[84:85], v[38:39], v[42:43], v[84:85] op_sel:[0,1,0] op_sel_hi:[1,1,1]
	ds_read_b128 v[76:79], v97 offset:17152
	v_pk_mul_f32 v[94:95], v[32:33], v[80:81] op_sel_hi:[1,0]
	v_add_f32_dpp v84, v84, v84 quad_perm:[1,0,3,2] row_mask:0xf bank_mask:0xf bound_ctrl:1
	v_add_f32_dpp v85, v85, v85 quad_perm:[1,0,3,2] row_mask:0xf bank_mask:0xf bound_ctrl:1
	v_pk_fma_f32 v[94:95], v[34:35], v[80:81], v[94:95] op_sel:[0,1,0] op_sel_hi:[1,1,1]
	v_add_f32_dpp v84, v84, v84 quad_perm:[2,3,0,1] row_mask:0xf bank_mask:0xf bound_ctrl:1
	v_add_f32_dpp v85, v85, v85 quad_perm:[2,3,0,1] row_mask:0xf bank_mask:0xf bound_ctrl:1
	v_pk_fma_f32 v[94:95], v[36:37], v[82:83], v[94:95] op_sel_hi:[1,0,1]
	v_add_f32_dpp v84, v84, v84 row_half_mirror row_mask:0xf bank_mask:0xf bound_ctrl:1
	v_add_f32_dpp v85, v85, v85 row_half_mirror row_mask:0xf bank_mask:0xf bound_ctrl:1
	v_pk_fma_f32 v[94:95], v[38:39], v[82:83], v[94:95] op_sel:[0,1,0] op_sel_hi:[1,1,1]
	v_add_f32_dpp v84, v84, v84 row_mirror row_mask:0xf bank_mask:0xf bound_ctrl:1
	v_add_f32_dpp v85, v85, v85 row_mirror row_mask:0xf bank_mask:0xf bound_ctrl:1
	ds_read_b128 v[80:83], v97 offset:16896
	v_pk_mul_f32 v[86:87], v[84:85], v[44:45] op_sel_hi:[1,0]
	v_pk_mul_f32 v[88:89], v[84:85], v[44:45] op_sel:[0,1] op_sel_hi:[1,1]
	v_pk_mul_f32 v[90:91], v[84:85], v[46:47] op_sel_hi:[1,0]
	v_pk_mul_f32 v[92:93], v[84:85], v[46:47] op_sel:[0,1] op_sel_hi:[1,1]
	v_pk_fma_f32 v[86:87], v[56:57], v[48:49], v[86:87] op_sel_hi:[1,0,1]
	v_pk_fma_f32 v[88:89], v[56:57], v[48:49], v[88:89] op_sel:[0,1,0] op_sel_hi:[1,1,1]
	v_pk_fma_f32 v[90:91], v[56:57], v[50:51], v[90:91] op_sel_hi:[1,0,1]
	v_pk_fma_f32 v[92:93], v[56:57], v[50:51], v[92:93] op_sel:[0,1,0] op_sel_hi:[1,1,1]
	v_pk_fma_f32 v[32:33], v[32:33], v[52:53], v[86:87] op_sel_hi:[1,0,1]
	v_pk_fma_f32 v[34:35], v[34:35], v[52:53], v[88:89] op_sel:[0,1,0] op_sel_hi:[1,1,1]
	v_pk_fma_f32 v[36:37], v[36:37], v[54:55], v[90:91] op_sel_hi:[1,0,1]
	v_pk_fma_f32 v[38:39], v[38:39], v[54:55], v[92:93] op_sel:[0,1,0] op_sel_hi:[1,1,1]
	v_add_f32_dpp v94, v94, v94 quad_perm:[1,0,3,2] row_mask:0xf bank_mask:0xf bound_ctrl:1
	v_add_f32_dpp v95, v95, v95 quad_perm:[1,0,3,2] row_mask:0xf bank_mask:0xf bound_ctrl:1
	v_cndmask_b32_e32 v96, v94, v95, vcc
	ds_write_b32 v99, v96 offset:9216
	ds_read_b128 v[40:43], v97 offset:19200
	s_waitcnt lgkmcnt(3)
; __device__ __forceinline__ float reduce8(float x) { x += dppf<0xB1>(x); x += dppf<0x4E>(x); x += dppf<0x141>(x); return x; }
; __device__ __forceinline__ void phase_scan(CParams& p, LAS unsigned char* lds) {
;     ...
;                     for (int s16 = 0; s16 < 16; ++s16) {
;                         scan_ld(nxt, base + (g16 + s16 + 1) * 384, vb + (g16 + s16 + 1) * 384);
;                         f32x2 d = S[0] * cur.n0.lo; d = S[1] * cur.n0.hi + d; d = S[2] * cur.n1.lo + d; d = S[3] * cur.n1.hi + d;
;                         const float sa = reduce8(d.x + d.y);
;                         const f32x2 sa2 = (f32x2){sa, sa}, v2 = (f32x2){cur.v, cur.v};
;                         S[0] = S[0] * cur.w0.lo + (cur.b0.lo * sa2 + cur.k0.lo * v2);
;                         S[1] = S[1] * cur.w0.hi + (cur.b0.hi * sa2 + cur.k0.hi * v2);
;                         S[2] = S[2] * cur.w1.lo + (cur.b1.lo * sa2 + cur.k1.lo * v2);
;                         S[3] = S[3] * cur.w1.hi + (cur.b1.hi * sa2 + cur.k1.hi * v2);
;                         f32x2 e = S[0] * cur.r0.lo; e = S[1] * cur.r0.hi + e; e = S[2] * cur.r1.lo + e; e = S[3] * cur.r1.hi + e;
;                         yw[s16 * 256] = e.x + e.y;
;                         cur = nxt;
;                     }
	v_pk_mul_f32 v[84:85], v[32:33], v[64:65] op_sel_hi:[1,0]
	ds_read_b128 v[44:47], v97 offset:19456
	v_pk_fma_f32 v[84:85], v[34:35], v[64:65], v[84:85] op_sel:[0,1,0] op_sel_hi:[1,1,1]
	ds_read_b64 v[56:57], v98 offset:18432
	v_pk_fma_f32 v[84:85], v[36:37], v[66:67], v[84:85] op_sel_hi:[1,0,1]
	ds_read_b128 v[48:51], v97 offset:18944
	v_pk_fma_f32 v[84:85], v[38:39], v[66:67], v[84:85] op_sel:[0,1,0] op_sel_hi:[1,1,1]
	ds_read_b128 v[52:55], v97 offset:18688
	v_pk_mul_f32 v[94:95], v[32:33], v[60:61] op_sel_hi:[1,0]
	v_add_f32_dpp v84, v84, v84 quad_perm:[1,0,3,2] row_mask:0xf bank_mask:0xf bound_ctrl:1
	v_add_f32_dpp v85, v85, v85 quad_perm:[1,0,3,2] row_mask:0xf bank_mask:0xf bound_ctrl:1
	v_pk_fma_f32 v[94:95], v[34:35], v[60:61], v[94:95] op_sel:[0,1,0] op_sel_hi:[1,1,1]
	v_add_f32_dpp v84, v84, v84 quad_perm:[2,3,0,1] row_mask:0xf bank_mask:0xf bound_ctrl:1
	v_add_f32_dpp v85, v85, v85 quad_perm:[2,3,0,1] row_mask:0xf bank_mask:0xf bound_ctrl:1
	v_pk_fma_f32 v[94:95], v[36:37], v[62:63], v[94:95] op_sel_hi:[1,0,1]
	v_add_f32_dpp v84, v84, v84 row_half_mirror row_mask:0xf bank_mask:0xf bound_ctrl:1
	v_add_f32_dpp v85, v85, v85 row_half_mirror row_mask:0xf bank_mask:0xf bound_ctrl:1
	v_pk_fma_f32 v[94:95], v[38:39], v[62:63], v[94:95] op_sel:[0,1,0] op_sel_hi:[1,1,1]
	v_add_f32_dpp v84, v84, v84 row_mirror row_mask:0xf bank_mask:0xf bound_ctrl:1
	v_add_f32_dpp v85, v85, v85 row_mirror row_mask:0xf bank_mask:0xf bound_ctrl:1
	ds_read_b128 v[60:63], v97 offset:18432
	v_pk_mul_f32 v[86:87], v[84:85], v[68:69] op_sel_hi:[1,0]
	v_pk_mul_f32 v[88:89], v[84:85], v[68:69] op_sel:[0,1] op_sel_hi:[1,1]
	v_pk_mul_f32 v[90:91], v[84:85], v[70:71] op_sel_hi:[1,0]
	v_pk_mul_f32 v[92:93], v[84:85], v[70:71] op_sel:[0,1] op_sel_hi:[1,1]
	v_pk_fma_f32 v[86:87], v[58:59], v[72:73], v[86:87] op_sel_hi:[1,0,1]
	v_pk_fma_f32 v[88:89], v[58:59], v[72:73], v[88:89] op_sel:[0,1,0] op_sel_hi:[1,1,1]
	v_pk_fma_f32 v[90:91], v[58:59], v[74:75], v[90:91] op_sel_hi:[1,0,1]
	v_pk_fma_f32 v[92:93], v[58:59], v[74:75], v[92:93] op_sel:[0,1,0] op_sel_hi:[1,1,1]
	v_pk_fma_f32 v[32:33], v[32:33], v[76:77], v[86:87] op_sel_hi:[1,0,1]
	v_pk_fma_f32 v[34:35], v[34:35], v[76:77], v[88:89] op_sel:[0,1,0] op_sel_hi:[1,1,1]
	v_pk_fma_f32 v[36:37], v[36:37], v[78:79], v[90:91] op_sel_hi:[1,0,1]
	v_pk_fma_f32 v[38:39], v[38:39], v[78:79], v[92:93] op_sel:[0,1,0] op_sel_hi:[1,1,1]
	v_add_f32_dpp v94, v94, v94 quad_perm:[1,0,3,2] row_mask:0xf bank_mask:0xf bound_ctrl:1
	v_add_f32_dpp v95, v95, v95 quad_perm:[1,0,3,2] row_mask:0xf bank_mask:0xf bound_ctrl:1
	v_cndmask_b32_e32 v96, v94, v95, vcc
	ds_write_b32 v99, v96 offset:10240
	ds_read_b128 v[64:67], v97 offset:20736
	s_waitcnt lgkmcnt(3)
	v_pk_mul_f32 v[84:85], v[32:33], v[40:41] op_sel_hi:[1,0]
	ds_read_b128 v[68:71], v97 offset:20992
	v_pk_fma_f32 v[84:85], v[34:35], v[40:41], v[84:85] op_sel:[0,1,0] op_sel_hi:[1,1,1]
	ds_read_b64 v[58:59], v98 offset:19968
	v_pk_fma_f32 v[84:85], v[36:37], v[42:43], v[84:85] op_sel_hi:[1,0,1]
	ds_read_b128 v[72:75], v97 offset:20480
	v_pk_fma_f32 v[84:85], v[38:39], v[42:43], v[84:85] op_sel:[0,1,0] op_sel_hi:[1,1,1]
	ds_read_b128 v[76:79], v97 offset:20224
	v_pk_mul_f32 v[94:95], v[32:33], v[80:81] op_sel_hi:[1,0]
	v_add_f32_dpp v84, v84, v84 quad_perm:[1,0,3,2] row_mask:0xf bank_mask:0xf bound_ctrl:1
	v_add_f32_dpp v85, v85, v85 quad_perm:[1,0,3,2] row_mask:0xf bank_mask:0xf bound_ctrl:1
	v_pk_fma_f32 v[94:95], v[34:35], v[80:81], v[94:95] op_sel:[0,1,0] op_sel_hi:[1,1,1]
	v_add_f32_dpp v84, v84, v84 quad_perm:[2,3,0,1] row_mask:0xf bank_mask:0xf bound_ctrl:1
	v_add_f32_dpp v85, v85, v85 quad_perm:[2,3,0,1] row_mask:0xf bank_mask:0xf bound_ctrl:1
	v_pk_fma_f32 v[94:95], v[36:37], v[82:83], v[94:95] op_sel_hi:[1,0,1]
	v_add_f32_dpp v84, v84, v84 row_half_mirror row_mask:0xf bank_mask:0xf bound_ctrl:1
	v_add_f32_dpp v85, v85, v85 row_half_mirror row_mask:0xf bank_mask:0xf bound_ctrl:1
	v_pk_fma_f32 v[94:95], v[38:39], v[82:83], v[94:95] op_sel:[0,1,0] op_sel_hi:[1,1,1]
	v_add_f32_dpp v84, v84, v84 row_mirror row_mask:0xf bank_mask:0xf bound_ctrl:1
	v_add_f32_dpp v85, v85, v85 row_mirror row_mask:0xf bank_mask:0xf bound_ctrl:1
	ds_read_b128 v[80:83], v97 offset:19968
	v_pk_mul_f32 v[86:87], v[84:85], v[44:45] op_sel_hi:[1,0]
	v_pk_mul_f32 v[88:89], v[84:85], v[44:45] op_sel:[0,1] op_sel_hi:[1,1]
	v_pk_mul_f32 v[90:91], v[84:85], v[46:47] op_sel_hi:[1,0]
	v_pk_mul_f32 v[92:93], v[84:85], v[46:47] op_sel:[0,1] op_sel_hi:[1,1]
	v_pk_fma_f32 v[86:87], v[56:57], v[48:49], v[86:87] op_sel_hi:[1,0,1]
	v_pk_fma_f32 v[88:89], v[56:57], v[48:49], v[88:89] op_sel:[0,1,0] op_sel_hi:[1,1,1]
	v_pk_fma_f32 v[90:91], v[56:57], v[50:51], v[90:91] op_sel_hi:[1,0,1]
	v_pk_fma_f32 v[92:93], v[56:57], v[50:51], v[92:93] op_sel:[0,1,0] op_sel_hi:[1,1,1]
	v_pk_fma_f32 v[32:33], v[32:33], v[52:53], v[86:87] op_sel_hi:[1,0,1]
	v_pk_fma_f32 v[34:35], v[34:35], v[52:53], v[88:89] op_sel:[0,1,0] op_sel_hi:[1,1,1]
	v_pk_fma_f32 v[36:37], v[36:37], v[54:55], v[90:91] op_sel_hi:[1,0,1]
	v_pk_fma_f32 v[38:39], v[38:39], v[54:55], v[92:93] op_sel:[0,1,0] op_sel_hi:[1,1,1]
	v_add_f32_dpp v94, v94, v94 quad_perm:[1,0,3,2] row_mask:0xf bank_mask:0xf bound_ctrl:1
	v_add_f32_dpp v95, v95, v95 quad_perm:[1,0,3,2] row_mask:0xf bank_mask:0xf bound_ctrl:1
	v_cndmask_b32_e32 v96, v94, v95, vcc
	ds_write_b32 v99, v96 offset:11264
	ds_read_b128 v[40:43], v97 offset:22272
	s_waitcnt lgkmcnt(3)
; __device__ __forceinline__ float reduce8(float x) { x += dppf<0xB1>(x); x += dppf<0x4E>(x); x += dppf<0x141>(x); return x; }
; __device__ __forceinline__ void phase_scan(CParams& p, LAS unsigned char* lds) {
;     ...
;                     for (int s16 = 0; s16 < 16; ++s16) {
;                         scan_ld(nxt, base + (g16 + s16 + 1) * 384, vb + (g16 + s16 + 1) * 384);
;                         f32x2 d = S[0] * cur.n0.lo; d = S[1] * cur.n0.hi + d; d = S[2] * cur.n1.lo + d; d = S[3] * cur.n1.hi + d;
;                         const float sa = reduce8(d.x + d.y);
;                         const f32x2 sa2 = (f32x2){sa, sa}, v2 = (f32x2){cur.v, cur.v};
;                         S[0] = S[0] * cur.w0.lo + (cur.b0.lo * sa2 + cur.k0.lo * v2);
;                         S[1] = S[1] * cur.w0.hi + (cur.b0.hi * sa2 + cur.k0.hi * v2);
;                         S[2] = S[2] * cur.w1.lo + (cur.b1.lo * sa2 + cur.k1.lo * v2);
;                         S[3] = S[3] * cur.w1.hi + (cur.b1.hi * sa2 + cur.k1.hi * v2);
;                         f32x2 e = S[0] * cur.r0.lo; e = S[1] * cur.r0.hi + e; e = S[2] * cur.r1.lo + e; e = S[3] * cur.r1.hi + e;
;                         yw[s16 * 256] = e.x + e.y;
;                         cur = nxt;
;                     }
	v_pk_mul_f32 v[84:85], v[32:33], v[64:65] op_sel_hi:[1,0]
	ds_read_b128 v[44:47], v97 offset:22528
	v_pk_fma_f32 v[84:85], v[34:35], v[64:65], v[84:85] op_sel:[0,1,0] op_sel_hi:[1,1,1]
	ds_read_b64 v[56:57], v98 offset:21504
	v_pk_fma_f32 v[84:85], v[36:37], v[66:67], v[84:85] op_sel_hi:[1,0,1]
	ds_read_b128 v[48:51], v97 offset:22016
	v_pk_fma_f32 v[84:85], v[38:39], v[66:67], v[84:85] op_sel:[0,1,0] op_sel_hi:[1,1,1]
	ds_read_b128 v[52:55], v97 offset:21760
	v_pk_mul_f32 v[94:95], v[32:33], v[60:61] op_sel_hi:[1,0]
	v_add_f32_dpp v84, v84, v84 quad_perm:[1,0,3,2] row_mask:0xf bank_mask:0xf bound_ctrl:1
	v_add_f32_dpp v85, v85, v85 quad_perm:[1,0,3,2] row_mask:0xf bank_mask:0xf bound_ctrl:1
	v_pk_fma_f32 v[94:95], v[34:35], v[60:61], v[94:95] op_sel:[0,1,0] op_sel_hi:[1,1,1]
	v_add_f32_dpp v84, v84, v84 quad_perm:[2,3,0,1] row_mask:0xf bank_mask:0xf bound_ctrl:1
	v_add_f32_dpp v85, v85, v85 quad_perm:[2,3,0,1] row_mask:0xf bank_mask:0xf bound_ctrl:1
	v_pk_fma_f32 v[94:95], v[36:37], v[62:63], v[94:95] op_sel_hi:[1,0,1]
	v_add_f32_dpp v84, v84, v84 row_half_mirror row_mask:0xf bank_mask:0xf bound_ctrl:1
	v_add_f32_dpp v85, v85, v85 row_half_mirror row_mask:0xf bank_mask:0xf bound_ctrl:1
	v_pk_fma_f32 v[94:95], v[38:39], v[62:63], v[94:95] op_sel:[0,1,0] op_sel_hi:[1,1,1]
	v_add_f32_dpp v84, v84, v84 row_mirror row_mask:0xf bank_mask:0xf bound_ctrl:1
	v_add_f32_dpp v85, v85, v85 row_mirror row_mask:0xf bank_mask:0xf bound_ctrl:1
	ds_read_b128 v[60:63], v97 offset:21504
	v_pk_mul_f32 v[86:87], v[84:85], v[68:69] op_sel_hi:[1,0]
	v_pk_mul_f32 v[88:89], v[84:85], v[68:69] op_sel:[0,1] op_sel_hi:[1,1]
	v_pk_mul_f32 v[90:91], v[84:85], v[70:71] op_sel_hi:[1,0]
	v_pk_mul_f32 v[92:93], v[84:85], v[70:71] op_sel:[0,1] op_sel_hi:[1,1]
	v_pk_fma_f32 v[86:87], v[58:59], v[72:73], v[86:87] op_sel_hi:[1,0,1]
	v_pk_fma_f32 v[88:89], v[58:59], v[72:73], v[88:89] op_sel:[0,1,0] op_sel_hi:[1,1,1]
	v_pk_fma_f32 v[90:91], v[58:59], v[74:75], v[90:91] op_sel_hi:[1,0,1]
	v_pk_fma_f32 v[92:93], v[58:59], v[74:75], v[92:93] op_sel:[0,1,0] op_sel_hi:[1,1,1]
	v_pk_fma_f32 v[32:33], v[32:33], v[76:77], v[86:87] op_sel_hi:[1,0,1]
	v_pk_fma_f32 v[34:35], v[34:35], v[76:77], v[88:89] op_sel:[0,1,0] op_sel_hi:[1,1,1]
	v_pk_fma_f32 v[36:37], v[36:37], v[78:79], v[90:91] op_sel_hi:[1,0,1]
	v_pk_fma_f32 v[38:39], v[38:39], v[78:79], v[92:93] op_sel:[0,1,0] op_sel_hi:[1,1,1]
	v_add_f32_dpp v94, v94, v94 quad_perm:[1,0,3,2] row_mask:0xf bank_mask:0xf bound_ctrl:1
	v_add_f32_dpp v95, v95, v95 quad_perm:[1,0,3,2] row_mask:0xf bank_mask:0xf bound_ctrl:1
	v_cndmask_b32_e32 v96, v94, v95, vcc
	ds_write_b32 v99, v96 offset:12288
	ds_read_b128 v[64:67], v97 offset:23808
	s_waitcnt lgkmcnt(3)
	v_pk_mul_f32 v[84:85], v[32:33], v[40:41] op_sel_hi:[1,0]
	ds_read_b128 v[68:71], v97 offset:24064
	v_pk_fma_f32 v[84:85], v[34:35], v[40:41], v[84:85] op_sel:[0,1,0] op_sel_hi:[1,1,1]
	ds_read_b64 v[58:59], v98 offset:23040
	v_pk_fma_f32 v[84:85], v[36:37], v[42:43], v[84:85] op_sel_hi:[1,0,1]
	ds_read_b128 v[72:75], v97 offset:23552
	v_pk_fma_f32 v[84:85], v[38:39], v[42:43], v[84:85] op_sel:[0,1,0] op_sel_hi:[1,1,1]
	ds_read_b128 v[76:79], v97 offset:23296
	v_pk_mul_f32 v[94:95], v[32:33], v[80:81] op_sel_hi:[1,0]
	v_add_f32_dpp v84, v84, v84 quad_perm:[1,0,3,2] row_mask:0xf bank_mask:0xf bound_ctrl:1
	v_add_f32_dpp v85, v85, v85 quad_perm:[1,0,3,2] row_mask:0xf bank_mask:0xf bound_ctrl:1
	v_pk_fma_f32 v[94:95], v[34:35], v[80:81], v[94:95] op_sel:[0,1,0] op_sel_hi:[1,1,1]
	v_add_f32_dpp v84, v84, v84 quad_perm:[2,3,0,1] row_mask:0xf bank_mask:0xf bound_ctrl:1
	v_add_f32_dpp v85, v85, v85 quad_perm:[2,3,0,1] row_mask:0xf bank_mask:0xf bound_ctrl:1
	v_pk_fma_f32 v[94:95], v[36:37], v[82:83], v[94:95] op_sel_hi:[1,0,1]
	v_add_f32_dpp v84, v84, v84 row_half_mirror row_mask:0xf bank_mask:0xf bound_ctrl:1
	v_add_f32_dpp v85, v85, v85 row_half_mirror row_mask:0xf bank_mask:0xf bound_ctrl:1
	v_pk_fma_f32 v[94:95], v[38:39], v[82:83], v[94:95] op_sel:[0,1,0] op_sel_hi:[1,1,1]
	v_add_f32_dpp v84, v84, v84 row_mirror row_mask:0xf bank_mask:0xf bound_ctrl:1
	v_add_f32_dpp v85, v85, v85 row_mirror row_mask:0xf bank_mask:0xf bound_ctrl:1
	ds_read_b128 v[80:83], v97 offset:23040
	v_pk_mul_f32 v[86:87], v[84:85], v[44:45] op_sel_hi:[1,0]
	v_pk_mul_f32 v[88:89], v[84:85], v[44:45] op_sel:[0,1] op_sel_hi:[1,1]
	v_pk_mul_f32 v[90:91], v[84:85], v[46:47] op_sel_hi:[1,0]
	v_pk_mul_f32 v[92:93], v[84:85], v[46:47] op_sel:[0,1] op_sel_hi:[1,1]
	v_pk_fma_f32 v[86:87], v[56:57], v[48:49], v[86:87] op_sel_hi:[1,0,1]
	v_pk_fma_f32 v[88:89], v[56:57], v[48:49], v[88:89] op_sel:[0,1,0] op_sel_hi:[1,1,1]
	v_pk_fma_f32 v[90:91], v[56:57], v[50:51], v[90:91] op_sel_hi:[1,0,1]
	v_pk_fma_f32 v[92:93], v[56:57], v[50:51], v[92:93] op_sel:[0,1,0] op_sel_hi:[1,1,1]
	v_pk_fma_f32 v[32:33], v[32:33], v[52:53], v[86:87] op_sel_hi:[1,0,1]
	v_pk_fma_f32 v[34:35], v[34:35], v[52:53], v[88:89] op_sel:[0,1,0] op_sel_hi:[1,1,1]
	v_pk_fma_f32 v[36:37], v[36:37], v[54:55], v[90:91] op_sel_hi:[1,0,1]
	v_pk_fma_f32 v[38:39], v[38:39], v[54:55], v[92:93] op_sel:[0,1,0] op_sel_hi:[1,1,1]
	v_add_f32_dpp v94, v94, v94 quad_perm:[1,0,3,2] row_mask:0xf bank_mask:0xf bound_ctrl:1
	v_add_f32_dpp v95, v95, v95 quad_perm:[1,0,3,2] row_mask:0xf bank_mask:0xf bound_ctrl:1
	v_cndmask_b32_e32 v96, v94, v95, vcc
	ds_write_b32 v99, v96 offset:13312
	ds_read_b128 v[40:43], v97 offset:25344
	s_waitcnt lgkmcnt(3)
; __device__ __forceinline__ float reduce8(float x) { x += dppf<0xB1>(x); x += dppf<0x4E>(x); x += dppf<0x141>(x); return x; }
; __device__ __forceinline__ void phase_scan(CParams& p, LAS unsigned char* lds) {
;     ...
;                     for (int s16 = 0; s16 < 16; ++s16) {
;                         scan_ld(nxt, base + (g16 + s16 + 1) * 384, vb + (g16 + s16 + 1) * 384);
;                         f32x2 d = S[0] * cur.n0.lo; d = S[1] * cur.n0.hi + d; d = S[2] * cur.n1.lo + d; d = S[3] * cur.n1.hi + d;
;                         const float sa = reduce8(d.x + d.y);
;                         const f32x2 sa2 = (f32x2){sa, sa}, v2 = (f32x2){cur.v, cur.v};
;                         S[0] = S[0] * cur.w0.lo + (cur.b0.lo * sa2 + cur.k0.lo * v2);
;                         S[1] = S[1] * cur.w0.hi + (cur.b0.hi * sa2 + cur.k0.hi * v2);
;                         S[2] = S[2] * cur.w1.lo + (cur.b1.lo * sa2 + cur.k1.lo * v2);
;                         S[3] = S[3] * cur.w1.hi + (cur.b1.hi * sa2 + cur.k1.hi * v2);
;                         f32x2 e = S[0] * cur.r0.lo; e = S[1] * cur.r0.hi + e; e = S[2] * cur.r1.lo + e; e = S[3] * cur.r1.hi + e;
;                         yw[s16 * 256] = e.x + e.y;
;                         cur = nxt;
;                     }
;                     __syncthreads();
;                 }
;             }
;             float* so = p.out + (prompt ? O_WP : O_WS) + ((size_t)chain * 64 + row) * 64;
;             *(f32x4*)(so + 4 * j) = (f32x4){S[0].x, S[0].y, S[1].x, S[1].y}; *(f32x4*)(so + 32 + 4 * j) = (f32x4){S[2].x, S[2].y, S[3].x, S[3].y};
	v_pk_mul_f32 v[84:85], v[32:33], v[64:65] op_sel_hi:[1,0]
	ds_read_b128 v[44:47], v97 offset:25600
	v_pk_fma_f32 v[84:85], v[34:35], v[64:65], v[84:85] op_sel:[0,1,0] op_sel_hi:[1,1,1]
	ds_read_b64 v[56:57], v98 offset:24576
	v_pk_fma_f32 v[84:85], v[36:37], v[66:67], v[84:85] op_sel_hi:[1,0,1]
	ds_read_b128 v[48:51], v97 offset:25088
	v_pk_fma_f32 v[84:85], v[38:39], v[66:67], v[84:85] op_sel:[0,1,0] op_sel_hi:[1,1,1]
	ds_read_b128 v[52:55], v97 offset:24832
	v_pk_mul_f32 v[94:95], v[32:33], v[60:61] op_sel_hi:[1,0]
	v_add_f32_dpp v84, v84, v84 quad_perm:[1,0,3,2] row_mask:0xf bank_mask:0xf bound_ctrl:1
	v_add_f32_dpp v85, v85, v85 quad_perm:[1,0,3,2] row_mask:0xf bank_mask:0xf bound_ctrl:1
	v_pk_fma_f32 v[94:95], v[34:35], v[60:61], v[94:95] op_sel:[0,1,0] op_sel_hi:[1,1,1]
	v_add_f32_dpp v84, v84, v84 quad_perm:[2,3,0,1] row_mask:0xf bank_mask:0xf bound_ctrl:1
	v_add_f32_dpp v85, v85, v85 quad_perm:[2,3,0,1] row_mask:0xf bank_mask:0xf bound_ctrl:1
	v_pk_fma_f32 v[94:95], v[36:37], v[62:63], v[94:95] op_sel_hi:[1,0,1]
	v_add_f32_dpp v84, v84, v84 row_half_mirror row_mask:0xf bank_mask:0xf bound_ctrl:1
	v_add_f32_dpp v85, v85, v85 row_half_mirror row_mask:0xf bank_mask:0xf bound_ctrl:1
	v_pk_fma_f32 v[94:95], v[38:39], v[62:63], v[94:95] op_sel:[0,1,0] op_sel_hi:[1,1,1]
	v_add_f32_dpp v84, v84, v84 row_mirror row_mask:0xf bank_mask:0xf bound_ctrl:1
	v_add_f32_dpp v85, v85, v85 row_mirror row_mask:0xf bank_mask:0xf bound_ctrl:1
	ds_read_b128 v[60:63], v97 offset:24576
	v_pk_mul_f32 v[86:87], v[84:85], v[68:69] op_sel_hi:[1,0]
	v_pk_mul_f32 v[88:89], v[84:85], v[68:69] op_sel:[0,1] op_sel_hi:[1,1]
	v_pk_mul_f32 v[90:91], v[84:85], v[70:71] op_sel_hi:[1,0]
	v_pk_mul_f32 v[92:93], v[84:85], v[70:71] op_sel:[0,1] op_sel_hi:[1,1]
	v_pk_fma_f32 v[86:87], v[58:59], v[72:73], v[86:87] op_sel_hi:[1,0,1]
	v_pk_fma_f32 v[88:89], v[58:59], v[72:73], v[88:89] op_sel:[0,1,0] op_sel_hi:[1,1,1]
	v_pk_fma_f32 v[90:91], v[58:59], v[74:75], v[90:91] op_sel_hi:[1,0,1]
	v_pk_fma_f32 v[92:93], v[58:59], v[74:75], v[92:93] op_sel:[0,1,0] op_sel_hi:[1,1,1]
	v_pk_fma_f32 v[32:33], v[32:33], v[76:77], v[86:87] op_sel_hi:[1,0,1]
	v_pk_fma_f32 v[34:35], v[34:35], v[76:77], v[88:89] op_sel:[0,1,0] op_sel_hi:[1,1,1]
	v_pk_fma_f32 v[36:37], v[36:37], v[78:79], v[90:91] op_sel_hi:[1,0,1]
	v_pk_fma_f32 v[38:39], v[38:39], v[78:79], v[92:93] op_sel:[0,1,0] op_sel_hi:[1,1,1]
	v_add_f32_dpp v94, v94, v94 quad_perm:[1,0,3,2] row_mask:0xf bank_mask:0xf bound_ctrl:1
	v_add_f32_dpp v95, v95, v95 quad_perm:[1,0,3,2] row_mask:0xf bank_mask:0xf bound_ctrl:1
	v_cndmask_b32_e32 v96, v94, v95, vcc
	ds_write_b32 v99, v96 offset:14336
	s_waitcnt lgkmcnt(8)
	v_pk_mul_f32 v[94:95], v[32:33], v[80:81] op_sel_hi:[1,0]
	s_nop 0
	v_pk_fma_f32 v[94:95], v[34:35], v[80:81], v[94:95] op_sel:[0,1,0] op_sel_hi:[1,1,1]
	s_nop 0
	v_pk_fma_f32 v[94:95], v[36:37], v[82:83], v[94:95] op_sel_hi:[1,0,1]
	s_nop 0
	v_pk_fma_f32 v[94:95], v[38:39], v[82:83], v[94:95] op_sel:[0,1,0] op_sel_hi:[1,1,1]
	s_nop 1
	v_add_f32_dpp v94, v94, v94 quad_perm:[1,0,3,2] row_mask:0xf bank_mask:0xf bound_ctrl:1
	v_add_f32_dpp v95, v95, v95 quad_perm:[1,0,3,2] row_mask:0xf bank_mask:0xf bound_ctrl:1
	v_cndmask_b32_e32 v96, v94, v95, vcc
	ds_write_b32 v99, v96 offset:15360
	s_add_i32 s15, s15, 16
	v_add_u32_e32 v97, 0x6000, v97
	v_add_u32_e32 v98, 0x6000, v98
	v_add_u32_e32 v99, 0x4000, v99
	s_waitcnt lgkmcnt(0)
	s_barrier
	s_cmp_lt_i32 s15, s54
	s_cbranch_scc1 .Lsc_grp
	s_add_i32 s13, s13, 1
	s_cmp_lt_u32 s13, s3
	s_cbranch_scc1 .Lsc_chunk
	s_mov_b32 s13, 0
	s_lshl_b64 s[54:55], s[12:13], 14
	s_cmp_eq_u64 s[50:51], 0
	s_mov_b32 s15, 0x94b6000
	s_cselect_b32 s15, 0x9192000, s15
	s_add_u32 s54, s54, s15
	s_addc_u32 s55, s55, 0
	s_add_u32 s54, s54, s40
	s_addc_u32 s55, s55, s41
	v_mov_b32_e32 v104, v32
	v_mov_b32_e32 v108, v33
	v_mov_b32_e32 v105, v34
	v_mov_b32_e32 v109, v35
	v_mov_b32_e32 v106, v36
	v_mov_b32_e32 v110, v37
	v_mov_b32_e32 v107, v38
	v_mov_b32_e32 v111, v39
	s_nop 1
	global_store_dwordx4 v103, v[104:107], s[54:55]
	global_store_dwordx4 v103, v[108:111], s[54:55] offset:256
	s_mov_b64 s[54:55], 0
	s_barrier

; #define LAS __attribute__((address_space(3)))
; __device__ __forceinline__ void unpack8(u32x4 w, f32x4& a, f32x4& b) { a = (f32x4){bf_lo(w.x), bf_hi(w.x), bf_lo(w.y), bf_hi(w.y)}; b = (f32x4){bf_lo(w.z), bf_hi(w.z), bf_lo(w.w), bf_hi(w.w)}; }
; __device__ __forceinline__ void phase_conv(CParams& p, LAS unsigned char* lds) {
;     ...
;         for (int j0 = 0; j0 < 32; j0 += 8) {
;             u32x4 xr[8]; f32x4 s0[8], s1[8];
; #pragma unroll
;             for (int jj = 0; jj < 8; ++jj) { const int j = j0 + jj; const bool ok = j < 31 && tt + j >= 30; xr[jj] = *(const u32x4*)(p.u + (size_t)(ok ? mm + j - 30 : mm) * DCV + ch0); }
;             if (!prompt) {
; #pragma unroll
;                 for (int jj = 0; jj < 8; ++jj) { const int j = j0 + jj, i = tt + j; const bool ok = j < 31 && i < 30;
;                     const float* sp = p.in[I_SCONV] + ((size_t)sidx * 30 + (ok ? i : 0)) * 512 + ch0; s0[jj] = *(const f32x4*)sp; s1[jj] = *(const f32x4*)(sp + 4); }
;             }
; #pragma unroll
;             for (int jj = 0; jj < 8; ++jj) { const int j = j0 + jj; const float f = (j < 31 && tt + j >= 30) ? 1.f : 0.f; const int jc = j < 31 ? j : 30; f32x4 x0, x1; unpack8(xr[jj], x0, x1);
;                 const f32x4 w0 = *(const LAS f32x4*)(wl + jc * 512 + ch0), w1 = *(const LAS f32x4*)(wl + jc * 512 + ch0 + 4);
;                 c0 += x0 * (w0 * f); c1 += x1 * (w1 * f);
;                 if (!prompt) { const float g = (j < 31 && tt + j < 30) ? 1.f : 0.f; c0 += s0[jj] * (w0 * g); c1 += s1[jj] * (w1 * g); } }
;         }
.LBB0_210:
	v_add_u32_e32 v40, s0, v73
	v_add_u32_e32 v32, 8, v40
	v_add_u32_e32 v41, s0, v76
	v_cmp_lt_u32_e64 s[16:17], 29, v32
	v_subrev_u32_e32 v32, 22, v41
	s_add_i32 s1, s0, 15
	v_cndmask_b32_e64 v32, v70, v32, s[16:17]
	v_ashrrev_i32_e32 v33, 31, v32
	v_lshlrev_b64 v[32:33], 10, v[32:33]
	v_lshl_add_u64 v[32:33], v[66:67], 0, v[32:33]
	global_load_dwordx4 v[60:63], v[32:33], off
	v_subrev_u32_e32 v32, 21, v41
	v_cndmask_b32_e64 v32, v70, v32, s[16:17]
	v_ashrrev_i32_e32 v33, 31, v32
	v_lshlrev_b64 v[32:33], 10, v[32:33]
	v_lshl_add_u64 v[32:33], v[66:67], 0, v[32:33]
	global_load_dwordx4 v[56:59], v[32:33], off
	v_add_u32_e32 v32, 10, v40
	v_cmp_lt_u32_e64 s[14:15], 29, v32
	v_subrev_u32_e32 v32, 20, v41
	s_cmp_lt_u32 s1, 31
	v_cndmask_b32_e64 v32, v70, v32, s[14:15]
	v_ashrrev_i32_e32 v33, 31, v32
	v_lshlrev_b64 v[32:33], 10, v[32:33]
	v_lshl_add_u64 v[32:33], v[66:67], 0, v[32:33]
	global_load_dwordx4 v[52:55], v[32:33], off
	v_add_u32_e32 v32, 11, v40
	v_cmp_lt_u32_e64 s[12:13], 29, v32
	v_subrev_u32_e32 v32, 19, v41
	s_cselect_b64 s[2:3], -1, 0
	v_cndmask_b32_e64 v32, v70, v32, s[12:13]
	v_ashrrev_i32_e32 v33, 31, v32
	v_lshlrev_b64 v[32:33], 10, v[32:33]
	v_lshl_add_u64 v[32:33], v[66:67], 0, v[32:33]
	global_load_dwordx4 v[48:51], v[32:33], off
	v_add_u32_e32 v32, 12, v40
	v_cmp_lt_u32_e64 s[10:11], 29, v32
	v_subrev_u32_e32 v32, 18, v41
	v_cndmask_b32_e64 v72, 0, 1.0, s[16:17]
	v_cndmask_b32_e64 v32, v70, v32, s[10:11]
	v_ashrrev_i32_e32 v33, 31, v32
	v_lshlrev_b64 v[32:33], 10, v[32:33]
	v_lshl_add_u64 v[32:33], v[66:67], 0, v[32:33]
	global_load_dwordx4 v[44:47], v[32:33], off
	v_add_u32_e32 v32, 13, v40
	v_cmp_lt_u32_e64 s[6:7], 29, v32
	v_subrev_u32_e32 v32, 17, v41
	s_min_u32 s1, s1, 30
	v_cndmask_b32_e64 v32, v70, v32, s[6:7]
	v_ashrrev_i32_e32 v33, 31, v32
	v_lshlrev_b64 v[32:33], 10, v[32:33]
	v_lshl_add_u64 v[32:33], v[66:67], 0, v[32:33]
	global_load_dwordx4 v[36:39], v[32:33], off
	v_add_u32_e32 v32, 14, v40
	v_cmp_lt_u32_e32 vcc, 29, v32
	v_add_u32_e32 v32, -16, v41
	v_add_u32_e32 v40, 15, v40
	v_cndmask_b32_e32 v32, v70, v32, vcc
	v_ashrrev_i32_e32 v33, 31, v32
	v_lshlrev_b64 v[32:33], 10, v[32:33]
	v_lshl_add_u64 v[32:33], v[66:67], 0, v[32:33]
	global_load_dwordx4 v[32:35], v[32:33], off
	v_cmp_lt_u32_e64 s[8:9], 29, v40
	s_and_b64 s[8:9], s[2:3], s[8:9]
	v_add_u32_e32 v40, -15, v41
	v_cndmask_b32_e64 v40, v70, v40, s[8:9]
	v_ashrrev_i32_e32 v41, 31, v40
	v_lshlrev_b64 v[40:41], 10, v[40:41]
	v_lshl_add_u64 v[40:41], v[66:67], 0, v[40:41]
	global_load_dwordx4 v[40:43], v[40:41], off
	s_add_i32 s0, s0, 8
	s_cmp_lt_u32 s0, 24
	s_waitcnt vmcnt(7)
	v_lshlrev_b32_e32 v82, 16, v60
	v_and_b32_e32 v83, 0xffff0000, v60
	v_lshlrev_b32_e32 v84, 16, v61
	v_and_b32_e32 v85, 0xffff0000, v61
	v_lshlrev_b32_e32 v86, 16, v62
	v_and_b32_e32 v87, 0xffff0000, v62
	v_lshlrev_b32_e32 v90, 16, v63
	v_and_b32_e32 v91, 0xffff0000, v63
	ds_read_b128 v[60:63], v71
	ds_read_b128 v[78:81], v71 offset:16
	s_waitcnt lgkmcnt(1)
	v_pk_mul_f32 v[62:63], v[72:73], v[62:63] op_sel_hi:[0,1]
	v_pk_mul_f32 v[60:61], v[72:73], v[60:61] op_sel_hi:[0,1]
	v_pk_fma_f32 v[60:61], v[60:61], v[82:83], v[28:29]
	v_pk_fma_f32 v[62:63], v[62:63], v[84:85], v[30:31]
	s_waitcnt lgkmcnt(0)
	v_pk_mul_f32 v[28:29], v[72:73], v[80:81] op_sel_hi:[0,1]
	v_pk_mul_f32 v[30:31], v[72:73], v[78:79] op_sel_hi:[0,1]
	v_pk_fma_f32 v[78:79], v[30:31], v[86:87], v[24:25]
	v_pk_fma_f32 v[80:81], v[28:29], v[90:91], v[26:27]
	ds_read_b128 v[24:27], v71 offset:2048
	ds_read_b128 v[28:31], v71 offset:2064
	s_waitcnt vmcnt(6)
	v_lshlrev_b32_e32 v82, 16, v56
	v_and_b32_e32 v83, 0xffff0000, v56
	v_lshlrev_b32_e32 v56, 16, v57
	v_and_b32_e32 v57, 0xffff0000, v57
	s_waitcnt lgkmcnt(1)
	v_pk_mul_f32 v[26:27], v[72:73], v[26:27] op_sel_hi:[0,1]
	v_pk_mul_f32 v[24:25], v[72:73], v[24:25] op_sel_hi:[0,1]
	v_lshlrev_b32_e32 v84, 16, v58
	v_and_b32_e32 v85, 0xffff0000, v58
	v_lshlrev_b32_e32 v58, 16, v59
	v_and_b32_e32 v59, 0xffff0000, v59
	v_pk_fma_f32 v[56:57], v[26:27], v[56:57], v[62:63]
	v_pk_fma_f32 v[60:61], v[24:25], v[82:83], v[60:61]
	s_waitcnt lgkmcnt(0)
	v_pk_mul_f32 v[24:25], v[72:73], v[30:31] op_sel_hi:[0,1]
	v_pk_mul_f32 v[26:27], v[72:73], v[28:29] op_sel_hi:[0,1]
	v_pk_fma_f32 v[58:59], v[24:25], v[58:59], v[80:81]
	v_pk_fma_f32 v[62:63], v[26:27], v[84:85], v[78:79]
	ds_read_b128 v[24:27], v71 offset:4096
	ds_read_b128 v[28:31], v71 offset:4112
	v_cndmask_b32_e64 v72, 0, 1.0, s[14:15]
	s_waitcnt vmcnt(5)
	v_lshlrev_b32_e32 v78, 16, v52
	v_and_b32_e32 v79, 0xffff0000, v52
	v_lshlrev_b32_e32 v52, 16, v53
	v_and_b32_e32 v53, 0xffff0000, v53
	s_waitcnt lgkmcnt(1)
	v_pk_mul_f32 v[26:27], v[72:73], v[26:27] op_sel_hi:[0,1]
	v_pk_mul_f32 v[24:25], v[72:73], v[24:25] op_sel_hi:[0,1]
	v_lshlrev_b32_e32 v80, 16, v54
	v_and_b32_e32 v81, 0xffff0000, v54
	v_lshlrev_b32_e32 v54, 16, v55
	v_and_b32_e32 v55, 0xffff0000, v55
	v_pk_fma_f32 v[60:61], v[24:25], v[78:79], v[60:61]
	v_pk_fma_f32 v[52:53], v[26:27], v[52:53], v[56:57]
	s_waitcnt lgkmcnt(0)
	v_pk_mul_f32 v[24:25], v[72:73], v[30:31] op_sel_hi:[0,1]
	v_pk_mul_f32 v[26:27], v[72:73], v[28:29] op_sel_hi:[0,1]
	v_pk_fma_f32 v[56:57], v[26:27], v[80:81], v[62:63]
	v_pk_fma_f32 v[54:55], v[24:25], v[54:55], v[58:59]
	ds_read_b128 v[24:27], v71 offset:6144
	ds_read_b128 v[28:31], v71 offset:6160
	v_cndmask_b32_e64 v58, 0, 1.0, s[12:13]
	s_waitcnt vmcnt(4)
	v_lshlrev_b32_e32 v62, 16, v48
	v_and_b32_e32 v63, 0xffff0000, v48
	v_lshlrev_b32_e32 v48, 16, v49
	v_and_b32_e32 v49, 0xffff0000, v49
	s_waitcnt lgkmcnt(1)
; #define LAS __attribute__((address_space(3)))
; __device__ __forceinline__ void unpack8(u32x4 w, f32x4& a, f32x4& b) { a = (f32x4){bf_lo(w.x), bf_hi(w.x), bf_lo(w.y), bf_hi(w.y)}; b = (f32x4){bf_lo(w.z), bf_hi(w.z), bf_lo(w.w), bf_hi(w.w)}; }
; __device__ __forceinline__ void phase_conv(CParams& p, LAS unsigned char* lds) {
;     ...
;         for (int j0 = 0; j0 < 32; j0 += 8) {
;             u32x4 xr[8]; f32x4 s0[8], s1[8];
; #pragma unroll
;             for (int jj = 0; jj < 8; ++jj) { const int j = j0 + jj; const bool ok = j < 31 && tt + j >= 30; xr[jj] = *(const u32x4*)(p.u + (size_t)(ok ? mm + j - 30 : mm) * DCV + ch0); }
;             if (!prompt) {
; #pragma unroll
;                 for (int jj = 0; jj < 8; ++jj) { const int j = j0 + jj, i = tt + j; const bool ok = j < 31 && i < 30;
;                     const float* sp = p.in[I_SCONV] + ((size_t)sidx * 30 + (ok ? i : 0)) * 512 + ch0; s0[jj] = *(const f32x4*)sp; s1[jj] = *(const f32x4*)(sp + 4); }
;             }
; #pragma unroll
;             for (int jj = 0; jj < 8; ++jj) { const int j = j0 + jj; const float f = (j < 31 && tt + j >= 30) ? 1.f : 0.f; const int jc = j < 31 ? j : 30; f32x4 x0, x1; unpack8(xr[jj], x0, x1);
;                 const f32x4 w0 = *(const LAS f32x4*)(wl + jc * 512 + ch0), w1 = *(const LAS f32x4*)(wl + jc * 512 + ch0 + 4);
;                 c0 += x0 * (w0 * f); c1 += x1 * (w1 * f);
;                 if (!prompt) { const float g = (j < 31 && tt + j < 30) ? 1.f : 0.f; c0 += s0[jj] * (w0 * g); c1 += s1[jj] * (w1 * g); } }
;         }
	v_pk_mul_f32 v[26:27], v[58:59], v[26:27] op_sel_hi:[0,1]
	v_pk_mul_f32 v[24:25], v[58:59], v[24:25] op_sel_hi:[0,1]
	v_lshlrev_b32_e32 v78, 16, v50
	v_and_b32_e32 v79, 0xffff0000, v50
	v_lshlrev_b32_e32 v50, 16, v51
	v_and_b32_e32 v51, 0xffff0000, v51
	v_pk_fma_f32 v[48:49], v[26:27], v[48:49], v[52:53]
	v_pk_fma_f32 v[52:53], v[24:25], v[62:63], v[60:61]
	s_waitcnt lgkmcnt(0)
	v_pk_mul_f32 v[24:25], v[58:59], v[30:31] op_sel_hi:[0,1]
	v_pk_mul_f32 v[26:27], v[58:59], v[28:29] op_sel_hi:[0,1]
	v_pk_fma_f32 v[50:51], v[24:25], v[50:51], v[54:55]
	v_pk_fma_f32 v[54:55], v[26:27], v[78:79], v[56:57]
	ds_read_b128 v[24:27], v71 offset:8192
	ds_read_b128 v[28:31], v71 offset:8208
	v_cndmask_b32_e64 v56, 0, 1.0, s[10:11]
	s_waitcnt vmcnt(3)
	v_lshlrev_b32_e32 v58, 16, v44
	v_and_b32_e32 v59, 0xffff0000, v44
	v_lshlrev_b32_e32 v44, 16, v45
	v_and_b32_e32 v45, 0xffff0000, v45
	s_waitcnt lgkmcnt(1)
	v_pk_mul_f32 v[26:27], v[56:57], v[26:27] op_sel_hi:[0,1]
	v_pk_mul_f32 v[24:25], v[56:57], v[24:25] op_sel_hi:[0,1]
	v_lshlrev_b32_e32 v60, 16, v46
	v_and_b32_e32 v61, 0xffff0000, v46
	v_lshlrev_b32_e32 v46, 16, v47
	v_and_b32_e32 v47, 0xffff0000, v47
	v_pk_fma_f32 v[52:53], v[24:25], v[58:59], v[52:53]
	v_pk_fma_f32 v[44:45], v[26:27], v[44:45], v[48:49]
	s_waitcnt lgkmcnt(0)
	v_pk_mul_f32 v[24:25], v[56:57], v[30:31] op_sel_hi:[0,1]
	v_pk_mul_f32 v[26:27], v[56:57], v[28:29] op_sel_hi:[0,1]
	v_pk_fma_f32 v[48:49], v[26:27], v[60:61], v[54:55]
	v_pk_fma_f32 v[46:47], v[24:25], v[46:47], v[50:51]
	ds_read_b128 v[24:27], v71 offset:10240
	ds_read_b128 v[28:31], v71 offset:10256
	v_cndmask_b32_e64 v50, 0, 1.0, s[6:7]
	s_waitcnt vmcnt(2)
	v_lshlrev_b32_e32 v54, 16, v36
	v_and_b32_e32 v55, 0xffff0000, v36
	v_lshlrev_b32_e32 v36, 16, v37
	v_and_b32_e32 v37, 0xffff0000, v37
	s_waitcnt lgkmcnt(1)
	v_pk_mul_f32 v[26:27], v[50:51], v[26:27] op_sel_hi:[0,1]
	v_pk_mul_f32 v[24:25], v[50:51], v[24:25] op_sel_hi:[0,1]
	v_lshlrev_b32_e32 v56, 16, v38
	v_and_b32_e32 v57, 0xffff0000, v38
	v_lshlrev_b32_e32 v38, 16, v39
	v_and_b32_e32 v39, 0xffff0000, v39
	v_pk_fma_f32 v[36:37], v[26:27], v[36:37], v[44:45]
	v_pk_fma_f32 v[44:45], v[24:25], v[54:55], v[52:53]
	s_waitcnt lgkmcnt(0)
	v_pk_mul_f32 v[24:25], v[50:51], v[30:31] op_sel_hi:[0,1]
	v_pk_mul_f32 v[26:27], v[50:51], v[28:29] op_sel_hi:[0,1]
	v_pk_fma_f32 v[38:39], v[24:25], v[38:39], v[46:47]
	v_pk_fma_f32 v[46:47], v[26:27], v[56:57], v[48:49]
	ds_read_b128 v[24:27], v71 offset:12288
	ds_read_b128 v[28:31], v71 offset:12304
	v_cndmask_b32_e64 v48, 0, 1.0, vcc
	s_waitcnt vmcnt(1)
	v_lshlrev_b32_e32 v50, 16, v32
	v_and_b32_e32 v51, 0xffff0000, v32
	v_lshlrev_b32_e32 v32, 16, v33
	v_and_b32_e32 v33, 0xffff0000, v33
	s_waitcnt lgkmcnt(1)
	v_pk_mul_f32 v[26:27], v[48:49], v[26:27] op_sel_hi:[0,1]
	v_pk_mul_f32 v[24:25], v[48:49], v[24:25] op_sel_hi:[0,1]
	v_lshlrev_b32_e32 v52, 16, v34
	v_and_b32_e32 v53, 0xffff0000, v34
	v_lshlrev_b32_e32 v34, 16, v35
	v_and_b32_e32 v35, 0xffff0000, v35
	v_pk_fma_f32 v[44:45], v[24:25], v[50:51], v[44:45]
	v_pk_fma_f32 v[36:37], v[26:27], v[32:33], v[36:37]
	s_waitcnt lgkmcnt(0)
	v_pk_mul_f32 v[24:25], v[48:49], v[30:31] op_sel_hi:[0,1]
	v_pk_mul_f32 v[26:27], v[48:49], v[28:29] op_sel_hi:[0,1]
	v_lshl_add_u32 v32, s1, 11, v75
	v_pk_fma_f32 v[46:47], v[26:27], v[52:53], v[46:47]
	v_pk_fma_f32 v[38:39], v[24:25], v[34:35], v[38:39]
	ds_read_b128 v[24:27], v32
	ds_read_b128 v[32:35], v32 offset:16
	v_cndmask_b32_e64 v48, 0, 1.0, s[8:9]
	s_waitcnt vmcnt(0)
	v_lshlrev_b32_e32 v28, 16, v40
	v_and_b32_e32 v29, 0xffff0000, v40
	s_waitcnt lgkmcnt(1)
	v_pk_mul_f32 v[24:25], v[48:49], v[24:25] op_sel_hi:[0,1]
	v_lshlrev_b32_e32 v30, 16, v41
	v_and_b32_e32 v31, 0xffff0000, v41
	v_lshlrev_b32_e32 v40, 16, v42
	v_and_b32_e32 v41, 0xffff0000, v42
	v_lshlrev_b32_e32 v42, 16, v43
	v_and_b32_e32 v43, 0xffff0000, v43
	v_pk_mul_f32 v[26:27], v[48:49], v[26:27] op_sel_hi:[0,1]
	v_pk_fma_f32 v[28:29], v[24:25], v[28:29], v[44:45]
	s_waitcnt lgkmcnt(0)
	v_pk_mul_f32 v[24:25], v[48:49], v[34:35] op_sel_hi:[0,1]
	v_pk_mul_f32 v[32:33], v[48:49], v[32:33] op_sel_hi:[0,1]
	v_pk_fma_f32 v[30:31], v[26:27], v[30:31], v[36:37]
	v_pk_fma_f32 v[26:27], v[24:25], v[42:43], v[38:39]
	v_pk_fma_f32 v[24:25], v[32:33], v[40:41], v[46:47]
	v_add_u32_e32 v71, 0x4000, v71
	s_cbranch_scc1 .LBB0_210
; __device__ __forceinline__ u32x4 pack8(f32x4 a, f32x4 b) { u32x4 w; w.x = pk2(a[0], a[1]); w.y = pk2(a[2], a[3]); w.z = pk2(b[0], b[1]); w.w = pk2(b[2], b[3]); return w; }
; __device__ __forceinline__ f32x4 sigm4(f32x4 v) { return (f32x4){sigm(v[0]), sigm(v[1]), sigm(v[2]), sigm(v[3])}; }
; __device__ __forceinline__ void phase_conv(CParams& p, LAS unsigned char* lds) {
;     ...
;     auto finish = [&](f32x4 c0, f32x4 c1, int mm) {
;         const float mean = wave_sum((c0[0] + c0[1]) + (c0[2] + c0[3]) + (c1[0] + c1[1]) + (c1[2] + c1[3])) * (1.f / 512.f);
;         c0 -= mean; c1 -= mean;
;         const float var = wave_sum(dot4(c0, c0) + dot4(c1, c1)) * (1.f / 512.f);
;         const float rstd = rsqrtf(var + 1e-5f);
;         c0 = c0 * rstd * lg0 + lb0; c1 = c1 * rstd * lg1 + lb1;
;         *(u32x4*)(p.sconv + (size_t)mm * DCV + ch0) = pack8(c0 * sigm4(c0), c1 * sigm4(c1));
;     };
	v_mov_b32_e32 v32, v29
	v_mov_b32_e32 v33, v30
	v_mov_b32_e32 v34, v28
	v_mov_b32_e32 v35, v31
	v_pk_add_f32 v[32:33], v[32:33], v[34:35]
	v_mov_b32_e32 v34, v26
	v_mov_b32_e32 v35, v24
	v_mov_b32_e32 v36, v27
	v_mov_b32_e32 v37, v25
	v_pk_add_f32 v[34:35], v[34:35], v[36:37]
	v_add_f32_e32 v32, v32, v33
	v_add_f32_e32 v32, v35, v32
	v_add_f32_e32 v32, v34, v32
	v_mov_b32_e32 v33, v161
	v_ashrrev_i32_e32 v71, 31, v70
	v_add_f32_dpp v32, v32, v32 quad_perm:[1,0,3,2] row_mask:0xf bank_mask:0xf bound_ctrl:1
	v_or_b32_e32 v72, 1, v70
	s_nop 0
	v_add_f32_dpp v32, v32, v32 quad_perm:[2,3,0,1] row_mask:0xf bank_mask:0xf bound_ctrl:1
	s_nop 1
	v_add_f32_dpp v32, v32, v32 row_half_mirror row_mask:0xf bank_mask:0xf bound_ctrl:1
	s_nop 1
	v_add_f32_dpp v32, v32, v32 row_mirror row_mask:0xf bank_mask:0xf bound_ctrl:1
	s_nop 1
	v_mov_b32_dpp v33, v32 row_bcast:15 row_mask:0xa bank_mask:0xf
	v_add_f32_e32 v32, v32, v33
	v_mov_b32_e32 v33, v161
	s_nop 1
	v_mov_b32_dpp v33, v32 row_bcast:31 row_mask:0xc bank_mask:0xf
	v_add_f32_e32 v32, v32, v33
	s_nop 0
	v_readlane_b32 s0, v32, 63
	s_nop 1
	v_fma_f32 v29, s0, v204, v29
	v_fma_f32 v25, s0, v204, v25
	v_fmac_f32_e32 v28, s0, v204
	v_fmac_f32_e32 v24, s0, v204
	v_mov_b32_e32 v34, v29
	v_mov_b32_e32 v35, v25
	v_fmac_f32_e32 v30, s0, v204
	v_fmac_f32_e32 v26, s0, v204
	v_mov_b32_e32 v32, v28
	v_mov_b32_e32 v33, v24
	v_pk_mul_f32 v[34:35], v[34:35], v[34:35]
	v_fma_f32 v31, s0, v204, v31
	v_fma_f32 v27, s0, v204, v27
	v_pk_fma_f32 v[32:33], v[32:33], v[32:33], v[34:35]
	v_mov_b32_e32 v34, v30
	v_mov_b32_e32 v35, v26
	v_pk_fma_f32 v[32:33], v[34:35], v[34:35], v[32:33]
	v_mov_b32_e32 v34, v31
	v_mov_b32_e32 v35, v27
	v_pk_fma_f32 v[32:33], v[34:35], v[34:35], v[32:33]
	s_nop 0
	v_add_f32_e32 v32, v32, v33
	v_mov_b32_e32 v33, v161
	s_nop 0
	v_add_f32_dpp v32, v32, v32 quad_perm:[1,0,3,2] row_mask:0xf bank_mask:0xf bound_ctrl:1
	s_nop 1
	v_add_f32_dpp v32, v32, v32 quad_perm:[2,3,0,1] row_mask:0xf bank_mask:0xf bound_ctrl:1
	s_nop 1
	v_add_f32_dpp v32, v32, v32 row_half_mirror row_mask:0xf bank_mask:0xf bound_ctrl:1
	s_nop 1
	v_add_f32_dpp v32, v32, v32 row_mirror row_mask:0xf bank_mask:0xf bound_ctrl:1
	s_nop 1
	v_mov_b32_dpp v33, v32 row_bcast:15 row_mask:0xa bank_mask:0xf
	v_add_f32_e32 v32, v32, v33
	v_mov_b32_e32 v33, v161
	s_nop 1
	v_mov_b32_dpp v33, v32 row_bcast:31 row_mask:0xc bank_mask:0xf
	v_add_f32_e32 v32, v32, v33
	s_nop 0
	v_readlane_b32 s0, v32, 63
	s_nop 1
	v_fma_f32 v32, s0, v205, v196
	s_mov_b32 s0, 0x800000
	v_mul_f32_e32 v33, 0x4b800000, v32
	v_cmp_gt_f32_e32 vcc, s0, v32
	s_nop 1
	v_cndmask_b32_e32 v32, v32, v33, vcc
	v_rsq_f32_e32 v32, v32
	s_nop 0
	v_mul_f32_e32 v33, 0x45800000, v32
	v_cndmask_b32_e32 v32, v32, v33, vcc
	v_pk_mul_f32 v[28:29], v[28:29], v[32:33] op_sel_hi:[1,0]
	v_pk_mul_f32 v[30:31], v[30:31], v[32:33] op_sel_hi:[1,0]
	v_pk_fma_f32 v[28:29], v[12:13], v[28:29], v[20:21]
	v_pk_mul_f32 v[24:25], v[24:25], v[32:33] op_sel_hi:[1,0]
	v_pk_mul_f32 v[26:27], v[26:27], v[32:33] op_sel_hi:[1,0]
	v_mul_f32_e32 v32, 0xbfb8aa3b, v28
	v_mul_f32_e32 v33, 0xbfb8aa3b, v29
	v_exp_f32_e32 v32, v32
	v_exp_f32_e32 v33, v33
	v_pk_fma_f32 v[30:31], v[14:15], v[30:31], v[22:23]
	v_pk_fma_f32 v[24:25], v[4:5], v[24:25], v[16:17]
	v_mul_f32_e32 v34, 0xbfb8aa3b, v30
	v_pk_add_f32 v[32:33], v[32:33], 1.0 op_sel_hi:[1,0]
	v_mul_f32_e32 v35, 0xbfb8aa3b, v31
	v_exp_f32_e32 v34, v34
	v_exp_f32_e32 v35, v35
	v_pk_fma_f32 v[26:27], v[6:7], v[26:27], v[18:19]
	v_rcp_f32_e32 v33, v33
	v_pk_add_f32 v[34:35], v[34:35], 1.0 op_sel_hi:[1,0]
	v_rcp_f32_e32 v32, v32
	s_nop 0
	v_pk_mul_f32 v[28:29], v[28:29], v[32:33]
	v_rcp_f32_e32 v35, v35
	v_rcp_f32_e32 v34, v34
	v_mul_f32_e32 v36, 0xbfb8aa3b, v24
	v_mul_f32_e32 v37, 0xbfb8aa3b, v25
	v_exp_f32_e32 v36, v36
	v_exp_f32_e32 v37, v37
	v_mul_f32_e32 v38, 0xbfb8aa3b, v26
	v_mul_f32_e32 v39, 0xbfb8aa3b, v27
	v_exp_f32_e32 v38, v38
	v_pk_add_f32 v[36:37], v[36:37], 1.0 op_sel_hi:[1,0]
	v_exp_f32_e32 v39, v39
	v_pk_mul_f32 v[30:31], v[30:31], v[34:35]
	v_pk_add_f32 v[32:33], v[38:39], 1.0 op_sel_hi:[1,0]
	v_rcp_f32_e32 v35, v37
	v_rcp_f32_e32 v34, v36
	v_rcp_f32_e32 v33, v33
	s_mov_b32 s0, -8
	v_rcp_f32_e32 v32, v32
	s_nop 0
	v_pk_mul_f32 v[32:33], v[26:27], v[32:33]
	v_pk_mul_f32 v[26:27], v[24:25], v[34:35]
	v_cvt_pk_bf16_f32 v24, v28, v29
	v_lshlrev_b64 v[28:29], 10, v[70:71]
	v_cvt_pk_bf16_f32 v25, v30, v31
	v_cvt_pk_bf16_f32 v26, v26, v27
	v_cvt_pk_bf16_f32 v27, v32, v33
	v_lshl_add_u64 v[28:29], v[68:69], 0, v[28:29]
	global_store_dwordx4 v[28:29], v[24:27], off
	v_mov_b64_e32 v[30:31], v[10:11]
	v_mov_b32_e32 v70, v75
	v_mov_b64_e32 v[26:27], v[2:3]
	v_mov_b64_e32 v[28:29], v[8:9]
	v_mov_b64_e32 v[24:25], v[0:1]
; #define LAS __attribute__((address_space(3)))
; __device__ __forceinline__ void unpack8(u32x4 w, f32x4& a, f32x4& b) { a = (f32x4){bf_lo(w.x), bf_hi(w.x), bf_lo(w.y), bf_hi(w.y)}; b = (f32x4){bf_lo(w.z), bf_hi(w.z), bf_lo(w.w), bf_hi(w.w)}; }
; __device__ __forceinline__ void phase_conv(CParams& p, LAS unsigned char* lds) {
;     ...
;         for (int j0 = 0; j0 < 32; j0 += 8) {
;             u32x4 xr[8]; f32x4 s0[8], s1[8];
; #pragma unroll
;             for (int jj = 0; jj < 8; ++jj) { const int j = j0 + jj; const bool ok = j < 31 && tt + j >= 30; xr[jj] = *(const u32x4*)(p.u + (size_t)(ok ? mm + j - 30 : mm) * DCV + ch0); }
;             if (!prompt) {
; #pragma unroll
;                 for (int jj = 0; jj < 8; ++jj) { const int j = j0 + jj, i = tt + j; const bool ok = j < 31 && i < 30;
;                     const float* sp = p.in[I_SCONV] + ((size_t)sidx * 30 + (ok ? i : 0)) * 512 + ch0; s0[jj] = *(const f32x4*)sp; s1[jj] = *(const f32x4*)(sp + 4); }
;             }
; #pragma unroll
;             for (int jj = 0; jj < 8; ++jj) { const int j = j0 + jj; const float f = (j < 31 && tt + j >= 30) ? 1.f : 0.f; const int jc = j < 31 ? j : 30; f32x4 x0, x1; unpack8(xr[jj], x0, x1);
;                 const f32x4 w0 = *(const LAS f32x4*)(wl + jc * 512 + ch0), w1 = *(const LAS f32x4*)(wl + jc * 512 + ch0 + 4);
;                 c0 += x0 * (w0 * f); c1 += x1 * (w1 * f);
;                 if (!prompt) { const float g = (j < 31 && tt + j < 30) ? 1.f : 0.f; c0 += s0[jj] * (w0 * g); c1 += s1[jj] * (w1 * g); } }
;         }
.LBB0_212:
	v_add_u32_e32 v40, s0, v73
	v_add_u32_e32 v32, 9, v40
	v_add_u32_e32 v41, s0, v76
	v_cmp_lt_u32_e64 s[18:19], 29, v32
	v_subrev_u32_e32 v32, 21, v41
	s_add_i32 s1, s0, 15
	v_cndmask_b32_e64 v32, v72, v32, s[18:19]
	v_ashrrev_i32_e32 v33, 31, v32
	v_lshlrev_b64 v[32:33], 10, v[32:33]
	v_lshl_add_u64 v[32:33], v[66:67], 0, v[32:33]
	global_load_dwordx4 v[60:63], v[32:33], off
	v_add_u32_e32 v32, 10, v40
	v_cmp_lt_u32_e64 s[16:17], 29, v32
	v_subrev_u32_e32 v32, 20, v41
	s_cmp_lt_u32 s1, 31
	v_cndmask_b32_e64 v32, v72, v32, s[16:17]
	v_ashrrev_i32_e32 v33, 31, v32
	v_lshlrev_b64 v[32:33], 10, v[32:33]
	v_lshl_add_u64 v[32:33], v[66:67], 0, v[32:33]
	global_load_dwordx4 v[56:59], v[32:33], off
	v_add_u32_e32 v32, 11, v40
	v_cmp_lt_u32_e64 s[14:15], 29, v32
	v_subrev_u32_e32 v32, 19, v41
	s_cselect_b64 s[2:3], -1, 0
	v_cndmask_b32_e64 v32, v72, v32, s[14:15]
	v_ashrrev_i32_e32 v33, 31, v32
	v_lshlrev_b64 v[32:33], 10, v[32:33]
	v_lshl_add_u64 v[32:33], v[66:67], 0, v[32:33]
	global_load_dwordx4 v[52:55], v[32:33], off
	v_add_u32_e32 v32, 12, v40
	v_cmp_lt_u32_e64 s[12:13], 29, v32
	v_subrev_u32_e32 v32, 18, v41
	v_cndmask_b32_e64 v82, 0, 1.0, s[18:19]
	v_cndmask_b32_e64 v32, v72, v32, s[12:13]
	v_ashrrev_i32_e32 v33, 31, v32
	v_lshlrev_b64 v[32:33], 10, v[32:33]
	v_lshl_add_u64 v[32:33], v[66:67], 0, v[32:33]
	global_load_dwordx4 v[48:51], v[32:33], off
	v_add_u32_e32 v32, 13, v40
	v_cmp_lt_u32_e64 s[10:11], 29, v32
	v_subrev_u32_e32 v32, 17, v41
	s_min_u32 s1, s1, 30
	v_cndmask_b32_e64 v32, v72, v32, s[10:11]
	v_ashrrev_i32_e32 v33, 31, v32
	v_lshlrev_b64 v[32:33], 10, v[32:33]
	v_lshl_add_u64 v[32:33], v[66:67], 0, v[32:33]
	global_load_dwordx4 v[44:47], v[32:33], off
	v_add_u32_e32 v32, 14, v40
	v_cmp_lt_u32_e64 s[6:7], 29, v32
	v_add_u32_e32 v32, -16, v41
	s_add_i32 s0, s0, 8
	v_cndmask_b32_e64 v32, v72, v32, s[6:7]
	v_ashrrev_i32_e32 v33, 31, v32
	v_lshlrev_b64 v[32:33], 10, v[32:33]
	v_lshl_add_u64 v[32:33], v[66:67], 0, v[32:33]
	global_load_dwordx4 v[36:39], v[32:33], off
	v_add_u32_e32 v32, 15, v40
	v_cmp_lt_u32_e32 vcc, 29, v32
	v_add_u32_e32 v32, -15, v41
	v_add_u32_e32 v40, 16, v40
	v_cndmask_b32_e32 v32, v72, v32, vcc
	v_ashrrev_i32_e32 v33, 31, v32
	v_lshlrev_b64 v[32:33], 10, v[32:33]
	v_lshl_add_u64 v[32:33], v[66:67], 0, v[32:33]
	global_load_dwordx4 v[32:35], v[32:33], off
	v_cmp_lt_u32_e64 s[8:9], 29, v40
	s_and_b64 s[8:9], s[2:3], s[8:9]
	v_add_u32_e32 v40, -14, v41
	v_cndmask_b32_e64 v40, v72, v40, s[8:9]
	v_ashrrev_i32_e32 v41, 31, v40
	v_lshlrev_b64 v[40:41], 10, v[40:41]
	v_lshl_add_u64 v[40:41], v[66:67], 0, v[40:41]
	global_load_dwordx4 v[40:43], v[40:41], off
	s_cmp_lt_u32 s0, 24
	s_waitcnt vmcnt(7)
	v_lshlrev_b32_e32 v84, 16, v60
	v_and_b32_e32 v85, 0xffff0000, v60
	v_lshlrev_b32_e32 v86, 16, v61
	v_and_b32_e32 v87, 0xffff0000, v61
	v_lshlrev_b32_e32 v90, 16, v62
	v_and_b32_e32 v91, 0xffff0000, v62
	v_lshlrev_b32_e32 v92, 16, v63
	v_and_b32_e32 v93, 0xffff0000, v63
	ds_read_b128 v[60:63], v70
	ds_read_b128 v[78:81], v70 offset:16
	s_waitcnt lgkmcnt(1)
	v_pk_mul_f32 v[62:63], v[82:83], v[62:63] op_sel_hi:[0,1]
	v_pk_mul_f32 v[60:61], v[82:83], v[60:61] op_sel_hi:[0,1]
	v_pk_fma_f32 v[60:61], v[60:61], v[84:85], v[28:29]
	v_pk_fma_f32 v[62:63], v[62:63], v[86:87], v[30:31]
	s_waitcnt lgkmcnt(0)
	v_pk_mul_f32 v[28:29], v[82:83], v[80:81] op_sel_hi:[0,1]
	v_pk_mul_f32 v[30:31], v[82:83], v[78:79] op_sel_hi:[0,1]
	v_pk_fma_f32 v[78:79], v[30:31], v[90:91], v[24:25]
	v_pk_fma_f32 v[80:81], v[28:29], v[92:93], v[26:27]
	ds_read_b128 v[24:27], v70 offset:2048
	ds_read_b128 v[28:31], v70 offset:2064
	v_cndmask_b32_e64 v82, 0, 1.0, s[16:17]
	s_waitcnt vmcnt(6)
	v_lshlrev_b32_e32 v84, 16, v56
	v_and_b32_e32 v85, 0xffff0000, v56
	v_lshlrev_b32_e32 v56, 16, v57
	v_and_b32_e32 v57, 0xffff0000, v57
	s_waitcnt lgkmcnt(1)
	v_pk_mul_f32 v[26:27], v[82:83], v[26:27] op_sel_hi:[0,1]
	v_pk_mul_f32 v[24:25], v[82:83], v[24:25] op_sel_hi:[0,1]
	v_lshlrev_b32_e32 v86, 16, v58
	v_and_b32_e32 v87, 0xffff0000, v58
	v_lshlrev_b32_e32 v58, 16, v59
	v_and_b32_e32 v59, 0xffff0000, v59
	v_pk_fma_f32 v[56:57], v[26:27], v[56:57], v[62:63]
	v_pk_fma_f32 v[60:61], v[24:25], v[84:85], v[60:61]
	s_waitcnt lgkmcnt(0)
	v_pk_mul_f32 v[24:25], v[82:83], v[30:31] op_sel_hi:[0,1]
	v_pk_mul_f32 v[26:27], v[82:83], v[28:29] op_sel_hi:[0,1]
	v_pk_fma_f32 v[58:59], v[24:25], v[58:59], v[80:81]
	v_pk_fma_f32 v[62:63], v[26:27], v[86:87], v[78:79]
	ds_read_b128 v[24:27], v70 offset:4096
	ds_read_b128 v[28:31], v70 offset:4112
	v_cndmask_b32_e64 v78, 0, 1.0, s[14:15]
	s_waitcnt vmcnt(5)
	v_lshlrev_b32_e32 v80, 16, v52
	v_and_b32_e32 v81, 0xffff0000, v52
	v_lshlrev_b32_e32 v52, 16, v53
	v_and_b32_e32 v53, 0xffff0000, v53
	s_waitcnt lgkmcnt(1)
	v_pk_mul_f32 v[26:27], v[78:79], v[26:27] op_sel_hi:[0,1]
	v_pk_mul_f32 v[24:25], v[78:79], v[24:25] op_sel_hi:[0,1]
	v_lshlrev_b32_e32 v82, 16, v54
	v_and_b32_e32 v83, 0xffff0000, v54
	v_lshlrev_b32_e32 v54, 16, v55
	v_and_b32_e32 v55, 0xffff0000, v55
	v_pk_fma_f32 v[60:61], v[24:25], v[80:81], v[60:61]
	v_pk_fma_f32 v[52:53], v[26:27], v[52:53], v[56:57]
	s_waitcnt lgkmcnt(0)
	v_pk_mul_f32 v[24:25], v[78:79], v[30:31] op_sel_hi:[0,1]
	v_pk_mul_f32 v[26:27], v[78:79], v[28:29] op_sel_hi:[0,1]
	v_pk_fma_f32 v[56:57], v[26:27], v[82:83], v[62:63]
	v_pk_fma_f32 v[54:55], v[24:25], v[54:55], v[58:59]
	ds_read_b128 v[24:27], v70 offset:6144
	ds_read_b128 v[28:31], v70 offset:6160
	v_cndmask_b32_e64 v58, 0, 1.0, s[12:13]
	s_waitcnt vmcnt(4)
	v_lshlrev_b32_e32 v62, 16, v48
	v_and_b32_e32 v63, 0xffff0000, v48
	v_lshlrev_b32_e32 v48, 16, v49
	v_and_b32_e32 v49, 0xffff0000, v49
	s_waitcnt lgkmcnt(1)
; #define LAS __attribute__((address_space(3)))
; __device__ __forceinline__ void unpack8(u32x4 w, f32x4& a, f32x4& b) { a = (f32x4){bf_lo(w.x), bf_hi(w.x), bf_lo(w.y), bf_hi(w.y)}; b = (f32x4){bf_lo(w.z), bf_hi(w.z), bf_lo(w.w), bf_hi(w.w)}; }
; __device__ __forceinline__ void phase_conv(CParams& p, LAS unsigned char* lds) {
;     ...
;         for (int j0 = 0; j0 < 32; j0 += 8) {
;             u32x4 xr[8]; f32x4 s0[8], s1[8];
; #pragma unroll
;             for (int jj = 0; jj < 8; ++jj) { const int j = j0 + jj; const bool ok = j < 31 && tt + j >= 30; xr[jj] = *(const u32x4*)(p.u + (size_t)(ok ? mm + j - 30 : mm) * DCV + ch0); }
;             if (!prompt) {
; #pragma unroll
;                 for (int jj = 0; jj < 8; ++jj) { const int j = j0 + jj, i = tt + j; const bool ok = j < 31 && i < 30;
;                     const float* sp = p.in[I_SCONV] + ((size_t)sidx * 30 + (ok ? i : 0)) * 512 + ch0; s0[jj] = *(const f32x4*)sp; s1[jj] = *(const f32x4*)(sp + 4); }
;             }
; #pragma unroll
;             for (int jj = 0; jj < 8; ++jj) { const int j = j0 + jj; const float f = (j < 31 && tt + j >= 30) ? 1.f : 0.f; const int jc = j < 31 ? j : 30; f32x4 x0, x1; unpack8(xr[jj], x0, x1);
;                 const f32x4 w0 = *(const LAS f32x4*)(wl + jc * 512 + ch0), w1 = *(const LAS f32x4*)(wl + jc * 512 + ch0 + 4);
;                 c0 += x0 * (w0 * f); c1 += x1 * (w1 * f);
;                 if (!prompt) { const float g = (j < 31 && tt + j < 30) ? 1.f : 0.f; c0 += s0[jj] * (w0 * g); c1 += s1[jj] * (w1 * g); } }
;         }
	v_pk_mul_f32 v[26:27], v[58:59], v[26:27] op_sel_hi:[0,1]
	v_pk_mul_f32 v[24:25], v[58:59], v[24:25] op_sel_hi:[0,1]
	v_lshlrev_b32_e32 v78, 16, v50
	v_and_b32_e32 v79, 0xffff0000, v50
	v_lshlrev_b32_e32 v50, 16, v51
	v_and_b32_e32 v51, 0xffff0000, v51
	v_pk_fma_f32 v[48:49], v[26:27], v[48:49], v[52:53]
	v_pk_fma_f32 v[52:53], v[24:25], v[62:63], v[60:61]
	s_waitcnt lgkmcnt(0)
	v_pk_mul_f32 v[24:25], v[58:59], v[30:31] op_sel_hi:[0,1]
	v_pk_mul_f32 v[26:27], v[58:59], v[28:29] op_sel_hi:[0,1]
	v_pk_fma_f32 v[50:51], v[24:25], v[50:51], v[54:55]
	v_pk_fma_f32 v[54:55], v[26:27], v[78:79], v[56:57]
	ds_read_b128 v[24:27], v70 offset:8192
	ds_read_b128 v[28:31], v70 offset:8208
	v_cndmask_b32_e64 v56, 0, 1.0, s[10:11]
	s_waitcnt vmcnt(3)
	v_lshlrev_b32_e32 v58, 16, v44
	v_and_b32_e32 v59, 0xffff0000, v44
	v_lshlrev_b32_e32 v44, 16, v45
	v_and_b32_e32 v45, 0xffff0000, v45
	s_waitcnt lgkmcnt(1)
	v_pk_mul_f32 v[26:27], v[56:57], v[26:27] op_sel_hi:[0,1]
	v_pk_mul_f32 v[24:25], v[56:57], v[24:25] op_sel_hi:[0,1]
	v_lshlrev_b32_e32 v60, 16, v46
	v_and_b32_e32 v61, 0xffff0000, v46
	v_lshlrev_b32_e32 v46, 16, v47
	v_and_b32_e32 v47, 0xffff0000, v47
	v_pk_fma_f32 v[52:53], v[24:25], v[58:59], v[52:53]
	v_pk_fma_f32 v[44:45], v[26:27], v[44:45], v[48:49]
	s_waitcnt lgkmcnt(0)
	v_pk_mul_f32 v[24:25], v[56:57], v[30:31] op_sel_hi:[0,1]
	v_pk_mul_f32 v[26:27], v[56:57], v[28:29] op_sel_hi:[0,1]
	v_pk_fma_f32 v[48:49], v[26:27], v[60:61], v[54:55]
	v_pk_fma_f32 v[46:47], v[24:25], v[46:47], v[50:51]
	ds_read_b128 v[24:27], v70 offset:10240
	ds_read_b128 v[28:31], v70 offset:10256
	v_cndmask_b32_e64 v50, 0, 1.0, s[6:7]
	s_waitcnt vmcnt(2)
	v_lshlrev_b32_e32 v54, 16, v36
	v_and_b32_e32 v55, 0xffff0000, v36
	v_lshlrev_b32_e32 v36, 16, v37
	v_and_b32_e32 v37, 0xffff0000, v37
	s_waitcnt lgkmcnt(1)
	v_pk_mul_f32 v[26:27], v[50:51], v[26:27] op_sel_hi:[0,1]
	v_pk_mul_f32 v[24:25], v[50:51], v[24:25] op_sel_hi:[0,1]
	v_lshlrev_b32_e32 v56, 16, v38
	v_and_b32_e32 v57, 0xffff0000, v38
	v_lshlrev_b32_e32 v38, 16, v39
	v_and_b32_e32 v39, 0xffff0000, v39
	v_pk_fma_f32 v[36:37], v[26:27], v[36:37], v[44:45]
	v_pk_fma_f32 v[44:45], v[24:25], v[54:55], v[52:53]
	s_waitcnt lgkmcnt(0)
	v_pk_mul_f32 v[24:25], v[50:51], v[30:31] op_sel_hi:[0,1]
	v_pk_mul_f32 v[26:27], v[50:51], v[28:29] op_sel_hi:[0,1]
	v_pk_fma_f32 v[38:39], v[24:25], v[38:39], v[46:47]
	v_pk_fma_f32 v[46:47], v[26:27], v[56:57], v[48:49]
	ds_read_b128 v[24:27], v70 offset:12288
	ds_read_b128 v[28:31], v70 offset:12304
	v_cndmask_b32_e64 v48, 0, 1.0, vcc
	s_waitcnt vmcnt(1)
	v_lshlrev_b32_e32 v50, 16, v32
	v_and_b32_e32 v51, 0xffff0000, v32
	v_lshlrev_b32_e32 v32, 16, v33
	v_and_b32_e32 v33, 0xffff0000, v33
	s_waitcnt lgkmcnt(1)
	v_pk_mul_f32 v[26:27], v[48:49], v[26:27] op_sel_hi:[0,1]
	v_pk_mul_f32 v[24:25], v[48:49], v[24:25] op_sel_hi:[0,1]
	v_lshlrev_b32_e32 v52, 16, v34
	v_and_b32_e32 v53, 0xffff0000, v34
	v_lshlrev_b32_e32 v34, 16, v35
	v_and_b32_e32 v35, 0xffff0000, v35
	v_pk_fma_f32 v[44:45], v[24:25], v[50:51], v[44:45]
	v_pk_fma_f32 v[36:37], v[26:27], v[32:33], v[36:37]
	s_waitcnt lgkmcnt(0)
	v_pk_mul_f32 v[24:25], v[48:49], v[30:31] op_sel_hi:[0,1]
	v_pk_mul_f32 v[26:27], v[48:49], v[28:29] op_sel_hi:[0,1]
	v_lshl_add_u32 v32, s1, 11, v75
	v_pk_fma_f32 v[46:47], v[26:27], v[52:53], v[46:47]
	v_pk_fma_f32 v[38:39], v[24:25], v[34:35], v[38:39]
	ds_read_b128 v[24:27], v32
	ds_read_b128 v[32:35], v32 offset:16
	v_cndmask_b32_e64 v48, 0, 1.0, s[8:9]
	s_waitcnt vmcnt(0)
	v_lshlrev_b32_e32 v28, 16, v40
	v_and_b32_e32 v29, 0xffff0000, v40
	s_waitcnt lgkmcnt(1)
	v_pk_mul_f32 v[24:25], v[48:49], v[24:25] op_sel_hi:[0,1]
	v_lshlrev_b32_e32 v30, 16, v41
	v_and_b32_e32 v31, 0xffff0000, v41
	v_lshlrev_b32_e32 v40, 16, v42
	v_and_b32_e32 v41, 0xffff0000, v42
	v_lshlrev_b32_e32 v42, 16, v43
	v_and_b32_e32 v43, 0xffff0000, v43
	v_pk_mul_f32 v[26:27], v[48:49], v[26:27] op_sel_hi:[0,1]
	v_pk_fma_f32 v[28:29], v[24:25], v[28:29], v[44:45]
	s_waitcnt lgkmcnt(0)
	v_pk_mul_f32 v[24:25], v[48:49], v[34:35] op_sel_hi:[0,1]
	v_pk_mul_f32 v[32:33], v[48:49], v[32:33] op_sel_hi:[0,1]
	v_pk_fma_f32 v[30:31], v[26:27], v[30:31], v[36:37]
	v_pk_fma_f32 v[26:27], v[24:25], v[42:43], v[38:39]
	v_pk_fma_f32 v[24:25], v[32:33], v[40:41], v[46:47]
	v_add_u32_e32 v70, 0x4000, v70
	s_cbranch_scc1 .LBB0_212
; __device__ __forceinline__ u32x4 pack8(f32x4 a, f32x4 b) { u32x4 w; w.x = pk2(a[0], a[1]); w.y = pk2(a[2], a[3]); w.z = pk2(b[0], b[1]); w.w = pk2(b[2], b[3]); return w; }
; __device__ __forceinline__ f32x4 sigm4(f32x4 v) { return (f32x4){sigm(v[0]), sigm(v[1]), sigm(v[2]), sigm(v[3])}; }
; __device__ __forceinline__ void phase_conv(CParams& p, LAS unsigned char* lds) {
;     ...
;     auto finish = [&](f32x4 c0, f32x4 c1, int mm) {
;         const float mean = wave_sum((c0[0] + c0[1]) + (c0[2] + c0[3]) + (c1[0] + c1[1]) + (c1[2] + c1[3])) * (1.f / 512.f);
;         c0 -= mean; c1 -= mean;
;         const float var = wave_sum(dot4(c0, c0) + dot4(c1, c1)) * (1.f / 512.f);
;         const float rstd = rsqrtf(var + 1e-5f);
;         c0 = c0 * rstd * lg0 + lb0; c1 = c1 * rstd * lg1 + lb1;
;         *(u32x4*)(p.sconv + (size_t)mm * DCV + ch0) = pack8(c0 * sigm4(c0), c1 * sigm4(c1));
;     };
	v_mov_b32_e32 v32, v29
	v_mov_b32_e32 v33, v30
	v_mov_b32_e32 v34, v28
	v_mov_b32_e32 v35, v31
	v_pk_add_f32 v[32:33], v[32:33], v[34:35]
	v_mov_b32_e32 v34, v26
	v_mov_b32_e32 v35, v24
	v_mov_b32_e32 v36, v27
	v_mov_b32_e32 v37, v25
	v_pk_add_f32 v[34:35], v[34:35], v[36:37]
	v_add_f32_e32 v32, v32, v33
	v_add_f32_e32 v32, v35, v32
	v_add_f32_e32 v32, v34, v32
	v_mov_b32_e32 v33, v161
	s_nop 0
	v_add_f32_dpp v32, v32, v32 quad_perm:[1,0,3,2] row_mask:0xf bank_mask:0xf bound_ctrl:1
	s_nop 1
	v_add_f32_dpp v32, v32, v32 quad_perm:[2,3,0,1] row_mask:0xf bank_mask:0xf bound_ctrl:1
	s_nop 1
	v_add_f32_dpp v32, v32, v32 row_half_mirror row_mask:0xf bank_mask:0xf bound_ctrl:1
	s_nop 1
	v_add_f32_dpp v32, v32, v32 row_mirror row_mask:0xf bank_mask:0xf bound_ctrl:1
	s_nop 1
	v_mov_b32_dpp v33, v32 row_bcast:15 row_mask:0xa bank_mask:0xf
	v_add_f32_e32 v32, v32, v33
	v_mov_b32_e32 v33, v161
	s_nop 1
	v_mov_b32_dpp v33, v32 row_bcast:31 row_mask:0xc bank_mask:0xf
	v_add_f32_e32 v32, v32, v33
	s_nop 0
	v_readlane_b32 s0, v32, 63
	s_nop 1
	v_fma_f32 v29, s0, v204, v29
	v_fma_f32 v25, s0, v204, v25
	v_fmac_f32_e32 v28, s0, v204
	v_fmac_f32_e32 v24, s0, v204
	v_mov_b32_e32 v34, v29
	v_mov_b32_e32 v35, v25
	v_fmac_f32_e32 v30, s0, v204
	v_fmac_f32_e32 v26, s0, v204
	v_mov_b32_e32 v32, v28
	v_mov_b32_e32 v33, v24
	v_pk_mul_f32 v[34:35], v[34:35], v[34:35]
	v_fma_f32 v31, s0, v204, v31
	v_fma_f32 v27, s0, v204, v27
	v_pk_fma_f32 v[32:33], v[32:33], v[32:33], v[34:35]
	v_mov_b32_e32 v34, v30
	v_mov_b32_e32 v35, v26
	v_pk_fma_f32 v[32:33], v[34:35], v[34:35], v[32:33]
	v_mov_b32_e32 v34, v31
	v_mov_b32_e32 v35, v27
	v_pk_fma_f32 v[32:33], v[34:35], v[34:35], v[32:33]
	s_nop 0
	v_add_f32_e32 v32, v32, v33
	v_mov_b32_e32 v33, v161
	s_nop 0
	v_add_f32_dpp v32, v32, v32 quad_perm:[1,0,3,2] row_mask:0xf bank_mask:0xf bound_ctrl:1
	s_nop 1
	v_add_f32_dpp v32, v32, v32 quad_perm:[2,3,0,1] row_mask:0xf bank_mask:0xf bound_ctrl:1
	s_nop 1
	v_add_f32_dpp v32, v32, v32 row_half_mirror row_mask:0xf bank_mask:0xf bound_ctrl:1
	s_nop 1
	v_add_f32_dpp v32, v32, v32 row_mirror row_mask:0xf bank_mask:0xf bound_ctrl:1
	s_nop 1
	v_mov_b32_dpp v33, v32 row_bcast:15 row_mask:0xa bank_mask:0xf
	v_add_f32_e32 v32, v32, v33
	v_mov_b32_e32 v33, v161
	s_nop 1
	v_mov_b32_dpp v33, v32 row_bcast:31 row_mask:0xc bank_mask:0xf
	v_add_f32_e32 v32, v32, v33
	s_nop 0
	v_readlane_b32 s0, v32, 63
	s_nop 1
	v_fma_f32 v32, s0, v205, v196
	s_mov_b32 s0, 0x800000
	v_mul_f32_e32 v33, 0x4b800000, v32
	v_cmp_gt_f32_e32 vcc, s0, v32
	s_nop 1
	v_cndmask_b32_e32 v32, v32, v33, vcc
	v_rsq_f32_e32 v32, v32
	s_nop 0
	v_mul_f32_e32 v33, 0x45800000, v32
	v_cndmask_b32_e32 v32, v32, v33, vcc
	v_pk_mul_f32 v[28:29], v[28:29], v[32:33] op_sel_hi:[1,0]
	v_pk_mul_f32 v[30:31], v[30:31], v[32:33] op_sel_hi:[1,0]
	v_pk_fma_f32 v[28:29], v[12:13], v[28:29], v[20:21]
	v_pk_mul_f32 v[24:25], v[24:25], v[32:33] op_sel_hi:[1,0]
	v_pk_mul_f32 v[26:27], v[26:27], v[32:33] op_sel_hi:[1,0]
	v_mul_f32_e32 v32, 0xbfb8aa3b, v28
	v_mul_f32_e32 v33, 0xbfb8aa3b, v29
	v_exp_f32_e32 v32, v32
	v_exp_f32_e32 v33, v33
	v_pk_fma_f32 v[30:31], v[14:15], v[30:31], v[22:23]
	v_pk_fma_f32 v[24:25], v[4:5], v[24:25], v[16:17]
	v_mul_f32_e32 v34, 0xbfb8aa3b, v30
	v_pk_add_f32 v[32:33], v[32:33], 1.0 op_sel_hi:[1,0]
	v_mul_f32_e32 v35, 0xbfb8aa3b, v31
	v_exp_f32_e32 v34, v34
	v_exp_f32_e32 v35, v35
	v_pk_fma_f32 v[26:27], v[6:7], v[26:27], v[18:19]
	v_rcp_f32_e32 v33, v33
	v_pk_add_f32 v[34:35], v[34:35], 1.0 op_sel_hi:[1,0]
	v_rcp_f32_e32 v32, v32
	s_nop 0
	v_pk_mul_f32 v[28:29], v[28:29], v[32:33]
	v_rcp_f32_e32 v35, v35
	v_rcp_f32_e32 v34, v34
	v_mul_f32_e32 v36, 0xbfb8aa3b, v24
	v_mul_f32_e32 v37, 0xbfb8aa3b, v25
	v_exp_f32_e32 v36, v36
	v_exp_f32_e32 v37, v37
	v_mul_f32_e32 v38, 0xbfb8aa3b, v26
	v_mul_f32_e32 v39, 0xbfb8aa3b, v27
	v_exp_f32_e32 v38, v38
	v_pk_add_f32 v[36:37], v[36:37], 1.0 op_sel_hi:[1,0]
	v_exp_f32_e32 v39, v39
	v_pk_mul_f32 v[30:31], v[30:31], v[34:35]
	v_pk_add_f32 v[32:33], v[38:39], 1.0 op_sel_hi:[1,0]
	v_rcp_f32_e32 v35, v37
	v_rcp_f32_e32 v34, v36
	v_rcp_f32_e32 v33, v33
	v_rcp_f32_e32 v32, v32
	s_nop 0
	v_pk_mul_f32 v[32:33], v[26:27], v[32:33]
	v_pk_mul_f32 v[26:27], v[24:25], v[34:35]
	v_cvt_pk_bf16_f32 v24, v28, v29
	v_cvt_pk_bf16_f32 v25, v30, v31
	s_nop 0
	v_cvt_pk_bf16_f32 v26, v26, v27
	v_cvt_pk_bf16_f32 v27, v32, v33
; #define LAS __attribute__((address_space(3)))
; __device__ __forceinline__ void unpack8(u32x4 w, f32x4& a, f32x4& b) { a = (f32x4){bf_lo(w.x), bf_hi(w.x), bf_lo(w.y), bf_hi(w.y)}; b = (f32x4){bf_lo(w.z), bf_hi(w.z), bf_lo(w.w), bf_hi(w.w)}; }
; __device__ __forceinline__ void phase_conv(CParams& p, LAS unsigned char* lds) {
;     ...
;         if (t >= 30) {
;             u32x4 xr[32];
;             const bf16_t* up = p.u + (size_t)(m - 30) * DCV + ch0;
; #pragma unroll
;             for (int j = 0; j < 32; ++j) xr[j] = *(const u32x4*)(up + (size_t)j * DCV);
;             f32x4 a0 = bd0, a1 = bd1, b0 = bd0, b1 = bd1, x0, x1, y0, y1;
;             unpack8(xr[0], x0, x1);
; #pragma unroll
;             for (int j = 0; j < 31; ++j) {
;                 unpack8(xr[j + 1], y0, y1);
;                 const f32x4 w0 = *(const LAS f32x4*)(wl + j * 512 + ch0), w1 = *(const LAS f32x4*)(wl + j * 512 + ch0 + 4);
;                 a0 += x0 * w0; a1 += x1 * w1; b0 += y0 * w0; b1 += y1 * w1;
;                 x0 = y0; x1 = y1;
;             }
.LBB0_214:
	s_andn2_saveexec_b64 s[10:11], s[22:23]
	s_cbranch_execz .LBB0_207
	v_subrev_u32_e32 v24, 30, v70
	v_ashrrev_i32_e32 v25, 31, v24
	v_lshlrev_b64 v[24:25], 10, v[24:25]
	v_lshl_add_u64 v[48:49], v[66:67], 0, v[24:25]
	global_load_dwordx4 v[44:47], v[48:49], off
	global_load_dwordx4 v[40:43], v[48:49], off offset:1024
	global_load_dwordx4 v[36:39], v[48:49], off offset:2048
	global_load_dwordx4 v[28:31], v[48:49], off offset:3072
	v_add_co_u32_e32 v24, vcc, 0x1000, v48
	s_movk_i32 s0, 0x2000
	s_nop 0
	v_addc_co_u32_e32 v25, vcc, 0, v49, vcc
	global_load_dwordx4 v[52:55], v[24:25], off
	ds_read_b128 v[56:59], v75
	ds_read_b128 v[60:63], v75 offset:16
	ds_read_b128 v[78:81], v75 offset:2048
	ds_read_b128 v[82:85], v75 offset:2064
	ds_read_b128 v[90:93], v75 offset:4096
	ds_read_b128 v[94:97], v75 offset:4112
	global_load_dwordx4 v[98:101], v[24:25], off offset:1024
	global_load_dwordx4 v[32:35], v[24:25], off offset:2048
	s_nop 0
	global_load_dwordx4 v[24:27], v[24:25], off offset:3072
	v_add_co_u32_e32 v50, vcc, s0, v48
	s_movk_i32 s0, 0x3000
	s_mov_b64 s[6:7], vcc
	s_mov_b32 s2, 0x800000
	v_ashrrev_i32_e32 v71, 31, v70
	s_waitcnt vmcnt(7)
	v_lshlrev_b32_e32 v72, 16, v44
	v_and_b32_e32 v73, 0xffff0000, v44
	v_lshlrev_b32_e32 v44, 16, v45
	v_and_b32_e32 v45, 0xffff0000, v45
	v_lshlrev_b32_e32 v86, 16, v46
	v_and_b32_e32 v87, 0xffff0000, v46
	v_lshlrev_b32_e32 v46, 16, v47
	v_and_b32_e32 v47, 0xffff0000, v47
	s_waitcnt vmcnt(6)
	v_lshlrev_b32_e32 v102, 16, v40
	v_and_b32_e32 v103, 0xffff0000, v40
	v_lshlrev_b32_e32 v40, 16, v41
	v_and_b32_e32 v41, 0xffff0000, v41
	v_lshlrev_b32_e32 v104, 16, v42
	v_and_b32_e32 v105, 0xffff0000, v42
	v_lshlrev_b32_e32 v42, 16, v43
	v_and_b32_e32 v43, 0xffff0000, v43
	s_waitcnt vmcnt(5)
	v_lshlrev_b32_e32 v106, 16, v36
	v_and_b32_e32 v107, 0xffff0000, v36
	v_lshlrev_b32_e32 v36, 16, v37
	v_and_b32_e32 v37, 0xffff0000, v37
	s_waitcnt vmcnt(4)
	v_lshlrev_b32_e32 v110, 16, v28
	v_and_b32_e32 v111, 0xffff0000, v28
	v_lshlrev_b32_e32 v112, 16, v29
	v_and_b32_e32 v113, 0xffff0000, v29
	v_lshlrev_b32_e32 v114, 16, v30
	v_and_b32_e32 v115, 0xffff0000, v30
	v_lshlrev_b32_e32 v116, 16, v31
	v_and_b32_e32 v117, 0xffff0000, v31
	s_waitcnt lgkmcnt(5)
	v_pk_fma_f32 v[28:29], v[58:59], v[44:45], v[10:11]
	v_pk_fma_f32 v[30:31], v[56:57], v[72:73], v[8:9]
	s_waitcnt lgkmcnt(4)
	v_pk_fma_f32 v[44:45], v[62:63], v[46:47], v[2:3]
	v_pk_fma_f32 v[46:47], v[60:61], v[86:87], v[0:1]
	v_pk_fma_f32 v[58:59], v[58:59], v[40:41], v[10:11]
	v_pk_fma_f32 v[56:57], v[56:57], v[102:103], v[8:9]
	v_lshlrev_b32_e32 v108, 16, v38
	v_and_b32_e32 v109, 0xffff0000, v38
	v_lshlrev_b32_e32 v38, 16, v39
	v_and_b32_e32 v39, 0xffff0000, v39
	v_pk_fma_f32 v[62:63], v[62:63], v[42:43], v[2:3]
	v_pk_fma_f32 v[60:61], v[60:61], v[104:105], v[0:1]
	s_waitcnt lgkmcnt(3)
	v_pk_fma_f32 v[28:29], v[80:81], v[40:41], v[28:29]
	s_waitcnt lgkmcnt(2)
	v_pk_fma_f32 v[40:41], v[82:83], v[104:105], v[46:47]
	v_pk_fma_f32 v[42:43], v[84:85], v[42:43], v[44:45]
	v_pk_fma_f32 v[44:45], v[78:79], v[106:107], v[56:57]
	v_pk_fma_f32 v[46:47], v[80:81], v[36:37], v[58:59]
	v_pk_fma_f32 v[56:57], v[82:83], v[108:109], v[60:61]
	v_pk_fma_f32 v[58:59], v[84:85], v[38:39], v[62:63]
	s_waitcnt vmcnt(3)
	v_lshlrev_b32_e32 v60, 16, v52
	v_and_b32_e32 v61, 0xffff0000, v52
	v_lshlrev_b32_e32 v62, 16, v53
	v_and_b32_e32 v63, 0xffff0000, v53
	s_waitcnt lgkmcnt(1)
	v_pk_fma_f32 v[52:53], v[92:93], v[36:37], v[28:29]
	v_pk_fma_f32 v[82:83], v[92:93], v[112:113], v[46:47]
	v_pk_fma_f32 v[84:85], v[90:91], v[110:111], v[44:45]
	s_waitcnt lgkmcnt(0)
	v_pk_fma_f32 v[86:87], v[96:97], v[38:39], v[42:43]
	ds_read_b128 v[36:39], v75 offset:6144
	ds_read_b128 v[44:47], v75 offset:6160
	v_add_co_u32_e32 v42, vcc, s0, v48
	v_pk_fma_f32 v[30:31], v[78:79], v[102:103], v[30:31]
	s_nop 0
	v_addc_co_u32_e32 v43, vcc, 0, v49, vcc
	v_pk_fma_f32 v[80:81], v[90:91], v[106:107], v[30:31]
	global_load_dwordx4 v[28:31], v[42:43], off offset:-4096
	v_lshlrev_b32_e32 v72, 16, v54
	v_and_b32_e32 v73, 0xffff0000, v54
	v_lshlrev_b32_e32 v78, 16, v55
	v_pk_fma_f32 v[40:41], v[94:95], v[108:109], v[40:41]
	v_pk_fma_f32 v[58:59], v[96:97], v[116:117], v[58:59]
	v_pk_fma_f32 v[56:57], v[94:95], v[114:115], v[56:57]
	v_and_b32_e32 v79, 0xffff0000, v55
	v_addc_co_u32_e64 v51, vcc, 0, v49, s[6:7]
	s_waitcnt lgkmcnt(0)
	v_pk_fma_f32 v[92:93], v[44:45], v[114:115], v[40:41]
	v_pk_fma_f32 v[86:87], v[46:47], v[116:117], v[86:87]
	v_pk_fma_f32 v[56:57], v[44:45], v[72:73], v[56:57]
	v_pk_fma_f32 v[58:59], v[46:47], v[78:79], v[58:59]
	global_load_dwordx4 v[44:47], v[50:51], off offset:1024
	v_pk_fma_f32 v[80:81], v[36:37], v[110:111], v[80:81]
	v_pk_fma_f32 v[90:91], v[38:39], v[112:113], v[52:53]
	v_pk_fma_f32 v[84:85], v[36:37], v[60:61], v[84:85]
	v_pk_fma_f32 v[82:83], v[38:39], v[62:63], v[82:83]
	ds_read_b128 v[36:39], v75 offset:8192
	ds_read_b128 v[52:55], v75 offset:8208
	s_waitcnt vmcnt(4)
	v_lshlrev_b32_e32 v94, 16, v98
	v_and_b32_e32 v95, 0xffff0000, v98
	v_lshlrev_b32_e32 v96, 16, v99
	v_and_b32_e32 v97, 0xffff0000, v99
	v_lshlrev_b32_e32 v98, 16, v100
	v_and_b32_e32 v99, 0xffff0000, v100
	v_lshlrev_b32_e32 v100, 16, v101
	v_and_b32_e32 v101, 0xffff0000, v101
	s_waitcnt lgkmcnt(1)
	v_pk_fma_f32 v[62:63], v[38:39], v[62:63], v[90:91]
	v_pk_fma_f32 v[60:61], v[36:37], v[60:61], v[80:81]
	s_waitcnt lgkmcnt(0)
	v_pk_fma_f32 v[78:79], v[54:55], v[78:79], v[86:87]
	v_pk_fma_f32 v[72:73], v[52:53], v[72:73], v[92:93]
	v_pk_fma_f32 v[80:81], v[38:39], v[96:97], v[82:83]
	v_pk_fma_f32 v[82:83], v[36:37], v[94:95], v[84:85]
	v_pk_fma_f32 v[84:85], v[54:55], v[100:101], v[58:59]
	v_pk_fma_f32 v[86:87], v[52:53], v[98:99], v[56:57]
	ds_read_b128 v[52:55], v75 offset:10240
	ds_read_b128 v[56:59], v75 offset:10256
	global_load_dwordx4 v[36:39], v[50:51], off offset:2048
	s_waitcnt vmcnt(4)
; #define LAS __attribute__((address_space(3)))
; __device__ __forceinline__ void unpack8(u32x4 w, f32x4& a, f32x4& b) { a = (f32x4){bf_lo(w.x), bf_hi(w.x), bf_lo(w.y), bf_hi(w.y)}; b = (f32x4){bf_lo(w.z), bf_hi(w.z), bf_lo(w.w), bf_hi(w.w)}; }
; __device__ __forceinline__ void phase_conv(CParams& p, LAS unsigned char* lds) {
;     ...
;         if (t >= 30) {
;             u32x4 xr[32];
;             const bf16_t* up = p.u + (size_t)(m - 30) * DCV + ch0;
; #pragma unroll
;             for (int j = 0; j < 32; ++j) xr[j] = *(const u32x4*)(up + (size_t)j * DCV);
;             f32x4 a0 = bd0, a1 = bd1, b0 = bd0, b1 = bd1, x0, x1, y0, y1;
;             unpack8(xr[0], x0, x1);
; #pragma unroll
;             for (int j = 0; j < 31; ++j) {
;                 unpack8(xr[j + 1], y0, y1);
;                 const f32x4 w0 = *(const LAS f32x4*)(wl + j * 512 + ch0), w1 = *(const LAS f32x4*)(wl + j * 512 + ch0 + 4);
;                 a0 += x0 * w0; a1 += x1 * w1; b0 += y0 * w0; b1 += y1 * w1;
;                 x0 = y0; x1 = y1;
;             }
	v_lshlrev_b32_e32 v90, 16, v32
	v_and_b32_e32 v91, 0xffff0000, v32
	s_waitcnt lgkmcnt(1)
	v_pk_fma_f32 v[94:95], v[52:53], v[94:95], v[60:61]
	v_pk_fma_f32 v[82:83], v[52:53], v[90:91], v[82:83]
	global_load_dwordx4 v[50:53], v[50:51], off offset:3072
	v_lshlrev_b32_e32 v92, 16, v33
	v_and_b32_e32 v93, 0xffff0000, v33
	v_lshlrev_b32_e32 v102, 16, v34
	v_and_b32_e32 v103, 0xffff0000, v34
	v_lshlrev_b32_e32 v104, 16, v35
	v_and_b32_e32 v105, 0xffff0000, v35
	v_pk_fma_f32 v[62:63], v[54:55], v[96:97], v[62:63]
	s_waitcnt lgkmcnt(0)
	v_pk_fma_f32 v[72:73], v[56:57], v[98:99], v[72:73]
	v_pk_fma_f32 v[78:79], v[58:59], v[100:101], v[78:79]
	v_pk_fma_f32 v[80:81], v[54:55], v[92:93], v[80:81]
	v_pk_fma_f32 v[86:87], v[56:57], v[102:103], v[86:87]
	v_pk_fma_f32 v[84:85], v[58:59], v[104:105], v[84:85]
	ds_read_b128 v[54:57], v75 offset:12288
	ds_read_b128 v[58:61], v75 offset:12304
	s_waitcnt vmcnt(4)
	v_lshlrev_b32_e32 v96, 16, v24
	v_and_b32_e32 v97, 0xffff0000, v24
	v_lshlrev_b32_e32 v98, 16, v25
	v_and_b32_e32 v99, 0xffff0000, v25
	v_lshlrev_b32_e32 v100, 16, v26
	v_and_b32_e32 v101, 0xffff0000, v26
	v_lshlrev_b32_e32 v106, 16, v27
	v_and_b32_e32 v107, 0xffff0000, v27
	s_waitcnt lgkmcnt(1)
	v_pk_fma_f32 v[62:63], v[56:57], v[92:93], v[62:63]
	v_pk_fma_f32 v[90:91], v[54:55], v[90:91], v[94:95]
	s_waitcnt lgkmcnt(0)
	v_pk_fma_f32 v[92:93], v[60:61], v[104:105], v[78:79]
	v_pk_fma_f32 v[72:73], v[58:59], v[102:103], v[72:73]
	v_pk_fma_f32 v[94:95], v[56:57], v[98:99], v[80:81]
	v_pk_fma_f32 v[82:83], v[54:55], v[96:97], v[82:83]
	v_pk_fma_f32 v[84:85], v[60:61], v[106:107], v[84:85]
	v_pk_fma_f32 v[86:87], v[58:59], v[100:101], v[86:87]
	global_load_dwordx4 v[54:57], v[42:43], off
	ds_read_b128 v[58:61], v75 offset:14336
	ds_read_b128 v[78:81], v75 offset:14352
	s_movk_i32 s0, 0x4000
	v_add_co_u32_e32 v40, vcc, s0, v48
	s_waitcnt vmcnt(4)
	v_lshlrev_b32_e32 v102, 16, v28
	v_and_b32_e32 v103, 0xffff0000, v28
	v_lshlrev_b32_e32 v104, 16, v29
	v_and_b32_e32 v105, 0xffff0000, v29
	v_lshlrev_b32_e32 v108, 16, v30
	v_and_b32_e32 v109, 0xffff0000, v30
	v_lshlrev_b32_e32 v110, 16, v31
	v_and_b32_e32 v111, 0xffff0000, v31
	s_waitcnt lgkmcnt(1)
	v_pk_fma_f32 v[90:91], v[58:59], v[96:97], v[90:91]
	v_pk_fma_f32 v[62:63], v[60:61], v[98:99], v[62:63]
	s_waitcnt lgkmcnt(0)
	v_pk_fma_f32 v[72:73], v[78:79], v[100:101], v[72:73]
	v_pk_fma_f32 v[92:93], v[80:81], v[106:107], v[92:93]
	v_pk_fma_f32 v[82:83], v[58:59], v[102:103], v[82:83]
	v_pk_fma_f32 v[94:95], v[60:61], v[104:105], v[94:95]
	v_pk_fma_f32 v[86:87], v[78:79], v[108:109], v[86:87]
	v_pk_fma_f32 v[84:85], v[80:81], v[110:111], v[84:85]
	global_load_dwordx4 v[58:61], v[42:43], off offset:1024
	ds_read_b128 v[28:31], v75 offset:16384
	ds_read_b128 v[78:81], v75 offset:16400
	s_waitcnt vmcnt(4)
	v_lshlrev_b32_e32 v96, 16, v44
	v_and_b32_e32 v97, 0xffff0000, v44
	v_lshlrev_b32_e32 v98, 16, v45
	v_and_b32_e32 v99, 0xffff0000, v45
	v_lshlrev_b32_e32 v100, 16, v46
	v_and_b32_e32 v101, 0xffff0000, v46
	v_lshlrev_b32_e32 v106, 16, v47
	v_and_b32_e32 v107, 0xffff0000, v47
	global_load_dwordx4 v[44:47], v[42:43], off offset:2048
	s_waitcnt lgkmcnt(1)
	v_pk_fma_f32 v[90:91], v[28:29], v[102:103], v[90:91]
	s_waitcnt lgkmcnt(0)
	v_pk_fma_f32 v[92:93], v[80:81], v[110:111], v[92:93]
	v_pk_fma_f32 v[72:73], v[78:79], v[108:109], v[72:73]
	v_pk_fma_f32 v[102:103], v[80:81], v[106:107], v[84:85]
	v_pk_fma_f32 v[86:87], v[78:79], v[100:101], v[86:87]
	ds_read_b128 v[78:81], v75 offset:18432
	v_pk_fma_f32 v[62:63], v[30:31], v[104:105], v[62:63]
	s_movk_i32 s0, 0x5000
	s_mov_b64 s[8:9], vcc
	v_add_co_u32_e32 v34, vcc, s0, v48
	s_waitcnt vmcnt(4)
	v_lshlrev_b32_e32 v104, 16, v36
	v_and_b32_e32 v105, 0xffff0000, v36
	v_lshlrev_b32_e32 v108, 16, v37
	v_and_b32_e32 v109, 0xffff0000, v37
	v_lshlrev_b32_e32 v110, 16, v38
	v_and_b32_e32 v111, 0xffff0000, v38
	v_lshlrev_b32_e32 v112, 16, v39
	v_and_b32_e32 v113, 0xffff0000, v39
	ds_read_b128 v[36:39], v75 offset:18448
	s_movk_i32 s0, 0x6000
	v_pk_fma_f32 v[82:83], v[28:29], v[96:97], v[82:83]
	s_mov_b64 s[6:7], vcc
	v_add_co_u32_e32 v32, vcc, s0, v48
	s_waitcnt lgkmcnt(1)
	v_pk_fma_f32 v[90:91], v[78:79], v[96:97], v[90:91]
	v_pk_fma_f32 v[96:97], v[78:79], v[104:105], v[82:83]
	global_load_dwordx4 v[82:85], v[42:43], off offset:3072
	v_addc_co_u32_e32 v33, vcc, 0, v49, vcc
	v_pk_fma_f32 v[94:95], v[30:31], v[98:99], v[94:95]
	v_addc_co_u32_e64 v41, vcc, 0, v49, s[8:9]
	v_addc_co_u32_e64 v35, vcc, 0, v49, s[6:7]
	global_load_dwordx4 v[24:27], v[32:33], off offset:3072
	v_pk_fma_f32 v[62:63], v[80:81], v[98:99], v[62:63]
	s_waitcnt lgkmcnt(0)
	v_pk_fma_f32 v[72:73], v[36:37], v[100:101], v[72:73]
	global_load_dwordx4 v[28:31], v[40:41], off offset:1024
	v_pk_fma_f32 v[92:93], v[38:39], v[106:107], v[92:93]
	v_pk_fma_f32 v[42:43], v[80:81], v[108:109], v[94:95]
	v_pk_fma_f32 v[94:95], v[38:39], v[112:113], v[102:103]
	s_waitcnt vmcnt(6)
	v_lshlrev_b32_e32 v98, 16, v50
	v_and_b32_e32 v99, 0xffff0000, v50
	v_lshlrev_b32_e32 v100, 16, v51
	v_and_b32_e32 v101, 0xffff0000, v51
	v_lshlrev_b32_e32 v102, 16, v52
	v_and_b32_e32 v103, 0xffff0000, v52
	v_lshlrev_b32_e32 v106, 16, v53
	v_and_b32_e32 v107, 0xffff0000, v53
	global_load_dwordx4 v[50:53], v[34:35], off offset:-4096
	v_pk_fma_f32 v[86:87], v[36:37], v[110:111], v[86:87]
	ds_read_b128 v[36:39], v75 offset:20480
	ds_read_b128 v[78:81], v75 offset:20496
	s_movk_i32 s0, 0x7000
	s_waitcnt lgkmcnt(1)
	v_pk_fma_f32 v[62:63], v[38:39], v[108:109], v[62:63]
	v_pk_fma_f32 v[90:91], v[36:37], v[104:105], v[90:91]
	v_pk_fma_f32 v[42:43], v[38:39], v[100:101], v[42:43]
	v_pk_fma_f32 v[96:97], v[36:37], v[98:99], v[96:97]
	ds_read_b128 v[36:39], v75 offset:22528
	s_waitcnt lgkmcnt(1)
; #define LAS __attribute__((address_space(3)))
; __device__ __forceinline__ void unpack8(u32x4 w, f32x4& a, f32x4& b) { a = (f32x4){bf_lo(w.x), bf_hi(w.x), bf_lo(w.y), bf_hi(w.y)}; b = (f32x4){bf_lo(w.z), bf_hi(w.z), bf_lo(w.w), bf_hi(w.w)}; }
; __device__ __forceinline__ void phase_conv(CParams& p, LAS unsigned char* lds) {
;     ...
;         if (t >= 30) {
;             u32x4 xr[32];
;             const bf16_t* up = p.u + (size_t)(m - 30) * DCV + ch0;
; #pragma unroll
;             for (int j = 0; j < 32; ++j) xr[j] = *(const u32x4*)(up + (size_t)j * DCV);
;             f32x4 a0 = bd0, a1 = bd1, b0 = bd0, b1 = bd1, x0, x1, y0, y1;
;             unpack8(xr[0], x0, x1);
; #pragma unroll
;             for (int j = 0; j < 31; ++j) {
;                 unpack8(xr[j + 1], y0, y1);
;                 const f32x4 w0 = *(const LAS f32x4*)(wl + j * 512 + ch0), w1 = *(const LAS f32x4*)(wl + j * 512 + ch0 + 4);
;                 a0 += x0 * w0; a1 += x1 * w1; b0 += y0 * w0; b1 += y1 * w1;
;                 x0 = y0; x1 = y1;
;             }
	v_pk_fma_f32 v[92:93], v[80:81], v[112:113], v[92:93]
	v_pk_fma_f32 v[72:73], v[78:79], v[110:111], v[72:73]
	v_pk_fma_f32 v[94:95], v[80:81], v[106:107], v[94:95]
	v_pk_fma_f32 v[86:87], v[78:79], v[102:103], v[86:87]
	s_waitcnt vmcnt(6)
	v_lshlrev_b32_e32 v104, 16, v54
	v_and_b32_e32 v105, 0xffff0000, v54
	v_lshlrev_b32_e32 v108, 16, v55
	v_and_b32_e32 v109, 0xffff0000, v55
	ds_read_b128 v[78:81], v75 offset:22544
	v_lshlrev_b32_e32 v110, 16, v56
	v_and_b32_e32 v111, 0xffff0000, v56
	v_lshlrev_b32_e32 v112, 16, v57
	v_and_b32_e32 v113, 0xffff0000, v57
	s_waitcnt lgkmcnt(1)
	v_pk_fma_f32 v[90:91], v[36:37], v[98:99], v[90:91]
	v_pk_fma_f32 v[62:63], v[38:39], v[100:101], v[62:63]
	v_pk_fma_f32 v[96:97], v[36:37], v[104:105], v[96:97]
	v_pk_fma_f32 v[42:43], v[38:39], v[108:109], v[42:43]
	ds_read_b128 v[36:39], v75 offset:24576
	ds_read_b128 v[54:57], v75 offset:24592
	s_waitcnt lgkmcnt(2)
	v_pk_fma_f32 v[72:73], v[78:79], v[102:103], v[72:73]
	v_pk_fma_f32 v[92:93], v[80:81], v[106:107], v[92:93]
	v_pk_fma_f32 v[78:79], v[78:79], v[110:111], v[86:87]
	v_pk_fma_f32 v[80:81], v[80:81], v[112:113], v[94:95]
	s_waitcnt vmcnt(5)
	v_lshlrev_b32_e32 v86, 16, v58
	v_and_b32_e32 v87, 0xffff0000, v58
	v_lshlrev_b32_e32 v58, 16, v59
	v_and_b32_e32 v59, 0xffff0000, v59
	v_lshlrev_b32_e32 v94, 16, v60
	v_and_b32_e32 v95, 0xffff0000, v60
	v_lshlrev_b32_e32 v60, 16, v61
	v_and_b32_e32 v61, 0xffff0000, v61
	s_waitcnt lgkmcnt(0)
	v_pk_fma_f32 v[92:93], v[56:57], v[112:113], v[92:93]
	v_pk_fma_f32 v[72:73], v[54:55], v[110:111], v[72:73]
	v_pk_fma_f32 v[98:99], v[38:39], v[58:59], v[42:43]
	v_pk_fma_f32 v[80:81], v[56:57], v[60:61], v[80:81]
	v_pk_fma_f32 v[78:79], v[54:55], v[94:95], v[78:79]
	s_waitcnt vmcnt(4)
	v_lshlrev_b32_e32 v100, 16, v44
	v_and_b32_e32 v101, 0xffff0000, v44
	v_lshlrev_b32_e32 v102, 16, v45
	v_and_b32_e32 v103, 0xffff0000, v45
	ds_read_b128 v[42:45], v75 offset:26624
	ds_read_b128 v[54:57], v75 offset:26640
	v_pk_fma_f32 v[62:63], v[38:39], v[108:109], v[62:63]
	v_pk_fma_f32 v[90:91], v[36:37], v[104:105], v[90:91]
	v_lshlrev_b32_e32 v104, 16, v46
	v_and_b32_e32 v105, 0xffff0000, v46
	v_lshlrev_b32_e32 v106, 16, v47
	v_and_b32_e32 v107, 0xffff0000, v47
	v_pk_fma_f32 v[96:97], v[36:37], v[86:87], v[96:97]
	s_waitcnt lgkmcnt(1)
	v_pk_fma_f32 v[86:87], v[42:43], v[86:87], v[90:91]
	v_pk_fma_f32 v[58:59], v[44:45], v[58:59], v[62:63]
	s_waitcnt lgkmcnt(0)
	v_pk_fma_f32 v[62:63], v[54:55], v[94:95], v[72:73]
	v_pk_fma_f32 v[60:61], v[56:57], v[60:61], v[92:93]
	v_pk_fma_f32 v[90:91], v[44:45], v[102:103], v[98:99]
	v_pk_fma_f32 v[78:79], v[54:55], v[104:105], v[78:79]
	v_pk_fma_f32 v[80:81], v[56:57], v[106:107], v[80:81]
	ds_read_b128 v[44:47], v75 offset:28672
	ds_read_b128 v[54:57], v75 offset:28688
	v_pk_fma_f32 v[72:73], v[42:43], v[100:101], v[96:97]
	s_waitcnt vmcnt(3)
	v_lshlrev_b32_e32 v92, 16, v82
	v_and_b32_e32 v93, 0xffff0000, v82
	v_lshlrev_b32_e32 v82, 16, v83
	v_and_b32_e32 v83, 0xffff0000, v83
	v_lshlrev_b32_e32 v94, 16, v84
	v_and_b32_e32 v95, 0xffff0000, v84
	v_lshlrev_b32_e32 v84, 16, v85
	v_and_b32_e32 v85, 0xffff0000, v85
	s_waitcnt lgkmcnt(1)
	v_pk_fma_f32 v[96:97], v[46:47], v[102:103], v[58:59]
	v_pk_fma_f32 v[86:87], v[44:45], v[100:101], v[86:87]
	s_waitcnt lgkmcnt(0)
	v_pk_fma_f32 v[98:99], v[56:57], v[106:107], v[60:61]
	v_pk_fma_f32 v[62:63], v[54:55], v[104:105], v[62:63]
	v_pk_fma_f32 v[90:91], v[46:47], v[82:83], v[90:91]
	v_pk_fma_f32 v[72:73], v[44:45], v[92:93], v[72:73]
	v_pk_fma_f32 v[80:81], v[56:57], v[84:85], v[80:81]
	v_pk_fma_f32 v[78:79], v[54:55], v[94:95], v[78:79]
	ds_read_b128 v[44:47], v75 offset:30720
	ds_read_b128 v[54:57], v75 offset:30736
	global_load_dwordx4 v[36:39], v[40:41], off offset:2048
	s_waitcnt vmcnt(1)
	v_lshlrev_b32_e32 v100, 16, v50
	v_and_b32_e32 v101, 0xffff0000, v50
	v_lshlrev_b32_e32 v102, 16, v51
	v_and_b32_e32 v103, 0xffff0000, v51
	v_lshlrev_b32_e32 v104, 16, v52
	v_and_b32_e32 v105, 0xffff0000, v52
	v_lshlrev_b32_e32 v106, 16, v53
	v_and_b32_e32 v107, 0xffff0000, v53
	ds_read_b128 v[50:53], v75 offset:32768
	s_waitcnt lgkmcnt(2)
	v_pk_fma_f32 v[86:87], v[44:45], v[92:93], v[86:87]
	v_pk_fma_f32 v[82:83], v[46:47], v[82:83], v[96:97]
	s_waitcnt lgkmcnt(1)
	v_pk_fma_f32 v[62:63], v[54:55], v[94:95], v[62:63]
	v_pk_fma_f32 v[72:73], v[44:45], v[100:101], v[72:73]
	v_pk_fma_f32 v[90:91], v[46:47], v[102:103], v[90:91]
	v_lshlrev_b32_e32 v92, 16, v28
	v_and_b32_e32 v93, 0xffff0000, v28
	v_lshlrev_b32_e32 v94, 16, v29
	v_and_b32_e32 v95, 0xffff0000, v29
	v_pk_fma_f32 v[84:85], v[56:57], v[84:85], v[98:99]
	v_pk_fma_f32 v[78:79], v[54:55], v[104:105], v[78:79]
	v_pk_fma_f32 v[80:81], v[56:57], v[106:107], v[80:81]
	ds_read_b128 v[54:57], v75 offset:32784
	s_waitcnt lgkmcnt(1)
	v_pk_fma_f32 v[82:83], v[52:53], v[102:103], v[82:83]
	v_pk_fma_f32 v[86:87], v[50:51], v[100:101], v[86:87]
	v_pk_fma_f32 v[90:91], v[52:53], v[94:95], v[90:91]
	v_pk_fma_f32 v[72:73], v[50:51], v[92:93], v[72:73]
	global_load_dwordx4 v[50:53], v[34:35], off offset:2048
	global_load_dwordx4 v[58:61], v[34:35], off
	global_load_dwordx4 v[44:47], v[34:35], off offset:1024
	v_lshlrev_b32_e32 v96, 16, v30
	global_load_dwordx4 v[40:43], v[40:41], off offset:3072
	v_and_b32_e32 v97, 0xffff0000, v30
	v_lshlrev_b32_e32 v30, 16, v31
	v_and_b32_e32 v31, 0xffff0000, v31
	s_waitcnt lgkmcnt(0)
	v_pk_fma_f32 v[84:85], v[56:57], v[106:107], v[84:85]
	v_pk_fma_f32 v[62:63], v[54:55], v[104:105], v[62:63]
	v_pk_fma_f32 v[98:99], v[56:57], v[30:31], v[80:81]
	v_pk_fma_f32 v[100:101], v[54:55], v[96:97], v[78:79]
	v_add_co_u32_e32 v28, vcc, s0, v48
	s_waitcnt vmcnt(4)
; #define LAS __attribute__((address_space(3)))
; __device__ __forceinline__ void unpack8(u32x4 w, f32x4& a, f32x4& b) { a = (f32x4){bf_lo(w.x), bf_hi(w.x), bf_lo(w.y), bf_hi(w.y)}; b = (f32x4){bf_lo(w.z), bf_hi(w.z), bf_lo(w.w), bf_hi(w.w)}; }
; __device__ __forceinline__ void phase_conv(CParams& p, LAS unsigned char* lds) {
;     ...
;         if (t >= 30) {
;             u32x4 xr[32];
;             const bf16_t* up = p.u + (size_t)(m - 30) * DCV + ch0;
; #pragma unroll
;             for (int j = 0; j < 32; ++j) xr[j] = *(const u32x4*)(up + (size_t)j * DCV);
;             f32x4 a0 = bd0, a1 = bd1, b0 = bd0, b1 = bd1, x0, x1, y0, y1;
;             unpack8(xr[0], x0, x1);
; #pragma unroll
;             for (int j = 0; j < 31; ++j) {
;                 unpack8(xr[j + 1], y0, y1);
;                 const f32x4 w0 = *(const LAS f32x4*)(wl + j * 512 + ch0), w1 = *(const LAS f32x4*)(wl + j * 512 + ch0 + 4);
;                 a0 += x0 * w0; a1 += x1 * w1; b0 += y0 * w0; b1 += y1 * w1;
;                 x0 = y0; x1 = y1;
;             }
	v_lshlrev_b32_e32 v102, 16, v36
	v_and_b32_e32 v103, 0xffff0000, v36
	v_lshlrev_b32_e32 v104, 16, v37
	v_and_b32_e32 v105, 0xffff0000, v37
	v_lshlrev_b32_e32 v106, 16, v38
	v_and_b32_e32 v107, 0xffff0000, v38
	v_lshlrev_b32_e32 v108, 16, v39
	v_and_b32_e32 v109, 0xffff0000, v39
	ds_read_b128 v[36:39], v75 offset:34816
	ds_read_b128 v[54:57], v75 offset:34832
	v_addc_co_u32_e32 v29, vcc, 0, v49, vcc
	global_load_dwordx4 v[78:81], v[34:35], off offset:3072
	s_waitcnt lgkmcnt(1)
	v_pk_fma_f32 v[48:49], v[36:37], v[92:93], v[86:87]
	v_pk_fma_f32 v[82:83], v[38:39], v[94:95], v[82:83]
	s_waitcnt lgkmcnt(0)
	v_pk_fma_f32 v[30:31], v[56:57], v[30:31], v[84:85]
	v_pk_fma_f32 v[72:73], v[36:37], v[102:103], v[72:73]
	v_pk_fma_f32 v[84:85], v[38:39], v[104:105], v[90:91]
	ds_read_b128 v[34:37], v75 offset:36864
	v_pk_fma_f32 v[62:63], v[54:55], v[96:97], v[62:63]
	v_pk_fma_f32 v[86:87], v[54:55], v[106:107], v[100:101]
	v_pk_fma_f32 v[90:91], v[56:57], v[108:109], v[98:99]
	global_load_dwordx4 v[54:57], v[28:29], off offset:-4096
	s_waitcnt vmcnt(4)
	v_lshlrev_b32_e32 v98, 16, v58
	v_and_b32_e32 v99, 0xffff0000, v58
	v_lshlrev_b32_e32 v100, 16, v59
	s_waitcnt vmcnt(2)
	v_lshlrev_b32_e32 v92, 16, v40
	v_and_b32_e32 v93, 0xffff0000, v40
	v_lshlrev_b32_e32 v94, 16, v41
	v_and_b32_e32 v95, 0xffff0000, v41
	ds_read_b128 v[38:41], v75 offset:36880
	v_lshlrev_b32_e32 v96, 16, v42
	v_and_b32_e32 v97, 0xffff0000, v42
	v_lshlrev_b32_e32 v42, 16, v43
	v_and_b32_e32 v43, 0xffff0000, v43
	s_waitcnt lgkmcnt(1)
	v_pk_fma_f32 v[82:83], v[36:37], v[104:105], v[82:83]
	v_pk_fma_f32 v[48:49], v[34:35], v[102:103], v[48:49]
	s_waitcnt lgkmcnt(0)
	v_pk_fma_f32 v[30:31], v[40:41], v[108:109], v[30:31]
	v_pk_fma_f32 v[62:63], v[38:39], v[106:107], v[62:63]
	v_pk_fma_f32 v[84:85], v[36:37], v[94:95], v[84:85]
	v_pk_fma_f32 v[72:73], v[34:35], v[92:93], v[72:73]
	v_pk_fma_f32 v[90:91], v[40:41], v[42:43], v[90:91]
	v_pk_fma_f32 v[86:87], v[38:39], v[96:97], v[86:87]
	ds_read_b128 v[34:37], v75 offset:38912
	ds_read_b128 v[38:41], v75 offset:38928
	v_and_b32_e32 v101, 0xffff0000, v59
	v_lshlrev_b32_e32 v102, 16, v60
	v_and_b32_e32 v103, 0xffff0000, v60
	v_lshlrev_b32_e32 v104, 16, v61
	v_and_b32_e32 v105, 0xffff0000, v61
	s_waitcnt lgkmcnt(1)
	v_pk_fma_f32 v[48:49], v[34:35], v[92:93], v[48:49]
	v_pk_fma_f32 v[82:83], v[36:37], v[94:95], v[82:83]
	s_waitcnt lgkmcnt(0)
	v_pk_fma_f32 v[62:63], v[38:39], v[96:97], v[62:63]
	v_pk_fma_f32 v[30:31], v[40:41], v[42:43], v[30:31]
	v_pk_fma_f32 v[42:43], v[34:35], v[98:99], v[72:73]
	v_pk_fma_f32 v[72:73], v[36:37], v[100:101], v[84:85]
	v_pk_fma_f32 v[84:85], v[38:39], v[102:103], v[86:87]
	v_pk_fma_f32 v[86:87], v[40:41], v[104:105], v[90:91]
	ds_read_b128 v[34:37], v75 offset:40960
	ds_read_b128 v[38:41], v75 offset:40976
	global_load_dwordx4 v[58:61], v[32:33], off offset:1024
	v_lshlrev_b32_e32 v90, 16, v44
	v_and_b32_e32 v91, 0xffff0000, v44
	v_lshlrev_b32_e32 v44, 16, v45
	s_waitcnt lgkmcnt(0)
	v_pk_fma_f32 v[94:95], v[40:41], v[104:105], v[30:31]
	global_load_dwordx4 v[30:33], v[32:33], off offset:2048
	v_and_b32_e32 v45, 0xffff0000, v45
	v_lshlrev_b32_e32 v92, 16, v46
	v_and_b32_e32 v93, 0xffff0000, v46
	v_lshlrev_b32_e32 v46, 16, v47
	v_and_b32_e32 v47, 0xffff0000, v47
	v_pk_fma_f32 v[82:83], v[36:37], v[100:101], v[82:83]
	v_pk_fma_f32 v[48:49], v[34:35], v[98:99], v[48:49]
	v_pk_fma_f32 v[62:63], v[38:39], v[102:103], v[62:63]
	v_pk_fma_f32 v[72:73], v[36:37], v[44:45], v[72:73]
	v_pk_fma_f32 v[42:43], v[34:35], v[90:91], v[42:43]
	v_pk_fma_f32 v[86:87], v[40:41], v[46:47], v[86:87]
	v_pk_fma_f32 v[84:85], v[38:39], v[92:93], v[84:85]
	ds_read_b128 v[34:37], v75 offset:43008
	ds_read_b128 v[38:41], v75 offset:43024
	v_lshlrev_b32_e32 v96, 16, v50
	v_and_b32_e32 v97, 0xffff0000, v50
	v_lshlrev_b32_e32 v50, 16, v51
	v_and_b32_e32 v51, 0xffff0000, v51
	v_lshlrev_b32_e32 v98, 16, v52
	v_and_b32_e32 v99, 0xffff0000, v52
	v_lshlrev_b32_e32 v52, 16, v53
	v_and_b32_e32 v53, 0xffff0000, v53
	s_waitcnt lgkmcnt(1)
	v_pk_fma_f32 v[48:49], v[34:35], v[90:91], v[48:49]
	v_pk_fma_f32 v[44:45], v[36:37], v[44:45], v[82:83]
	s_waitcnt lgkmcnt(0)
	v_pk_fma_f32 v[62:63], v[38:39], v[92:93], v[62:63]
	v_pk_fma_f32 v[46:47], v[40:41], v[46:47], v[94:95]
	v_pk_fma_f32 v[82:83], v[34:35], v[96:97], v[42:43]
	v_pk_fma_f32 v[72:73], v[36:37], v[50:51], v[72:73]
	v_pk_fma_f32 v[84:85], v[38:39], v[98:99], v[84:85]
	v_pk_fma_f32 v[86:87], v[40:41], v[52:53], v[86:87]
	ds_read_b128 v[34:37], v75 offset:45056
	ds_read_b128 v[38:41], v75 offset:45072
	s_waitcnt vmcnt(3)
	v_lshlrev_b32_e32 v90, 16, v78
	v_and_b32_e32 v91, 0xffff0000, v78
	v_lshlrev_b32_e32 v78, 16, v79
	v_and_b32_e32 v79, 0xffff0000, v79
	v_lshlrev_b32_e32 v92, 16, v80
	v_and_b32_e32 v93, 0xffff0000, v80
	v_lshlrev_b32_e32 v80, 16, v81
	v_and_b32_e32 v81, 0xffff0000, v81
	s_waitcnt lgkmcnt(1)
	v_pk_fma_f32 v[50:51], v[36:37], v[50:51], v[44:45]
	v_pk_fma_f32 v[48:49], v[34:35], v[96:97], v[48:49]
	s_waitcnt lgkmcnt(0)
	v_pk_fma_f32 v[52:53], v[40:41], v[52:53], v[46:47]
	v_pk_fma_f32 v[46:47], v[38:39], v[98:99], v[62:63]
	global_load_dwordx4 v[42:45], v[28:29], off
	v_pk_fma_f32 v[62:63], v[36:37], v[78:79], v[72:73]
	v_pk_fma_f32 v[72:73], v[34:35], v[90:91], v[82:83]
	v_pk_fma_f32 v[82:83], v[40:41], v[80:81], v[86:87]
	v_pk_fma_f32 v[84:85], v[38:39], v[92:93], v[84:85]
	ds_read_b128 v[34:37], v75 offset:47104
	ds_read_b128 v[38:41], v75 offset:47120
	s_waitcnt vmcnt(3)
	v_lshlrev_b32_e32 v86, 16, v54
	v_and_b32_e32 v87, 0xffff0000, v54
	v_lshlrev_b32_e32 v54, 16, v55
	v_and_b32_e32 v55, 0xffff0000, v55
	v_lshlrev_b32_e32 v94, 16, v56
	v_and_b32_e32 v95, 0xffff0000, v56
	v_lshlrev_b32_e32 v56, 16, v57
	v_and_b32_e32 v57, 0xffff0000, v57
	s_waitcnt lgkmcnt(1)
; #define LAS __attribute__((address_space(3)))
; __device__ __forceinline__ void unpack8(u32x4 w, f32x4& a, f32x4& b) { a = (f32x4){bf_lo(w.x), bf_hi(w.x), bf_lo(w.y), bf_hi(w.y)}; b = (f32x4){bf_lo(w.z), bf_hi(w.z), bf_lo(w.w), bf_hi(w.w)}; }
; __device__ __forceinline__ void phase_conv(CParams& p, LAS unsigned char* lds) {
;     ...
;         if (t >= 30) {
;             u32x4 xr[32];
;             const bf16_t* up = p.u + (size_t)(m - 30) * DCV + ch0;
; #pragma unroll
;             for (int j = 0; j < 32; ++j) xr[j] = *(const u32x4*)(up + (size_t)j * DCV);
;             f32x4 a0 = bd0, a1 = bd1, b0 = bd0, b1 = bd1, x0, x1, y0, y1;
;             unpack8(xr[0], x0, x1);
; #pragma unroll
;             for (int j = 0; j < 31; ++j) {
;                 unpack8(xr[j + 1], y0, y1);
;                 const f32x4 w0 = *(const LAS f32x4*)(wl + j * 512 + ch0), w1 = *(const LAS f32x4*)(wl + j * 512 + ch0 + 4);
;                 a0 += x0 * w0; a1 += x1 * w1; b0 += y0 * w0; b1 += y1 * w1;
;                 x0 = y0; x1 = y1;
;             }
	v_pk_fma_f32 v[90:91], v[34:35], v[90:91], v[48:49]
	v_pk_fma_f32 v[50:51], v[36:37], v[78:79], v[50:51]
	s_waitcnt lgkmcnt(0)
	v_pk_fma_f32 v[78:79], v[38:39], v[92:93], v[46:47]
	global_load_dwordx4 v[46:49], v[28:29], off offset:1024
	v_pk_fma_f32 v[72:73], v[34:35], v[86:87], v[72:73]
	v_pk_fma_f32 v[62:63], v[36:37], v[54:55], v[62:63]
	ds_read_b128 v[34:37], v75 offset:49152
	v_pk_fma_f32 v[80:81], v[40:41], v[80:81], v[52:53]
	v_pk_fma_f32 v[84:85], v[38:39], v[94:95], v[84:85]
	v_pk_fma_f32 v[82:83], v[40:41], v[56:57], v[82:83]
	ds_read_b128 v[38:41], v75 offset:49168
	s_waitcnt lgkmcnt(1)
	v_pk_fma_f32 v[54:55], v[36:37], v[54:55], v[50:51]
	global_load_dwordx4 v[50:53], v[28:29], off offset:2048
	v_pk_fma_f32 v[86:87], v[34:35], v[86:87], v[90:91]
	s_waitcnt vmcnt(4)
	v_lshlrev_b32_e32 v96, 16, v60
	v_and_b32_e32 v97, 0xffff0000, v60
	v_lshlrev_b32_e32 v60, 16, v61
	v_and_b32_e32 v61, 0xffff0000, v61
	s_waitcnt lgkmcnt(0)
	v_pk_fma_f32 v[56:57], v[40:41], v[56:57], v[80:81]
	v_pk_fma_f32 v[80:81], v[40:41], v[60:61], v[82:83]
	v_pk_fma_f32 v[82:83], v[38:39], v[96:97], v[84:85]
	s_waitcnt vmcnt(3)
	v_lshlrev_b32_e32 v84, 16, v30
	v_and_b32_e32 v85, 0xffff0000, v30
	v_lshlrev_b32_e32 v90, 16, v31
	v_and_b32_e32 v91, 0xffff0000, v31
	global_load_dwordx4 v[28:31], v[28:29], off offset:3072
	v_lshlrev_b32_e32 v92, 16, v58
	v_and_b32_e32 v93, 0xffff0000, v58
	v_lshlrev_b32_e32 v58, 16, v59
	v_and_b32_e32 v59, 0xffff0000, v59
	v_pk_fma_f32 v[78:79], v[38:39], v[94:95], v[78:79]
	v_pk_fma_f32 v[62:63], v[36:37], v[58:59], v[62:63]
	v_pk_fma_f32 v[72:73], v[34:35], v[92:93], v[72:73]
	ds_read_b128 v[34:37], v75 offset:51200
	ds_read_b128 v[38:41], v75 offset:51216
	v_lshlrev_b32_e32 v94, 16, v32
	v_and_b32_e32 v95, 0xffff0000, v32
	v_lshlrev_b32_e32 v98, 16, v33
	v_and_b32_e32 v99, 0xffff0000, v33
	s_waitcnt lgkmcnt(1)
	v_pk_fma_f32 v[86:87], v[34:35], v[92:93], v[86:87]
	s_waitcnt lgkmcnt(0)
	v_pk_fma_f32 v[56:57], v[40:41], v[60:61], v[56:57]
	v_pk_fma_f32 v[60:61], v[34:35], v[84:85], v[72:73]
	ds_read_b128 v[32:35], v75 offset:53248
	v_pk_fma_f32 v[54:55], v[36:37], v[58:59], v[54:55]
	v_pk_fma_f32 v[58:59], v[38:39], v[96:97], v[78:79]
	v_pk_fma_f32 v[62:63], v[36:37], v[90:91], v[62:63]
	v_pk_fma_f32 v[72:73], v[38:39], v[94:95], v[82:83]
	v_pk_fma_f32 v[40:41], v[40:41], v[98:99], v[80:81]
	v_lshlrev_b32_e32 v78, 16, v24
	v_and_b32_e32 v79, 0xffff0000, v24
	v_lshlrev_b32_e32 v80, 16, v25
	v_and_b32_e32 v81, 0xffff0000, v25
	ds_read_b128 v[36:39], v75 offset:53264
	v_lshlrev_b32_e32 v82, 16, v26
	v_and_b32_e32 v83, 0xffff0000, v26
	v_lshlrev_b32_e32 v92, 16, v27
	v_and_b32_e32 v93, 0xffff0000, v27
	s_waitcnt lgkmcnt(1)
	v_pk_fma_f32 v[54:55], v[34:35], v[90:91], v[54:55]
	v_pk_fma_f32 v[84:85], v[32:33], v[84:85], v[86:87]
	v_pk_fma_f32 v[62:63], v[34:35], v[80:81], v[62:63]
	v_pk_fma_f32 v[60:61], v[32:33], v[78:79], v[60:61]
	ds_read_b128 v[24:27], v75 offset:55296
	ds_read_b128 v[32:35], v75 offset:55312
	s_waitcnt lgkmcnt(2)
	v_pk_fma_f32 v[56:57], v[38:39], v[98:99], v[56:57]
	v_pk_fma_f32 v[58:59], v[36:37], v[94:95], v[58:59]
	v_pk_fma_f32 v[38:39], v[38:39], v[92:93], v[40:41]
	v_pk_fma_f32 v[36:37], v[36:37], v[82:83], v[72:73]
	s_waitcnt vmcnt(3)
	v_lshlrev_b32_e32 v40, 16, v42
	v_and_b32_e32 v41, 0xffff0000, v42
	v_lshlrev_b32_e32 v42, 16, v43
	v_and_b32_e32 v43, 0xffff0000, v43
	v_lshlrev_b32_e32 v72, 16, v44
	v_and_b32_e32 v73, 0xffff0000, v44
	v_lshlrev_b32_e32 v44, 16, v45
	v_and_b32_e32 v45, 0xffff0000, v45
	s_waitcnt lgkmcnt(1)
	v_pk_fma_f32 v[78:79], v[24:25], v[78:79], v[84:85]
	v_pk_fma_f32 v[54:55], v[26:27], v[80:81], v[54:55]
	s_waitcnt lgkmcnt(0)
	v_pk_fma_f32 v[58:59], v[32:33], v[82:83], v[58:59]
	v_pk_fma_f32 v[56:57], v[34:35], v[92:93], v[56:57]
	v_pk_fma_f32 v[60:61], v[24:25], v[40:41], v[60:61]
	v_pk_fma_f32 v[62:63], v[26:27], v[42:43], v[62:63]
	v_pk_fma_f32 v[36:37], v[32:33], v[72:73], v[36:37]
	v_pk_fma_f32 v[38:39], v[34:35], v[44:45], v[38:39]
	ds_read_b128 v[24:27], v75 offset:57344
	ds_read_b128 v[32:35], v75 offset:57360
	s_waitcnt vmcnt(2)
	v_lshlrev_b32_e32 v80, 16, v46
	v_and_b32_e32 v81, 0xffff0000, v46
	v_lshlrev_b32_e32 v46, 16, v47
	v_and_b32_e32 v47, 0xffff0000, v47
	v_lshlrev_b32_e32 v82, 16, v48
	v_and_b32_e32 v83, 0xffff0000, v48
	v_lshlrev_b32_e32 v48, 16, v49
	v_and_b32_e32 v49, 0xffff0000, v49
	s_waitcnt lgkmcnt(1)
	v_pk_fma_f32 v[42:43], v[26:27], v[42:43], v[54:55]
	v_pk_fma_f32 v[40:41], v[24:25], v[40:41], v[78:79]
	s_waitcnt lgkmcnt(0)
	v_pk_fma_f32 v[44:45], v[34:35], v[44:45], v[56:57]
	v_pk_fma_f32 v[54:55], v[32:33], v[72:73], v[58:59]
	v_pk_fma_f32 v[56:57], v[26:27], v[46:47], v[62:63]
	v_pk_fma_f32 v[58:59], v[24:25], v[80:81], v[60:61]
	v_pk_fma_f32 v[38:39], v[34:35], v[48:49], v[38:39]
	v_pk_fma_f32 v[36:37], v[32:33], v[82:83], v[36:37]
	ds_read_b128 v[24:27], v75 offset:59392
	ds_read_b128 v[32:35], v75 offset:59408
	s_waitcnt vmcnt(1)
	v_lshlrev_b32_e32 v60, 16, v50
	v_and_b32_e32 v61, 0xffff0000, v50
	v_lshlrev_b32_e32 v50, 16, v51
	v_and_b32_e32 v51, 0xffff0000, v51
	v_lshlrev_b32_e32 v62, 16, v52
	v_and_b32_e32 v63, 0xffff0000, v52
	v_lshlrev_b32_e32 v52, 16, v53
	v_and_b32_e32 v53, 0xffff0000, v53
	s_waitcnt lgkmcnt(1)
	v_pk_fma_f32 v[40:41], v[24:25], v[80:81], v[40:41]
	v_pk_fma_f32 v[42:43], v[26:27], v[46:47], v[42:43]
	s_waitcnt lgkmcnt(0)
	v_pk_fma_f32 v[46:47], v[32:33], v[82:83], v[54:55]
	v_pk_fma_f32 v[44:45], v[34:35], v[48:49], v[44:45]
	v_pk_fma_f32 v[48:49], v[24:25], v[60:61], v[58:59]
	v_pk_fma_f32 v[24:25], v[26:27], v[50:51], v[56:57]
	s_waitcnt vmcnt(0)
; __device__ __forceinline__ u32x4 pack8(f32x4 a, f32x4 b) { u32x4 w; w.x = pk2(a[0], a[1]); w.y = pk2(a[2], a[3]); w.z = pk2(b[0], b[1]); w.w = pk2(b[2], b[3]); return w; }
; __device__ __forceinline__ f32x4 sigm4(f32x4 v) { return (f32x4){sigm(v[0]), sigm(v[1]), sigm(v[2]), sigm(v[3])}; }
; __device__ __forceinline__ void phase_conv(CParams& p, LAS unsigned char* lds) {
;     ...
;     auto finish = [&](f32x4 c0, f32x4 c1, int mm) {
;         const float mean = wave_sum((c0[0] + c0[1]) + (c0[2] + c0[3]) + (c1[0] + c1[1]) + (c1[2] + c1[3])) * (1.f / 512.f);
;         c0 -= mean; c1 -= mean;
;         const float var = wave_sum(dot4(c0, c0) + dot4(c1, c1)) * (1.f / 512.f);
;         const float rstd = rsqrtf(var + 1e-5f);
;         c0 = c0 * rstd * lg0 + lb0; c1 = c1 * rstd * lg1 + lb1;
;         *(u32x4*)(p.sconv + (size_t)mm * DCV + ch0) = pack8(c0 * sigm4(c0), c1 * sigm4(c1));
;     };
	v_lshlrev_b32_e32 v54, 16, v28
	v_and_b32_e32 v55, 0xffff0000, v28
	v_lshlrev_b32_e32 v56, 16, v29
	v_and_b32_e32 v57, 0xffff0000, v29
	ds_read_b128 v[26:29], v75 offset:61440
	v_pk_fma_f32 v[36:37], v[32:33], v[62:63], v[36:37]
	v_pk_fma_f32 v[38:39], v[34:35], v[52:53], v[38:39]
	ds_read_b128 v[32:35], v75 offset:61456
	v_lshlrev_b32_e32 v58, 16, v30
	s_waitcnt lgkmcnt(1)
	v_pk_fma_f32 v[42:43], v[28:29], v[50:51], v[42:43]
	v_pk_fma_f32 v[40:41], v[26:27], v[60:61], v[40:41]
	v_and_b32_e32 v59, 0xffff0000, v30
	v_lshlrev_b32_e32 v72, 16, v31
	v_and_b32_e32 v73, 0xffff0000, v31
	s_waitcnt lgkmcnt(0)
	v_pk_fma_f32 v[44:45], v[34:35], v[52:53], v[44:45]
	v_pk_fma_f32 v[46:47], v[32:33], v[62:63], v[46:47]
	v_pk_fma_f32 v[24:25], v[28:29], v[56:57], v[24:25]
	v_pk_mov_b32 v[28:29], v[40:41], v[42:43] op_sel:[1,0]
	v_mov_b32_e32 v30, v40
	v_mov_b32_e32 v31, v43
	v_pk_add_f32 v[28:29], v[28:29], v[30:31]
	v_mov_b32_e32 v30, v44
	v_mov_b32_e32 v31, v46
	v_mov_b32_e32 v50, v45
	v_mov_b32_e32 v51, v47
	v_pk_add_f32 v[30:31], v[30:31], v[50:51]
	v_add_f32_e32 v28, v28, v29
	v_add_f32_e32 v28, v31, v28
	v_add_f32_e32 v28, v30, v28
	v_mov_b32_e32 v29, v161
	s_nop 0
	v_add_f32_dpp v28, v28, v28 quad_perm:[1,0,3,2] row_mask:0xf bank_mask:0xf bound_ctrl:1
	s_nop 1
	v_add_f32_dpp v28, v28, v28 quad_perm:[2,3,0,1] row_mask:0xf bank_mask:0xf bound_ctrl:1
	s_nop 1
	v_add_f32_dpp v28, v28, v28 row_half_mirror row_mask:0xf bank_mask:0xf bound_ctrl:1
	s_nop 1
	v_add_f32_dpp v28, v28, v28 row_mirror row_mask:0xf bank_mask:0xf bound_ctrl:1
	s_nop 1
	v_mov_b32_dpp v29, v28 row_bcast:15 row_mask:0xa bank_mask:0xf
	v_add_f32_e32 v28, v28, v29
	v_mov_b32_e32 v29, v161
	s_nop 1
	v_mov_b32_dpp v29, v28 row_bcast:31 row_mask:0xc bank_mask:0xf
	v_add_f32_e32 v28, v28, v29
	s_nop 0
	v_readlane_b32 s0, v28, 63
	s_nop 1
	v_fma_f32 v41, s0, v204, v41
	v_fma_f32 v47, s0, v204, v47
	v_fmac_f32_e32 v40, s0, v204
	v_fmac_f32_e32 v46, s0, v204
	v_mov_b32_e32 v30, v41
	v_mov_b32_e32 v31, v47
	v_fmac_f32_e32 v42, s0, v204
	v_fmac_f32_e32 v44, s0, v204
	v_mov_b32_e32 v28, v40
	v_mov_b32_e32 v29, v46
	v_pk_mul_f32 v[30:31], v[30:31], v[30:31]
	v_fma_f32 v43, s0, v204, v43
	v_fma_f32 v45, s0, v204, v45
	v_pk_fma_f32 v[28:29], v[28:29], v[28:29], v[30:31]
	v_mov_b32_e32 v30, v42
	v_mov_b32_e32 v31, v44
	v_pk_fma_f32 v[28:29], v[30:31], v[30:31], v[28:29]
	v_mov_b32_e32 v30, v43
	v_mov_b32_e32 v31, v45
	v_pk_fma_f32 v[28:29], v[30:31], v[30:31], v[28:29]
	v_pk_fma_f32 v[30:31], v[26:27], v[54:55], v[48:49]
	v_add_f32_e32 v28, v28, v29
	v_mov_b32_e32 v29, v161
	v_pk_fma_f32 v[26:27], v[34:35], v[72:73], v[38:39]
	v_add_f32_dpp v28, v28, v28 quad_perm:[1,0,3,2] row_mask:0xf bank_mask:0xf bound_ctrl:1
	v_or_b32_e32 v72, 1, v70
	s_nop 0
	v_add_f32_dpp v28, v28, v28 quad_perm:[2,3,0,1] row_mask:0xf bank_mask:0xf bound_ctrl:1
	s_nop 1
	v_add_f32_dpp v28, v28, v28 row_half_mirror row_mask:0xf bank_mask:0xf bound_ctrl:1
	s_nop 1
	v_add_f32_dpp v28, v28, v28 row_mirror row_mask:0xf bank_mask:0xf bound_ctrl:1
	s_nop 1
	v_mov_b32_dpp v29, v28 row_bcast:15 row_mask:0xa bank_mask:0xf
	v_add_f32_e32 v28, v28, v29
	v_mov_b32_e32 v29, v161
	s_nop 1
	v_mov_b32_dpp v29, v28 row_bcast:31 row_mask:0xc bank_mask:0xf
	v_add_f32_e32 v28, v28, v29
	s_nop 0
	v_readlane_b32 s0, v28, 63
	s_nop 1
	v_fma_f32 v28, s0, v205, v196
	v_mul_f32_e32 v29, 0x4b800000, v28
	v_cmp_gt_f32_e32 vcc, s2, v28
	s_nop 1
	v_cndmask_b32_e32 v28, v28, v29, vcc
	v_rsq_f32_e32 v50, v28
	v_pk_fma_f32 v[28:29], v[32:33], v[58:59], v[36:37]
	v_mul_f32_e32 v32, 0x45800000, v50
	v_cndmask_b32_e32 v32, v50, v32, vcc
	v_pk_mul_f32 v[34:35], v[40:41], v[32:33] op_sel_hi:[1,0]
	v_pk_mul_f32 v[36:37], v[42:43], v[32:33] op_sel_hi:[1,0]
	v_pk_fma_f32 v[34:35], v[12:13], v[34:35], v[20:21]
	v_pk_mul_f32 v[38:39], v[46:47], v[32:33] op_sel_hi:[1,0]
	v_mul_f32_e32 v40, 0xbfb8aa3b, v34
	v_mul_f32_e32 v41, 0xbfb8aa3b, v35
	v_exp_f32_e32 v40, v40
	v_exp_f32_e32 v41, v41
	v_pk_mul_f32 v[32:33], v[44:45], v[32:33] op_sel_hi:[1,0]
	v_pk_fma_f32 v[36:37], v[14:15], v[36:37], v[22:23]
	v_pk_fma_f32 v[38:39], v[4:5], v[38:39], v[16:17]
	v_pk_add_f32 v[40:41], v[40:41], 1.0 op_sel_hi:[1,0]
	v_mul_f32_e32 v42, 0xbfb8aa3b, v36
	v_mul_f32_e32 v43, 0xbfb8aa3b, v37
	v_exp_f32_e32 v42, v42
	v_exp_f32_e32 v43, v43
	v_rcp_f32_e32 v41, v41
	v_pk_add_f32 v[42:43], v[42:43], 1.0 op_sel_hi:[1,0]
	v_rcp_f32_e32 v40, v40
	v_pk_fma_f32 v[32:33], v[6:7], v[32:33], v[18:19]
	v_rcp_f32_e32 v43, v43
	v_pk_mul_f32 v[34:35], v[34:35], v[40:41]
	v_rcp_f32_e32 v42, v42
	v_mul_f32_e32 v44, 0xbfb8aa3b, v38
	v_mul_f32_e32 v45, 0xbfb8aa3b, v39
	v_exp_f32_e32 v44, v44
	v_exp_f32_e32 v45, v45
	v_mul_f32_e32 v46, 0xbfb8aa3b, v32
	v_mul_f32_e32 v47, 0xbfb8aa3b, v33
	v_exp_f32_e32 v46, v46
	v_pk_add_f32 v[44:45], v[44:45], 1.0 op_sel_hi:[1,0]
	v_exp_f32_e32 v47, v47
	v_pk_mul_f32 v[36:37], v[36:37], v[42:43]
; __device__ __forceinline__ u32x4 pack8(f32x4 a, f32x4 b) { u32x4 w; w.x = pk2(a[0], a[1]); w.y = pk2(a[2], a[3]); w.z = pk2(b[0], b[1]); w.w = pk2(b[2], b[3]); return w; }
; __device__ __forceinline__ f32x4 sigm4(f32x4 v) { return (f32x4){sigm(v[0]), sigm(v[1]), sigm(v[2]), sigm(v[3])}; }
; __device__ __forceinline__ void phase_conv(CParams& p, LAS unsigned char* lds) {
;     ...
;     auto finish = [&](f32x4 c0, f32x4 c1, int mm) {
;         const float mean = wave_sum((c0[0] + c0[1]) + (c0[2] + c0[3]) + (c1[0] + c1[1]) + (c1[2] + c1[3])) * (1.f / 512.f);
;         c0 -= mean; c1 -= mean;
;         const float var = wave_sum(dot4(c0, c0) + dot4(c1, c1)) * (1.f / 512.f);
;         const float rstd = rsqrtf(var + 1e-5f);
;         c0 = c0 * rstd * lg0 + lb0; c1 = c1 * rstd * lg1 + lb1;
;         *(u32x4*)(p.sconv + (size_t)mm * DCV + ch0) = pack8(c0 * sigm4(c0), c1 * sigm4(c1));
;     };
;     ...
;             finish(a0, a1, m); finish(b0, b1, m + 1);
	v_pk_add_f32 v[40:41], v[46:47], 1.0 op_sel_hi:[1,0]
	v_rcp_f32_e32 v43, v45
	v_rcp_f32_e32 v42, v44
	s_nop 0
	v_pk_mul_f32 v[38:39], v[38:39], v[42:43]
	v_rcp_f32_e32 v41, v41
	v_mov_b32_e32 v42, v27
	v_rcp_f32_e32 v40, v40
	s_nop 0
	v_pk_mul_f32 v[40:41], v[32:33], v[40:41]
	v_cvt_pk_bf16_f32 v32, v34, v35
	v_cvt_pk_bf16_f32 v34, v38, v39
	v_pk_mov_b32 v[38:39], v[30:31], v[24:25] op_sel:[1,0]
	v_cvt_pk_bf16_f32 v35, v40, v41
	v_mov_b32_e32 v40, v30
	v_mov_b32_e32 v41, v25
	v_pk_add_f32 v[38:39], v[38:39], v[40:41]
	v_mov_b32_e32 v40, v26
	v_mov_b32_e32 v41, v28
	v_mov_b32_e32 v43, v29
	v_pk_add_f32 v[40:41], v[40:41], v[42:43]
	v_add_f32_e32 v38, v38, v39
	v_add_f32_e32 v38, v41, v38
	v_add_f32_e32 v38, v40, v38
	v_mov_b32_e32 v39, v161
	v_cvt_pk_bf16_f32 v33, v36, v37
	v_lshlrev_b64 v[36:37], 10, v[70:71]
	v_add_f32_dpp v38, v38, v38 quad_perm:[1,0,3,2] row_mask:0xf bank_mask:0xf bound_ctrl:1
	v_lshl_add_u64 v[36:37], v[68:69], 0, v[36:37]
	global_store_dwordx4 v[36:37], v[32:35], off
	v_add_f32_dpp v38, v38, v38 quad_perm:[2,3,0,1] row_mask:0xf bank_mask:0xf bound_ctrl:1
	s_nop 1
	v_add_f32_dpp v38, v38, v38 row_half_mirror row_mask:0xf bank_mask:0xf bound_ctrl:1
	s_nop 1
	v_add_f32_dpp v38, v38, v38 row_mirror row_mask:0xf bank_mask:0xf bound_ctrl:1
	s_nop 1
	v_mov_b32_dpp v39, v38 row_bcast:15 row_mask:0xa bank_mask:0xf
	v_add_f32_e32 v38, v38, v39
	v_mov_b32_e32 v39, v161
	s_nop 1
	v_mov_b32_dpp v39, v38 row_bcast:31 row_mask:0xc bank_mask:0xf
	v_add_f32_e32 v38, v38, v39
	s_nop 0
	v_readlane_b32 s0, v38, 63
	s_nop 1
	v_fma_f32 v31, s0, v204, v31
	v_fma_f32 v29, s0, v204, v29
	v_fmac_f32_e32 v30, s0, v204
	v_fmac_f32_e32 v28, s0, v204
	v_mov_b32_e32 v40, v31
	v_mov_b32_e32 v41, v29
	v_fmac_f32_e32 v24, s0, v204
	v_fmac_f32_e32 v26, s0, v204
	v_mov_b32_e32 v38, v30
	v_mov_b32_e32 v39, v28
	v_pk_mul_f32 v[40:41], v[40:41], v[40:41]
	v_fma_f32 v25, s0, v204, v25
	v_fma_f32 v27, s0, v204, v27
	v_pk_fma_f32 v[38:39], v[38:39], v[38:39], v[40:41]
	v_mov_b32_e32 v40, v24
	v_mov_b32_e32 v41, v26
	v_pk_fma_f32 v[38:39], v[40:41], v[40:41], v[38:39]
	v_mov_b32_e32 v40, v25
	v_mov_b32_e32 v41, v27
	v_pk_fma_f32 v[38:39], v[40:41], v[40:41], v[38:39]
	s_nop 0
	v_add_f32_e32 v38, v38, v39
	v_mov_b32_e32 v39, v161
	s_nop 0
	v_add_f32_dpp v38, v38, v38 quad_perm:[1,0,3,2] row_mask:0xf bank_mask:0xf bound_ctrl:1
	s_nop 1
	v_add_f32_dpp v38, v38, v38 quad_perm:[2,3,0,1] row_mask:0xf bank_mask:0xf bound_ctrl:1
	s_nop 1
	v_add_f32_dpp v38, v38, v38 row_half_mirror row_mask:0xf bank_mask:0xf bound_ctrl:1
	s_nop 1
	v_add_f32_dpp v38, v38, v38 row_mirror row_mask:0xf bank_mask:0xf bound_ctrl:1
	s_nop 1
	v_mov_b32_dpp v39, v38 row_bcast:15 row_mask:0xa bank_mask:0xf
	v_add_f32_e32 v38, v38, v39
	v_mov_b32_e32 v39, v161
	s_nop 1
	v_mov_b32_dpp v39, v38 row_bcast:31 row_mask:0xc bank_mask:0xf
	v_add_f32_e32 v38, v38, v39
	s_nop 0
	v_readlane_b32 s0, v38, 63
	s_nop 1
	v_fma_f32 v38, s0, v205, v196
	v_mul_f32_e32 v39, 0x4b800000, v38
	v_cmp_gt_f32_e32 vcc, s2, v38
	s_nop 1
	v_cndmask_b32_e32 v38, v38, v39, vcc
	v_rsq_f32_e32 v38, v38
	s_nop 0
	v_mul_f32_e32 v32, 0x45800000, v38
	v_cndmask_b32_e32 v32, v38, v32, vcc
	v_pk_mul_f32 v[30:31], v[30:31], v[32:33] op_sel_hi:[1,0]
	v_pk_mul_f32 v[24:25], v[24:25], v[32:33] op_sel_hi:[1,0]
	v_pk_fma_f32 v[30:31], v[12:13], v[30:31], v[20:21]
	v_pk_mul_f32 v[28:29], v[28:29], v[32:33] op_sel_hi:[1,0]
	v_pk_mul_f32 v[26:27], v[26:27], v[32:33] op_sel_hi:[1,0]
	v_mul_f32_e32 v32, 0xbfb8aa3b, v30
	v_mul_f32_e32 v33, 0xbfb8aa3b, v31
	v_exp_f32_e32 v32, v32
	v_exp_f32_e32 v33, v33
	v_pk_fma_f32 v[24:25], v[14:15], v[24:25], v[22:23]
	v_pk_fma_f32 v[28:29], v[4:5], v[28:29], v[16:17]
	v_mul_f32_e32 v34, 0xbfb8aa3b, v24
	v_pk_add_f32 v[32:33], v[32:33], 1.0 op_sel_hi:[1,0]
	v_mul_f32_e32 v35, 0xbfb8aa3b, v25
	v_exp_f32_e32 v34, v34
	v_exp_f32_e32 v35, v35
	v_pk_fma_f32 v[26:27], v[6:7], v[26:27], v[18:19]
	v_rcp_f32_e32 v33, v33
	v_pk_add_f32 v[34:35], v[34:35], 1.0 op_sel_hi:[1,0]
	v_rcp_f32_e32 v32, v32
	v_rcp_f32_e32 v35, v35
	v_rcp_f32_e32 v34, v34
	v_mul_f32_e32 v36, 0xbfb8aa3b, v28
	v_mul_f32_e32 v37, 0xbfb8aa3b, v29
	v_exp_f32_e32 v36, v36
	v_exp_f32_e32 v37, v37
	v_mul_f32_e32 v38, 0xbfb8aa3b, v26
	v_mul_f32_e32 v39, 0xbfb8aa3b, v27
	v_exp_f32_e32 v38, v38
	v_pk_add_f32 v[36:37], v[36:37], 1.0 op_sel_hi:[1,0]
	v_exp_f32_e32 v39, v39
	v_pk_mul_f32 v[34:35], v[24:25], v[34:35]
	v_pk_mul_f32 v[24:25], v[30:31], v[32:33]
	v_pk_add_f32 v[30:31], v[38:39], 1.0 op_sel_hi:[1,0]
	v_rcp_f32_e32 v33, v37
	v_rcp_f32_e32 v32, v36
	v_cvt_pk_bf16_f32 v24, v24, v25
	v_rcp_f32_e32 v31, v31
	v_cvt_pk_bf16_f32 v25, v34, v35
	v_rcp_f32_e32 v30, v30
	s_nop 0
	v_pk_mul_f32 v[30:31], v[26:27], v[30:31]
	v_pk_mul_f32 v[26:27], v[28:29], v[32:33]
	s_nop 0
	v_cvt_pk_bf16_f32 v26, v26, v27
	v_cvt_pk_bf16_f32 v27, v30, v31
	s_branch .LBB0_207

; #define LAS __attribute__((address_space(3)))
; __device__ __forceinline__ void unpack8(u32x4 w, f32x4& a, f32x4& b) { a = (f32x4){bf_lo(w.x), bf_hi(w.x), bf_lo(w.y), bf_hi(w.y)}; b = (f32x4){bf_lo(w.z), bf_hi(w.z), bf_lo(w.w), bf_hi(w.w)}; }
; __device__ __forceinline__ void phase_conv(CParams& p, LAS unsigned char* lds) {
;     ...
;     auto boundary_token = [&](const int mm, const int tt, const int sidx, const bool prompt) {
;         f32x4 c0 = bd0, c1 = bd1;
; #pragma unroll 1
;         for (int j0 = 0; j0 < 32; j0 += 8) {
;             u32x4 xr[8]; f32x4 s0[8], s1[8];
; #pragma unroll
;             for (int jj = 0; jj < 8; ++jj) { const int j = j0 + jj; const bool ok = j < 31 && tt + j >= 30; xr[jj] = *(const u32x4*)(p.u + (size_t)(ok ? mm + j - 30 : mm) * DCV + ch0); }
;             if (!prompt) {
; #pragma unroll
;                 for (int jj = 0; jj < 8; ++jj) { const int j = j0 + jj, i = tt + j; const bool ok = j < 31 && i < 30;
;                     const float* sp = p.in[I_SCONV] + ((size_t)sidx * 30 + (ok ? i : 0)) * 512 + ch0; s0[jj] = *(const f32x4*)sp; s1[jj] = *(const f32x4*)(sp + 4); }
;             }
; #pragma unroll
;             for (int jj = 0; jj < 8; ++jj) { const int j = j0 + jj; const float f = (j < 31 && tt + j >= 30) ? 1.f : 0.f; const int jc = j < 31 ? j : 30; f32x4 x0, x1; unpack8(xr[jj], x0, x1);
;                 const f32x4 w0 = *(const LAS f32x4*)(wl + jc * 512 + ch0), w1 = *(const LAS f32x4*)(wl + jc * 512 + ch0 + 4);
;                 c0 += x0 * (w0 * f); c1 += x1 * (w1 * f);
;                 if (!prompt) { const float g = (j < 31 && tt + j < 30) ? 1.f : 0.f; c0 += s0[jj] * (w0 * g); c1 += s1[jj] * (w1 * g); } }
;         }
.LBB0_219:
	v_lshl_add_u64 v[108:109], v[102:103], 0, s[40:41]
	v_add_u32_e32 v101, s40, v98
	v_add_u32_e32 v111, 1, v108
	v_add_u32_e32 v110, 0x7fe2, v101
	v_add_u32_e32 v112, 0x7fe3, v101
	v_add_u32_e32 v121, 3, v108
	v_add_u32_e32 v165, 5, v108
	v_add_u32_e32 v170, 6, v108
	v_cmp_lt_u32_e64 s[14:15], 29, v108
	v_cmp_lt_u32_e64 s[30:31], 29, v111
	v_add_u32_e32 v114, 0x7fe5, v101
	v_add_u32_e32 v116, 0x7fe7, v101
	v_add_u32_e32 v119, 0x7fe8, v101
	v_cndmask_b32_e64 v118, v100, v110, s[14:15]
	v_cndmask_b32_e64 v122, v100, v112, s[30:31]
	v_cmp_lt_u32_e64 s[20:21], 29, v121
	v_cmp_lt_u32_e64 s[18:19], 29, v165
	v_cmp_lt_u32_e64 s[12:13], 29, v170
	v_cmp_gt_u32_e32 vcc, 30, v108
	v_cndmask_b32_e64 v110, v100, v114, s[20:21]
	v_cndmask_b32_e64 v114, v100, v116, s[18:19]
	v_cndmask_b32_e64 v116, v100, v119, s[12:13]
	v_ashrrev_i32_e32 v119, 31, v118
	v_ashrrev_i32_e32 v123, 31, v122
	v_cndmask_b32_e32 v160, 0, v108, vcc
	v_lshlrev_b64 v[118:119], 10, v[118:119]
	v_lshlrev_b64 v[122:123], 10, v[122:123]
	v_lshl_add_u64 v[124:125], v[104:105], 0, v[160:161]
	v_lshl_add_u64 v[118:119], v[92:93], 0, v[118:119]
	v_lshl_add_u64 v[126:127], v[92:93], 0, v[122:123]
	ds_read_b128 v[52:55], v91
	ds_read_b128 v[48:51], v91 offset:16
	ds_read_b128 v[76:79], v91 offset:2048
	ds_read_b128 v[72:75], v91 offset:2064
	ds_read_b128 v[68:71], v91 offset:4096
	ds_read_b128 v[64:67], v91 offset:4112
	ds_read_b128 v[84:87], v91 offset:6144
	ds_read_b128 v[80:83], v91 offset:6160
	ds_read_b128 v[36:39], v91 offset:8192
	ds_read_b128 v[32:35], v91 offset:8208
	ds_read_b128 v[44:47], v91 offset:10240
	ds_read_b128 v[40:43], v91 offset:10256
	ds_read_b128 v[60:63], v91 offset:12288
	ds_read_b128 v[56:59], v91 offset:12304
	v_lshlrev_b64 v[134:135], 11, v[124:125]
	global_load_dwordx4 v[122:125], v[118:119], off
	s_nop 0
	global_load_dwordx4 v[126:129], v[126:127], off
	v_cndmask_b32_e64 v130, 0, 1.0, s[14:15]
	s_waitcnt lgkmcnt(13)
	v_pk_mul_f32 v[142:143], v[130:131], v[52:53] op_sel_hi:[0,1]
	v_lshl_add_u64 v[134:135], v[94:95], 0, v[134:135]
	v_cndmask_b32_e64 v132, 0, 1.0, vcc
	v_pk_mul_f32 v[140:141], v[130:131], v[54:55] op_sel_hi:[0,1]
	v_pk_mul_f32 v[54:55], v[132:133], v[54:55] op_sel_hi:[0,1]
	v_pk_mul_f32 v[52:53], v[132:133], v[52:53] op_sel_hi:[0,1]
	v_cmp_gt_u32_e64 s[28:29], 30, v111
	v_add_u32_e32 v117, 2, v108
	v_cmp_lt_u32_e64 s[24:25], 29, v117
	v_cndmask_b32_e64 v160, 0, v111, s[28:29]
	v_cmp_gt_u32_e64 s[26:27], 30, v117
	v_lshl_add_u64 v[136:137], v[104:105], 0, v[160:161]
	v_cndmask_b32_e64 v138, 0, 1.0, s[30:31]
	s_waitcnt lgkmcnt(10)
	v_pk_mul_f32 v[146:147], v[138:139], v[72:73] op_sel_hi:[0,1]
	v_cmp_gt_u32_e64 s[16:17], 30, v121
	v_add_u32_e32 v113, 0x7fe4, v101
	s_add_i32 s0, s40, 7
	v_add_u32_e32 v145, 4, v108
	v_lshl_add_u64 v[106:107], v[108:109], 0, 7
	v_cndmask_b32_e64 v108, v100, v113, s[24:25]
	v_add_u32_e32 v115, 0x7fe6, v101
	s_cmp_lt_u32 s0, 31
	v_cmp_lt_u32_e64 s[22:23], 29, v145
	v_ashrrev_i32_e32 v109, 31, v108
	s_cselect_b64 s[2:3], -1, 0
	v_cndmask_b32_e64 v112, v100, v115, s[22:23]
	s_min_u32 s0, s0, 30
	v_ashrrev_i32_e32 v111, 31, v110
	v_ashrrev_i32_e32 v113, 31, v112
	v_ashrrev_i32_e32 v115, 31, v114
	v_lshlrev_b64 v[158:159], 10, v[112:113]
	v_lshlrev_b64 v[162:163], 10, v[114:115]
	v_cndmask_b32_e64 v160, 0, v117, s[26:27]
	v_cmp_gt_u32_e64 s[10:11], 30, v145
	v_cmp_gt_u32_e64 s[8:9], 30, v165
	v_cmp_gt_u32_e64 s[6:7], 30, v170
	v_cndmask_b32_e64 v144, 0, 1.0, s[22:23]
	v_cndmask_b32_e64 v148, 0, 1.0, s[18:19]
	v_cmp_lt_u32_e64 s[36:37], 29, v106
	v_add_u32_e32 v101, 0x7fe9, v101
	s_and_b64 s[14:15], s[2:3], s[36:37]
	v_cmp_gt_u32_e64 s[38:39], 30, v106
	v_cndmask_b32_e64 v120, v100, v101, s[14:15]
	v_ashrrev_i32_e32 v117, 31, v116
	s_and_b64 vcc, s[2:3], s[38:39]
	v_lshlrev_b64 v[116:117], 10, v[116:117]
	v_cndmask_b32_e64 v164, 0, 1.0, s[14:15]
	v_lshl_add_u64 v[116:117], v[92:93], 0, v[116:117]
	v_cndmask_b32_e32 v107, 0, v107, vcc
	v_cndmask_b32_e32 v106, 0, v106, vcc
	s_add_u32 s40, s40, 8
	s_addc_u32 s41, s41, 0
	v_add_u32_e32 v91, 0x4000, v91
	s_waitcnt vmcnt(1)
	v_lshlrev_b32_e32 v118, 16, v122
	v_and_b32_e32 v119, 0xffff0000, v122
	v_pk_fma_f32 v[28:29], v[142:143], v[118:119], v[28:29]
	v_lshlrev_b32_e32 v118, 16, v123
	v_and_b32_e32 v119, 0xffff0000, v123
	v_lshlrev_b32_e32 v122, 16, v124
	v_and_b32_e32 v123, 0xffff0000, v124
	v_pk_mul_f32 v[142:143], v[130:131], v[48:49] op_sel_hi:[0,1]
	v_lshlrev_b32_e32 v124, 16, v125
	v_and_b32_e32 v125, 0xffff0000, v125
	v_pk_fma_f32 v[122:123], v[142:143], v[122:123], v[24:25]
	v_pk_mul_f32 v[24:25], v[130:131], v[50:51] op_sel_hi:[0,1]
	v_pk_fma_f32 v[124:125], v[24:25], v[124:125], v[26:27]
	global_load_dwordx4 v[24:27], v[134:135], off
	v_pk_fma_f32 v[30:31], v[140:141], v[118:119], v[30:31]
	v_cndmask_b32_e64 v118, 0, 1.0, s[28:29]
	v_pk_mul_f32 v[48:49], v[132:133], v[48:49] op_sel_hi:[0,1]
	v_cndmask_b32_e64 v140, 0, 1.0, s[24:25]
	v_cndmask_b32_e64 v142, 0, 1.0, s[26:27]
	v_pk_mul_f32 v[50:51], v[132:133], v[50:51] op_sel_hi:[0,1]
	v_pk_mul_f32 v[132:133], v[138:139], v[74:75] op_sel_hi:[0,1]
	v_pk_mul_f32 v[74:75], v[118:119], v[74:75] op_sel_hi:[0,1]
	v_pk_mul_f32 v[72:73], v[118:119], v[72:73] op_sel_hi:[0,1]
	s_waitcnt lgkmcnt(8)
	v_pk_mul_f32 v[150:151], v[142:143], v[66:67] op_sel_hi:[0,1]
	v_cndmask_b32_e64 v130, 0, 1.0, s[20:21]
	s_waitcnt lgkmcnt(6)
	v_pk_mul_f32 v[154:155], v[130:131], v[80:81] op_sel_hi:[0,1]
	s_waitcnt vmcnt(0)
; #define LAS __attribute__((address_space(3)))
; __device__ __forceinline__ void unpack8(u32x4 w, f32x4& a, f32x4& b) { a = (f32x4){bf_lo(w.x), bf_hi(w.x), bf_lo(w.y), bf_hi(w.y)}; b = (f32x4){bf_lo(w.z), bf_hi(w.z), bf_lo(w.w), bf_hi(w.w)}; }
; __device__ __forceinline__ void phase_conv(CParams& p, LAS unsigned char* lds) {
;     ...
;     auto boundary_token = [&](const int mm, const int tt, const int sidx, const bool prompt) {
;         f32x4 c0 = bd0, c1 = bd1;
; #pragma unroll 1
;         for (int j0 = 0; j0 < 32; j0 += 8) {
;             u32x4 xr[8]; f32x4 s0[8], s1[8];
; #pragma unroll
;             for (int jj = 0; jj < 8; ++jj) { const int j = j0 + jj; const bool ok = j < 31 && tt + j >= 30; xr[jj] = *(const u32x4*)(p.u + (size_t)(ok ? mm + j - 30 : mm) * DCV + ch0); }
;             if (!prompt) {
; #pragma unroll
;                 for (int jj = 0; jj < 8; ++jj) { const int j = j0 + jj, i = tt + j; const bool ok = j < 31 && i < 30;
;                     const float* sp = p.in[I_SCONV] + ((size_t)sidx * 30 + (ok ? i : 0)) * 512 + ch0; s0[jj] = *(const f32x4*)sp; s1[jj] = *(const f32x4*)(sp + 4); }
;             }
; #pragma unroll
;             for (int jj = 0; jj < 8; ++jj) { const int j = j0 + jj; const float f = (j < 31 && tt + j >= 30) ? 1.f : 0.f; const int jc = j < 31 ? j : 30; f32x4 x0, x1; unpack8(xr[jj], x0, x1);
;                 const f32x4 w0 = *(const LAS f32x4*)(wl + jc * 512 + ch0), w1 = *(const LAS f32x4*)(wl + jc * 512 + ch0 + 4);
;                 c0 += x0 * (w0 * f); c1 += x1 * (w1 * f);
;                 if (!prompt) { const float g = (j < 31 && tt + j < 30) ? 1.f : 0.f; c0 += s0[jj] * (w0 * g); c1 += s1[jj] * (w1 * g); } }
;         }
	v_pk_fma_f32 v[30:31], v[26:27], v[54:55], v[30:31]
	v_pk_fma_f32 v[28:29], v[24:25], v[52:53], v[28:29]
	global_load_dwordx4 v[24:27], v[134:135], off offset:16
	v_pk_mul_f32 v[54:55], v[138:139], v[78:79] op_sel_hi:[0,1]
	v_pk_mul_f32 v[52:53], v[138:139], v[76:77] op_sel_hi:[0,1]
	v_pk_mul_f32 v[78:79], v[118:119], v[78:79] op_sel_hi:[0,1]
	v_pk_mul_f32 v[76:77], v[118:119], v[76:77] op_sel_hi:[0,1]
	v_lshlrev_b64 v[118:119], 11, v[136:137]
	v_pk_mul_f32 v[134:135], v[140:141], v[66:67] op_sel_hi:[0,1]
	v_lshl_add_u64 v[66:67], v[94:95], 0, v[118:119]
	s_waitcnt lgkmcnt(5)
	v_pk_mul_f32 v[118:119], v[144:145], v[38:39] op_sel_hi:[0,1]
	s_waitcnt vmcnt(0)
	v_pk_fma_f32 v[48:49], v[24:25], v[48:49], v[122:123]
	v_lshlrev_b32_e32 v24, 16, v126
	v_and_b32_e32 v25, 0xffff0000, v126
	v_pk_fma_f32 v[28:29], v[52:53], v[24:25], v[28:29]
	v_lshlrev_b32_e32 v24, 16, v127
	v_and_b32_e32 v25, 0xffff0000, v127
	v_pk_fma_f32 v[50:51], v[26:27], v[50:51], v[124:125]
	v_pk_fma_f32 v[30:31], v[54:55], v[24:25], v[30:31]
	global_load_dwordx4 v[24:27], v[66:67], off
	v_cndmask_b32_e64 v52, 0, 1.0, s[16:17]
	v_pk_mul_f32 v[156:157], v[52:53], v[84:85] op_sel_hi:[0,1]
	v_pk_mul_f32 v[138:139], v[52:53], v[82:83] op_sel_hi:[0,1]
	v_pk_mul_f32 v[136:137], v[52:53], v[80:81] op_sel_hi:[0,1]
	v_lshl_add_u32 v81, s0, 11, v152
	v_pk_mul_f32 v[124:125], v[140:141], v[70:71] op_sel_hi:[0,1]
	v_pk_mul_f32 v[122:123], v[140:141], v[68:69] op_sel_hi:[0,1]
	v_pk_mul_f32 v[140:141], v[140:141], v[64:65] op_sel_hi:[0,1]
	v_pk_mul_f32 v[70:71], v[142:143], v[70:71] op_sel_hi:[0,1]
	v_pk_mul_f32 v[68:69], v[142:143], v[68:69] op_sel_hi:[0,1]
	v_pk_mul_f32 v[142:143], v[142:143], v[64:65] op_sel_hi:[0,1]
	v_lshl_add_u64 v[64:65], v[104:105], 0, v[160:161]
	v_lshlrev_b64 v[64:65], 11, v[64:65]
	v_lshl_add_u64 v[64:65], v[94:95], 0, v[64:65]
	v_cndmask_b32_e64 v80, 0, 1.0, s[12:13]
	v_cndmask_b32_e64 v160, 0, v121, s[16:17]
	v_lshl_add_u64 v[166:167], v[104:105], 0, v[160:161]
	v_cndmask_b32_e64 v160, 0, v145, s[10:11]
	v_ashrrev_i32_e32 v121, 31, v120
	v_lshlrev_b64 v[120:121], 10, v[120:121]
	s_add_i32 s0, s40, -8
	s_cmp_lt_u32 s0, 24
	ds_read_b128 v[112:115], v81 offset:16
	s_waitcnt vmcnt(0)
	v_pk_fma_f32 v[26:27], v[26:27], v[78:79], v[30:31]
	v_pk_mul_f32 v[78:79], v[130:131], v[86:87] op_sel_hi:[0,1]
	v_pk_fma_f32 v[54:55], v[24:25], v[76:77], v[28:29]
	v_pk_mul_f32 v[76:77], v[130:131], v[84:85] op_sel_hi:[0,1]
	v_pk_mul_f32 v[24:25], v[130:131], v[82:83] op_sel_hi:[0,1]
	v_pk_mul_f32 v[130:131], v[52:53], v[86:87] op_sel_hi:[0,1]
	v_lshlrev_b32_e32 v28, 16, v128
	v_and_b32_e32 v29, 0xffff0000, v128
	v_lshlrev_b32_e32 v52, 16, v129
	v_and_b32_e32 v53, 0xffff0000, v129
	v_pk_fma_f32 v[86:87], v[146:147], v[28:29], v[48:49]
	v_pk_fma_f32 v[52:53], v[132:133], v[52:53], v[50:51]
	global_load_dwordx4 v[48:51], v[66:67], off offset:16
	v_lshlrev_b64 v[82:83], 10, v[108:109]
	v_lshlrev_b64 v[84:85], 10, v[110:111]
	ds_read_b128 v[28:31], v81
	v_lshl_add_u64 v[132:133], v[104:105], 0, v[160:161]
	v_cndmask_b32_e64 v160, 0, v165, s[8:9]
	s_waitcnt vmcnt(0)
	v_pk_fma_f32 v[74:75], v[50:51], v[74:75], v[52:53]
	v_lshl_add_u64 v[50:51], v[92:93], 0, v[82:83]
	v_lshl_add_u64 v[52:53], v[92:93], 0, v[84:85]
	v_pk_fma_f32 v[66:67], v[48:49], v[72:73], v[86:87]
	global_load_dwordx4 v[48:51], v[50:51], off
	s_nop 0
	global_load_dwordx4 v[126:129], v[52:53], off
	s_waitcnt lgkmcnt(6)
	v_pk_mul_f32 v[86:87], v[144:145], v[32:33] op_sel_hi:[0,1]
	v_pk_mul_f32 v[84:85], v[144:145], v[34:35] op_sel_hi:[0,1]
	s_waitcnt vmcnt(1)
	v_lshlrev_b32_e32 v52, 16, v48
	v_and_b32_e32 v53, 0xffff0000, v48
	v_pk_fma_f32 v[72:73], v[122:123], v[52:53], v[54:55]
	global_load_dwordx4 v[52:55], v[64:65], off
	v_lshlrev_b32_e32 v48, 16, v49
	v_and_b32_e32 v49, 0xffff0000, v49
	v_pk_fma_f32 v[26:27], v[124:125], v[48:49], v[26:27]
	v_lshlrev_b32_e32 v48, 16, v51
	v_and_b32_e32 v49, 0xffff0000, v51
	v_cndmask_b32_e64 v124, 0, 1.0, s[10:11]
	v_pk_mul_f32 v[110:111], v[124:125], v[38:39] op_sel_hi:[0,1]
	v_cndmask_b32_e64 v38, 0, 1.0, s[6:7]
	v_pk_mul_f32 v[122:123], v[144:145], v[36:37] op_sel_hi:[0,1]
	v_pk_mul_f32 v[108:109], v[124:125], v[36:37] op_sel_hi:[0,1]
	v_pk_mul_f32 v[82:83], v[124:125], v[34:35] op_sel_hi:[0,1]
	s_waitcnt lgkmcnt(3)
	v_pk_mul_f32 v[34:35], v[38:39], v[60:61] op_sel_hi:[0,1]
	s_waitcnt lgkmcnt(2)
	v_pk_mul_f32 v[36:37], v[38:39], v[58:59] op_sel_hi:[0,1]
	s_waitcnt vmcnt(0)
	v_pk_fma_f32 v[168:169], v[54:55], v[70:71], v[26:27]
	v_pk_fma_f32 v[146:147], v[52:53], v[68:69], v[72:73]
	global_load_dwordx4 v[70:73], v[64:65], off offset:16
	v_lshlrev_b32_e32 v26, 16, v50
	v_and_b32_e32 v27, 0xffff0000, v50
	v_pk_fma_f32 v[54:55], v[140:141], v[26:27], v[66:67]
	v_pk_mul_f32 v[50:51], v[148:149], v[46:47] op_sel_hi:[0,1]
	v_pk_mul_f32 v[66:67], v[148:149], v[44:45] op_sel_hi:[0,1]
	v_pk_mul_f32 v[52:53], v[148:149], v[42:43] op_sel_hi:[0,1]
	v_pk_mul_f32 v[68:69], v[148:149], v[40:41] op_sel_hi:[0,1]
	v_pk_fma_f32 v[26:27], v[134:135], v[48:49], v[74:75]
	v_pk_mul_f32 v[48:49], v[80:81], v[62:63] op_sel_hi:[0,1]
	v_pk_mul_f32 v[64:65], v[80:81], v[60:61] op_sel_hi:[0,1]
	v_cndmask_b32_e64 v74, 0, 1.0, vcc
	v_lshl_add_u64 v[134:135], v[92:93], 0, v[162:163]
	s_waitcnt vmcnt(0)
; #define LAS __attribute__((address_space(3)))
; __device__ __forceinline__ void unpack8(u32x4 w, f32x4& a, f32x4& b) { a = (f32x4){bf_lo(w.x), bf_hi(w.x), bf_lo(w.y), bf_hi(w.y)}; b = (f32x4){bf_lo(w.z), bf_hi(w.z), bf_lo(w.w), bf_hi(w.w)}; }
; __device__ __forceinline__ void phase_conv(CParams& p, LAS unsigned char* lds) {
;     ...
;     auto boundary_token = [&](const int mm, const int tt, const int sidx, const bool prompt) {
;         f32x4 c0 = bd0, c1 = bd1;
; #pragma unroll 1
;         for (int j0 = 0; j0 < 32; j0 += 8) {
;             u32x4 xr[8]; f32x4 s0[8], s1[8];
; #pragma unroll
;             for (int jj = 0; jj < 8; ++jj) { const int j = j0 + jj; const bool ok = j < 31 && tt + j >= 30; xr[jj] = *(const u32x4*)(p.u + (size_t)(ok ? mm + j - 30 : mm) * DCV + ch0); }
;             if (!prompt) {
; #pragma unroll
;                 for (int jj = 0; jj < 8; ++jj) { const int j = j0 + jj, i = tt + j; const bool ok = j < 31 && i < 30;
;                     const float* sp = p.in[I_SCONV] + ((size_t)sidx * 30 + (ok ? i : 0)) * 512 + ch0; s0[jj] = *(const f32x4*)sp; s1[jj] = *(const f32x4*)(sp + 4); }
;             }
; #pragma unroll
;             for (int jj = 0; jj < 8; ++jj) { const int j = j0 + jj; const float f = (j < 31 && tt + j >= 30) ? 1.f : 0.f; const int jc = j < 31 ? j : 30; f32x4 x0, x1; unpack8(xr[jj], x0, x1);
;                 const f32x4 w0 = *(const LAS f32x4*)(wl + jc * 512 + ch0), w1 = *(const LAS f32x4*)(wl + jc * 512 + ch0 + 4);
;                 c0 += x0 * (w0 * f); c1 += x1 * (w1 * f);
;                 if (!prompt) { const float g = (j < 31 && tt + j < 30) ? 1.f : 0.f; c0 += s0[jj] * (w0 * g); c1 += s1[jj] * (w1 * g); } }
;         }
	v_pk_fma_f32 v[148:149], v[70:71], v[142:143], v[54:55]
	v_pk_mul_f32 v[54:55], v[80:81], v[58:59] op_sel_hi:[0,1]
	v_pk_mul_f32 v[70:71], v[80:81], v[56:57] op_sel_hi:[0,1]
	v_pk_mul_f32 v[80:81], v[124:125], v[32:33] op_sel_hi:[0,1]
	v_cndmask_b32_e64 v32, 0, 1.0, s[8:9]
	v_pk_mul_f32 v[46:47], v[32:33], v[46:47] op_sel_hi:[0,1]
	v_pk_mul_f32 v[44:45], v[32:33], v[44:45] op_sel_hi:[0,1]
	v_pk_mul_f32 v[42:43], v[32:33], v[42:43] op_sel_hi:[0,1]
	v_pk_mul_f32 v[40:41], v[32:33], v[40:41] op_sel_hi:[0,1]
	v_pk_mul_f32 v[32:33], v[38:39], v[62:63] op_sel_hi:[0,1]
	v_pk_mul_f32 v[38:39], v[38:39], v[56:57] op_sel_hi:[0,1]
	v_lshl_add_u64 v[56:57], v[92:93], 0, v[158:159]
	v_lshlrev_b32_e32 v58, 16, v126
	v_and_b32_e32 v59, 0xffff0000, v126
	v_pk_fma_f32 v[62:63], v[76:77], v[58:59], v[146:147]
	global_load_dwordx4 v[144:147], v[56:57], off
	v_lshlrev_b64 v[56:57], 11, v[166:167]
	v_lshl_add_u64 v[140:141], v[94:95], 0, v[56:57]
	global_load_dwordx4 v[58:61], v[140:141], off
	v_lshlrev_b32_e32 v56, 16, v127
	v_and_b32_e32 v57, 0xffff0000, v127
	v_pk_fma_f32 v[26:27], v[72:73], v[150:151], v[26:27]
	v_pk_fma_f32 v[56:57], v[78:79], v[56:57], v[168:169]
	v_lshlrev_b32_e32 v150, 16, v128
	v_and_b32_e32 v151, 0xffff0000, v128
	s_waitcnt lgkmcnt(0)
	v_pk_mul_f32 v[76:77], v[164:165], v[28:29] op_sel_hi:[0,1]
	v_lshlrev_b32_e32 v142, 16, v129
	v_and_b32_e32 v143, 0xffff0000, v129
	v_pk_mul_f32 v[78:79], v[164:165], v[112:113] op_sel_hi:[0,1]
	v_pk_mul_f32 v[72:73], v[74:75], v[114:115] op_sel_hi:[0,1]
	v_lshl_add_u64 v[124:125], v[104:105], 0, v[160:161]
	v_cndmask_b32_e64 v160, 0, v170, s[6:7]
	s_waitcnt vmcnt(1)
	v_lshlrev_b32_e32 v128, 16, v145
	v_and_b32_e32 v129, 0xffff0000, v145
	s_waitcnt vmcnt(0)
	v_pk_fma_f32 v[126:127], v[60:61], v[130:131], v[56:57]
	v_pk_mul_f32 v[56:57], v[164:165], v[30:31] op_sel_hi:[0,1]
	v_pk_fma_f32 v[130:131], v[58:59], v[156:157], v[62:63]
	v_pk_mul_f32 v[60:61], v[74:75], v[30:31] op_sel_hi:[0,1]
	v_pk_mul_f32 v[62:63], v[74:75], v[28:29] op_sel_hi:[0,1]
	global_load_dwordx4 v[28:31], v[134:135], off
	v_lshlrev_b32_e32 v134, 16, v144
	v_and_b32_e32 v135, 0xffff0000, v144
	v_pk_fma_f32 v[144:145], v[154:155], v[150:151], v[148:149]
	global_load_dwordx4 v[154:157], v[116:117], off
	v_lshl_add_u64 v[116:117], v[92:93], 0, v[120:121]
	v_pk_fma_f32 v[120:121], v[24:25], v[142:143], v[26:27]
	global_load_dwordx4 v[24:27], v[116:117], off
	s_nop 0
	global_load_dwordx4 v[140:143], v[140:141], off offset:16
	v_pk_mul_f32 v[58:59], v[164:165], v[114:115] op_sel_hi:[0,1]
	v_pk_mul_f32 v[74:75], v[74:75], v[112:113] op_sel_hi:[0,1]
	v_lshlrev_b32_e32 v114, 16, v146
	v_and_b32_e32 v115, 0xffff0000, v146
	v_lshlrev_b32_e32 v112, 16, v147
	v_and_b32_e32 v113, 0xffff0000, v147
	v_pk_fma_f32 v[130:131], v[122:123], v[134:135], v[130:131]
	v_pk_fma_f32 v[118:119], v[118:119], v[128:129], v[126:127]
	s_waitcnt vmcnt(3)
	v_lshlrev_b32_e32 v116, 16, v28
	v_and_b32_e32 v117, 0xffff0000, v28
	v_lshlrev_b32_e32 v146, 16, v31
	v_and_b32_e32 v147, 0xffff0000, v31
	s_waitcnt vmcnt(0)
	v_pk_fma_f32 v[148:149], v[142:143], v[138:139], v[120:121]
	v_lshlrev_b32_e32 v138, 16, v29
	v_and_b32_e32 v139, 0xffff0000, v29
	v_lshl_add_u64 v[28:29], v[106:107], 0, v[104:105]
	v_lshlrev_b32_e32 v142, 16, v30
	v_and_b32_e32 v143, 0xffff0000, v30
	v_lshlrev_b64 v[28:29], 11, v[28:29]
	v_lshlrev_b64 v[30:31], 11, v[132:133]
	v_pk_fma_f32 v[150:151], v[140:141], v[136:137], v[144:145]
	v_lshlrev_b32_e32 v120, 16, v154
	v_and_b32_e32 v121, 0xffff0000, v154
	v_lshlrev_b32_e32 v136, 16, v155
	v_and_b32_e32 v137, 0xffff0000, v155
	v_lshl_add_u64 v[154:155], v[94:95], 0, v[28:29]
	v_lshl_add_u64 v[106:107], v[94:95], 0, v[30:31]
	v_lshlrev_b64 v[132:133], 11, v[124:125]
	global_load_dwordx4 v[28:31], v[154:155], off
	global_load_dwordx4 v[122:125], v[106:107], off
	v_lshlrev_b32_e32 v140, 16, v156
	v_and_b32_e32 v141, 0xffff0000, v156
	v_lshlrev_b32_e32 v144, 16, v157
	v_and_b32_e32 v145, 0xffff0000, v157
	v_lshl_add_u64 v[156:157], v[104:105], 0, v[160:161]
	v_pk_fma_f32 v[114:115], v[86:87], v[114:115], v[150:151]
	v_pk_fma_f32 v[148:149], v[84:85], v[112:113], v[148:149]
	s_waitcnt vmcnt(0)
	v_pk_fma_f32 v[118:119], v[124:125], v[110:111], v[118:119]
	global_load_dwordx4 v[124:127], v[106:107], off offset:16
	v_lshl_add_u64 v[110:111], v[94:95], 0, v[132:133]
	v_lshlrev_b64 v[132:133], 11, v[156:157]
	v_pk_fma_f32 v[122:123], v[122:123], v[108:109], v[130:131]
	global_load_dwordx4 v[106:109], v[110:111], off
	global_load_dwordx4 v[128:131], v[110:111], off offset:16
	v_lshl_add_u64 v[110:111], v[94:95], 0, v[132:133]
	global_load_dwordx4 v[132:135], v[110:111], off
	global_load_dwordx4 v[84:87], v[110:111], off offset:16
	s_nop 0
	global_load_dwordx4 v[110:113], v[154:155], off offset:16
	v_pk_fma_f32 v[66:67], v[66:67], v[116:117], v[122:123]
	v_pk_fma_f32 v[50:51], v[50:51], v[138:139], v[118:119]
	s_waitcnt vmcnt(5)
	v_pk_fma_f32 v[82:83], v[126:127], v[82:83], v[148:149]
	v_pk_fma_f32 v[80:81], v[124:125], v[80:81], v[114:115]
	v_pk_fma_f32 v[52:53], v[52:53], v[146:147], v[82:83]
	v_pk_fma_f32 v[68:69], v[68:69], v[142:143], v[80:81]
	s_waitcnt vmcnt(4)
	v_pk_fma_f32 v[46:47], v[108:109], v[46:47], v[50:51]
	v_pk_fma_f32 v[44:45], v[106:107], v[44:45], v[66:67]
	s_waitcnt vmcnt(3)
	v_pk_fma_f32 v[42:43], v[130:131], v[42:43], v[52:53]
	v_pk_fma_f32 v[40:41], v[128:129], v[40:41], v[68:69]
	v_pk_fma_f32 v[44:45], v[64:65], v[120:121], v[44:45]
	v_pk_fma_f32 v[46:47], v[48:49], v[136:137], v[46:47]
	v_pk_fma_f32 v[40:41], v[70:71], v[140:141], v[40:41]
	v_pk_fma_f32 v[42:43], v[54:55], v[144:145], v[42:43]
	v_lshlrev_b32_e32 v126, 16, v24
	v_and_b32_e32 v127, 0xffff0000, v24
	v_lshlrev_b32_e32 v24, 16, v25
	v_and_b32_e32 v25, 0xffff0000, v25
	v_lshlrev_b32_e32 v114, 16, v26
	v_and_b32_e32 v115, 0xffff0000, v26
	v_lshlrev_b32_e32 v26, 16, v27
	v_and_b32_e32 v27, 0xffff0000, v27
	s_waitcnt vmcnt(2)
	v_pk_fma_f32 v[32:33], v[134:135], v[32:33], v[46:47]
	v_pk_fma_f32 v[34:35], v[132:133], v[34:35], v[44:45]
	s_waitcnt vmcnt(1)
	v_pk_fma_f32 v[36:37], v[86:87], v[36:37], v[42:43]
	v_pk_fma_f32 v[38:39], v[84:85], v[38:39], v[40:41]
	v_pk_fma_f32 v[34:35], v[76:77], v[126:127], v[34:35]
	v_pk_fma_f32 v[24:25], v[56:57], v[24:25], v[32:33]
	v_pk_fma_f32 v[32:33], v[78:79], v[114:115], v[38:39]
	v_pk_fma_f32 v[26:27], v[58:59], v[26:27], v[36:37]
	v_pk_fma_f32 v[30:31], v[30:31], v[60:61], v[24:25]
	v_pk_fma_f32 v[28:29], v[28:29], v[62:63], v[34:35]
	s_waitcnt vmcnt(0)
	v_pk_fma_f32 v[26:27], v[112:113], v[72:73], v[26:27]
	v_pk_fma_f32 v[24:25], v[110:111], v[74:75], v[32:33]
	s_cbranch_scc1 .LBB0_219
; __device__ __forceinline__ u32x4 pack8(f32x4 a, f32x4 b) { u32x4 w; w.x = pk2(a[0], a[1]); w.y = pk2(a[2], a[3]); w.z = pk2(b[0], b[1]); w.w = pk2(b[2], b[3]); return w; }
; __device__ __forceinline__ f32x4 sigm4(f32x4 v) { return (f32x4){sigm(v[0]), sigm(v[1]), sigm(v[2]), sigm(v[3])}; }
; __device__ __forceinline__ void phase_conv(CParams& p, LAS unsigned char* lds) {
;     ...
;     auto finish = [&](f32x4 c0, f32x4 c1, int mm) {
;         const float mean = wave_sum((c0[0] + c0[1]) + (c0[2] + c0[3]) + (c1[0] + c1[1]) + (c1[2] + c1[3])) * (1.f / 512.f);
;         c0 -= mean; c1 -= mean;
;         const float var = wave_sum(dot4(c0, c0) + dot4(c1, c1)) * (1.f / 512.f);
;         const float rstd = rsqrtf(var + 1e-5f);
;         c0 = c0 * rstd * lg0 + lb0; c1 = c1 * rstd * lg1 + lb1;
;         *(u32x4*)(p.sconv + (size_t)mm * DCV + ch0) = pack8(c0 * sigm4(c0), c1 * sigm4(c1));
;     };
;     ...
;     for (int st = wid * (int)gridDim.x + (int)blockIdx.x; st < MS; st += nw) boundary_token(MP + st, st & 15, st >> 4, false);
	v_mov_b32_e32 v32, v29
	v_mov_b32_e32 v33, v30
	v_mov_b32_e32 v34, v28
	v_mov_b32_e32 v35, v31
	v_pk_add_f32 v[32:33], v[32:33], v[34:35]
	v_mov_b32_e32 v34, v26
	v_mov_b32_e32 v35, v24
	v_mov_b32_e32 v36, v27
	v_mov_b32_e32 v37, v25
	v_pk_add_f32 v[34:35], v[34:35], v[36:37]
	v_add_f32_e32 v32, v32, v33
	v_add_f32_e32 v32, v35, v32
	v_add_f32_e32 v32, v34, v32
	v_mov_b32_e32 v33, v161
	v_ashrrev_i32_e32 v101, 31, v100
	v_add_f32_dpp v32, v32, v32 quad_perm:[1,0,3,2] row_mask:0xf bank_mask:0xf bound_ctrl:1
	v_add_u32_e32 v90, s64, v90
	v_lshl_add_u64 v[98:99], v[98:99], 0, s[64:65]
	v_add_f32_dpp v32, v32, v32 quad_perm:[2,3,0,1] row_mask:0xf bank_mask:0xf bound_ctrl:1
	v_subrev_u16_e32 v153, s64, v153
	s_nop 0
	v_add_f32_dpp v32, v32, v32 row_half_mirror row_mask:0xf bank_mask:0xf bound_ctrl:1
	s_nop 1
	v_add_f32_dpp v32, v32, v32 row_mirror row_mask:0xf bank_mask:0xf bound_ctrl:1
	s_nop 1
	v_mov_b32_dpp v33, v32 row_bcast:15 row_mask:0xa bank_mask:0xf
	v_add_f32_e32 v32, v32, v33
	v_mov_b32_e32 v33, v161
	s_nop 1
	v_mov_b32_dpp v33, v32 row_bcast:31 row_mask:0xc bank_mask:0xf
	v_add_f32_e32 v32, v32, v33
	s_nop 0
	v_readlane_b32 s0, v32, 63
	s_nop 1
	v_fma_f32 v29, s0, v204, v29
	v_fma_f32 v25, s0, v204, v25
	v_fmac_f32_e32 v28, s0, v204
	v_fmac_f32_e32 v24, s0, v204
	v_mov_b32_e32 v34, v29
	v_mov_b32_e32 v35, v25
	v_fmac_f32_e32 v30, s0, v204
	v_fmac_f32_e32 v26, s0, v204
	v_mov_b32_e32 v32, v28
	v_mov_b32_e32 v33, v24
	v_pk_mul_f32 v[34:35], v[34:35], v[34:35]
	v_fma_f32 v31, s0, v204, v31
	v_fma_f32 v27, s0, v204, v27
	v_pk_fma_f32 v[32:33], v[32:33], v[32:33], v[34:35]
	v_mov_b32_e32 v34, v30
	v_mov_b32_e32 v35, v26
	v_pk_fma_f32 v[32:33], v[34:35], v[34:35], v[32:33]
	v_mov_b32_e32 v34, v31
	v_mov_b32_e32 v35, v27
	v_pk_fma_f32 v[32:33], v[34:35], v[34:35], v[32:33]
	s_nop 0
	v_add_f32_e32 v32, v32, v33
	v_mov_b32_e32 v33, v161
	s_nop 0
	v_add_f32_dpp v32, v32, v32 quad_perm:[1,0,3,2] row_mask:0xf bank_mask:0xf bound_ctrl:1
	s_nop 1
	v_add_f32_dpp v32, v32, v32 quad_perm:[2,3,0,1] row_mask:0xf bank_mask:0xf bound_ctrl:1
	s_nop 1
	v_add_f32_dpp v32, v32, v32 row_half_mirror row_mask:0xf bank_mask:0xf bound_ctrl:1
	s_nop 1
	v_add_f32_dpp v32, v32, v32 row_mirror row_mask:0xf bank_mask:0xf bound_ctrl:1
	s_nop 1
	v_mov_b32_dpp v33, v32 row_bcast:15 row_mask:0xa bank_mask:0xf
	v_add_f32_e32 v32, v32, v33
	v_mov_b32_e32 v33, v161
	s_nop 1
	v_mov_b32_dpp v33, v32 row_bcast:31 row_mask:0xc bank_mask:0xf
	v_add_f32_e32 v32, v32, v33
	s_nop 0
	v_readlane_b32 s0, v32, 63
	s_nop 1
	v_fma_f32 v32, s0, v205, v196
	s_mov_b32 s0, 0x800000
	v_cmp_gt_f32_e32 vcc, s0, v32
	v_mul_f32_e32 v33, 0x4b800000, v32
	s_nop 0
	v_cndmask_b32_e32 v32, v32, v33, vcc
	v_rsq_f32_e32 v32, v32
	s_nop 0
	v_mul_f32_e32 v33, 0x45800000, v32
	v_cndmask_b32_e32 v32, v32, v33, vcc
	v_pk_mul_f32 v[28:29], v[28:29], v[32:33] op_sel_hi:[1,0]
	v_pk_mul_f32 v[30:31], v[30:31], v[32:33] op_sel_hi:[1,0]
	v_pk_fma_f32 v[28:29], v[12:13], v[28:29], v[20:21]
	v_pk_mul_f32 v[24:25], v[24:25], v[32:33] op_sel_hi:[1,0]
	v_pk_mul_f32 v[26:27], v[26:27], v[32:33] op_sel_hi:[1,0]
	v_mul_f32_e32 v32, 0xbfb8aa3b, v28
	v_mul_f32_e32 v33, 0xbfb8aa3b, v29
	v_exp_f32_e32 v32, v32
	v_exp_f32_e32 v33, v33
	v_pk_fma_f32 v[30:31], v[14:15], v[30:31], v[22:23]
	v_pk_fma_f32 v[24:25], v[4:5], v[24:25], v[16:17]
	v_mul_f32_e32 v34, 0xbfb8aa3b, v30
	v_pk_add_f32 v[32:33], v[32:33], 1.0 op_sel_hi:[1,0]
	v_mul_f32_e32 v35, 0xbfb8aa3b, v31
	v_exp_f32_e32 v34, v34
	v_exp_f32_e32 v35, v35
	v_pk_fma_f32 v[26:27], v[6:7], v[26:27], v[18:19]
	v_rcp_f32_e32 v33, v33
	v_pk_add_f32 v[34:35], v[34:35], 1.0 op_sel_hi:[1,0]
	v_rcp_f32_e32 v32, v32
	s_nop 0
	v_pk_mul_f32 v[28:29], v[28:29], v[32:33]
	v_mul_f32_e32 v32, 0xbfb8aa3b, v24
	v_mul_f32_e32 v33, 0xbfb8aa3b, v25
	v_rcp_f32_e32 v35, v35
	v_exp_f32_e32 v32, v32
	v_exp_f32_e32 v33, v33
	s_nop 0
	v_pk_add_f32 v[32:33], v[32:33], 1.0 op_sel_hi:[1,0]
	v_rcp_f32_e32 v34, v34
	s_nop 0
	v_pk_mul_f32 v[30:31], v[30:31], v[34:35]
	v_mul_f32_e32 v34, 0xbfb8aa3b, v26
	v_mul_f32_e32 v35, 0xbfb8aa3b, v27
	v_rcp_f32_e32 v33, v33
	v_exp_f32_e32 v34, v34
	v_exp_f32_e32 v35, v35
	s_nop 0
	v_pk_add_f32 v[34:35], v[34:35], 1.0 op_sel_hi:[1,0]
	v_rcp_f32_e32 v32, v32
	s_nop 0
	v_rcp_f32_e32 v35, v35
	s_nop 0
	v_rcp_f32_e32 v34, v34
	s_nop 0
	v_pk_mul_f32 v[34:35], v[26:27], v[34:35]
	v_pk_mul_f32 v[26:27], v[24:25], v[32:33]
	v_cvt_pk_bf16_f32 v24, v28, v29
	v_lshlrev_b64 v[28:29], 10, v[100:101]
	v_cmp_lt_i32_e32 vcc, s94, v90
	v_lshl_add_u64 v[28:29], v[96:97], 0, v[28:29]
	s_or_b64 s[34:35], vcc, s[34:35]
	v_cvt_pk_bf16_f32 v25, v30, v31
	v_cvt_pk_bf16_f32 v26, v26, v27
	v_cvt_pk_bf16_f32 v27, v34, v35
	global_store_dwordx4 v[28:29], v[24:27], off
	s_andn2_b64 exec, exec, s[34:35]
	s_cbranch_execnz .LBB0_218

; __device__ __forceinline__ u32x4 pack8(f32x4 a, f32x4 b) { u32x4 w; w.x = pk2(a[0], a[1]); w.y = pk2(a[2], a[3]); w.z = pk2(b[0], b[1]); w.w = pk2(b[2], b[3]); return w; }
; __device__ __forceinline__ void unpack8(u32x4 w, f32x4& a, f32x4& b) { a = (f32x4){bf_lo(w.x), bf_hi(w.x), bf_lo(w.y), bf_hi(w.y)}; b = (f32x4){bf_lo(w.z), bf_hi(w.z), bf_lo(w.w), bf_hi(w.w)}; }
; __device__ __forceinline__ f32x4 sigm4(f32x4 v) { return (f32x4){sigm(v[0]), sigm(v[1]), sigm(v[2]), sigm(v[3])}; }
; __device__ __forceinline__ void phase_conv(CParams& p, LAS unsigned char* lds) {
;     ...
;     for (size_t it0 = gt; it0 < (size_t)M * 32; it0 += 2 * ntot) {
;         u32x4 xc[2], xp[2]; f32x4 q0[2], q1[2], mu0[2], mu1[2]; bool val[2], first[2];
; #pragma unroll
;         for (int b = 0; b < 2; ++b) {
;             const size_t it = it0 + b * ntot; val[b] = it < (size_t)M * 32; const size_t itc = val[b] ? it : it0;
;             const int m = (int)(itc >> 5), c8 = (int)(itc & 31) * 8, col = 3072 + c8;
;             const bool prompt = m < MP; const int t = prompt ? (m & 4095) : ((m - MP) & 15); const int s = prompt ? 0 : ((m - MP) >> 4);
;             xc[b] = *(const u32x4*)(p.pr + (size_t)m * DSH + col);
;             xp[b] = *(const u32x4*)(p.pr + (size_t)(t > 0 ? m - 1 : m) * DSH + col);
;             first[b] = (t == 0);
;             q0[b] = (f32x4){0.f, 0.f, 0.f, 0.f}; q1[b] = q0[b];
;             if (t == 0 && !prompt) { const float* sp = p.in[I_SSHIFT] + (size_t)s * DSH + col; q0[b] = *(const f32x4*)sp; q1[b] = *(const f32x4*)(sp + 4); }
;             mu0[b] = *(const f32x4*)(p.in[I_MU] + col); mu1[b] = *(const f32x4*)(p.in[I_MU] + col + 4);
;         }
; #pragma unroll
;         for (int b = 0; b < 2; ++b) {
;             const size_t it = it0 + b * ntot; const int m = (int)(it >> 5), c8 = (int)(it & 31) * 8;
;             f32x4 x0, x1, w0, w1; unpack8(xc[b], x0, x1); unpack8(xp[b], w0, w1);
;             if (first[b]) { w0 = q0[b]; w1 = q1[b]; }
;             x0 = x0 + (w0 - x0) * mu0[b]; x1 = x1 + (w1 - x1) * mu1[b];
;             if (c8 < 64) {
; #pragma unroll
;                 for (int j = 0; j < 4; ++j) { x0[j] = tanhf(x0[j]); x1[j] = tanhf(x1[j]); }
;             } else if (c8 >= 128) { x0 = sigm4(x0); x1 = sigm4(x1); }
;             if (val[b]) *(u32x4*)(p.lin + (size_t)m * 256 + c8) = pack8(x0, x1);
.LBB0_254:
	s_or_b64 exec, exec, s[8:9]
	global_load_dwordx4 v[16:19], v160, s[16:17] offset:16
	global_load_dwordx4 v[20:23], v160, s[16:17]
	s_waitcnt vmcnt(6)
	v_lshlrev_b32_e32 v55, 16, v24
	v_and_b32_e32 v24, 0xffff0000, v24
	v_lshlrev_b32_e32 v61, 16, v26
	v_and_b32_e32 v26, 0xffff0000, v26
	v_lshlrev_b32_e32 v62, 16, v27
	v_and_b32_e32 v27, 0xffff0000, v27
	v_cmp_eq_u32_e32 vcc, 0, v54
	v_lshlrev_b32_e32 v56, 16, v36
	v_and_b32_e32 v57, 0xffff0000, v36
	v_lshlrev_b32_e32 v60, 16, v25
	v_and_b32_e32 v25, 0xffff0000, v25
	v_cndmask_b32_e32 v54, v62, v34, vcc
	v_cndmask_b32_e32 v62, v27, v35, vcc
	v_cndmask_b32_e32 v35, v26, v33, vcc
	v_cndmask_b32_e32 v26, v55, v40, vcc
	v_cndmask_b32_e32 v24, v24, v41, vcc
	v_lshlrev_b32_e32 v36, 16, v37
	v_and_b32_e32 v37, 0xffff0000, v37
	v_lshlrev_b32_e32 v58, 16, v38
	v_and_b32_e32 v59, 0xffff0000, v38
	v_lshlrev_b32_e32 v38, 16, v39
	v_and_b32_e32 v39, 0xffff0000, v39
	v_cndmask_b32_e32 v34, v61, v32, vcc
	v_cndmask_b32_e32 v32, v60, v42, vcc
	v_cndmask_b32_e32 v25, v25, v43, vcc
	v_sub_f32_e32 v27, v24, v57
	v_sub_f32_e32 v26, v26, v56
	s_movk_i32 s0, 0x7f
	v_sub_f32_e32 v25, v25, v37
	v_sub_f32_e32 v24, v32, v36
	s_waitcnt vmcnt(4)
	v_pk_fma_f32 v[32:33], v[44:45], v[26:27], v[56:57]
	v_sub_f32_e32 v35, v35, v59
	v_sub_f32_e32 v34, v34, v58
	v_sub_f32_e32 v27, v62, v39
	v_sub_f32_e32 v26, v54, v38
	v_cmp_lt_u32_e64 s[10:11], 63, v52
	v_cmp_lt_u32_e64 s[8:9], s0, v52
	v_pk_fma_f32 v[24:25], v[46:47], v[24:25], v[36:37]
	v_pk_fma_f32 v[26:27], v[30:31], v[26:27], v[38:39]
	v_pk_fma_f32 v[28:29], v[28:29], v[34:35], v[58:59]
	s_and_saveexec_b64 s[0:1], s[10:11]
	s_xor_b64 s[20:21], exec, s[0:1]
	s_cbranch_execz .LBB0_258
	s_and_saveexec_b64 s[22:23], s[8:9]
	s_cbranch_execz .LBB0_257
	v_mul_f32_e32 v24, 0xbfb8aa3b, v24
	v_mul_f32_e32 v25, 0xbfb8aa3b, v25
	v_exp_f32_e32 v24, v24
	v_exp_f32_e32 v25, v25
	v_mul_f32_e32 v30, 0xbfb8aa3b, v32
	v_mul_f32_e32 v31, 0xbfb8aa3b, v33
	v_exp_f32_e32 v30, v30
	v_pk_add_f32 v[24:25], v[24:25], 1.0 op_sel_hi:[1,0]
	v_exp_f32_e32 v31, v31
	s_nop 0
	v_pk_add_f32 v[30:31], v[30:31], 1.0 op_sel_hi:[1,0]
	v_mul_f32_e32 v26, 0xbfb8aa3b, v26
	v_mul_f32_e32 v27, 0xbfb8aa3b, v27
	v_rcp_f32_e32 v25, v25
	v_exp_f32_e32 v26, v26
	v_exp_f32_e32 v27, v27
	v_mul_f32_e32 v28, 0xbfb8aa3b, v28
	v_rcp_f32_e32 v24, v24
	v_pk_add_f32 v[26:27], v[26:27], 1.0 op_sel_hi:[1,0]
	v_mul_f32_e32 v29, 0xbfb8aa3b, v29
	v_exp_f32_e32 v28, v28
	v_rcp_f32_e32 v33, v31
	v_exp_f32_e32 v29, v29
	v_rcp_f32_e32 v32, v30
	v_pk_add_f32 v[28:29], v[28:29], 1.0 op_sel_hi:[1,0]
	v_rcp_f32_e32 v27, v27
	s_nop 0
	v_rcp_f32_e32 v26, v26
	s_nop 0
	v_rcp_f32_e32 v29, v29
	s_nop 0
	v_rcp_f32_e32 v28, v28

; __device__ __forceinline__ u32x4 pack8(f32x4 a, f32x4 b) { u32x4 w; w.x = pk2(a[0], a[1]); w.y = pk2(a[2], a[3]); w.z = pk2(b[0], b[1]); w.w = pk2(b[2], b[3]); return w; }
; __device__ __forceinline__ void unpack8(u32x4 w, f32x4& a, f32x4& b) { a = (f32x4){bf_lo(w.x), bf_hi(w.x), bf_lo(w.y), bf_hi(w.y)}; b = (f32x4){bf_lo(w.z), bf_hi(w.z), bf_lo(w.w), bf_hi(w.w)}; }
; __device__ __forceinline__ f32x4 sigm4(f32x4 v) { return (f32x4){sigm(v[0]), sigm(v[1]), sigm(v[2]), sigm(v[3])}; }
; __device__ __forceinline__ void phase_conv(CParams& p, LAS unsigned char* lds) {
;     ...
; #pragma unroll
;         for (int b = 0; b < 2; ++b) {
;             const size_t it = it0 + b * ntot; const int m = (int)(it >> 5), c8 = (int)(it & 31) * 8;
;             f32x4 x0, x1, w0, w1; unpack8(xc[b], x0, x1); unpack8(xp[b], w0, w1);
;             if (first[b]) { w0 = q0[b]; w1 = q1[b]; }
;             x0 = x0 + (w0 - x0) * mu0[b]; x1 = x1 + (w1 - x1) * mu1[b];
;             if (c8 < 64) {
; #pragma unroll
;                 for (int j = 0; j < 4; ++j) { x0[j] = tanhf(x0[j]); x1[j] = tanhf(x1[j]); }
;             } else if (c8 >= 128) { x0 = sigm4(x0); x1 = sigm4(x1); }
;             if (val[b]) *(u32x4*)(p.lin + (size_t)m * 256 + c8) = pack8(x0, x1);
.LBB0_292:
	s_or_b64 exec, exec, s[20:21]
	s_load_dwordx2 s[0:1], s[62:63], 0x228
	v_lshlrev_b32_e32 v160, 1, v52
	v_cvt_pk_bf16_f32 v30, v32, v33
	v_cvt_pk_bf16_f32 v31, v24, v25
	v_cvt_pk_bf16_f32 v33, v26, v27
	s_waitcnt lgkmcnt(0)
	v_lshl_add_u64 v[24:25], s[0:1], 0, v[160:161]
	v_and_b32_e32 v27, 0x7fffffff, v49
	v_and_b32_e32 v26, 0xffffff00, v48
	v_lshl_add_u64 v[26:27], v[26:27], 1, v[24:25]
	v_cvt_pk_bf16_f32 v32, v28, v29
	global_store_dwordx4 v[26:27], v[30:33], off
	v_cmp_eq_u32_e32 vcc, 0, v53
	s_waitcnt vmcnt(4)
	v_lshlrev_b32_e32 v26, 16, v8
	s_waitcnt vmcnt(3)
	v_lshlrev_b32_e32 v30, 16, v4
	v_and_b32_e32 v4, 0xffff0000, v4
	v_lshlrev_b32_e32 v33, 16, v7
	v_and_b32_e32 v7, 0xffff0000, v7
	v_and_b32_e32 v27, 0xffff0000, v8
	v_lshlrev_b32_e32 v31, 16, v5
	v_and_b32_e32 v5, 0xffff0000, v5
	v_lshlrev_b32_e32 v32, 16, v6
	v_and_b32_e32 v6, 0xffff0000, v6
	v_cndmask_b32_e32 v33, v33, v2, vcc
	v_cndmask_b32_e32 v34, v7, v3, vcc
	v_cndmask_b32_e32 v2, v30, v12, vcc
	v_cndmask_b32_e32 v3, v4, v13, vcc
	v_lshlrev_b32_e32 v8, 16, v9
	v_and_b32_e32 v9, 0xffff0000, v9
	v_lshlrev_b32_e32 v28, 16, v10
	v_and_b32_e32 v29, 0xffff0000, v10
	v_lshlrev_b32_e32 v10, 16, v11
	v_and_b32_e32 v11, 0xffff0000, v11
	v_cndmask_b32_e32 v32, v32, v0, vcc
	v_cndmask_b32_e32 v6, v6, v1, vcc
	v_cndmask_b32_e32 v0, v31, v14, vcc
	v_cndmask_b32_e32 v1, v5, v15, vcc
	v_sub_f32_e32 v3, v3, v27
	v_sub_f32_e32 v2, v2, v26
	v_sub_f32_e32 v1, v1, v9
	v_sub_f32_e32 v0, v0, v8
	s_waitcnt vmcnt(1)
	v_pk_fma_f32 v[4:5], v[20:21], v[2:3], v[26:27]
	v_sub_f32_e32 v7, v6, v29
	v_sub_f32_e32 v6, v32, v28
	v_sub_f32_e32 v3, v34, v11
	v_sub_f32_e32 v2, v33, v10
	v_pk_fma_f32 v[0:1], v[22:23], v[0:1], v[8:9]
	v_pk_fma_f32 v[2:3], v[2:3], v[18:19], v[10:11]
	v_pk_fma_f32 v[6:7], v[6:7], v[16:17], v[28:29]
	s_and_saveexec_b64 s[0:1], s[10:11]
	s_xor_b64 s[10:11], exec, s[0:1]
	s_cbranch_execz .LBB0_297
	s_and_saveexec_b64 s[20:21], s[8:9]
	s_cbranch_execz .LBB0_295
	v_mul_f32_e32 v0, 0xbfb8aa3b, v0
	v_mul_f32_e32 v1, 0xbfb8aa3b, v1
	v_exp_f32_e32 v0, v0
	v_exp_f32_e32 v1, v1
	v_mul_f32_e32 v4, 0xbfb8aa3b, v4
	v_mul_f32_e32 v5, 0xbfb8aa3b, v5
	v_exp_f32_e32 v4, v4
	v_pk_add_f32 v[0:1], v[0:1], 1.0 op_sel_hi:[1,0]
	v_exp_f32_e32 v5, v5
	s_nop 0
	v_pk_add_f32 v[4:5], v[4:5], 1.0 op_sel_hi:[1,0]
	v_mul_f32_e32 v2, 0xbfb8aa3b, v2
	v_mul_f32_e32 v3, 0xbfb8aa3b, v3
	v_rcp_f32_e32 v1, v1
	v_exp_f32_e32 v2, v2
	v_exp_f32_e32 v3, v3
	v_mul_f32_e32 v6, 0xbfb8aa3b, v6
	v_rcp_f32_e32 v0, v0
	v_pk_add_f32 v[2:3], v[2:3], 1.0 op_sel_hi:[1,0]
	v_mul_f32_e32 v7, 0xbfb8aa3b, v7
	v_exp_f32_e32 v6, v6
	v_rcp_f32_e32 v5, v5
	v_exp_f32_e32 v7, v7
	v_rcp_f32_e32 v4, v4
	v_pk_add_f32 v[6:7], v[6:7], 1.0 op_sel_hi:[1,0]
	v_rcp_f32_e32 v3, v3
	s_nop 0
	v_rcp_f32_e32 v2, v2
	s_nop 0
	v_rcp_f32_e32 v7, v7
	s_nop 0
	v_rcp_f32_e32 v6, v6

; __device__ __forceinline__ u32x4 pack8(f32x4 a, f32x4 b) { u32x4 w; w.x = pk2(a[0], a[1]); w.y = pk2(a[2], a[3]); w.z = pk2(b[0], b[1]); w.w = pk2(b[2], b[3]); return w; }
; __device__ __forceinline__ f32x4 sigm4(f32x4 v) { return (f32x4){sigm(v[0]), sigm(v[1]), sigm(v[2]), sigm(v[3])}; }
; #define FOR_ROWS _Pragma("unroll") for (int ai = 0; ai < 2; ++ai) _Pragma("unroll") for (int m = 0; m < 4; ++m)
; __device__ __forceinline__ void epilogue(const int kind, CParams& p, const f32x4 (&acc)[2][2][4][2], const Unit& u, const int wr, const int wc, const int fr_in, const int fq_in) {
;     ...
;     case E_FFN1: {
;         float rsv[2][4];
;         FOR_ROWS { ROWDEF rsv[ai][m] = p.ss2[row]; }
;         FOR_ROWS { ROWDEF
;             const float rs = rsqrtf(rsv[ai][m] * (1.f / 1024.f) + 1e-6f);
;             const f32x4 g0 = acc[ai][0][m][0] * rs, g1 = acc[ai][0][m][1] * rs, u0 = acc[ai][1][m][0] * rs, u1 = acc[ai][1][m][1] * rs;
;             *(u32x4*)(p.hid + row * DFF + u.pn * 128 + cw) = pack8(g0 * sigm4(g0) * u0, g1 * sigm4(g1) * u1);
;         }
;     } break;
.LBB0_642:
	s_cmp_gt_i32 s3, 11
	s_mov_b64 s[26:27], -1
	s_cbranch_scc0 .LBB0_644
	s_ashr_i32 s79, s78, 31
	v_readlane_b32 s12, v244, 20
	s_lshl_b64 s[10:11], s[78:79], 2
	v_readlane_b32 s18, v244, 26
	v_add_u32_e32 v130, s0, v215
	v_readlane_b32 s19, v244, 27
	s_add_u32 s10, s18, s10
	s_addc_u32 s11, s19, s11
	v_ashrrev_i32_e32 v131, 31, v130
	v_lshl_add_u64 v[128:129], v[130:131], 2, s[10:11]
	global_load_dword v146, v[128:129], off
	v_add_u32_e32 v144, 16, v130
	v_ashrrev_i32_e32 v145, 31, v144
	v_add_u32_e32 v142, 32, v130
	v_lshl_add_u64 v[128:129], v[144:145], 2, s[10:11]
	v_ashrrev_i32_e32 v143, 31, v142
	v_add_u32_e32 v140, 48, v130
	global_load_dword v184, v[128:129], off
	v_lshl_add_u64 v[128:129], v[142:143], 2, s[10:11]
	v_ashrrev_i32_e32 v141, 31, v140
	v_add_u32_e32 v138, 0x80, v130
	global_load_dword v183, v[128:129], off
	v_lshl_add_u64 v[128:129], v[140:141], 2, s[10:11]
	v_ashrrev_i32_e32 v139, 31, v138
	v_add_u32_e32 v136, 0x90, v130
	global_load_dword v182, v[128:129], off
	v_lshl_add_u64 v[128:129], v[138:139], 2, s[10:11]
	v_ashrrev_i32_e32 v137, 31, v136
	v_add_u32_e32 v134, 0xa0, v130
	global_load_dword v181, v[128:129], off
	v_lshl_add_u64 v[128:129], v[136:137], 2, s[10:11]
	v_ashrrev_i32_e32 v135, 31, v134
	global_load_dword v180, v[128:129], off
	v_lshl_add_u64 v[128:129], v[134:135], 2, s[10:11]
	global_load_dword v179, v[128:129], off
	v_add_u32_e32 v128, 0xb0, v130
	v_ashrrev_i32_e32 v129, 31, v128
	v_lshl_add_u64 v[132:133], v[128:129], 2, s[10:11]
	global_load_dword v178, v[132:133], off
	v_lshl_add_u64 v[132:133], v[130:131], 0, s[78:79]
	s_mov_b32 s1, 0x800000
	v_readlane_b32 s14, v244, 22
	s_movk_i32 s14, 0x1600
	v_ashrrev_i32_e32 v173, 31, v172
	v_readlane_b32 s13, v244, 21
	v_lshl_add_u64 v[144:145], v[144:145], 0, s[78:79]
	v_lshl_add_u64 v[142:143], v[142:143], 0, s[78:79]
	v_lshl_add_u64 v[140:141], v[140:141], 0, s[78:79]
	v_lshl_add_u64 v[138:139], v[138:139], 0, s[78:79]
	v_lshl_add_u64 v[136:137], v[136:137], 0, s[78:79]
	v_lshl_add_u64 v[134:135], v[134:135], 0, s[78:79]
	v_lshl_add_u64 v[128:129], v[128:129], 0, s[78:79]
	v_readlane_b32 s15, v244, 23
	v_readlane_b32 s16, v244, 24
	v_readlane_b32 s17, v244, 25
	s_mov_b64 s[26:27], 0
	s_waitcnt vmcnt(0)
	v_fmamk_f32 v130, v146, 0x3a800000, v193
	v_cmp_gt_f32_e32 vcc, s1, v130
	v_mul_f32_e32 v131, 0x4b800000, v130
	s_nop 0
	v_cndmask_b32_e32 v130, v130, v131, vcc
	v_rsq_f32_e32 v130, v130
	s_nop 0
	v_mul_f32_e32 v131, 0x45800000, v130
	v_cndmask_b32_e32 v150, v130, v131, vcc
	v_pk_mul_f32 v[152:153], v[126:127], v[150:151] op_sel_hi:[1,0]
	v_pk_mul_f32 v[154:155], v[124:125], v[150:151] op_sel_hi:[1,0]
	v_mul_f32_e32 v176, 0xbfb8aa3b, v152
	v_mul_f32_e32 v177, 0xbfb8aa3b, v153
	v_exp_f32_e32 v176, v176
	v_exp_f32_e32 v177, v177
	v_mul_f32_e32 v174, 0xbfb8aa3b, v154
	v_mul_f32_e32 v175, 0xbfb8aa3b, v155
	v_exp_f32_e32 v174, v174
	v_pk_add_f32 v[176:177], v[176:177], 1.0 op_sel_hi:[1,0]
	v_exp_f32_e32 v175, v175
	s_nop 0
	v_pk_add_f32 v[174:175], v[174:175], 1.0 op_sel_hi:[1,0]
	v_pk_mul_f32 v[130:131], v[122:123], v[150:151] op_sel_hi:[1,0]
	v_pk_mul_f32 v[158:159], v[94:95], v[150:151] op_sel_hi:[1,0]
	v_rcp_f32_e32 v177, v177
	v_pk_mul_f32 v[146:147], v[120:121], v[150:151] op_sel_hi:[1,0]
	v_pk_mul_f32 v[156:157], v[92:93], v[150:151] op_sel_hi:[1,0]
	v_pk_mul_f32 v[148:149], v[88:89], v[150:151] op_sel_hi:[1,0]
	v_rcp_f32_e32 v176, v176
	s_nop 0
	v_pk_mul_f32 v[152:153], v[152:153], v[176:177]
	v_pk_mul_f32 v[150:151], v[90:91], v[150:151] op_sel_hi:[1,0]
	v_pk_mul_f32 v[152:153], v[158:159], v[152:153]
	v_rcp_f32_e32 v175, v175
	v_mul_f32_e32 v158, 0xbfb8aa3b, v130
	v_mul_f32_e32 v159, 0xbfb8aa3b, v131
	v_exp_f32_e32 v158, v158
	v_exp_f32_e32 v159, v159
	v_rcp_f32_e32 v174, v174
	v_pk_add_f32 v[158:159], v[158:159], 1.0 op_sel_hi:[1,0]
	v_pk_mul_f32 v[154:155], v[154:155], v[174:175]
	v_pk_mul_f32 v[154:155], v[156:157], v[154:155]
	v_mul_f32_e32 v156, 0xbfb8aa3b, v146
	v_mul_f32_e32 v157, 0xbfb8aa3b, v147
	v_rcp_f32_e32 v159, v159
	v_exp_f32_e32 v156, v156
	v_exp_f32_e32 v157, v157
	s_nop 0
	v_pk_add_f32 v[156:157], v[156:157], 1.0 op_sel_hi:[1,0]
	v_rcp_f32_e32 v158, v158
	s_nop 0
	v_pk_mul_f32 v[130:131], v[130:131], v[158:159]
	v_rcp_f32_e32 v157, v157
	v_pk_mul_f32 v[130:131], v[150:151], v[130:131]
	v_rcp_f32_e32 v156, v156
	s_nop 0
	v_pk_mul_f32 v[146:147], v[146:147], v[156:157]
	s_nop 0
	v_pk_mul_f32 v[148:149], v[148:149], v[146:147]
	v_cvt_pk_bf16_f32 v146, v154, v155
	v_cvt_pk_bf16_f32 v147, v152, v153
	s_nop 0
	v_cvt_pk_bf16_f32 v148, v148, v149
	v_cvt_pk_bf16_f32 v149, v130, v131
	v_mov_b64_e32 v[130:131], s[40:41]
	v_mad_u64_u32 v[150:151], s[10:11], v132, s14, v[130:131]
	s_lshl_b32 s10, s92, 7
	s_ashr_i32 s11, s10, 31
	v_mad_i32_i24 v151, v133, s14, v151
	s_lshl_b64 s[10:11], s[10:11], 1
	v_lshl_add_u64 v[150:151], v[150:151], 0, s[10:11]
	v_lshlrev_b64 v[132:133], 1, v[172:173]
	v_lshl_add_u64 v[150:151], v[150:151], 0, v[132:133]
	global_store_dwordx4 v[150:151], v[146:149], off
	s_nop 1
	v_fmamk_f32 v146, v184, 0x3a800000, v193
	v_cmp_gt_f32_e32 vcc, s1, v146
	v_mul_f32_e32 v147, 0x4b800000, v146
	s_nop 0
	v_cndmask_b32_e32 v146, v146, v147, vcc
	v_rsq_f32_e32 v146, v146
	s_nop 0
	v_mul_f32_e32 v147, 0x45800000, v146
	v_cndmask_b32_e32 v152, v146, v147, vcc
	v_pk_mul_f32 v[156:157], v[116:117], v[152:153] op_sel_hi:[1,0]
	v_pk_mul_f32 v[154:155], v[118:119], v[152:153] op_sel_hi:[1,0]
	v_mul_f32_e32 v173, 0xbfb8aa3b, v156
	v_exp_f32_e32 v176, v173
	v_mul_f32_e32 v173, 0xbfb8aa3b, v157
	v_exp_f32_e32 v177, v173
	v_mul_f32_e32 v173, 0xbfb8aa3b, v154
	v_exp_f32_e32 v184, v173
	v_mul_f32_e32 v173, 0xbfb8aa3b, v155
; __device__ __forceinline__ u32x4 pack8(f32x4 a, f32x4 b) { u32x4 w; w.x = pk2(a[0], a[1]); w.y = pk2(a[2], a[3]); w.z = pk2(b[0], b[1]); w.w = pk2(b[2], b[3]); return w; }
; __device__ __forceinline__ f32x4 sigm4(f32x4 v) { return (f32x4){sigm(v[0]), sigm(v[1]), sigm(v[2]), sigm(v[3])}; }
; #define FOR_ROWS _Pragma("unroll") for (int ai = 0; ai < 2; ++ai) _Pragma("unroll") for (int m = 0; m < 4; ++m)
; __device__ __forceinline__ void epilogue(const int kind, CParams& p, const f32x4 (&acc)[2][2][4][2], const Unit& u, const int wr, const int wc, const int fr_in, const int fq_in) {
;     ...
;     case E_FFN1: {
;         float rsv[2][4];
;         FOR_ROWS { ROWDEF rsv[ai][m] = p.ss2[row]; }
;         FOR_ROWS { ROWDEF
;             const float rs = rsqrtf(rsv[ai][m] * (1.f / 1024.f) + 1e-6f);
;             const f32x4 g0 = acc[ai][0][m][0] * rs, g1 = acc[ai][0][m][1] * rs, u0 = acc[ai][1][m][0] * rs, u1 = acc[ai][1][m][1] * rs;
;             *(u32x4*)(p.hid + row * DFF + u.pn * 128 + cw) = pack8(g0 * sigm4(g0) * u0, g1 * sigm4(g1) * u1);
;         }
;     } break;
	v_exp_f32_e32 v185, v173
	v_pk_add_f32 v[176:177], v[176:177], 1.0 op_sel_hi:[1,0]
	v_pk_mul_f32 v[146:147], v[114:115], v[152:153] op_sel_hi:[1,0]
	v_pk_mul_f32 v[174:175], v[86:87], v[152:153] op_sel_hi:[1,0]
	v_pk_add_f32 v[184:185], v[184:185], 1.0 op_sel_hi:[1,0]
	v_pk_mul_f32 v[148:149], v[112:113], v[152:153] op_sel_hi:[1,0]
	v_pk_mul_f32 v[158:159], v[84:85], v[152:153] op_sel_hi:[1,0]
	v_pk_mul_f32 v[150:151], v[80:81], v[152:153] op_sel_hi:[1,0]
	v_pk_mul_f32 v[152:153], v[82:83], v[152:153] op_sel_hi:[1,0]
	v_rcp_f32_e32 v185, v185
	s_nop 0
	v_rcp_f32_e32 v184, v184
	s_nop 0
	v_pk_mul_f32 v[154:155], v[154:155], v[184:185]
	v_rcp_f32_e32 v177, v177
	v_pk_mul_f32 v[154:155], v[174:175], v[154:155]
	v_rcp_f32_e32 v176, v176
	v_mul_f32_e32 v173, 0xbfb8aa3b, v146
	v_exp_f32_e32 v174, v173
	v_mul_f32_e32 v173, 0xbfb8aa3b, v147
	v_exp_f32_e32 v175, v173
	v_pk_mul_f32 v[156:157], v[156:157], v[176:177]
	v_pk_add_f32 v[174:175], v[174:175], 1.0 op_sel_hi:[1,0]
	s_nop 0
	v_pk_mul_f32 v[156:157], v[158:159], v[156:157]
	v_mul_f32_e32 v158, 0xbfb8aa3b, v148
	v_mul_f32_e32 v159, 0xbfb8aa3b, v149
	v_rcp_f32_e32 v175, v175
	v_exp_f32_e32 v158, v158
	v_exp_f32_e32 v159, v159
	s_nop 0
	v_pk_add_f32 v[158:159], v[158:159], 1.0 op_sel_hi:[1,0]
	v_rcp_f32_e32 v174, v174
	s_nop 0
	v_pk_mul_f32 v[146:147], v[146:147], v[174:175]
	v_rcp_f32_e32 v159, v159
	v_pk_mul_f32 v[152:153], v[152:153], v[146:147]
	v_cvt_pk_bf16_f32 v146, v156, v157
	v_cvt_pk_bf16_f32 v147, v154, v155
	v_rcp_f32_e32 v158, v158
	s_nop 0
	v_pk_mul_f32 v[148:149], v[148:149], v[158:159]
	s_nop 0
	v_pk_mul_f32 v[148:149], v[150:151], v[148:149]
	v_mad_u64_u32 v[150:151], s[12:13], v144, s14, v[130:131]
	v_mad_i32_i24 v151, v145, s14, v151
	v_lshl_add_u64 v[144:145], v[150:151], 0, s[10:11]
	v_lshl_add_u64 v[144:145], v[144:145], 0, v[132:133]
	v_cvt_pk_bf16_f32 v148, v148, v149
	v_cvt_pk_bf16_f32 v149, v152, v153
	global_store_dwordx4 v[144:145], v[146:149], off
	v_fmamk_f32 v144, v183, 0x3a800000, v193
	v_cmp_gt_f32_e32 vcc, s1, v144
	v_mul_f32_e32 v145, 0x4b800000, v144
	s_nop 0
	v_cndmask_b32_e32 v144, v144, v145, vcc
	v_rsq_f32_e32 v144, v144
	s_nop 0
	v_mul_f32_e32 v145, 0x45800000, v144
	v_cndmask_b32_e32 v150, v144, v145, vcc
	v_pk_mul_f32 v[154:155], v[108:109], v[150:151] op_sel_hi:[1,0]
	v_pk_mul_f32 v[152:153], v[110:111], v[150:151] op_sel_hi:[1,0]
	v_mul_f32_e32 v173, 0xbfb8aa3b, v154
	v_exp_f32_e32 v174, v173
	v_mul_f32_e32 v173, 0xbfb8aa3b, v155
	v_exp_f32_e32 v175, v173
	v_mul_f32_e32 v173, 0xbfb8aa3b, v152
	v_exp_f32_e32 v176, v173
	v_mul_f32_e32 v173, 0xbfb8aa3b, v153
	v_exp_f32_e32 v177, v173
	v_pk_add_f32 v[174:175], v[174:175], 1.0 op_sel_hi:[1,0]
	v_pk_mul_f32 v[144:145], v[106:107], v[150:151] op_sel_hi:[1,0]
	v_pk_mul_f32 v[158:159], v[78:79], v[150:151] op_sel_hi:[1,0]
	v_pk_add_f32 v[176:177], v[176:177], 1.0 op_sel_hi:[1,0]
	v_pk_mul_f32 v[146:147], v[104:105], v[150:151] op_sel_hi:[1,0]
	v_pk_mul_f32 v[156:157], v[76:77], v[150:151] op_sel_hi:[1,0]
	v_pk_mul_f32 v[148:149], v[72:73], v[150:151] op_sel_hi:[1,0]
	v_pk_mul_f32 v[150:151], v[74:75], v[150:151] op_sel_hi:[1,0]
	v_rcp_f32_e32 v177, v177
	s_nop 0
	v_rcp_f32_e32 v176, v176
	s_nop 0
	v_pk_mul_f32 v[152:153], v[152:153], v[176:177]
	v_rcp_f32_e32 v175, v175
	v_pk_mul_f32 v[152:153], v[158:159], v[152:153]
	v_mul_f32_e32 v158, 0xbfb8aa3b, v144
	v_mul_f32_e32 v159, 0xbfb8aa3b, v145
	v_exp_f32_e32 v158, v158
	v_exp_f32_e32 v159, v159
	s_nop 0
	v_pk_add_f32 v[158:159], v[158:159], 1.0 op_sel_hi:[1,0]
	v_rcp_f32_e32 v174, v174
	s_nop 0
	v_pk_mul_f32 v[154:155], v[154:155], v[174:175]
	v_pk_mul_f32 v[154:155], v[156:157], v[154:155]
	v_mul_f32_e32 v156, 0xbfb8aa3b, v146
	v_mul_f32_e32 v157, 0xbfb8aa3b, v147
	v_rcp_f32_e32 v159, v159
	v_exp_f32_e32 v156, v156
	v_exp_f32_e32 v157, v157
	s_nop 0
	v_pk_add_f32 v[156:157], v[156:157], 1.0 op_sel_hi:[1,0]
	v_rcp_f32_e32 v158, v158
	s_nop 0
	v_pk_mul_f32 v[144:145], v[144:145], v[158:159]
	v_rcp_f32_e32 v157, v157
	v_pk_mul_f32 v[150:151], v[150:151], v[144:145]
	v_cvt_pk_bf16_f32 v144, v154, v155
	v_cvt_pk_bf16_f32 v145, v152, v153
	v_rcp_f32_e32 v156, v156
	s_nop 0
	v_pk_mul_f32 v[146:147], v[146:147], v[156:157]
	s_nop 0
	v_pk_mul_f32 v[146:147], v[148:149], v[146:147]
	v_mad_u64_u32 v[148:149], s[12:13], v142, s14, v[130:131]
	v_mad_i32_i24 v149, v143, s14, v149
	v_lshl_add_u64 v[142:143], v[148:149], 0, s[10:11]
	v_lshl_add_u64 v[142:143], v[142:143], 0, v[132:133]
	v_cvt_pk_bf16_f32 v146, v146, v147
	v_cvt_pk_bf16_f32 v147, v150, v151
	global_store_dwordx4 v[142:143], v[144:147], off
	v_fmamk_f32 v142, v182, 0x3a800000, v193
	v_cmp_gt_f32_e32 vcc, s1, v142
	v_mul_f32_e32 v143, 0x4b800000, v142
	s_nop 0
	v_cndmask_b32_e32 v142, v142, v143, vcc
	v_rsq_f32_e32 v142, v142
	s_nop 0
	v_mul_f32_e32 v143, 0x45800000, v142
	v_cndmask_b32_e32 v148, v142, v143, vcc
	v_pk_mul_f32 v[150:151], v[102:103], v[148:149] op_sel_hi:[1,0]
	v_pk_mul_f32 v[152:153], v[100:101], v[148:149] op_sel_hi:[1,0]
	v_mul_f32_e32 v173, 0xbfb8aa3b, v150
	v_exp_f32_e32 v174, v173
	v_mul_f32_e32 v173, 0xbfb8aa3b, v151
	v_exp_f32_e32 v175, v173
	v_mul_f32_e32 v158, 0xbfb8aa3b, v152
	v_mul_f32_e32 v159, 0xbfb8aa3b, v153
	v_exp_f32_e32 v158, v158
	v_pk_add_f32 v[174:175], v[174:175], 1.0 op_sel_hi:[1,0]
	v_exp_f32_e32 v159, v159
	s_nop 0
	v_pk_add_f32 v[158:159], v[158:159], 1.0 op_sel_hi:[1,0]
	v_pk_mul_f32 v[142:143], v[98:99], v[148:149] op_sel_hi:[1,0]
	v_pk_mul_f32 v[156:157], v[70:71], v[148:149] op_sel_hi:[1,0]
	v_rcp_f32_e32 v175, v175
	v_pk_mul_f32 v[144:145], v[96:97], v[148:149] op_sel_hi:[1,0]
	v_pk_mul_f32 v[154:155], v[68:69], v[148:149] op_sel_hi:[1,0]
; __device__ __forceinline__ u32x4 pack8(f32x4 a, f32x4 b) { u32x4 w; w.x = pk2(a[0], a[1]); w.y = pk2(a[2], a[3]); w.z = pk2(b[0], b[1]); w.w = pk2(b[2], b[3]); return w; }
; __device__ __forceinline__ f32x4 sigm4(f32x4 v) { return (f32x4){sigm(v[0]), sigm(v[1]), sigm(v[2]), sigm(v[3])}; }
; #define FOR_ROWS _Pragma("unroll") for (int ai = 0; ai < 2; ++ai) _Pragma("unroll") for (int m = 0; m < 4; ++m)
; __device__ __forceinline__ void epilogue(const int kind, CParams& p, const f32x4 (&acc)[2][2][4][2], const Unit& u, const int wr, const int wc, const int fr_in, const int fq_in) {
;     ...
;     case E_FFN1: {
;         float rsv[2][4];
;         FOR_ROWS { ROWDEF rsv[ai][m] = p.ss2[row]; }
;         FOR_ROWS { ROWDEF
;             const float rs = rsqrtf(rsv[ai][m] * (1.f / 1024.f) + 1e-6f);
;             const f32x4 g0 = acc[ai][0][m][0] * rs, g1 = acc[ai][0][m][1] * rs, u0 = acc[ai][1][m][0] * rs, u1 = acc[ai][1][m][1] * rs;
;             *(u32x4*)(p.hid + row * DFF + u.pn * 128 + cw) = pack8(g0 * sigm4(g0) * u0, g1 * sigm4(g1) * u1);
;         }
;     } break;
	v_pk_mul_f32 v[146:147], v[64:65], v[148:149] op_sel_hi:[1,0]
	v_rcp_f32_e32 v174, v174
	s_nop 0
	v_pk_mul_f32 v[150:151], v[150:151], v[174:175]
	v_pk_mul_f32 v[148:149], v[66:67], v[148:149] op_sel_hi:[1,0]
	v_pk_mul_f32 v[150:151], v[156:157], v[150:151]
	v_rcp_f32_e32 v159, v159
	v_mul_f32_e32 v156, 0xbfb8aa3b, v142
	v_mul_f32_e32 v157, 0xbfb8aa3b, v143
	v_exp_f32_e32 v156, v156
	v_exp_f32_e32 v157, v157
	v_rcp_f32_e32 v158, v158
	v_pk_add_f32 v[156:157], v[156:157], 1.0 op_sel_hi:[1,0]
	v_pk_mul_f32 v[152:153], v[152:153], v[158:159]
	v_pk_mul_f32 v[152:153], v[154:155], v[152:153]
	v_mul_f32_e32 v154, 0xbfb8aa3b, v144
	v_mul_f32_e32 v155, 0xbfb8aa3b, v145
	v_rcp_f32_e32 v157, v157
	v_exp_f32_e32 v154, v154
	v_exp_f32_e32 v155, v155
	s_nop 0
	v_pk_add_f32 v[154:155], v[154:155], 1.0 op_sel_hi:[1,0]
	v_rcp_f32_e32 v156, v156
	s_nop 0
	v_pk_mul_f32 v[142:143], v[142:143], v[156:157]
	v_rcp_f32_e32 v155, v155
	v_pk_mul_f32 v[148:149], v[148:149], v[142:143]
	v_cvt_pk_bf16_f32 v142, v152, v153
	v_cvt_pk_bf16_f32 v143, v150, v151
	v_rcp_f32_e32 v154, v154
	s_nop 0
	v_pk_mul_f32 v[144:145], v[144:145], v[154:155]
	s_nop 0
	v_pk_mul_f32 v[144:145], v[146:147], v[144:145]
	v_mad_u64_u32 v[146:147], s[12:13], v140, s14, v[130:131]
	v_mad_i32_i24 v147, v141, s14, v147
	v_lshl_add_u64 v[140:141], v[146:147], 0, s[10:11]
	v_lshl_add_u64 v[140:141], v[140:141], 0, v[132:133]
	v_cvt_pk_bf16_f32 v144, v144, v145
	v_cvt_pk_bf16_f32 v145, v148, v149
	global_store_dwordx4 v[140:141], v[142:145], off
	v_fmamk_f32 v140, v181, 0x3a800000, v193
	v_cmp_gt_f32_e32 vcc, s1, v140
	v_mul_f32_e32 v141, 0x4b800000, v140
	s_nop 0
	v_cndmask_b32_e32 v140, v140, v141, vcc
	v_rsq_f32_e32 v140, v140
	s_nop 0
	v_mul_f32_e32 v141, 0x45800000, v140
	v_cndmask_b32_e32 v146, v140, v141, vcc
	v_pk_mul_f32 v[148:149], v[62:63], v[146:147] op_sel_hi:[1,0]
	v_pk_mul_f32 v[150:151], v[60:61], v[146:147] op_sel_hi:[1,0]
	v_mul_f32_e32 v158, 0xbfb8aa3b, v148
	v_mul_f32_e32 v159, 0xbfb8aa3b, v149
	v_exp_f32_e32 v158, v158
	v_exp_f32_e32 v159, v159
	v_mul_f32_e32 v156, 0xbfb8aa3b, v150
	v_mul_f32_e32 v157, 0xbfb8aa3b, v151
	v_exp_f32_e32 v156, v156
	v_pk_add_f32 v[158:159], v[158:159], 1.0 op_sel_hi:[1,0]
	v_exp_f32_e32 v157, v157
	s_nop 0
	v_pk_add_f32 v[156:157], v[156:157], 1.0 op_sel_hi:[1,0]
	v_pk_mul_f32 v[140:141], v[58:59], v[146:147] op_sel_hi:[1,0]
	v_pk_mul_f32 v[154:155], v[30:31], v[146:147] op_sel_hi:[1,0]
	v_rcp_f32_e32 v159, v159
	v_pk_mul_f32 v[142:143], v[56:57], v[146:147] op_sel_hi:[1,0]
	v_pk_mul_f32 v[152:153], v[28:29], v[146:147] op_sel_hi:[1,0]
	v_pk_mul_f32 v[144:145], v[24:25], v[146:147] op_sel_hi:[1,0]
	v_rcp_f32_e32 v158, v158
	s_nop 0
	v_pk_mul_f32 v[148:149], v[148:149], v[158:159]
	v_pk_mul_f32 v[146:147], v[26:27], v[146:147] op_sel_hi:[1,0]
	v_pk_mul_f32 v[148:149], v[154:155], v[148:149]
	v_rcp_f32_e32 v157, v157
	v_mul_f32_e32 v154, 0xbfb8aa3b, v140
	v_mul_f32_e32 v155, 0xbfb8aa3b, v141
	v_exp_f32_e32 v154, v154
	v_exp_f32_e32 v155, v155
	v_rcp_f32_e32 v156, v156
	v_pk_add_f32 v[154:155], v[154:155], 1.0 op_sel_hi:[1,0]
	v_pk_mul_f32 v[150:151], v[150:151], v[156:157]
	v_pk_mul_f32 v[150:151], v[152:153], v[150:151]
	v_mul_f32_e32 v152, 0xbfb8aa3b, v142
	v_mul_f32_e32 v153, 0xbfb8aa3b, v143
	v_rcp_f32_e32 v155, v155
	v_exp_f32_e32 v152, v152
	v_exp_f32_e32 v153, v153
	s_nop 0
	v_pk_add_f32 v[152:153], v[152:153], 1.0 op_sel_hi:[1,0]
	v_rcp_f32_e32 v154, v154
	s_nop 0
	v_pk_mul_f32 v[140:141], v[140:141], v[154:155]
	v_rcp_f32_e32 v153, v153
	v_pk_mul_f32 v[146:147], v[146:147], v[140:141]
	v_cvt_pk_bf16_f32 v140, v150, v151
	v_cvt_pk_bf16_f32 v141, v148, v149
	v_rcp_f32_e32 v152, v152
	s_nop 0
	v_pk_mul_f32 v[142:143], v[142:143], v[152:153]
	s_nop 0
	v_pk_mul_f32 v[142:143], v[144:145], v[142:143]
	v_mad_u64_u32 v[144:145], s[12:13], v138, s14, v[130:131]
	v_mad_i32_i24 v145, v139, s14, v145
	v_lshl_add_u64 v[138:139], v[144:145], 0, s[10:11]
	v_lshl_add_u64 v[138:139], v[138:139], 0, v[132:133]
	v_cvt_pk_bf16_f32 v142, v142, v143
	v_cvt_pk_bf16_f32 v143, v146, v147
	global_store_dwordx4 v[138:139], v[140:143], off
	v_fmamk_f32 v138, v180, 0x3a800000, v193
	v_cmp_gt_f32_e32 vcc, s1, v138
	v_mul_f32_e32 v139, 0x4b800000, v138
	s_nop 0
	v_cndmask_b32_e32 v138, v138, v139, vcc
	v_rsq_f32_e32 v138, v138
	s_nop 0
	v_mul_f32_e32 v139, 0x45800000, v138
	v_cndmask_b32_e32 v144, v138, v139, vcc
	v_pk_mul_f32 v[146:147], v[54:55], v[144:145] op_sel_hi:[1,0]
	v_pk_mul_f32 v[148:149], v[52:53], v[144:145] op_sel_hi:[1,0]
	v_mul_f32_e32 v156, 0xbfb8aa3b, v146
	v_mul_f32_e32 v157, 0xbfb8aa3b, v147
	v_exp_f32_e32 v156, v156
	v_exp_f32_e32 v157, v157
	v_mul_f32_e32 v154, 0xbfb8aa3b, v148
	v_mul_f32_e32 v155, 0xbfb8aa3b, v149
	v_exp_f32_e32 v154, v154
	v_pk_add_f32 v[156:157], v[156:157], 1.0 op_sel_hi:[1,0]
	v_exp_f32_e32 v155, v155
	s_nop 0
	v_pk_add_f32 v[154:155], v[154:155], 1.0 op_sel_hi:[1,0]
	v_pk_mul_f32 v[138:139], v[50:51], v[144:145] op_sel_hi:[1,0]
	v_pk_mul_f32 v[152:153], v[22:23], v[144:145] op_sel_hi:[1,0]
	v_rcp_f32_e32 v157, v157
	v_pk_mul_f32 v[140:141], v[48:49], v[144:145] op_sel_hi:[1,0]
	v_pk_mul_f32 v[150:151], v[20:21], v[144:145] op_sel_hi:[1,0]
	v_pk_mul_f32 v[142:143], v[16:17], v[144:145] op_sel_hi:[1,0]
	v_rcp_f32_e32 v156, v156
	s_nop 0
	v_pk_mul_f32 v[146:147], v[146:147], v[156:157]
	v_pk_mul_f32 v[144:145], v[18:19], v[144:145] op_sel_hi:[1,0]
	v_pk_mul_f32 v[146:147], v[152:153], v[146:147]
	v_rcp_f32_e32 v155, v155
	v_mul_f32_e32 v152, 0xbfb8aa3b, v138
	v_mul_f32_e32 v153, 0xbfb8aa3b, v139
	v_exp_f32_e32 v152, v152
	v_exp_f32_e32 v153, v153
	v_rcp_f32_e32 v154, v154
	v_pk_add_f32 v[152:153], v[152:153], 1.0 op_sel_hi:[1,0]
; __device__ __forceinline__ u32x4 pack8(f32x4 a, f32x4 b) { u32x4 w; w.x = pk2(a[0], a[1]); w.y = pk2(a[2], a[3]); w.z = pk2(b[0], b[1]); w.w = pk2(b[2], b[3]); return w; }
; __device__ __forceinline__ f32x4 sigm4(f32x4 v) { return (f32x4){sigm(v[0]), sigm(v[1]), sigm(v[2]), sigm(v[3])}; }
; #define FOR_ROWS _Pragma("unroll") for (int ai = 0; ai < 2; ++ai) _Pragma("unroll") for (int m = 0; m < 4; ++m)
; __device__ __forceinline__ void epilogue(const int kind, CParams& p, const f32x4 (&acc)[2][2][4][2], const Unit& u, const int wr, const int wc, const int fr_in, const int fq_in) {
;     ...
;     case E_FFN1: {
;         float rsv[2][4];
;         FOR_ROWS { ROWDEF rsv[ai][m] = p.ss2[row]; }
;         FOR_ROWS { ROWDEF
;             const float rs = rsqrtf(rsv[ai][m] * (1.f / 1024.f) + 1e-6f);
;             const f32x4 g0 = acc[ai][0][m][0] * rs, g1 = acc[ai][0][m][1] * rs, u0 = acc[ai][1][m][0] * rs, u1 = acc[ai][1][m][1] * rs;
;             *(u32x4*)(p.hid + row * DFF + u.pn * 128 + cw) = pack8(g0 * sigm4(g0) * u0, g1 * sigm4(g1) * u1);
;         }
;     } break;
	v_pk_mul_f32 v[148:149], v[148:149], v[154:155]
	v_pk_mul_f32 v[148:149], v[150:151], v[148:149]
	v_mul_f32_e32 v150, 0xbfb8aa3b, v140
	v_mul_f32_e32 v151, 0xbfb8aa3b, v141
	v_rcp_f32_e32 v153, v153
	v_exp_f32_e32 v150, v150
	v_exp_f32_e32 v151, v151
	s_nop 0
	v_pk_add_f32 v[150:151], v[150:151], 1.0 op_sel_hi:[1,0]
	v_rcp_f32_e32 v152, v152
	s_nop 0
	v_pk_mul_f32 v[138:139], v[138:139], v[152:153]
	v_rcp_f32_e32 v151, v151
	v_pk_mul_f32 v[144:145], v[144:145], v[138:139]
	v_cvt_pk_bf16_f32 v138, v148, v149
	v_cvt_pk_bf16_f32 v139, v146, v147
	v_rcp_f32_e32 v150, v150
	s_nop 0
	v_pk_mul_f32 v[140:141], v[140:141], v[150:151]
	s_nop 0
	v_pk_mul_f32 v[140:141], v[142:143], v[140:141]
	v_mad_u64_u32 v[142:143], s[12:13], v136, s14, v[130:131]
	v_mad_i32_i24 v143, v137, s14, v143
	v_lshl_add_u64 v[136:137], v[142:143], 0, s[10:11]
	v_lshl_add_u64 v[136:137], v[136:137], 0, v[132:133]
	v_cvt_pk_bf16_f32 v140, v140, v141
	v_cvt_pk_bf16_f32 v141, v144, v145
	global_store_dwordx4 v[136:137], v[138:141], off
	v_fmamk_f32 v136, v179, 0x3a800000, v193
	v_cmp_gt_f32_e32 vcc, s1, v136
	v_mul_f32_e32 v137, 0x4b800000, v136
	s_nop 0
	v_cndmask_b32_e32 v136, v136, v137, vcc
	v_rsq_f32_e32 v136, v136
	s_nop 0
	v_mul_f32_e32 v137, 0x45800000, v136
	v_cndmask_b32_e32 v142, v136, v137, vcc
	v_pk_mul_f32 v[144:145], v[46:47], v[142:143] op_sel_hi:[1,0]
	v_pk_mul_f32 v[146:147], v[44:45], v[142:143] op_sel_hi:[1,0]
	v_mul_f32_e32 v154, 0xbfb8aa3b, v144
	v_mul_f32_e32 v155, 0xbfb8aa3b, v145
	v_exp_f32_e32 v154, v154
	v_exp_f32_e32 v155, v155
	v_mul_f32_e32 v152, 0xbfb8aa3b, v146
	v_mul_f32_e32 v153, 0xbfb8aa3b, v147
	v_exp_f32_e32 v152, v152
	v_pk_add_f32 v[154:155], v[154:155], 1.0 op_sel_hi:[1,0]
	v_exp_f32_e32 v153, v153
	s_nop 0
	v_pk_add_f32 v[152:153], v[152:153], 1.0 op_sel_hi:[1,0]
	v_pk_mul_f32 v[136:137], v[42:43], v[142:143] op_sel_hi:[1,0]
	v_pk_mul_f32 v[150:151], v[14:15], v[142:143] op_sel_hi:[1,0]
	v_rcp_f32_e32 v155, v155
	v_pk_mul_f32 v[138:139], v[40:41], v[142:143] op_sel_hi:[1,0]
	v_pk_mul_f32 v[148:149], v[12:13], v[142:143] op_sel_hi:[1,0]
	v_pk_mul_f32 v[140:141], v[8:9], v[142:143] op_sel_hi:[1,0]
	v_rcp_f32_e32 v154, v154
	s_nop 0
	v_pk_mul_f32 v[144:145], v[144:145], v[154:155]
	v_pk_mul_f32 v[142:143], v[10:11], v[142:143] op_sel_hi:[1,0]
	v_pk_mul_f32 v[144:145], v[150:151], v[144:145]
	v_rcp_f32_e32 v153, v153
	v_mul_f32_e32 v150, 0xbfb8aa3b, v136
	v_mul_f32_e32 v151, 0xbfb8aa3b, v137
	v_exp_f32_e32 v150, v150
	v_exp_f32_e32 v151, v151
	v_rcp_f32_e32 v152, v152
	v_pk_add_f32 v[150:151], v[150:151], 1.0 op_sel_hi:[1,0]
	v_pk_mul_f32 v[146:147], v[146:147], v[152:153]
	v_pk_mul_f32 v[146:147], v[148:149], v[146:147]
	v_mul_f32_e32 v148, 0xbfb8aa3b, v138
	v_mul_f32_e32 v149, 0xbfb8aa3b, v139
	v_rcp_f32_e32 v151, v151
	v_exp_f32_e32 v148, v148
	v_exp_f32_e32 v149, v149
	s_nop 0
	v_pk_add_f32 v[148:149], v[148:149], 1.0 op_sel_hi:[1,0]
	v_rcp_f32_e32 v150, v150
	s_nop 0
	v_pk_mul_f32 v[136:137], v[136:137], v[150:151]
	v_rcp_f32_e32 v149, v149
	v_pk_mul_f32 v[142:143], v[142:143], v[136:137]
	v_cvt_pk_bf16_f32 v136, v146, v147
	v_cvt_pk_bf16_f32 v137, v144, v145
	v_rcp_f32_e32 v148, v148
	s_nop 0
	v_pk_mul_f32 v[138:139], v[138:139], v[148:149]
	s_nop 0
	v_pk_mul_f32 v[138:139], v[140:141], v[138:139]
	v_mad_u64_u32 v[140:141], s[12:13], v134, s14, v[130:131]
	v_mad_i32_i24 v141, v135, s14, v141
	v_lshl_add_u64 v[134:135], v[140:141], 0, s[10:11]
	v_lshl_add_u64 v[134:135], v[134:135], 0, v[132:133]
	v_cvt_pk_bf16_f32 v138, v138, v139
	v_cvt_pk_bf16_f32 v139, v142, v143
	global_store_dwordx4 v[134:135], v[136:139], off
	v_fmamk_f32 v134, v178, 0x3a800000, v193
	v_cmp_gt_f32_e32 vcc, s1, v134
	v_mul_f32_e32 v135, 0x4b800000, v134
	v_mad_u64_u32 v[130:131], s[12:13], v128, s14, v[130:131]
	v_cndmask_b32_e32 v134, v134, v135, vcc
	v_rsq_f32_e32 v134, v134
	v_mad_i32_i24 v131, v129, s14, v131
	v_lshl_add_u64 v[128:129], v[130:131], 0, s[10:11]
	v_lshl_add_u64 v[128:129], v[128:129], 0, v[132:133]
	v_mul_f32_e32 v135, 0x45800000, v134
	v_cndmask_b32_e32 v140, v134, v135, vcc
	v_pk_mul_f32 v[142:143], v[38:39], v[140:141] op_sel_hi:[1,0]
	v_pk_mul_f32 v[144:145], v[36:37], v[140:141] op_sel_hi:[1,0]
	v_mul_f32_e32 v152, 0xbfb8aa3b, v142
	v_mul_f32_e32 v153, 0xbfb8aa3b, v143
	v_exp_f32_e32 v152, v152
	v_exp_f32_e32 v153, v153
	v_mul_f32_e32 v150, 0xbfb8aa3b, v144
	v_mul_f32_e32 v151, 0xbfb8aa3b, v145
	v_exp_f32_e32 v150, v150
	v_pk_add_f32 v[152:153], v[152:153], 1.0 op_sel_hi:[1,0]
	v_exp_f32_e32 v151, v151
	s_nop 0
	v_pk_add_f32 v[150:151], v[150:151], 1.0 op_sel_hi:[1,0]
	v_pk_mul_f32 v[134:135], v[34:35], v[140:141] op_sel_hi:[1,0]
	v_pk_mul_f32 v[148:149], v[6:7], v[140:141] op_sel_hi:[1,0]
	v_rcp_f32_e32 v153, v153
	v_pk_mul_f32 v[136:137], v[32:33], v[140:141] op_sel_hi:[1,0]
	v_pk_mul_f32 v[146:147], v[4:5], v[140:141] op_sel_hi:[1,0]
	v_pk_mul_f32 v[138:139], v[0:1], v[140:141] op_sel_hi:[1,0]
	v_rcp_f32_e32 v152, v152
	s_nop 0
	v_pk_mul_f32 v[142:143], v[142:143], v[152:153]
	v_pk_mul_f32 v[140:141], v[2:3], v[140:141] op_sel_hi:[1,0]
	v_pk_mul_f32 v[142:143], v[148:149], v[142:143]
	v_rcp_f32_e32 v151, v151
	v_mul_f32_e32 v148, 0xbfb8aa3b, v134
	v_mul_f32_e32 v149, 0xbfb8aa3b, v135
	v_exp_f32_e32 v148, v148
	v_exp_f32_e32 v149, v149
	v_rcp_f32_e32 v150, v150
	v_pk_add_f32 v[148:149], v[148:149], 1.0 op_sel_hi:[1,0]
	v_pk_mul_f32 v[144:145], v[144:145], v[150:151]
	v_pk_mul_f32 v[144:145], v[146:147], v[144:145]
	v_mul_f32_e32 v146, 0xbfb8aa3b, v136
	v_mul_f32_e32 v147, 0xbfb8aa3b, v137
	v_rcp_f32_e32 v149, v149
	v_exp_f32_e32 v146, v146
	v_exp_f32_e32 v147, v147
	s_mov_b64 s[10:11], 0
	v_pk_add_f32 v[146:147], v[146:147], 1.0 op_sel_hi:[1,0]
	v_rcp_f32_e32 v148, v148
	s_nop 0
	v_pk_mul_f32 v[134:135], v[134:135], v[148:149]
	v_rcp_f32_e32 v147, v147
	v_pk_mul_f32 v[140:141], v[140:141], v[134:135]
	v_cvt_pk_bf16_f32 v134, v144, v145
	v_cvt_pk_bf16_f32 v135, v142, v143
	v_rcp_f32_e32 v146, v146
	s_nop 0
	v_pk_mul_f32 v[136:137], v[136:137], v[146:147]
	s_nop 0
	v_pk_mul_f32 v[136:137], v[138:139], v[136:137]
	s_nop 0
	v_cvt_pk_bf16_f32 v136, v136, v137
	v_cvt_pk_bf16_f32 v137, v140, v141
	global_store_dwordx4 v[128:129], v[134:137], off
	s_branch .LBB0_645

; __device__ __forceinline__ u32x4 pack8(f32x4 a, f32x4 b) { u32x4 w; w.x = pk2(a[0], a[1]); w.y = pk2(a[2], a[3]); w.z = pk2(b[0], b[1]); w.w = pk2(b[2], b[3]); return w; }
; #define FOR_ROWS _Pragma("unroll") for (int ai = 0; ai < 2; ++ai) _Pragma("unroll") for (int m = 0; m < 4; ++m)
; __device__ __forceinline__ void epilogue(const int kind, CParams& p, const f32x4 (&acc)[2][2][4][2], const Unit& u, const int wr, const int wc, const int fr_in, const int fq_in) {
;     ...
;     case E_PV: {
;         float pv[2][4];
;         FOR_ROWS { ROWDEF pv[ai][m] = __hip_atomic_load(p.psum + (rt < u.aux ? row : (size_t)u.row0) * 4 + u.pn, __ATOMIC_RELAXED, __HIP_MEMORY_SCOPE_AGENT); }
;         FOR_ROWS { ROWDEF
;             if (rt < u.aux) {
;                 const float inv = 1.f / pv[ai][m];
; #pragma unroll
;                 for (int bj = 0; bj < 2; ++bj) *(u32x4*)(p.ob + row * 1024 + u.pn * 256 + bj * 128 + cw) = pack8(acc[ai][bj][m][0] * inv, acc[ai][bj][m][1] * inv);
;             }
;         }
;     } break;
.LBB0_645:
	s_and_b64 vcc, exec, s[10:11]
	s_cbranch_vccz .LBB0_719
	s_cmp_gt_i32 s3, 8
	s_mov_b64 s[10:11], -1
	s_cbranch_scc0 .LBB0_716
	s_cmp_gt_i32 s3, 9
	s_cbranch_scc0 .LBB0_665
	v_add_u32_e32 v142, s0, v215
	s_ashr_i32 s93, s92, 31
	v_cmp_gt_i32_e32 vcc, s95, v142
	s_ashr_i32 s79, s78, 31
	s_lshl_b64 s[10:11], s[92:93], 2
	v_readlane_b32 s12, v244, 28
	v_cndmask_b32_e32 v128, 0, v142, vcc
	v_readlane_b32 s13, v244, 29
	s_add_u32 s28, s12, s10
	v_ashrrev_i32_e32 v129, 31, v128
	s_addc_u32 s29, s13, s11
	v_lshl_add_u64 v[128:129], v[128:129], 0, s[78:79]
	v_add_u32_e32 v140, 16, v142
	v_lshl_add_u64 v[128:129], v[128:129], 4, s[28:29]
	v_cmp_gt_i32_e64 s[22:23], s95, v140
	global_load_dword v141, v[128:129], off sc1
	v_add_u32_e32 v138, 32, v142
	v_cndmask_b32_e64 v128, 0, v140, s[22:23]
	v_ashrrev_i32_e32 v129, 31, v128
	v_lshl_add_u64 v[128:129], v[128:129], 0, s[78:79]
	v_lshl_add_u64 v[128:129], v[128:129], 4, s[28:29]
	v_cmp_gt_i32_e64 s[20:21], s95, v138
	global_load_dword v139, v[128:129], off sc1
	v_add_u32_e32 v136, 48, v142
	v_cndmask_b32_e64 v128, 0, v138, s[20:21]
	v_ashrrev_i32_e32 v129, 31, v128
	v_lshl_add_u64 v[128:129], v[128:129], 0, s[78:79]
	v_lshl_add_u64 v[128:129], v[128:129], 4, s[28:29]
	v_cmp_gt_i32_e64 s[18:19], s95, v136
	global_load_dword v137, v[128:129], off sc1
	v_add_u32_e32 v134, 0x80, v142
	v_cndmask_b32_e64 v128, 0, v136, s[18:19]
	v_ashrrev_i32_e32 v129, 31, v128
	v_lshl_add_u64 v[128:129], v[128:129], 0, s[78:79]
	v_lshl_add_u64 v[128:129], v[128:129], 4, s[28:29]
	v_cmp_gt_i32_e64 s[16:17], s95, v134
	global_load_dword v135, v[128:129], off sc1
	v_add_u32_e32 v132, 0x90, v142
	v_cndmask_b32_e64 v128, 0, v134, s[16:17]
	v_ashrrev_i32_e32 v129, 31, v128
	v_lshl_add_u64 v[128:129], v[128:129], 0, s[78:79]
	v_lshl_add_u64 v[128:129], v[128:129], 4, s[28:29]
	v_cmp_gt_i32_e64 s[14:15], s95, v132
	global_load_dword v133, v[128:129], off sc1
	v_add_u32_e32 v130, 0xa0, v142
	v_cndmask_b32_e64 v128, 0, v132, s[14:15]
	v_ashrrev_i32_e32 v129, 31, v128
	v_lshl_add_u64 v[128:129], v[128:129], 0, s[78:79]
	v_lshl_add_u64 v[128:129], v[128:129], 4, s[28:29]
	v_cmp_gt_i32_e64 s[12:13], s95, v130
	global_load_dword v131, v[128:129], off sc1
	v_ashrrev_i32_e32 v173, 31, v172
	v_cndmask_b32_e64 v128, 0, v130, s[12:13]
	v_ashrrev_i32_e32 v129, 31, v128
	v_lshl_add_u64 v[128:129], v[128:129], 0, s[78:79]
	v_lshl_add_u64 v[128:129], v[128:129], 4, s[28:29]
	global_load_dword v129, v[128:129], off sc1
	v_add_u32_e32 v128, 0xb0, v142
	v_cmp_gt_i32_e64 s[10:11], s95, v128
	s_nop 1
	v_cndmask_b32_e64 v144, 0, v128, s[10:11]
	v_ashrrev_i32_e32 v145, 31, v144
	v_lshl_add_u64 v[144:145], v[144:145], 0, s[78:79]
	v_lshl_add_u64 v[144:145], v[144:145], 4, s[28:29]
	global_load_dword v144, v[144:145], off sc1
	s_and_saveexec_b64 s[28:29], vcc
	s_cbranch_execz .LBB0_650
	s_waitcnt vmcnt(0)
	v_ashrrev_i32_e32 v143, 31, v142
	v_lshl_add_u64 v[142:143], v[142:143], 0, s[78:79]
	v_lshlrev_b64 v[142:143], 11, v[142:143]
	s_lshl_b32 vcc_lo, s92, 8
	v_rcp_f32_e32 v150, v141
	v_lshl_add_u64 v[142:143], s[48:49], 0, v[142:143]
	s_ashr_i32 vcc_hi, vcc_lo, 31
	v_pk_mul_f32 v[148:149], v[126:127], v[150:151] op_sel_hi:[1,0]
	v_pk_mul_f32 v[146:147], v[124:125], v[150:151] op_sel_hi:[1,0]
	v_lshl_add_u64 v[142:143], vcc, 1, v[142:143]
	v_pk_mul_f32 v[152:153], v[122:123], v[150:151] op_sel_hi:[1,0]
	v_pk_mul_f32 v[154:155], v[120:121], v[150:151] op_sel_hi:[1,0]
	v_cvt_pk_bf16_f32 v146, v146, v147
	v_cvt_pk_bf16_f32 v147, v148, v149
	v_cvt_pk_bf16_f32 v149, v152, v153
	v_lshl_add_u64 v[142:143], v[172:173], 1, v[142:143]
	v_cvt_pk_bf16_f32 v148, v154, v155
	global_store_dwordx4 v[142:143], v[146:149], off
	v_pk_mul_f32 v[152:153], v[90:91], v[150:151] op_sel_hi:[1,0]
	s_nop 0
	v_pk_mul_f32 v[148:149], v[94:95], v[150:151] op_sel_hi:[1,0]
	v_pk_mul_f32 v[146:147], v[92:93], v[150:151] op_sel_hi:[1,0]
	v_pk_mul_f32 v[150:151], v[88:89], v[150:151] op_sel_hi:[1,0]
	v_cvt_pk_bf16_f32 v146, v146, v147
	v_cvt_pk_bf16_f32 v147, v148, v149
	v_cvt_pk_bf16_f32 v149, v152, v153
	s_nop 0
	v_cvt_pk_bf16_f32 v148, v150, v151
	global_store_dwordx4 v[142:143], v[146:149], off offset:256
; __device__ __forceinline__ u32x4 pack8(f32x4 a, f32x4 b) { u32x4 w; w.x = pk2(a[0], a[1]); w.y = pk2(a[2], a[3]); w.z = pk2(b[0], b[1]); w.w = pk2(b[2], b[3]); return w; }
; #define FOR_ROWS _Pragma("unroll") for (int ai = 0; ai < 2; ++ai) _Pragma("unroll") for (int m = 0; m < 4; ++m)
; __device__ __forceinline__ void epilogue(const int kind, CParams& p, const f32x4 (&acc)[2][2][4][2], const Unit& u, const int wr, const int wc, const int fr_in, const int fq_in) {
;     ...
;         FOR_ROWS { ROWDEF
;             if (rt < u.aux) {
;                 const float inv = 1.f / pv[ai][m];
; #pragma unroll
;                 for (int bj = 0; bj < 2; ++bj) *(u32x4*)(p.ob + row * 1024 + u.pn * 256 + bj * 128 + cw) = pack8(acc[ai][bj][m][0] * inv, acc[ai][bj][m][1] * inv);
;             }
;         }
.LBB0_650:
	s_or_b64 exec, exec, s[28:29]
	s_and_saveexec_b64 s[28:29], s[22:23]
	s_cbranch_execz .LBB0_652
	s_waitcnt vmcnt(0)
	v_ashrrev_i32_e32 v141, 31, v140
	v_lshl_add_u64 v[140:141], v[140:141], 0, s[78:79]
	v_lshlrev_b64 v[140:141], 11, v[140:141]
	s_lshl_b32 s22, s92, 8
	v_rcp_f32_e32 v146, v139
	v_lshl_add_u64 v[148:149], s[48:49], 0, v[140:141]
	s_ashr_i32 s23, s22, 31
	v_pk_mul_f32 v[142:143], v[118:119], v[146:147] op_sel_hi:[1,0]
	v_pk_mul_f32 v[140:141], v[116:117], v[146:147] op_sel_hi:[1,0]
	v_lshl_add_u64 v[148:149], s[22:23], 1, v[148:149]
	v_pk_mul_f32 v[150:151], v[114:115], v[146:147] op_sel_hi:[1,0]
	v_pk_mul_f32 v[152:153], v[112:113], v[146:147] op_sel_hi:[1,0]
	v_cvt_pk_bf16_f32 v140, v140, v141
	v_cvt_pk_bf16_f32 v141, v142, v143
	v_cvt_pk_bf16_f32 v143, v150, v151
	v_lshl_add_u64 v[148:149], v[172:173], 1, v[148:149]
	v_cvt_pk_bf16_f32 v142, v152, v153
	global_store_dwordx4 v[148:149], v[140:143], off
	v_pk_mul_f32 v[150:151], v[82:83], v[146:147] op_sel_hi:[1,0]
	s_nop 0
	v_pk_mul_f32 v[142:143], v[86:87], v[146:147] op_sel_hi:[1,0]
	v_pk_mul_f32 v[140:141], v[84:85], v[146:147] op_sel_hi:[1,0]
	v_pk_mul_f32 v[146:147], v[80:81], v[146:147] op_sel_hi:[1,0]
	v_cvt_pk_bf16_f32 v140, v140, v141
	v_cvt_pk_bf16_f32 v141, v142, v143
	v_cvt_pk_bf16_f32 v143, v150, v151
	s_nop 0
	v_cvt_pk_bf16_f32 v142, v146, v147
	global_store_dwordx4 v[148:149], v[140:143], off offset:256
.LBB0_652:
	s_or_b64 exec, exec, s[28:29]
	s_and_saveexec_b64 s[22:23], s[20:21]
	v_readlane_b32 s93, v245, 52
	s_cbranch_execz .LBB0_658
	s_waitcnt vmcnt(0)
	v_ashrrev_i32_e32 v139, 31, v138
	v_lshl_add_u64 v[138:139], v[138:139], 0, s[78:79]
	v_lshlrev_b64 v[138:139], 11, v[138:139]
	s_lshl_b32 s20, s92, 8
	v_rcp_f32_e32 v142, v137
	v_lshl_add_u64 v[146:147], s[48:49], 0, v[138:139]
	s_ashr_i32 s21, s20, 31
	v_pk_mul_f32 v[140:141], v[110:111], v[142:143] op_sel_hi:[1,0]
	v_pk_mul_f32 v[138:139], v[108:109], v[142:143] op_sel_hi:[1,0]
	v_lshl_add_u64 v[146:147], s[20:21], 1, v[146:147]
	v_pk_mul_f32 v[148:149], v[106:107], v[142:143] op_sel_hi:[1,0]
	v_pk_mul_f32 v[150:151], v[104:105], v[142:143] op_sel_hi:[1,0]
	v_cvt_pk_bf16_f32 v138, v138, v139
	v_cvt_pk_bf16_f32 v139, v140, v141
	v_cvt_pk_bf16_f32 v141, v148, v149
	v_lshl_add_u64 v[146:147], v[172:173], 1, v[146:147]
	v_cvt_pk_bf16_f32 v140, v150, v151
	global_store_dwordx4 v[146:147], v[138:141], off
	v_pk_mul_f32 v[148:149], v[74:75], v[142:143] op_sel_hi:[1,0]
	s_nop 0
	v_pk_mul_f32 v[140:141], v[78:79], v[142:143] op_sel_hi:[1,0]
	v_pk_mul_f32 v[138:139], v[76:77], v[142:143] op_sel_hi:[1,0]
	v_pk_mul_f32 v[142:143], v[72:73], v[142:143] op_sel_hi:[1,0]
	v_cvt_pk_bf16_f32 v138, v138, v139
	v_cvt_pk_bf16_f32 v139, v140, v141
	v_cvt_pk_bf16_f32 v141, v148, v149
	s_nop 0
	v_cvt_pk_bf16_f32 v140, v142, v143
	global_store_dwordx4 v[146:147], v[138:141], off offset:256
	s_or_b64 exec, exec, s[22:23]
	s_and_saveexec_b64 s[20:21], s[18:19]
	s_cbranch_execnz .LBB0_659

; __device__ __forceinline__ u32x4 pack8(f32x4 a, f32x4 b) { u32x4 w; w.x = pk2(a[0], a[1]); w.y = pk2(a[2], a[3]); w.z = pk2(b[0], b[1]); w.w = pk2(b[2], b[3]); return w; }
; #define FOR_ROWS _Pragma("unroll") for (int ai = 0; ai < 2; ++ai) _Pragma("unroll") for (int m = 0; m < 4; ++m)
; __device__ __forceinline__ void epilogue(const int kind, CParams& p, const f32x4 (&acc)[2][2][4][2], const Unit& u, const int wr, const int wc, const int fr_in, const int fq_in) {
;     ...
;         FOR_ROWS { ROWDEF
;             if (rt < u.aux) {
;                 const float inv = 1.f / pv[ai][m];
; #pragma unroll
;                 for (int bj = 0; bj < 2; ++bj) *(u32x4*)(p.ob + row * 1024 + u.pn * 256 + bj * 128 + cw) = pack8(acc[ai][bj][m][0] * inv, acc[ai][bj][m][1] * inv);
;             }
;         }
.LBB0_655:
	s_waitcnt vmcnt(0)
	v_ashrrev_i32_e32 v135, 31, v134
	v_lshl_add_u64 v[134:135], v[134:135], 0, s[78:79]
	v_lshlrev_b64 v[134:135], 11, v[134:135]
	s_lshl_b32 s16, s92, 8
	v_rcp_f32_e32 v138, v133
	v_lshl_add_u64 v[140:141], s[48:49], 0, v[134:135]
	s_ashr_i32 s17, s16, 31
	v_pk_mul_f32 v[136:137], v[62:63], v[138:139] op_sel_hi:[1,0]
	v_pk_mul_f32 v[134:135], v[60:61], v[138:139] op_sel_hi:[1,0]
	v_lshl_add_u64 v[140:141], s[16:17], 1, v[140:141]
	v_pk_mul_f32 v[142:143], v[58:59], v[138:139] op_sel_hi:[1,0]
	v_pk_mul_f32 v[146:147], v[56:57], v[138:139] op_sel_hi:[1,0]
	v_cvt_pk_bf16_f32 v134, v134, v135
	v_cvt_pk_bf16_f32 v135, v136, v137
	v_cvt_pk_bf16_f32 v137, v142, v143
	v_lshl_add_u64 v[140:141], v[172:173], 1, v[140:141]
	v_cvt_pk_bf16_f32 v136, v146, v147
	global_store_dwordx4 v[140:141], v[134:137], off
	v_pk_mul_f32 v[142:143], v[26:27], v[138:139] op_sel_hi:[1,0]
	s_nop 0
	v_pk_mul_f32 v[136:137], v[30:31], v[138:139] op_sel_hi:[1,0]
	v_pk_mul_f32 v[134:135], v[28:29], v[138:139] op_sel_hi:[1,0]
	v_pk_mul_f32 v[138:139], v[24:25], v[138:139] op_sel_hi:[1,0]
	v_cvt_pk_bf16_f32 v134, v134, v135
	v_cvt_pk_bf16_f32 v135, v136, v137
	v_cvt_pk_bf16_f32 v137, v142, v143
	s_nop 0
	v_cvt_pk_bf16_f32 v136, v138, v139
	global_store_dwordx4 v[140:141], v[134:137], off offset:256
	s_or_b64 exec, exec, s[18:19]
	s_and_saveexec_b64 s[16:17], s[14:15]
	s_cbranch_execnz .LBB0_661

; __device__ __forceinline__ u32x4 pack8(f32x4 a, f32x4 b) { u32x4 w; w.x = pk2(a[0], a[1]); w.y = pk2(a[2], a[3]); w.z = pk2(b[0], b[1]); w.w = pk2(b[2], b[3]); return w; }
; #define FOR_ROWS _Pragma("unroll") for (int ai = 0; ai < 2; ++ai) _Pragma("unroll") for (int m = 0; m < 4; ++m)
; __device__ __forceinline__ void epilogue(const int kind, CParams& p, const f32x4 (&acc)[2][2][4][2], const Unit& u, const int wr, const int wc, const int fr_in, const int fq_in) {
;     ...
;         FOR_ROWS { ROWDEF
;             if (rt < u.aux) {
;                 const float inv = 1.f / pv[ai][m];
; #pragma unroll
;                 for (int bj = 0; bj < 2; ++bj) *(u32x4*)(p.ob + row * 1024 + u.pn * 256 + bj * 128 + cw) = pack8(acc[ai][bj][m][0] * inv, acc[ai][bj][m][1] * inv);
;             }
;         }
.LBB0_657:
	s_waitcnt vmcnt(0)
	v_ashrrev_i32_e32 v131, 31, v130
	v_lshl_add_u64 v[130:131], v[130:131], 0, s[78:79]
	v_lshlrev_b64 v[130:131], 11, v[130:131]
	s_lshl_b32 s12, s92, 8
	v_rcp_f32_e32 v134, v129
	v_lshl_add_u64 v[136:137], s[48:49], 0, v[130:131]
	s_ashr_i32 s13, s12, 31
	v_pk_mul_f32 v[132:133], v[46:47], v[134:135] op_sel_hi:[1,0]
	v_pk_mul_f32 v[130:131], v[44:45], v[134:135] op_sel_hi:[1,0]
	v_lshl_add_u64 v[136:137], s[12:13], 1, v[136:137]
	v_pk_mul_f32 v[138:139], v[42:43], v[134:135] op_sel_hi:[1,0]
	v_pk_mul_f32 v[140:141], v[40:41], v[134:135] op_sel_hi:[1,0]
	v_cvt_pk_bf16_f32 v130, v130, v131
	v_cvt_pk_bf16_f32 v131, v132, v133
	v_cvt_pk_bf16_f32 v133, v138, v139
	v_lshl_add_u64 v[136:137], v[172:173], 1, v[136:137]
	v_cvt_pk_bf16_f32 v132, v140, v141
	global_store_dwordx4 v[136:137], v[130:133], off
	v_pk_mul_f32 v[138:139], v[10:11], v[134:135] op_sel_hi:[1,0]
	s_nop 0
	v_pk_mul_f32 v[132:133], v[14:15], v[134:135] op_sel_hi:[1,0]
	v_pk_mul_f32 v[130:131], v[12:13], v[134:135] op_sel_hi:[1,0]
	v_pk_mul_f32 v[134:135], v[8:9], v[134:135] op_sel_hi:[1,0]
	v_cvt_pk_bf16_f32 v130, v130, v131
	v_cvt_pk_bf16_f32 v131, v132, v133
	v_cvt_pk_bf16_f32 v133, v138, v139
	s_nop 0
	v_cvt_pk_bf16_f32 v132, v134, v135
	global_store_dwordx4 v[136:137], v[130:133], off offset:256
	s_or_b64 exec, exec, s[14:15]
	s_and_saveexec_b64 s[12:13], s[10:11]
	s_cbranch_execnz .LBB0_663
	s_branch .LBB0_664

; __device__ __forceinline__ u32x4 pack8(f32x4 a, f32x4 b) { u32x4 w; w.x = pk2(a[0], a[1]); w.y = pk2(a[2], a[3]); w.z = pk2(b[0], b[1]); w.w = pk2(b[2], b[3]); return w; }
; #define FOR_ROWS _Pragma("unroll") for (int ai = 0; ai < 2; ++ai) _Pragma("unroll") for (int m = 0; m < 4; ++m)
; __device__ __forceinline__ void epilogue(const int kind, CParams& p, const f32x4 (&acc)[2][2][4][2], const Unit& u, const int wr, const int wc, const int fr_in, const int fq_in) {
;     ...
;         FOR_ROWS { ROWDEF
;             if (rt < u.aux) {
;                 const float inv = 1.f / pv[ai][m];
; #pragma unroll
;                 for (int bj = 0; bj < 2; ++bj) *(u32x4*)(p.ob + row * 1024 + u.pn * 256 + bj * 128 + cw) = pack8(acc[ai][bj][m][0] * inv, acc[ai][bj][m][1] * inv);
;             }
;         }
.LBB0_659:
	s_waitcnt vmcnt(0)
	v_ashrrev_i32_e32 v137, 31, v136
	v_lshl_add_u64 v[136:137], v[136:137], 0, s[78:79]
	v_lshlrev_b64 v[136:137], 11, v[136:137]
	s_lshl_b32 s18, s92, 8
	v_rcp_f32_e32 v140, v135
	v_lshl_add_u64 v[142:143], s[48:49], 0, v[136:137]
	s_ashr_i32 s19, s18, 31
	v_pk_mul_f32 v[138:139], v[102:103], v[140:141] op_sel_hi:[1,0]
	v_pk_mul_f32 v[136:137], v[100:101], v[140:141] op_sel_hi:[1,0]
	v_lshl_add_u64 v[142:143], s[18:19], 1, v[142:143]
	v_pk_mul_f32 v[146:147], v[98:99], v[140:141] op_sel_hi:[1,0]
	v_pk_mul_f32 v[148:149], v[96:97], v[140:141] op_sel_hi:[1,0]
	v_cvt_pk_bf16_f32 v136, v136, v137
	v_cvt_pk_bf16_f32 v137, v138, v139
	v_cvt_pk_bf16_f32 v139, v146, v147
	v_lshl_add_u64 v[142:143], v[172:173], 1, v[142:143]
	v_cvt_pk_bf16_f32 v138, v148, v149
	global_store_dwordx4 v[142:143], v[136:139], off
	v_pk_mul_f32 v[146:147], v[66:67], v[140:141] op_sel_hi:[1,0]
	s_nop 0
	v_pk_mul_f32 v[138:139], v[70:71], v[140:141] op_sel_hi:[1,0]
	v_pk_mul_f32 v[136:137], v[68:69], v[140:141] op_sel_hi:[1,0]
	v_pk_mul_f32 v[140:141], v[64:65], v[140:141] op_sel_hi:[1,0]
	v_cvt_pk_bf16_f32 v136, v136, v137
	v_cvt_pk_bf16_f32 v137, v138, v139
	v_cvt_pk_bf16_f32 v139, v146, v147
	s_nop 0
	v_cvt_pk_bf16_f32 v138, v140, v141
	global_store_dwordx4 v[142:143], v[136:139], off offset:256
	s_or_b64 exec, exec, s[20:21]
	s_and_saveexec_b64 s[18:19], s[16:17]
	s_cbranch_execnz .LBB0_655

; __device__ __forceinline__ u32x4 pack8(f32x4 a, f32x4 b) { u32x4 w; w.x = pk2(a[0], a[1]); w.y = pk2(a[2], a[3]); w.z = pk2(b[0], b[1]); w.w = pk2(b[2], b[3]); return w; }
; #define FOR_ROWS _Pragma("unroll") for (int ai = 0; ai < 2; ++ai) _Pragma("unroll") for (int m = 0; m < 4; ++m)
; __device__ __forceinline__ void epilogue(const int kind, CParams& p, const f32x4 (&acc)[2][2][4][2], const Unit& u, const int wr, const int wc, const int fr_in, const int fq_in) {
;     ...
;         FOR_ROWS { ROWDEF
;             if (rt < u.aux) {
;                 const float inv = 1.f / pv[ai][m];
; #pragma unroll
;                 for (int bj = 0; bj < 2; ++bj) *(u32x4*)(p.ob + row * 1024 + u.pn * 256 + bj * 128 + cw) = pack8(acc[ai][bj][m][0] * inv, acc[ai][bj][m][1] * inv);
;             }
;         }
.LBB0_661:
	s_waitcnt vmcnt(0)
	v_ashrrev_i32_e32 v133, 31, v132
	v_lshl_add_u64 v[132:133], v[132:133], 0, s[78:79]
	v_lshlrev_b64 v[132:133], 11, v[132:133]
	s_lshl_b32 s14, s92, 8
	v_rcp_f32_e32 v136, v131
	v_lshl_add_u64 v[138:139], s[48:49], 0, v[132:133]
	s_ashr_i32 s15, s14, 31
	v_pk_mul_f32 v[134:135], v[54:55], v[136:137] op_sel_hi:[1,0]
	v_pk_mul_f32 v[132:133], v[52:53], v[136:137] op_sel_hi:[1,0]
	v_lshl_add_u64 v[138:139], s[14:15], 1, v[138:139]
	v_pk_mul_f32 v[140:141], v[50:51], v[136:137] op_sel_hi:[1,0]
	v_pk_mul_f32 v[142:143], v[48:49], v[136:137] op_sel_hi:[1,0]
	v_cvt_pk_bf16_f32 v132, v132, v133
	v_cvt_pk_bf16_f32 v133, v134, v135
	v_cvt_pk_bf16_f32 v135, v140, v141
	v_lshl_add_u64 v[138:139], v[172:173], 1, v[138:139]
	v_cvt_pk_bf16_f32 v134, v142, v143
	global_store_dwordx4 v[138:139], v[132:135], off
	v_pk_mul_f32 v[140:141], v[18:19], v[136:137] op_sel_hi:[1,0]
	s_nop 0
	v_pk_mul_f32 v[134:135], v[22:23], v[136:137] op_sel_hi:[1,0]
	v_pk_mul_f32 v[132:133], v[20:21], v[136:137] op_sel_hi:[1,0]
	v_pk_mul_f32 v[136:137], v[16:17], v[136:137] op_sel_hi:[1,0]
	v_cvt_pk_bf16_f32 v132, v132, v133
	v_cvt_pk_bf16_f32 v133, v134, v135
	v_cvt_pk_bf16_f32 v135, v140, v141
	s_nop 0
	v_cvt_pk_bf16_f32 v134, v136, v137
	global_store_dwordx4 v[138:139], v[132:135], off offset:256
	s_or_b64 exec, exec, s[16:17]
	s_and_saveexec_b64 s[14:15], s[12:13]
	s_cbranch_execnz .LBB0_657

; __device__ __forceinline__ u32x4 pack8(f32x4 a, f32x4 b) { u32x4 w; w.x = pk2(a[0], a[1]); w.y = pk2(a[2], a[3]); w.z = pk2(b[0], b[1]); w.w = pk2(b[2], b[3]); return w; }
; #define FOR_ROWS _Pragma("unroll") for (int ai = 0; ai < 2; ++ai) _Pragma("unroll") for (int m = 0; m < 4; ++m)
; __device__ __forceinline__ void epilogue(const int kind, CParams& p, const f32x4 (&acc)[2][2][4][2], const Unit& u, const int wr, const int wc, const int fr_in, const int fq_in) {
;     ...
;         FOR_ROWS { ROWDEF
;             if (rt < u.aux) {
;                 const float inv = 1.f / pv[ai][m];
; #pragma unroll
;                 for (int bj = 0; bj < 2; ++bj) *(u32x4*)(p.ob + row * 1024 + u.pn * 256 + bj * 128 + cw) = pack8(acc[ai][bj][m][0] * inv, acc[ai][bj][m][1] * inv);
;             }
;         }
.LBB0_663:
	s_waitcnt vmcnt(0)
	v_ashrrev_i32_e32 v129, 31, v128
	v_lshl_add_u64 v[128:129], v[128:129], 0, s[78:79]
	v_lshlrev_b64 v[128:129], 11, v[128:129]
	s_lshl_b32 s10, s92, 8
	v_rcp_f32_e32 v132, v144
	v_lshl_add_u64 v[134:135], s[48:49], 0, v[128:129]
	s_ashr_i32 s11, s10, 31
	v_pk_mul_f32 v[130:131], v[38:39], v[132:133] op_sel_hi:[1,0]
	v_pk_mul_f32 v[128:129], v[36:37], v[132:133] op_sel_hi:[1,0]
	v_lshl_add_u64 v[134:135], s[10:11], 1, v[134:135]
	v_pk_mul_f32 v[136:137], v[34:35], v[132:133] op_sel_hi:[1,0]
	v_pk_mul_f32 v[138:139], v[32:33], v[132:133] op_sel_hi:[1,0]
	v_cvt_pk_bf16_f32 v128, v128, v129
	v_cvt_pk_bf16_f32 v129, v130, v131
	v_cvt_pk_bf16_f32 v131, v136, v137
	v_lshl_add_u64 v[134:135], v[172:173], 1, v[134:135]
	v_cvt_pk_bf16_f32 v130, v138, v139
	global_store_dwordx4 v[134:135], v[128:131], off
	v_pk_mul_f32 v[136:137], v[2:3], v[132:133] op_sel_hi:[1,0]
	s_nop 0
	v_pk_mul_f32 v[130:131], v[6:7], v[132:133] op_sel_hi:[1,0]
	v_pk_mul_f32 v[128:129], v[4:5], v[132:133] op_sel_hi:[1,0]
	v_pk_mul_f32 v[132:133], v[0:1], v[132:133] op_sel_hi:[1,0]
	v_cvt_pk_bf16_f32 v128, v128, v129
	v_cvt_pk_bf16_f32 v129, v130, v131
	v_cvt_pk_bf16_f32 v131, v136, v137
	s_nop 0
	v_cvt_pk_bf16_f32 v130, v132, v133
	global_store_dwordx4 v[134:135], v[128:131], off offset:256

; __device__ __forceinline__ u32x4 pack8(f32x4 a, f32x4 b) { u32x4 w; w.x = pk2(a[0], a[1]); w.y = pk2(a[2], a[3]); w.z = pk2(b[0], b[1]); w.w = pk2(b[2], b[3]); return w; }
; __device__ __forceinline__ f32x4 sigm4(f32x4 v) { return (f32x4){sigm(v[0]), sigm(v[1]), sigm(v[2]), sigm(v[3])}; }
; #define FOR_ROWS _Pragma("unroll") for (int ai = 0; ai < 2; ++ai) _Pragma("unroll") for (int m = 0; m < 4; ++m)
; __device__ __forceinline__ void epilogue(const int kind, CParams& p, const f32x4 (&acc)[2][2][4][2], const Unit& u, const int wr, const int wc, const int fr_in, const int fq_in) {
;     ...
;     case E_EA: {
;         const float* bias = u.pn < 4 ? p.in[I_W0] : p.in[I_A0];
;         bf16_t* o = u.pn < 4 ? p.ebuf : p.abuf;
;         const float sc = u.pn < 4 ? 0.60653066f : 1.0f;
;         f32x4 bv[2][2];
; #pragma unroll
;         for (int bj = 0; bj < 2; ++bj) { const int col = (u.pn & 3) * 256 + bj * 128 + cw; bv[bj][0] = *(const f32x4*)(bias + col); bv[bj][1] = *(const f32x4*)(bias + col + 4); }
;         FOR_ROWS { ROWDEF
; #pragma unroll
;             for (int bj = 0; bj < 2; ++bj) {
;                 const int col = (u.pn & 3) * 256 + bj * 128 + cw;
;                 *(u32x4*)(o + row * 1024 + col) = pack8(sigm4(acc[ai][bj][m][0] + bv[bj][0]) * sc, sigm4(acc[ai][bj][m][1] + bv[bj][1]) * sc);
;             } }
;     } break;
.LBB0_860:
	s_andn2_b64 vcc, exec, s[10:11]
	s_cbranch_vccnz .LBB0_862
	s_cmp_lt_i32 s92, 4
	s_cselect_b64 vcc, -1, 0
	s_and_b64 s[10:11], vcc, exec
	s_movk_i32 s1, 0x90
	s_cselect_b32 s1, 0x80, s1
	s_movk_i32 s10, 0x1e0
	v_readlane_b32 s16, v245, 55
	s_cselect_b32 s14, s10, 0x240
	v_readlane_b32 s17, v245, 56
	s_add_u32 s10, s16, s1
	s_addc_u32 s11, s17, 0
	s_load_dwordx2 s[12:13], s[10:11], 0x0
	s_add_u32 s10, s16, s14
	s_addc_u32 s11, s17, 0
	s_lshl_b32 s1, s92, 8
	s_and_b32 s1, s1, 0x300
	v_add_u32_e32 v150, s1, v172
	v_ashrrev_i32_e32 v151, 31, v150
	s_waitcnt vmcnt(0) lgkmcnt(0)
	v_lshl_add_u64 v[132:133], v[150:151], 2, s[12:13]
	s_load_dwordx2 s[10:11], s[10:11], 0x0
	global_load_dwordx4 v[136:139], v[132:133], off offset:16
	global_load_dwordx4 v[140:143], v[132:133], off
	global_load_dwordx4 v[128:131], v[132:133], off offset:528
	s_nop 0
	global_load_dwordx4 v[132:135], v[132:133], off offset:512
	v_add_u32_e32 v146, s0, v215
	s_ashr_i32 s79, s78, 31
	v_ashrrev_i32_e32 v147, 31, v146
	v_lshl_add_u64 v[148:149], v[146:147], 0, s[78:79]
	v_lshlrev_b64 v[148:149], 11, v[148:149]
	s_waitcnt lgkmcnt(0)
	v_lshl_add_u64 v[152:153], s[10:11], 0, v[148:149]
	v_cndmask_b32_e32 v144, 1.0, v210, vcc
	s_waitcnt vmcnt(2)
	v_pk_add_f32 v[154:155], v[124:125], v[140:141]
	s_nop 0
	v_mul_f32_e32 v145, 0xbfb8aa3b, v154
	v_pk_add_f32 v[148:149], v[126:127], v[142:143]
	v_exp_f32_e32 v154, v145
	v_mul_f32_e32 v145, 0xbfb8aa3b, v155
	v_exp_f32_e32 v155, v145
	v_mul_f32_e32 v145, 0xbfb8aa3b, v148
	v_exp_f32_e32 v148, v145
	v_mul_f32_e32 v145, 0xbfb8aa3b, v149
	v_exp_f32_e32 v149, v145
	v_pk_add_f32 v[154:155], v[154:155], 1.0 op_sel_hi:[1,0]
	v_pk_add_f32 v[148:149], v[148:149], 1.0 op_sel_hi:[1,0]
	s_nop 0
	s_nop 0
	v_rcp_f32_e32 v149, v149
	s_nop 0
	v_rcp_f32_e32 v148, v148
	s_nop 0
	v_rcp_f32_e32 v155, v155
	s_nop 0
	v_rcp_f32_e32 v154, v154
	v_pk_add_f32 v[158:159], v[120:121], v[136:137]
	v_pk_mul_f32 v[148:149], v[144:145], v[148:149] op_sel_hi:[0,1]
	v_pk_mul_f32 v[154:155], v[144:145], v[154:155] op_sel_hi:[0,1]
	v_mul_f32_e32 v145, 0xbfb8aa3b, v158
	v_pk_add_f32 v[156:157], v[122:123], v[138:139]
	v_exp_f32_e32 v174, v145
	v_mul_f32_e32 v145, 0xbfb8aa3b, v159
	v_exp_f32_e32 v175, v145
	v_mul_f32_e32 v145, 0xbfb8aa3b, v156
	v_exp_f32_e32 v156, v145
	v_mul_f32_e32 v145, 0xbfb8aa3b, v157
	v_exp_f32_e32 v157, v145
	v_cvt_pk_bf16_f32 v154, v154, v155
	v_cvt_pk_bf16_f32 v155, v148, v149
	v_lshlrev_b64 v[148:149], 1, v[150:151]
	v_pk_add_f32 v[158:159], v[156:157], 1.0 op_sel_hi:[1,0]
	v_pk_add_f32 v[156:157], v[174:175], 1.0 op_sel_hi:[1,0]
	v_add_u32_e32 v150, 0x80, v150
	v_rcp_f32_e32 v159, v159
	s_nop 0
	v_rcp_f32_e32 v158, v158
	s_nop 0
	v_rcp_f32_e32 v157, v157
	s_nop 0
	v_rcp_f32_e32 v156, v156
	v_pk_mul_f32 v[158:159], v[144:145], v[158:159] op_sel_hi:[0,1]
	v_pk_mul_f32 v[156:157], v[144:145], v[156:157] op_sel_hi:[0,1]
	v_cvt_pk_bf16_f32 v156, v156, v157
	v_cvt_pk_bf16_f32 v157, v158, v159
	v_lshl_add_u64 v[158:159], v[152:153], 0, v[148:149]
	global_store_dwordx4 v[158:159], v[154:157], off
	s_waitcnt vmcnt(2)
	v_pk_add_f32 v[174:175], v[88:89], v[128:129]
	s_waitcnt vmcnt(1)
	v_pk_add_f32 v[156:157], v[92:93], v[132:133]
	v_pk_add_f32 v[154:155], v[94:95], v[134:135]
	v_mul_f32_e32 v145, 0xbfb8aa3b, v156
	v_exp_f32_e32 v156, v145
	v_mul_f32_e32 v145, 0xbfb8aa3b, v157
	v_exp_f32_e32 v157, v145
	v_mul_f32_e32 v145, 0xbfb8aa3b, v154
	v_exp_f32_e32 v154, v145
	v_mul_f32_e32 v145, 0xbfb8aa3b, v155
	v_exp_f32_e32 v155, v145
	v_pk_add_f32 v[156:157], v[156:157], 1.0 op_sel_hi:[1,0]
	v_pk_add_f32 v[154:155], v[154:155], 1.0 op_sel_hi:[1,0]
	s_nop 0
	s_nop 0
	v_rcp_f32_e32 v155, v155
	s_nop 0
	v_rcp_f32_e32 v154, v154
	s_nop 0
	v_rcp_f32_e32 v157, v157
	s_nop 0
	v_rcp_f32_e32 v156, v156
	v_pk_mul_f32 v[158:159], v[144:145], v[154:155] op_sel_hi:[0,1]
	v_pk_mul_f32 v[154:155], v[144:145], v[156:157] op_sel_hi:[0,1]
	v_mul_f32_e32 v145, 0xbfb8aa3b, v174
	v_pk_add_f32 v[156:157], v[90:91], v[130:131]
	v_exp_f32_e32 v174, v145
	v_mul_f32_e32 v145, 0xbfb8aa3b, v175
	v_exp_f32_e32 v175, v145
	v_mul_f32_e32 v145, 0xbfb8aa3b, v156
	v_exp_f32_e32 v156, v145
	v_mul_f32_e32 v145, 0xbfb8aa3b, v157
	v_exp_f32_e32 v157, v145
	v_pk_add_f32 v[174:175], v[174:175], 1.0 op_sel_hi:[1,0]
	v_cvt_pk_bf16_f32 v154, v154, v155
	v_cvt_pk_bf16_f32 v155, v158, v159
	v_pk_add_f32 v[156:157], v[156:157], 1.0 op_sel_hi:[1,0]
	s_nop 0
	s_nop 0
	v_rcp_f32_e32 v157, v157
	s_nop 0
	v_rcp_f32_e32 v156, v156
	s_nop 0
	v_rcp_f32_e32 v175, v175
	s_nop 0
	v_rcp_f32_e32 v174, v174
	v_ashrrev_i32_e32 v151, 31, v150
	v_pk_mul_f32 v[176:177], v[144:145], v[156:157] op_sel_hi:[0,1]
	v_pk_mul_f32 v[156:157], v[144:145], v[174:175] op_sel_hi:[0,1]
	v_lshlrev_b64 v[150:151], 1, v[150:151]
	v_cvt_pk_bf16_f32 v156, v156, v157
	v_cvt_pk_bf16_f32 v157, v176, v177
	v_lshl_add_u64 v[152:153], v[152:153], 0, v[150:151]
	global_store_dwordx4 v[152:153], v[154:157], off
	v_pk_add_f32 v[174:175], v[112:113], v[136:137]
	v_add_u32_e32 v152, 16, v146
	v_pk_add_f32 v[156:157], v[116:117], v[140:141]
	v_pk_add_f32 v[154:155], v[118:119], v[142:143]
	v_mul_f32_e32 v145, 0xbfb8aa3b, v156
	v_exp_f32_e32 v156, v145
	v_mul_f32_e32 v145, 0xbfb8aa3b, v157
	v_exp_f32_e32 v157, v145
	v_mul_f32_e32 v145, 0xbfb8aa3b, v154
	v_exp_f32_e32 v154, v145
	v_mul_f32_e32 v145, 0xbfb8aa3b, v155
	v_exp_f32_e32 v155, v145
	v_pk_add_f32 v[156:157], v[156:157], 1.0 op_sel_hi:[1,0]
	v_ashrrev_i32_e32 v153, 31, v152
	v_lshl_add_u64 v[152:153], v[152:153], 0, s[78:79]
	v_pk_add_f32 v[154:155], v[154:155], 1.0 op_sel_hi:[1,0]
	v_lshlrev_b64 v[152:153], 11, v[152:153]
	v_lshl_add_u64 v[152:153], s[10:11], 0, v[152:153]
; __device__ __forceinline__ u32x4 pack8(f32x4 a, f32x4 b) { u32x4 w; w.x = pk2(a[0], a[1]); w.y = pk2(a[2], a[3]); w.z = pk2(b[0], b[1]); w.w = pk2(b[2], b[3]); return w; }
; __device__ __forceinline__ f32x4 sigm4(f32x4 v) { return (f32x4){sigm(v[0]), sigm(v[1]), sigm(v[2]), sigm(v[3])}; }
; #define FOR_ROWS _Pragma("unroll") for (int ai = 0; ai < 2; ++ai) _Pragma("unroll") for (int m = 0; m < 4; ++m)
; __device__ __forceinline__ float sigm(float x) { return 1.f / (1.f + __expf(-x)); }
; __device__ __forceinline__ void epilogue(const int kind, CParams& p, const f32x4 (&acc)[2][2][4][2], const Unit& u, const int wr, const int wc, const int fr_in, const int fq_in) {
;     ...
;     case E_EA: {
;         const float* bias = u.pn < 4 ? p.in[I_W0] : p.in[I_A0];
;         bf16_t* o = u.pn < 4 ? p.ebuf : p.abuf;
;         const float sc = u.pn < 4 ? 0.60653066f : 1.0f;
;         f32x4 bv[2][2];
; #pragma unroll
;         for (int bj = 0; bj < 2; ++bj) { const int col = (u.pn & 3) * 256 + bj * 128 + cw; bv[bj][0] = *(const f32x4*)(bias + col); bv[bj][1] = *(const f32x4*)(bias + col + 4); }
;         FOR_ROWS { ROWDEF
; #pragma unroll
;             for (int bj = 0; bj < 2; ++bj) {
;                 const int col = (u.pn & 3) * 256 + bj * 128 + cw;
;                 *(u32x4*)(o + row * 1024 + col) = pack8(sigm4(acc[ai][bj][m][0] + bv[bj][0]) * sc, sigm4(acc[ai][bj][m][1] + bv[bj][1]) * sc);
;             } }
	v_rcp_f32_e32 v155, v155
	s_nop 0
	v_rcp_f32_e32 v154, v154
	s_nop 0
	v_rcp_f32_e32 v157, v157
	s_nop 0
	v_rcp_f32_e32 v156, v156
	v_pk_mul_f32 v[158:159], v[144:145], v[154:155] op_sel_hi:[0,1]
	v_pk_mul_f32 v[154:155], v[144:145], v[156:157] op_sel_hi:[0,1]
	v_mul_f32_e32 v145, 0xbfb8aa3b, v174
	v_pk_add_f32 v[156:157], v[114:115], v[138:139]
	v_exp_f32_e32 v174, v145
	v_mul_f32_e32 v145, 0xbfb8aa3b, v175
	v_exp_f32_e32 v175, v145
	v_mul_f32_e32 v145, 0xbfb8aa3b, v156
	v_exp_f32_e32 v156, v145
	v_mul_f32_e32 v145, 0xbfb8aa3b, v157
	v_exp_f32_e32 v157, v145
	v_pk_add_f32 v[174:175], v[174:175], 1.0 op_sel_hi:[1,0]
	v_cvt_pk_bf16_f32 v154, v154, v155
	v_cvt_pk_bf16_f32 v155, v158, v159
	v_pk_add_f32 v[156:157], v[156:157], 1.0 op_sel_hi:[1,0]
	v_lshl_add_u64 v[158:159], v[152:153], 0, v[148:149]
	v_lshl_add_u64 v[152:153], v[152:153], 0, v[150:151]
	v_rcp_f32_e32 v157, v157
	s_nop 0
	v_rcp_f32_e32 v156, v156
	s_nop 0
	v_rcp_f32_e32 v175, v175
	s_nop 0
	v_rcp_f32_e32 v174, v174
	v_pk_mul_f32 v[176:177], v[144:145], v[156:157] op_sel_hi:[0,1]
	v_pk_mul_f32 v[156:157], v[144:145], v[174:175] op_sel_hi:[0,1]
	v_cvt_pk_bf16_f32 v156, v156, v157
	v_cvt_pk_bf16_f32 v157, v176, v177
	global_store_dwordx4 v[158:159], v[154:157], off
	v_pk_add_f32 v[174:175], v[80:81], v[128:129]
	s_nop 0
	v_pk_add_f32 v[156:157], v[84:85], v[132:133]
	v_pk_add_f32 v[154:155], v[86:87], v[134:135]
	v_mul_f32_e32 v145, 0xbfb8aa3b, v156
	v_exp_f32_e32 v156, v145
	v_mul_f32_e32 v145, 0xbfb8aa3b, v157
	v_exp_f32_e32 v157, v145
	v_mul_f32_e32 v145, 0xbfb8aa3b, v154
	v_exp_f32_e32 v154, v145
	v_mul_f32_e32 v145, 0xbfb8aa3b, v155
	v_exp_f32_e32 v155, v145
	v_pk_add_f32 v[156:157], v[156:157], 1.0 op_sel_hi:[1,0]
	v_pk_add_f32 v[154:155], v[154:155], 1.0 op_sel_hi:[1,0]
	s_nop 0
	s_nop 0
	v_rcp_f32_e32 v155, v155
	s_nop 0
	v_rcp_f32_e32 v154, v154
	s_nop 0
	v_rcp_f32_e32 v157, v157
	s_nop 0
	v_rcp_f32_e32 v156, v156
	v_pk_mul_f32 v[158:159], v[144:145], v[154:155] op_sel_hi:[0,1]
	v_pk_mul_f32 v[154:155], v[144:145], v[156:157] op_sel_hi:[0,1]
	v_mul_f32_e32 v145, 0xbfb8aa3b, v174
	v_pk_add_f32 v[156:157], v[82:83], v[130:131]
	v_exp_f32_e32 v174, v145
	v_mul_f32_e32 v145, 0xbfb8aa3b, v175
	v_exp_f32_e32 v175, v145
	v_mul_f32_e32 v145, 0xbfb8aa3b, v156
	v_exp_f32_e32 v156, v145
	v_mul_f32_e32 v145, 0xbfb8aa3b, v157
	v_exp_f32_e32 v157, v145
	v_pk_add_f32 v[174:175], v[174:175], 1.0 op_sel_hi:[1,0]
	v_cvt_pk_bf16_f32 v154, v154, v155
	v_cvt_pk_bf16_f32 v155, v158, v159
	v_pk_add_f32 v[156:157], v[156:157], 1.0 op_sel_hi:[1,0]
	s_nop 0
	s_nop 0
	v_rcp_f32_e32 v157, v157
	s_nop 0
	v_rcp_f32_e32 v156, v156
	s_nop 0
	v_rcp_f32_e32 v175, v175
	s_nop 0
	v_rcp_f32_e32 v174, v174
	v_pk_mul_f32 v[176:177], v[144:145], v[156:157] op_sel_hi:[0,1]
	v_pk_mul_f32 v[156:157], v[144:145], v[174:175] op_sel_hi:[0,1]
	v_cvt_pk_bf16_f32 v156, v156, v157
	v_cvt_pk_bf16_f32 v157, v176, v177
	global_store_dwordx4 v[152:153], v[154:157], off
	v_pk_add_f32 v[174:175], v[104:105], v[136:137]
	v_add_u32_e32 v152, 32, v146
	v_pk_add_f32 v[156:157], v[108:109], v[140:141]
	v_pk_add_f32 v[154:155], v[110:111], v[142:143]
	v_mul_f32_e32 v145, 0xbfb8aa3b, v156
	v_exp_f32_e32 v156, v145
	v_mul_f32_e32 v145, 0xbfb8aa3b, v157
	v_exp_f32_e32 v157, v145
	v_mul_f32_e32 v145, 0xbfb8aa3b, v154
	v_exp_f32_e32 v154, v145
	v_mul_f32_e32 v145, 0xbfb8aa3b, v155
	v_exp_f32_e32 v155, v145
	v_pk_add_f32 v[156:157], v[156:157], 1.0 op_sel_hi:[1,0]
	v_ashrrev_i32_e32 v153, 31, v152
	v_lshl_add_u64 v[152:153], v[152:153], 0, s[78:79]
	v_pk_add_f32 v[154:155], v[154:155], 1.0 op_sel_hi:[1,0]
	v_lshlrev_b64 v[152:153], 11, v[152:153]
	v_lshl_add_u64 v[152:153], s[10:11], 0, v[152:153]
	v_rcp_f32_e32 v155, v155
	s_nop 0
	v_rcp_f32_e32 v154, v154
	s_nop 0
	v_rcp_f32_e32 v157, v157
	s_nop 0
	v_rcp_f32_e32 v156, v156
	v_pk_mul_f32 v[158:159], v[144:145], v[154:155] op_sel_hi:[0,1]
	v_pk_mul_f32 v[154:155], v[144:145], v[156:157] op_sel_hi:[0,1]
	v_mul_f32_e32 v145, 0xbfb8aa3b, v174
	v_pk_add_f32 v[156:157], v[106:107], v[138:139]
	v_exp_f32_e32 v174, v145
	v_mul_f32_e32 v145, 0xbfb8aa3b, v175
	v_exp_f32_e32 v175, v145
	v_mul_f32_e32 v145, 0xbfb8aa3b, v156
	v_exp_f32_e32 v156, v145
	v_mul_f32_e32 v145, 0xbfb8aa3b, v157
	v_exp_f32_e32 v157, v145
	v_pk_add_f32 v[174:175], v[174:175], 1.0 op_sel_hi:[1,0]
	v_cvt_pk_bf16_f32 v154, v154, v155
	v_cvt_pk_bf16_f32 v155, v158, v159
	v_pk_add_f32 v[156:157], v[156:157], 1.0 op_sel_hi:[1,0]
	v_lshl_add_u64 v[158:159], v[152:153], 0, v[148:149]
	v_lshl_add_u64 v[152:153], v[152:153], 0, v[150:151]
	v_rcp_f32_e32 v157, v157
	s_nop 0
	v_rcp_f32_e32 v156, v156
	s_nop 0
	v_rcp_f32_e32 v175, v175
	s_nop 0
	v_rcp_f32_e32 v174, v174
	v_pk_mul_f32 v[176:177], v[144:145], v[156:157] op_sel_hi:[0,1]
	v_pk_mul_f32 v[156:157], v[144:145], v[174:175] op_sel_hi:[0,1]
	v_cvt_pk_bf16_f32 v156, v156, v157
	v_cvt_pk_bf16_f32 v157, v176, v177
	global_store_dwordx4 v[158:159], v[154:157], off
	v_pk_add_f32 v[174:175], v[72:73], v[128:129]
	s_nop 0
	v_pk_add_f32 v[156:157], v[76:77], v[132:133]
	v_pk_add_f32 v[154:155], v[78:79], v[134:135]
	v_mul_f32_e32 v145, 0xbfb8aa3b, v156
	v_exp_f32_e32 v156, v145
	v_mul_f32_e32 v145, 0xbfb8aa3b, v157
	v_exp_f32_e32 v157, v145
	v_mul_f32_e32 v145, 0xbfb8aa3b, v154
	v_exp_f32_e32 v154, v145
	v_mul_f32_e32 v145, 0xbfb8aa3b, v155
	v_exp_f32_e32 v155, v145
	v_pk_add_f32 v[156:157], v[156:157], 1.0 op_sel_hi:[1,0]
	v_pk_add_f32 v[154:155], v[154:155], 1.0 op_sel_hi:[1,0]
	s_nop 0
	s_nop 0
	v_rcp_f32_e32 v155, v155
	s_nop 0
	v_rcp_f32_e32 v154, v154
	s_nop 0
	v_rcp_f32_e32 v157, v157
	s_nop 0
	v_rcp_f32_e32 v156, v156
	v_pk_mul_f32 v[158:159], v[144:145], v[154:155] op_sel_hi:[0,1]
; __device__ __forceinline__ u32x4 pack8(f32x4 a, f32x4 b) { u32x4 w; w.x = pk2(a[0], a[1]); w.y = pk2(a[2], a[3]); w.z = pk2(b[0], b[1]); w.w = pk2(b[2], b[3]); return w; }
; __device__ __forceinline__ f32x4 sigm4(f32x4 v) { return (f32x4){sigm(v[0]), sigm(v[1]), sigm(v[2]), sigm(v[3])}; }
; #define FOR_ROWS _Pragma("unroll") for (int ai = 0; ai < 2; ++ai) _Pragma("unroll") for (int m = 0; m < 4; ++m)
; __device__ __forceinline__ float sigm(float x) { return 1.f / (1.f + __expf(-x)); }
; __device__ __forceinline__ void epilogue(const int kind, CParams& p, const f32x4 (&acc)[2][2][4][2], const Unit& u, const int wr, const int wc, const int fr_in, const int fq_in) {
;     ...
;     case E_EA: {
;         const float* bias = u.pn < 4 ? p.in[I_W0] : p.in[I_A0];
;         bf16_t* o = u.pn < 4 ? p.ebuf : p.abuf;
;         const float sc = u.pn < 4 ? 0.60653066f : 1.0f;
;         f32x4 bv[2][2];
; #pragma unroll
;         for (int bj = 0; bj < 2; ++bj) { const int col = (u.pn & 3) * 256 + bj * 128 + cw; bv[bj][0] = *(const f32x4*)(bias + col); bv[bj][1] = *(const f32x4*)(bias + col + 4); }
;         FOR_ROWS { ROWDEF
; #pragma unroll
;             for (int bj = 0; bj < 2; ++bj) {
;                 const int col = (u.pn & 3) * 256 + bj * 128 + cw;
;                 *(u32x4*)(o + row * 1024 + col) = pack8(sigm4(acc[ai][bj][m][0] + bv[bj][0]) * sc, sigm4(acc[ai][bj][m][1] + bv[bj][1]) * sc);
;             } }
	v_pk_mul_f32 v[154:155], v[144:145], v[156:157] op_sel_hi:[0,1]
	v_mul_f32_e32 v145, 0xbfb8aa3b, v174
	v_pk_add_f32 v[156:157], v[74:75], v[130:131]
	v_exp_f32_e32 v174, v145
	v_mul_f32_e32 v145, 0xbfb8aa3b, v175
	v_exp_f32_e32 v175, v145
	v_mul_f32_e32 v145, 0xbfb8aa3b, v156
	v_exp_f32_e32 v156, v145
	v_mul_f32_e32 v145, 0xbfb8aa3b, v157
	v_exp_f32_e32 v157, v145
	v_pk_add_f32 v[174:175], v[174:175], 1.0 op_sel_hi:[1,0]
	v_cvt_pk_bf16_f32 v154, v154, v155
	v_cvt_pk_bf16_f32 v155, v158, v159
	v_pk_add_f32 v[156:157], v[156:157], 1.0 op_sel_hi:[1,0]
	s_nop 0
	s_nop 0
	v_rcp_f32_e32 v157, v157
	s_nop 0
	v_rcp_f32_e32 v156, v156
	s_nop 0
	v_rcp_f32_e32 v175, v175
	s_nop 0
	v_rcp_f32_e32 v174, v174
	v_pk_mul_f32 v[176:177], v[144:145], v[156:157] op_sel_hi:[0,1]
	v_pk_mul_f32 v[156:157], v[144:145], v[174:175] op_sel_hi:[0,1]
	v_cvt_pk_bf16_f32 v156, v156, v157
	v_cvt_pk_bf16_f32 v157, v176, v177
	global_store_dwordx4 v[152:153], v[154:157], off
	v_pk_add_f32 v[174:175], v[96:97], v[136:137]
	v_add_u32_e32 v152, 48, v146
	v_pk_add_f32 v[156:157], v[100:101], v[140:141]
	v_pk_add_f32 v[154:155], v[102:103], v[142:143]
	v_mul_f32_e32 v145, 0xbfb8aa3b, v156
	v_exp_f32_e32 v156, v145
	v_mul_f32_e32 v145, 0xbfb8aa3b, v157
	v_exp_f32_e32 v157, v145
	v_mul_f32_e32 v145, 0xbfb8aa3b, v154
	v_exp_f32_e32 v154, v145
	v_mul_f32_e32 v145, 0xbfb8aa3b, v155
	v_exp_f32_e32 v155, v145
	v_pk_add_f32 v[156:157], v[156:157], 1.0 op_sel_hi:[1,0]
	v_ashrrev_i32_e32 v153, 31, v152
	v_lshl_add_u64 v[152:153], v[152:153], 0, s[78:79]
	v_pk_add_f32 v[154:155], v[154:155], 1.0 op_sel_hi:[1,0]
	v_lshlrev_b64 v[152:153], 11, v[152:153]
	v_lshl_add_u64 v[152:153], s[10:11], 0, v[152:153]
	v_rcp_f32_e32 v155, v155
	s_nop 0
	v_rcp_f32_e32 v154, v154
	s_nop 0
	v_rcp_f32_e32 v157, v157
	s_nop 0
	v_rcp_f32_e32 v156, v156
	v_pk_mul_f32 v[158:159], v[144:145], v[154:155] op_sel_hi:[0,1]
	v_pk_mul_f32 v[154:155], v[144:145], v[156:157] op_sel_hi:[0,1]
	v_mul_f32_e32 v145, 0xbfb8aa3b, v174
	v_pk_add_f32 v[156:157], v[98:99], v[138:139]
	v_exp_f32_e32 v174, v145
	v_mul_f32_e32 v145, 0xbfb8aa3b, v175
	v_exp_f32_e32 v175, v145
	v_mul_f32_e32 v145, 0xbfb8aa3b, v156
	v_exp_f32_e32 v156, v145
	v_mul_f32_e32 v145, 0xbfb8aa3b, v157
	v_exp_f32_e32 v157, v145
	v_pk_add_f32 v[174:175], v[174:175], 1.0 op_sel_hi:[1,0]
	v_cvt_pk_bf16_f32 v154, v154, v155
	v_cvt_pk_bf16_f32 v155, v158, v159
	v_pk_add_f32 v[156:157], v[156:157], 1.0 op_sel_hi:[1,0]
	v_lshl_add_u64 v[158:159], v[152:153], 0, v[148:149]
	v_lshl_add_u64 v[152:153], v[152:153], 0, v[150:151]
	v_rcp_f32_e32 v157, v157
	s_nop 0
	v_rcp_f32_e32 v156, v156
	s_nop 0
	v_rcp_f32_e32 v175, v175
	s_nop 0
	v_rcp_f32_e32 v174, v174
	v_pk_mul_f32 v[176:177], v[144:145], v[156:157] op_sel_hi:[0,1]
	v_pk_mul_f32 v[156:157], v[144:145], v[174:175] op_sel_hi:[0,1]
	v_cvt_pk_bf16_f32 v156, v156, v157
	v_cvt_pk_bf16_f32 v157, v176, v177
	global_store_dwordx4 v[158:159], v[154:157], off
	v_pk_add_f32 v[174:175], v[64:65], v[128:129]
	s_nop 0
	v_pk_add_f32 v[156:157], v[68:69], v[132:133]
	v_pk_add_f32 v[154:155], v[70:71], v[134:135]
	v_mul_f32_e32 v145, 0xbfb8aa3b, v156
	v_exp_f32_e32 v156, v145
	v_mul_f32_e32 v145, 0xbfb8aa3b, v157
	v_exp_f32_e32 v157, v145
	v_mul_f32_e32 v145, 0xbfb8aa3b, v154
	v_exp_f32_e32 v154, v145
	v_mul_f32_e32 v145, 0xbfb8aa3b, v155
	v_exp_f32_e32 v155, v145
	v_pk_add_f32 v[156:157], v[156:157], 1.0 op_sel_hi:[1,0]
	v_pk_add_f32 v[154:155], v[154:155], 1.0 op_sel_hi:[1,0]
	s_nop 0
	s_nop 0
	v_rcp_f32_e32 v155, v155
	s_nop 0
	v_rcp_f32_e32 v154, v154
	s_nop 0
	v_rcp_f32_e32 v157, v157
	s_nop 0
	v_rcp_f32_e32 v156, v156
	v_pk_mul_f32 v[158:159], v[144:145], v[154:155] op_sel_hi:[0,1]
	v_pk_mul_f32 v[154:155], v[144:145], v[156:157] op_sel_hi:[0,1]
	v_mul_f32_e32 v145, 0xbfb8aa3b, v174
	v_pk_add_f32 v[156:157], v[66:67], v[130:131]
	v_exp_f32_e32 v174, v145
	v_mul_f32_e32 v145, 0xbfb8aa3b, v175
	v_exp_f32_e32 v175, v145
	v_mul_f32_e32 v145, 0xbfb8aa3b, v156
	v_exp_f32_e32 v156, v145
	v_mul_f32_e32 v145, 0xbfb8aa3b, v157
	v_exp_f32_e32 v157, v145
	v_pk_add_f32 v[174:175], v[174:175], 1.0 op_sel_hi:[1,0]
	v_cvt_pk_bf16_f32 v154, v154, v155
	v_cvt_pk_bf16_f32 v155, v158, v159
	v_pk_add_f32 v[156:157], v[156:157], 1.0 op_sel_hi:[1,0]
	s_nop 0
	s_nop 0
	v_rcp_f32_e32 v157, v157
	s_nop 0
	v_rcp_f32_e32 v156, v156
	s_nop 0
	v_rcp_f32_e32 v175, v175
	s_nop 0
	v_rcp_f32_e32 v174, v174
	v_pk_mul_f32 v[176:177], v[144:145], v[156:157] op_sel_hi:[0,1]
	v_pk_mul_f32 v[156:157], v[144:145], v[174:175] op_sel_hi:[0,1]
	v_cvt_pk_bf16_f32 v156, v156, v157
	v_cvt_pk_bf16_f32 v157, v176, v177
	global_store_dwordx4 v[152:153], v[154:157], off
	v_pk_add_f32 v[174:175], v[56:57], v[136:137]
	v_add_u32_e32 v152, 0x80, v146
	v_pk_add_f32 v[156:157], v[60:61], v[140:141]
	v_pk_add_f32 v[154:155], v[62:63], v[142:143]
	v_mul_f32_e32 v145, 0xbfb8aa3b, v156
	v_exp_f32_e32 v156, v145
	v_mul_f32_e32 v145, 0xbfb8aa3b, v157
	v_exp_f32_e32 v157, v145
	v_mul_f32_e32 v145, 0xbfb8aa3b, v154
	v_exp_f32_e32 v154, v145
	v_mul_f32_e32 v145, 0xbfb8aa3b, v155
	v_exp_f32_e32 v155, v145
	v_pk_add_f32 v[156:157], v[156:157], 1.0 op_sel_hi:[1,0]
	v_ashrrev_i32_e32 v153, 31, v152
	v_lshl_add_u64 v[152:153], v[152:153], 0, s[78:79]
	v_pk_add_f32 v[154:155], v[154:155], 1.0 op_sel_hi:[1,0]
	v_lshlrev_b64 v[152:153], 11, v[152:153]
	v_lshl_add_u64 v[152:153], s[10:11], 0, v[152:153]
	v_rcp_f32_e32 v155, v155
	s_nop 0
	v_rcp_f32_e32 v154, v154
	s_nop 0
	v_rcp_f32_e32 v157, v157
	s_nop 0
	v_rcp_f32_e32 v156, v156
	v_pk_mul_f32 v[158:159], v[144:145], v[154:155] op_sel_hi:[0,1]
	v_pk_mul_f32 v[154:155], v[144:145], v[156:157] op_sel_hi:[0,1]
	v_mul_f32_e32 v145, 0xbfb8aa3b, v174
; __device__ __forceinline__ u32x4 pack8(f32x4 a, f32x4 b) { u32x4 w; w.x = pk2(a[0], a[1]); w.y = pk2(a[2], a[3]); w.z = pk2(b[0], b[1]); w.w = pk2(b[2], b[3]); return w; }
; __device__ __forceinline__ f32x4 sigm4(f32x4 v) { return (f32x4){sigm(v[0]), sigm(v[1]), sigm(v[2]), sigm(v[3])}; }
; #define FOR_ROWS _Pragma("unroll") for (int ai = 0; ai < 2; ++ai) _Pragma("unroll") for (int m = 0; m < 4; ++m)
; __device__ __forceinline__ float sigm(float x) { return 1.f / (1.f + __expf(-x)); }
; __device__ __forceinline__ void epilogue(const int kind, CParams& p, const f32x4 (&acc)[2][2][4][2], const Unit& u, const int wr, const int wc, const int fr_in, const int fq_in) {
;     ...
;     case E_EA: {
;         const float* bias = u.pn < 4 ? p.in[I_W0] : p.in[I_A0];
;         bf16_t* o = u.pn < 4 ? p.ebuf : p.abuf;
;         const float sc = u.pn < 4 ? 0.60653066f : 1.0f;
;         f32x4 bv[2][2];
; #pragma unroll
;         for (int bj = 0; bj < 2; ++bj) { const int col = (u.pn & 3) * 256 + bj * 128 + cw; bv[bj][0] = *(const f32x4*)(bias + col); bv[bj][1] = *(const f32x4*)(bias + col + 4); }
;         FOR_ROWS { ROWDEF
; #pragma unroll
;             for (int bj = 0; bj < 2; ++bj) {
;                 const int col = (u.pn & 3) * 256 + bj * 128 + cw;
;                 *(u32x4*)(o + row * 1024 + col) = pack8(sigm4(acc[ai][bj][m][0] + bv[bj][0]) * sc, sigm4(acc[ai][bj][m][1] + bv[bj][1]) * sc);
;             } }
	v_pk_add_f32 v[156:157], v[58:59], v[138:139]
	v_exp_f32_e32 v174, v145
	v_mul_f32_e32 v145, 0xbfb8aa3b, v175
	v_exp_f32_e32 v175, v145
	v_mul_f32_e32 v145, 0xbfb8aa3b, v156
	v_exp_f32_e32 v156, v145
	v_mul_f32_e32 v145, 0xbfb8aa3b, v157
	v_exp_f32_e32 v157, v145
	v_pk_add_f32 v[174:175], v[174:175], 1.0 op_sel_hi:[1,0]
	v_cvt_pk_bf16_f32 v154, v154, v155
	v_cvt_pk_bf16_f32 v155, v158, v159
	v_pk_add_f32 v[156:157], v[156:157], 1.0 op_sel_hi:[1,0]
	v_lshl_add_u64 v[158:159], v[152:153], 0, v[148:149]
	v_lshl_add_u64 v[152:153], v[152:153], 0, v[150:151]
	v_rcp_f32_e32 v157, v157
	s_nop 0
	v_rcp_f32_e32 v156, v156
	s_nop 0
	v_rcp_f32_e32 v175, v175
	s_nop 0
	v_rcp_f32_e32 v174, v174
	v_pk_mul_f32 v[176:177], v[144:145], v[156:157] op_sel_hi:[0,1]
	v_pk_mul_f32 v[156:157], v[144:145], v[174:175] op_sel_hi:[0,1]
	v_cvt_pk_bf16_f32 v156, v156, v157
	v_cvt_pk_bf16_f32 v157, v176, v177
	global_store_dwordx4 v[158:159], v[154:157], off
	v_pk_add_f32 v[174:175], v[24:25], v[128:129]
	s_nop 0
	v_pk_add_f32 v[156:157], v[28:29], v[132:133]
	v_pk_add_f32 v[154:155], v[30:31], v[134:135]
	v_mul_f32_e32 v145, 0xbfb8aa3b, v156
	v_exp_f32_e32 v156, v145
	v_mul_f32_e32 v145, 0xbfb8aa3b, v157
	v_exp_f32_e32 v157, v145
	v_mul_f32_e32 v145, 0xbfb8aa3b, v154
	v_exp_f32_e32 v154, v145
	v_mul_f32_e32 v145, 0xbfb8aa3b, v155
	v_exp_f32_e32 v155, v145
	v_pk_add_f32 v[156:157], v[156:157], 1.0 op_sel_hi:[1,0]
	v_pk_add_f32 v[154:155], v[154:155], 1.0 op_sel_hi:[1,0]
	s_nop 0
	s_nop 0
	v_rcp_f32_e32 v155, v155
	s_nop 0
	v_rcp_f32_e32 v154, v154
	s_nop 0
	v_rcp_f32_e32 v157, v157
	s_nop 0
	v_rcp_f32_e32 v156, v156
	v_pk_mul_f32 v[158:159], v[144:145], v[154:155] op_sel_hi:[0,1]
	v_pk_mul_f32 v[154:155], v[144:145], v[156:157] op_sel_hi:[0,1]
	v_mul_f32_e32 v145, 0xbfb8aa3b, v174
	v_pk_add_f32 v[156:157], v[26:27], v[130:131]
	v_exp_f32_e32 v174, v145
	v_mul_f32_e32 v145, 0xbfb8aa3b, v175
	v_exp_f32_e32 v175, v145
	v_mul_f32_e32 v145, 0xbfb8aa3b, v156
	v_exp_f32_e32 v156, v145
	v_mul_f32_e32 v145, 0xbfb8aa3b, v157
	v_exp_f32_e32 v157, v145
	v_pk_add_f32 v[174:175], v[174:175], 1.0 op_sel_hi:[1,0]
	v_cvt_pk_bf16_f32 v154, v154, v155
	v_cvt_pk_bf16_f32 v155, v158, v159
	v_pk_add_f32 v[156:157], v[156:157], 1.0 op_sel_hi:[1,0]
	s_nop 0
	s_nop 0
	v_rcp_f32_e32 v157, v157
	s_nop 0
	v_rcp_f32_e32 v156, v156
	s_nop 0
	v_rcp_f32_e32 v175, v175
	s_nop 0
	v_rcp_f32_e32 v174, v174
	v_pk_mul_f32 v[176:177], v[144:145], v[156:157] op_sel_hi:[0,1]
	v_pk_mul_f32 v[156:157], v[144:145], v[174:175] op_sel_hi:[0,1]
	v_cvt_pk_bf16_f32 v156, v156, v157
	v_cvt_pk_bf16_f32 v157, v176, v177
	global_store_dwordx4 v[152:153], v[154:157], off
	v_pk_add_f32 v[174:175], v[48:49], v[136:137]
	v_add_u32_e32 v152, 0x90, v146
	v_pk_add_f32 v[156:157], v[52:53], v[140:141]
	v_pk_add_f32 v[154:155], v[54:55], v[142:143]
	v_mul_f32_e32 v145, 0xbfb8aa3b, v156
	v_exp_f32_e32 v156, v145
	v_mul_f32_e32 v145, 0xbfb8aa3b, v157
	v_exp_f32_e32 v157, v145
	v_mul_f32_e32 v145, 0xbfb8aa3b, v154
	v_exp_f32_e32 v154, v145
	v_mul_f32_e32 v145, 0xbfb8aa3b, v155
	v_exp_f32_e32 v155, v145
	v_pk_add_f32 v[156:157], v[156:157], 1.0 op_sel_hi:[1,0]
	v_ashrrev_i32_e32 v153, 31, v152
	v_lshl_add_u64 v[152:153], v[152:153], 0, s[78:79]
	v_pk_add_f32 v[154:155], v[154:155], 1.0 op_sel_hi:[1,0]
	v_lshlrev_b64 v[152:153], 11, v[152:153]
	v_lshl_add_u64 v[152:153], s[10:11], 0, v[152:153]
	v_rcp_f32_e32 v155, v155
	s_nop 0
	v_rcp_f32_e32 v154, v154
	s_nop 0
	v_rcp_f32_e32 v157, v157
	s_nop 0
	v_rcp_f32_e32 v156, v156
	v_pk_mul_f32 v[158:159], v[144:145], v[154:155] op_sel_hi:[0,1]
	v_pk_mul_f32 v[154:155], v[144:145], v[156:157] op_sel_hi:[0,1]
	v_mul_f32_e32 v145, 0xbfb8aa3b, v174
	v_pk_add_f32 v[156:157], v[50:51], v[138:139]
	v_exp_f32_e32 v174, v145
	v_mul_f32_e32 v145, 0xbfb8aa3b, v175
	v_exp_f32_e32 v175, v145
	v_mul_f32_e32 v145, 0xbfb8aa3b, v156
	v_exp_f32_e32 v156, v145
	v_mul_f32_e32 v145, 0xbfb8aa3b, v157
	v_exp_f32_e32 v157, v145
	v_pk_add_f32 v[174:175], v[174:175], 1.0 op_sel_hi:[1,0]
	v_cvt_pk_bf16_f32 v154, v154, v155
	v_cvt_pk_bf16_f32 v155, v158, v159
	v_pk_add_f32 v[156:157], v[156:157], 1.0 op_sel_hi:[1,0]
	v_lshl_add_u64 v[158:159], v[152:153], 0, v[148:149]
	v_lshl_add_u64 v[152:153], v[152:153], 0, v[150:151]
	v_rcp_f32_e32 v157, v157
	s_nop 0
	v_rcp_f32_e32 v156, v156
	s_nop 0
	v_rcp_f32_e32 v175, v175
	s_nop 0
	v_rcp_f32_e32 v174, v174
	v_pk_mul_f32 v[176:177], v[144:145], v[156:157] op_sel_hi:[0,1]
	v_pk_mul_f32 v[156:157], v[144:145], v[174:175] op_sel_hi:[0,1]
	v_cvt_pk_bf16_f32 v156, v156, v157
	v_cvt_pk_bf16_f32 v157, v176, v177
	global_store_dwordx4 v[158:159], v[154:157], off
	v_pk_add_f32 v[174:175], v[16:17], v[128:129]
	s_nop 0
	v_pk_add_f32 v[156:157], v[20:21], v[132:133]
	v_pk_add_f32 v[154:155], v[22:23], v[134:135]
	v_mul_f32_e32 v145, 0xbfb8aa3b, v156
	v_exp_f32_e32 v156, v145
	v_mul_f32_e32 v145, 0xbfb8aa3b, v157
	v_exp_f32_e32 v157, v145
	v_mul_f32_e32 v145, 0xbfb8aa3b, v154
	v_exp_f32_e32 v154, v145
	v_mul_f32_e32 v145, 0xbfb8aa3b, v155
	v_exp_f32_e32 v155, v145
	v_pk_add_f32 v[156:157], v[156:157], 1.0 op_sel_hi:[1,0]
	v_pk_add_f32 v[154:155], v[154:155], 1.0 op_sel_hi:[1,0]
	s_nop 0
	s_nop 0
	v_rcp_f32_e32 v155, v155
	s_nop 0
	v_rcp_f32_e32 v154, v154
	s_nop 0
	v_rcp_f32_e32 v157, v157
	s_nop 0
	v_rcp_f32_e32 v156, v156
	v_pk_mul_f32 v[158:159], v[144:145], v[154:155] op_sel_hi:[0,1]
	v_pk_mul_f32 v[154:155], v[144:145], v[156:157] op_sel_hi:[0,1]
	v_mul_f32_e32 v145, 0xbfb8aa3b, v174
	v_pk_add_f32 v[156:157], v[18:19], v[130:131]
	v_exp_f32_e32 v174, v145
	v_mul_f32_e32 v145, 0xbfb8aa3b, v175
	v_exp_f32_e32 v175, v145
	v_mul_f32_e32 v145, 0xbfb8aa3b, v156
	v_exp_f32_e32 v156, v145
; __device__ __forceinline__ u32x4 pack8(f32x4 a, f32x4 b) { u32x4 w; w.x = pk2(a[0], a[1]); w.y = pk2(a[2], a[3]); w.z = pk2(b[0], b[1]); w.w = pk2(b[2], b[3]); return w; }
; __device__ __forceinline__ f32x4 sigm4(f32x4 v) { return (f32x4){sigm(v[0]), sigm(v[1]), sigm(v[2]), sigm(v[3])}; }
; #define FOR_ROWS _Pragma("unroll") for (int ai = 0; ai < 2; ++ai) _Pragma("unroll") for (int m = 0; m < 4; ++m)
; __device__ __forceinline__ float sigm(float x) { return 1.f / (1.f + __expf(-x)); }
; __device__ __forceinline__ void epilogue(const int kind, CParams& p, const f32x4 (&acc)[2][2][4][2], const Unit& u, const int wr, const int wc, const int fr_in, const int fq_in) {
;     ...
;     case E_EA: {
;         const float* bias = u.pn < 4 ? p.in[I_W0] : p.in[I_A0];
;         bf16_t* o = u.pn < 4 ? p.ebuf : p.abuf;
;         const float sc = u.pn < 4 ? 0.60653066f : 1.0f;
;         f32x4 bv[2][2];
; #pragma unroll
;         for (int bj = 0; bj < 2; ++bj) { const int col = (u.pn & 3) * 256 + bj * 128 + cw; bv[bj][0] = *(const f32x4*)(bias + col); bv[bj][1] = *(const f32x4*)(bias + col + 4); }
;         FOR_ROWS { ROWDEF
; #pragma unroll
;             for (int bj = 0; bj < 2; ++bj) {
;                 const int col = (u.pn & 3) * 256 + bj * 128 + cw;
;                 *(u32x4*)(o + row * 1024 + col) = pack8(sigm4(acc[ai][bj][m][0] + bv[bj][0]) * sc, sigm4(acc[ai][bj][m][1] + bv[bj][1]) * sc);
;             } }
	v_mul_f32_e32 v145, 0xbfb8aa3b, v157
	v_exp_f32_e32 v157, v145
	v_pk_add_f32 v[174:175], v[174:175], 1.0 op_sel_hi:[1,0]
	v_cvt_pk_bf16_f32 v154, v154, v155
	v_cvt_pk_bf16_f32 v155, v158, v159
	v_pk_add_f32 v[156:157], v[156:157], 1.0 op_sel_hi:[1,0]
	s_nop 0
	s_nop 0
	v_rcp_f32_e32 v157, v157
	s_nop 0
	v_rcp_f32_e32 v156, v156
	s_nop 0
	v_rcp_f32_e32 v175, v175
	s_nop 0
	v_rcp_f32_e32 v174, v174
	v_pk_mul_f32 v[176:177], v[144:145], v[156:157] op_sel_hi:[0,1]
	v_pk_mul_f32 v[156:157], v[144:145], v[174:175] op_sel_hi:[0,1]
	v_cvt_pk_bf16_f32 v156, v156, v157
	v_cvt_pk_bf16_f32 v157, v176, v177
	global_store_dwordx4 v[152:153], v[154:157], off
	v_pk_add_f32 v[174:175], v[40:41], v[136:137]
	v_add_u32_e32 v152, 0xa0, v146
	v_pk_add_f32 v[156:157], v[44:45], v[140:141]
	v_pk_add_f32 v[154:155], v[46:47], v[142:143]
	v_mul_f32_e32 v145, 0xbfb8aa3b, v156
	v_exp_f32_e32 v156, v145
	v_mul_f32_e32 v145, 0xbfb8aa3b, v157
	v_exp_f32_e32 v157, v145
	v_mul_f32_e32 v145, 0xbfb8aa3b, v154
	v_exp_f32_e32 v154, v145
	v_mul_f32_e32 v145, 0xbfb8aa3b, v155
	v_exp_f32_e32 v155, v145
	v_pk_add_f32 v[156:157], v[156:157], 1.0 op_sel_hi:[1,0]
	v_ashrrev_i32_e32 v153, 31, v152
	v_lshl_add_u64 v[152:153], v[152:153], 0, s[78:79]
	v_pk_add_f32 v[154:155], v[154:155], 1.0 op_sel_hi:[1,0]
	v_lshlrev_b64 v[152:153], 11, v[152:153]
	v_lshl_add_u64 v[152:153], s[10:11], 0, v[152:153]
	v_pk_add_f32 v[142:143], v[38:39], v[142:143]
	v_add_u32_e32 v146, 0xb0, v146
	v_rcp_f32_e32 v155, v155
	v_mul_f32_e32 v142, 0xbfb8aa3b, v142
	v_mul_f32_e32 v143, 0xbfb8aa3b, v143
	v_exp_f32_e32 v142, v142
	v_rcp_f32_e32 v154, v154
	v_exp_f32_e32 v143, v143
	v_pk_add_f32 v[140:141], v[36:37], v[140:141]
	v_pk_add_f32 v[136:137], v[32:33], v[136:137]
	v_rcp_f32_e32 v157, v157
	v_pk_add_f32 v[142:143], v[142:143], 1.0 op_sel_hi:[1,0]
	v_mul_f32_e32 v140, 0xbfb8aa3b, v140
	v_mul_f32_e32 v141, 0xbfb8aa3b, v141
	v_rcp_f32_e32 v156, v156
	v_pk_mul_f32 v[158:159], v[144:145], v[154:155] op_sel_hi:[0,1]
	v_pk_mul_f32 v[154:155], v[144:145], v[156:157] op_sel_hi:[0,1]
	v_mul_f32_e32 v145, 0xbfb8aa3b, v174
	v_pk_add_f32 v[156:157], v[42:43], v[138:139]
	v_exp_f32_e32 v174, v145
	v_mul_f32_e32 v145, 0xbfb8aa3b, v175
	v_exp_f32_e32 v175, v145
	v_mul_f32_e32 v145, 0xbfb8aa3b, v156
	v_exp_f32_e32 v156, v145
	v_mul_f32_e32 v145, 0xbfb8aa3b, v157
	v_exp_f32_e32 v157, v145
	v_pk_add_f32 v[174:175], v[174:175], 1.0 op_sel_hi:[1,0]
	v_cvt_pk_bf16_f32 v154, v154, v155
	v_cvt_pk_bf16_f32 v155, v158, v159
	v_pk_add_f32 v[156:157], v[156:157], 1.0 op_sel_hi:[1,0]
	v_lshl_add_u64 v[158:159], v[152:153], 0, v[148:149]
	v_lshl_add_u64 v[152:153], v[152:153], 0, v[150:151]
	v_exp_f32_e32 v140, v140
	v_exp_f32_e32 v141, v141
	v_rcp_f32_e32 v157, v157
	v_pk_add_f32 v[140:141], v[140:141], 1.0 op_sel_hi:[1,0]
	v_pk_add_f32 v[138:139], v[34:35], v[138:139]
	v_mul_f32_e32 v136, 0xbfb8aa3b, v136
	v_rcp_f32_e32 v156, v156
	v_mul_f32_e32 v138, 0xbfb8aa3b, v138
	v_mul_f32_e32 v139, 0xbfb8aa3b, v139
	v_exp_f32_e32 v138, v138
	v_rcp_f32_e32 v175, v175
	v_exp_f32_e32 v139, v139
	v_mul_f32_e32 v137, 0xbfb8aa3b, v137
	v_exp_f32_e32 v136, v136
	v_rcp_f32_e32 v174, v174
	v_pk_mul_f32 v[176:177], v[144:145], v[156:157] op_sel_hi:[0,1]
	v_pk_mul_f32 v[156:157], v[144:145], v[174:175] op_sel_hi:[0,1]
	v_cvt_pk_bf16_f32 v156, v156, v157
	v_cvt_pk_bf16_f32 v157, v176, v177
	global_store_dwordx4 v[158:159], v[154:157], off
	v_pk_add_f32 v[174:175], v[8:9], v[128:129]
	v_pk_add_f32 v[138:139], v[138:139], 1.0 op_sel_hi:[1,0]
	v_pk_add_f32 v[156:157], v[12:13], v[132:133]
	v_pk_add_f32 v[154:155], v[14:15], v[134:135]
	v_mul_f32_e32 v145, 0xbfb8aa3b, v156
	v_exp_f32_e32 v156, v145
	v_mul_f32_e32 v145, 0xbfb8aa3b, v157
	v_exp_f32_e32 v157, v145
	v_mul_f32_e32 v145, 0xbfb8aa3b, v154
	v_exp_f32_e32 v154, v145
	v_mul_f32_e32 v145, 0xbfb8aa3b, v155
	v_exp_f32_e32 v155, v145
	v_pk_add_f32 v[156:157], v[156:157], 1.0 op_sel_hi:[1,0]
; __device__ __forceinline__ u32x4 pack8(f32x4 a, f32x4 b) { u32x4 w; w.x = pk2(a[0], a[1]); w.y = pk2(a[2], a[3]); w.z = pk2(b[0], b[1]); w.w = pk2(b[2], b[3]); return w; }
; __device__ __forceinline__ f32x4 sigm4(f32x4 v) { return (f32x4){sigm(v[0]), sigm(v[1]), sigm(v[2]), sigm(v[3])}; }
; #define FOR_ROWS _Pragma("unroll") for (int ai = 0; ai < 2; ++ai) _Pragma("unroll") for (int m = 0; m < 4; ++m)
; __device__ __forceinline__ float sigm(float x) { return 1.f / (1.f + __expf(-x)); }
; __device__ __forceinline__ void epilogue(const int kind, CParams& p, const f32x4 (&acc)[2][2][4][2], const Unit& u, const int wr, const int wc, const int fr_in, const int fq_in) {
;     ...
;     case E_EA: {
;         const float* bias = u.pn < 4 ? p.in[I_W0] : p.in[I_A0];
;         bf16_t* o = u.pn < 4 ? p.ebuf : p.abuf;
;         const float sc = u.pn < 4 ? 0.60653066f : 1.0f;
;         f32x4 bv[2][2];
; #pragma unroll
;         for (int bj = 0; bj < 2; ++bj) { const int col = (u.pn & 3) * 256 + bj * 128 + cw; bv[bj][0] = *(const f32x4*)(bias + col); bv[bj][1] = *(const f32x4*)(bias + col + 4); }
;         FOR_ROWS { ROWDEF
; #pragma unroll
;             for (int bj = 0; bj < 2; ++bj) {
;                 const int col = (u.pn & 3) * 256 + bj * 128 + cw;
;                 *(u32x4*)(o + row * 1024 + col) = pack8(sigm4(acc[ai][bj][m][0] + bv[bj][0]) * sc, sigm4(acc[ai][bj][m][1] + bv[bj][1]) * sc);
;             } }
	v_exp_f32_e32 v137, v137
	v_pk_add_f32 v[134:135], v[6:7], v[134:135]
	v_pk_add_f32 v[154:155], v[154:155], 1.0 op_sel_hi:[1,0]
	v_mul_f32_e32 v134, 0xbfb8aa3b, v134
	v_pk_add_f32 v[136:137], v[136:137], 1.0 op_sel_hi:[1,0]
	v_mul_f32_e32 v135, 0xbfb8aa3b, v135
	v_exp_f32_e32 v134, v134
	v_rcp_f32_e32 v155, v155
	v_exp_f32_e32 v135, v135
	v_pk_add_f32 v[132:133], v[4:5], v[132:133]
	v_pk_add_f32 v[128:129], v[0:1], v[128:129]
	v_rcp_f32_e32 v154, v154
	v_pk_add_f32 v[134:135], v[134:135], 1.0 op_sel_hi:[1,0]
	v_mul_f32_e32 v132, 0xbfb8aa3b, v132
	v_mul_f32_e32 v133, 0xbfb8aa3b, v133
	v_rcp_f32_e32 v157, v157
	v_exp_f32_e32 v132, v132
	v_exp_f32_e32 v133, v133
	v_mul_f32_e32 v128, 0xbfb8aa3b, v128
	v_rcp_f32_e32 v156, v156
	v_pk_mul_f32 v[158:159], v[144:145], v[154:155] op_sel_hi:[0,1]
	v_pk_mul_f32 v[154:155], v[144:145], v[156:157] op_sel_hi:[0,1]
	v_mul_f32_e32 v145, 0xbfb8aa3b, v174
	v_pk_add_f32 v[156:157], v[10:11], v[130:131]
	v_exp_f32_e32 v174, v145
	v_mul_f32_e32 v145, 0xbfb8aa3b, v175
	v_exp_f32_e32 v175, v145
	v_mul_f32_e32 v145, 0xbfb8aa3b, v156
	v_exp_f32_e32 v156, v145
	v_mul_f32_e32 v145, 0xbfb8aa3b, v157
	v_exp_f32_e32 v157, v145
	v_pk_add_f32 v[174:175], v[174:175], 1.0 op_sel_hi:[1,0]
	v_cvt_pk_bf16_f32 v154, v154, v155
	v_cvt_pk_bf16_f32 v155, v158, v159
	v_pk_add_f32 v[156:157], v[156:157], 1.0 op_sel_hi:[1,0]
	v_pk_add_f32 v[132:133], v[132:133], 1.0 op_sel_hi:[1,0]
	v_pk_add_f32 v[130:131], v[2:3], v[130:131]
	v_mul_f32_e32 v129, 0xbfb8aa3b, v129
	v_mul_f32_e32 v130, 0xbfb8aa3b, v130
	v_rcp_f32_e32 v157, v157
	v_mul_f32_e32 v131, 0xbfb8aa3b, v131
	v_exp_f32_e32 v130, v130
	v_exp_f32_e32 v131, v131
	v_rcp_f32_e32 v156, v156
	v_pk_add_f32 v[130:131], v[130:131], 1.0 op_sel_hi:[1,0]
	v_exp_f32_e32 v128, v128
	v_exp_f32_e32 v129, v129
	v_rcp_f32_e32 v175, v175
	v_pk_add_f32 v[128:129], v[128:129], 1.0 op_sel_hi:[1,0]
	v_ashrrev_i32_e32 v147, 31, v146
	v_lshl_add_u64 v[146:147], v[146:147], 0, s[78:79]
	v_rcp_f32_e32 v174, v174
	v_lshlrev_b64 v[146:147], 11, v[146:147]
	v_pk_mul_f32 v[176:177], v[144:145], v[156:157] op_sel_hi:[0,1]
	v_pk_mul_f32 v[156:157], v[144:145], v[174:175] op_sel_hi:[0,1]
	v_lshl_add_u64 v[146:147], s[10:11], 0, v[146:147]
	v_cvt_pk_bf16_f32 v156, v156, v157
	v_cvt_pk_bf16_f32 v157, v176, v177
	global_store_dwordx4 v[152:153], v[154:157], off
	s_nop 0
	v_rcp_f32_e32 v143, v143
	s_nop 0
	v_rcp_f32_e32 v142, v142
	s_nop 0
	v_rcp_f32_e32 v141, v141
	s_nop 0
	v_rcp_f32_e32 v140, v140
	v_pk_mul_f32 v[142:143], v[144:145], v[142:143] op_sel_hi:[0,1]
	v_pk_mul_f32 v[140:141], v[144:145], v[140:141] op_sel_hi:[0,1]
	s_nop 0
	v_rcp_f32_e32 v139, v139
	s_nop 0
	v_rcp_f32_e32 v138, v138
	s_nop 0
	v_rcp_f32_e32 v137, v137
	s_nop 0
	v_rcp_f32_e32 v136, v136
	v_pk_mul_f32 v[152:153], v[144:145], v[138:139] op_sel_hi:[0,1]
	v_pk_mul_f32 v[138:139], v[144:145], v[136:137] op_sel_hi:[0,1]
	v_cvt_pk_bf16_f32 v136, v140, v141
	v_lshl_add_u64 v[140:141], v[146:147], 0, v[148:149]
	v_cvt_pk_bf16_f32 v137, v142, v143
	v_cvt_pk_bf16_f32 v138, v138, v139
	v_cvt_pk_bf16_f32 v139, v152, v153
	global_store_dwordx4 v[140:141], v[136:139], off
	s_nop 1
	s_nop 0
	v_rcp_f32_e32 v135, v135
	s_nop 0
	v_rcp_f32_e32 v134, v134
	s_nop 0
	v_pk_mul_f32 v[134:135], v[144:145], v[134:135] op_sel_hi:[0,1]
	v_rcp_f32_e32 v133, v133
	s_nop 0
	v_rcp_f32_e32 v132, v132
	s_nop 0
	v_pk_mul_f32 v[132:133], v[144:145], v[132:133] op_sel_hi:[0,1]
	v_rcp_f32_e32 v131, v131
	s_nop 0
	v_rcp_f32_e32 v130, v130
	s_nop 0
	v_rcp_f32_e32 v129, v129
	s_nop 0
	v_rcp_f32_e32 v128, v128
	v_pk_mul_f32 v[136:137], v[144:145], v[130:131] op_sel_hi:[0,1]
	v_pk_mul_f32 v[130:131], v[144:145], v[128:129] op_sel_hi:[0,1]
	v_cvt_pk_bf16_f32 v128, v132, v133
	v_lshl_add_u64 v[132:133], v[146:147], 0, v[150:151]
	v_cvt_pk_bf16_f32 v129, v134, v135
	v_cvt_pk_bf16_f32 v130, v130, v131
	v_cvt_pk_bf16_f32 v131, v136, v137
	global_store_dwordx4 v[132:133], v[128:131], off

; __device__ __forceinline__ u32x4 pack8(f32x4 a, f32x4 b) { u32x4 w; w.x = pk2(a[0], a[1]); w.y = pk2(a[2], a[3]); w.z = pk2(b[0], b[1]); w.w = pk2(b[2], b[3]); return w; }
; #define NTS(T, ptr, val) __builtin_nontemporal_store((val), (T*)(ptr))
; __device__ __forceinline__ f32x4 sigm4(f32x4 v) { return (f32x4){sigm(v[0]), sigm(v[1]), sigm(v[2]), sigm(v[3])}; }
; #define FOR_ROWS _Pragma("unroll") for (int ai = 0; ai < 2; ++ai) _Pragma("unroll") for (int m = 0; m < 4; ++m)
; __device__ __forceinline__ float sigm(float x) { return 1.f / (1.f + __expf(-x)); }
; __device__ __forceinline__ void epilogue(const int kind, CParams& p, const f32x4 (&acc)[2][2][4][2], const Unit& u, const int wr, const int wc, const int fr_in, const int fq_in) {
;     ...
;     case E_G1: {
;         if (u.pn < 4) {
;             FOR_ROWS { ROWDEF
;                 const f32x4 a0 = acc[ai][0][m][0], a1 = acc[ai][0][m][1], b0 = sigm4(acc[ai][1][m][0]), b1 = sigm4(acc[ai][1][m][1]);
;                 *(u32x4*)(p.u + row * DCV + u.pn * 128 + cw) = pack8(a0 * b0, a1 * b1); }
;         } else if (u.pn < 17) {
;             FOR_ROWS { ROWDEF
; #pragma unroll
;                 for (int bj = 0; bj < 2; ++bj) NTS(u32x4, p.pr + row * DSH + (u.pn - 4) * 256 + bj * 128 + cw, pack8(acc[ai][bj][m][0], acc[ai][bj][m][1])); }
;         } else {
;             FOR_ROWS { ROWDEF
; #pragma unroll
;                 for (int bj = 0; bj < 2; ++bj) NTS(u32x4, p.gates + row * 2048 + (u.pn - 17) * 256 + bj * 128 + cw, pack8(sigm4(acc[ai][bj][m][0]), sigm4(acc[ai][bj][m][1]))); }
.LBB0_901:
	s_andn2_b64 vcc, exec, s[10:11]
	s_cbranch_vccnz .LBB0_911
	s_cmp_eq_u32 s3, 0
	s_cbranch_scc0 .LBB0_911
	v_add_u32_e32 v128, s0, v215
	s_mov_b64 s[10:11], -1
	s_cmp_gt_i32 s92, 3
	v_ashrrev_i32_e32 v173, 31, v172
	s_waitcnt vmcnt(0) lgkmcnt(0)
	v_ashrrev_i32_e32 v129, 31, v128
	v_add_u32_e32 v130, 16, v128
	s_cbranch_scc0 .LBB0_909
	s_ashr_i32 s79, s78, 31
	s_cmp_lt_u32 s92, 17
	v_lshl_add_u64 v[134:135], v[128:129], 0, s[78:79]
	v_lshlrev_b64 v[132:133], 1, v[172:173]
	v_ashrrev_i32_e32 v131, 31, v130
	s_cbranch_scc1 .LBB0_906
	v_mul_f32_e32 v138, 0xbfb8aa3b, v124
	v_exp_f32_e32 v138, v138
	v_readlane_b32 s14, v244, 34
	s_lshl_b32 s1, s92, 8
	v_lshlrev_b64 v[136:137], 12, v[134:135]
	v_add_f32_e32 v138, 1.0, v138
	v_readlane_b32 s15, v244, 35
	v_rcp_f32_e32 v138, v138
	v_mul_f32_e32 v139, 0xbfb8aa3b, v125
	v_exp_f32_e32 v139, v139
	v_lshl_add_u64 v[136:137], s[14:15], 0, v[136:137]
	v_add_f32_e32 v139, 1.0, v139
	s_nop 0
	v_rcp_f32_e32 v139, v139
	v_mul_f32_e32 v140, 0xbfb8aa3b, v126
	v_exp_f32_e32 v140, v140
	v_cvt_pk_bf16_f32 v138, v138, v139
	s_nop 0
	v_add_f32_e32 v140, 1.0, v140
	s_nop 0
	v_rcp_f32_e32 v140, v140
	v_mul_f32_e32 v141, 0xbfb8aa3b, v127
	v_exp_f32_e32 v141, v141
	s_nop 0
	v_add_f32_e32 v141, 1.0, v141
	s_nop 0
	v_rcp_f32_e32 v141, v141
	v_mul_f32_e32 v142, 0xbfb8aa3b, v120
	v_exp_f32_e32 v142, v142
	v_cvt_pk_bf16_f32 v139, v140, v141
	s_nop 0
	v_add_f32_e32 v142, 1.0, v142
	s_nop 0
	v_rcp_f32_e32 v142, v142
	v_mul_f32_e32 v143, 0xbfb8aa3b, v121
	v_exp_f32_e32 v143, v143
	s_nop 0
	v_add_f32_e32 v143, 1.0, v143
	s_nop 0
	v_rcp_f32_e32 v143, v143
	v_mul_f32_e32 v144, 0xbfb8aa3b, v122
	v_exp_f32_e32 v144, v144
	v_cvt_pk_bf16_f32 v140, v142, v143
	s_nop 0
	v_add_f32_e32 v144, 1.0, v144
	s_nop 0
	v_rcp_f32_e32 v144, v144
	v_mul_f32_e32 v145, 0xbfb8aa3b, v123
	v_exp_f32_e32 v145, v145
	s_nop 0
	v_add_f32_e32 v145, 1.0, v145
	v_readlane_b32 s10, v244, 41
	v_readlane_b32 s11, v244, 42
	s_add_i32 s10, s1, 0xffffef00
	s_mov_b32 s1, s11
	s_lshl_b64 s[10:11], s[10:11], 1
	v_lshl_add_u64 v[136:137], v[136:137], 0, s[10:11]
	v_lshl_add_u64 v[136:137], v[136:137], 0, v[132:133]
	v_rcp_f32_e32 v145, v145
	s_nop 0
	v_cvt_pk_bf16_f32 v141, v144, v145
	global_store_dwordx4 v[136:137], v[138:141], off nt
	v_writelane_b32 v244, s0, 41
	s_nop 0
	v_mul_f32_e32 v138, 0xbfb8aa3b, v92
	v_exp_f32_e32 v138, v138
	v_writelane_b32 v244, s1, 42
	v_add_f32_e32 v138, 1.0, v138
	s_nop 0
	v_rcp_f32_e32 v138, v138
	v_mul_f32_e32 v139, 0xbfb8aa3b, v93
	v_exp_f32_e32 v139, v139
	s_nop 0
	v_add_f32_e32 v139, 1.0, v139
	s_nop 0
	v_rcp_f32_e32 v139, v139
	v_mul_f32_e32 v140, 0xbfb8aa3b, v94
	v_exp_f32_e32 v140, v140
	v_cvt_pk_bf16_f32 v138, v138, v139
	s_nop 0
	v_add_f32_e32 v140, 1.0, v140
	s_nop 0
	v_rcp_f32_e32 v140, v140
	v_mul_f32_e32 v141, 0xbfb8aa3b, v95
	v_exp_f32_e32 v141, v141
	s_nop 0
	v_add_f32_e32 v141, 1.0, v141
	s_nop 0
	v_rcp_f32_e32 v141, v141
	v_mul_f32_e32 v142, 0xbfb8aa3b, v88
	v_exp_f32_e32 v142, v142
	v_cvt_pk_bf16_f32 v139, v140, v141
	s_nop 0
	v_add_f32_e32 v142, 1.0, v142
	s_nop 0
	v_rcp_f32_e32 v142, v142
	v_mul_f32_e32 v143, 0xbfb8aa3b, v89
	v_exp_f32_e32 v143, v143
	s_nop 0
	v_add_f32_e32 v143, 1.0, v143
	s_nop 0
	v_rcp_f32_e32 v143, v143
	v_mul_f32_e32 v144, 0xbfb8aa3b, v90
	v_exp_f32_e32 v144, v144
	v_cvt_pk_bf16_f32 v140, v142, v143
	s_nop 0
	v_add_f32_e32 v144, 1.0, v144
	s_nop 0
	v_rcp_f32_e32 v144, v144
	v_mul_f32_e32 v145, 0xbfb8aa3b, v91
	v_exp_f32_e32 v145, v145
	s_nop 0
	v_add_f32_e32 v145, 1.0, v145
	s_nop 0
	v_rcp_f32_e32 v145, v145
	s_nop 0
	v_cvt_pk_bf16_f32 v141, v144, v145
	global_store_dwordx4 v[136:137], v[138:141], off offset:256 nt
	v_lshl_add_u64 v[136:137], v[130:131], 0, s[78:79]
	v_lshlrev_b64 v[136:137], 12, v[136:137]
	v_mul_f32_e32 v138, 0xbfb8aa3b, v116
	v_exp_f32_e32 v138, v138
	v_lshl_add_u64 v[136:137], s[14:15], 0, v[136:137]
	v_lshl_add_u64 v[136:137], v[136:137], 0, s[10:11]
	v_lshl_add_u64 v[136:137], v[136:137], 0, v[132:133]
	v_add_f32_e32 v138, 1.0, v138
	s_nop 0
	v_rcp_f32_e32 v138, v138
	v_mul_f32_e32 v139, 0xbfb8aa3b, v117
	v_exp_f32_e32 v139, v139
	s_nop 0
	v_add_f32_e32 v139, 1.0, v139
	s_nop 0
	v_rcp_f32_e32 v139, v139
	v_mul_f32_e32 v140, 0xbfb8aa3b, v118
	v_exp_f32_e32 v140, v140
	v_cvt_pk_bf16_f32 v138, v138, v139
	s_nop 0
	v_add_f32_e32 v140, 1.0, v140
	s_nop 0
	v_rcp_f32_e32 v140, v140
	v_mul_f32_e32 v141, 0xbfb8aa3b, v119
	v_exp_f32_e32 v141, v141
	s_nop 0
	v_add_f32_e32 v141, 1.0, v141
	s_nop 0
	v_rcp_f32_e32 v141, v141
	v_mul_f32_e32 v142, 0xbfb8aa3b, v112
	v_exp_f32_e32 v142, v142
	v_cvt_pk_bf16_f32 v139, v140, v141
	s_nop 0
	v_add_f32_e32 v142, 1.0, v142
	s_nop 0
	v_rcp_f32_e32 v142, v142
	v_mul_f32_e32 v143, 0xbfb8aa3b, v113
	v_exp_f32_e32 v143, v143
	s_nop 0
	v_add_f32_e32 v143, 1.0, v143
	s_nop 0
	v_rcp_f32_e32 v143, v143
	v_mul_f32_e32 v144, 0xbfb8aa3b, v114
	v_exp_f32_e32 v144, v144
	v_cvt_pk_bf16_f32 v140, v142, v143
	s_nop 0
	v_add_f32_e32 v144, 1.0, v144
	s_nop 0
	v_rcp_f32_e32 v144, v144
	v_mul_f32_e32 v145, 0xbfb8aa3b, v115
	v_exp_f32_e32 v145, v145
	s_nop 0
	v_add_f32_e32 v145, 1.0, v145
	s_nop 0
	v_rcp_f32_e32 v145, v145
	s_nop 0
	v_cvt_pk_bf16_f32 v141, v144, v145
	global_store_dwordx4 v[136:137], v[138:141], off nt
	s_nop 1
	v_mul_f32_e32 v138, 0xbfb8aa3b, v84
	v_exp_f32_e32 v138, v138
	s_nop 0
	v_add_f32_e32 v138, 1.0, v138
	s_nop 0
	v_rcp_f32_e32 v138, v138
	v_mul_f32_e32 v139, 0xbfb8aa3b, v85
	v_exp_f32_e32 v139, v139
	s_nop 0
	v_add_f32_e32 v139, 1.0, v139
	s_nop 0
	v_rcp_f32_e32 v139, v139
	v_mul_f32_e32 v140, 0xbfb8aa3b, v86
	v_exp_f32_e32 v140, v140
	v_cvt_pk_bf16_f32 v138, v138, v139
	s_nop 0
	v_add_f32_e32 v140, 1.0, v140
	s_nop 0
; __device__ __forceinline__ u32x4 pack8(f32x4 a, f32x4 b) { u32x4 w; w.x = pk2(a[0], a[1]); w.y = pk2(a[2], a[3]); w.z = pk2(b[0], b[1]); w.w = pk2(b[2], b[3]); return w; }
; #define NTS(T, ptr, val) __builtin_nontemporal_store((val), (T*)(ptr))
; __device__ __forceinline__ f32x4 sigm4(f32x4 v) { return (f32x4){sigm(v[0]), sigm(v[1]), sigm(v[2]), sigm(v[3])}; }
; #define FOR_ROWS _Pragma("unroll") for (int ai = 0; ai < 2; ++ai) _Pragma("unroll") for (int m = 0; m < 4; ++m)
; __device__ __forceinline__ float sigm(float x) { return 1.f / (1.f + __expf(-x)); }
; __device__ __forceinline__ void epilogue(const int kind, CParams& p, const f32x4 (&acc)[2][2][4][2], const Unit& u, const int wr, const int wc, const int fr_in, const int fq_in) {
;     ...
;             FOR_ROWS { ROWDEF
; #pragma unroll
;                 for (int bj = 0; bj < 2; ++bj) NTS(u32x4, p.gates + row * 2048 + (u.pn - 17) * 256 + bj * 128 + cw, pack8(sigm4(acc[ai][bj][m][0]), sigm4(acc[ai][bj][m][1]))); }
	v_rcp_f32_e32 v140, v140
	v_mul_f32_e32 v141, 0xbfb8aa3b, v87
	v_exp_f32_e32 v141, v141
	s_nop 0
	v_add_f32_e32 v141, 1.0, v141
	s_nop 0
	v_rcp_f32_e32 v141, v141
	v_mul_f32_e32 v142, 0xbfb8aa3b, v80
	v_exp_f32_e32 v142, v142
	v_cvt_pk_bf16_f32 v139, v140, v141
	s_nop 0
	v_add_f32_e32 v142, 1.0, v142
	s_nop 0
	v_rcp_f32_e32 v142, v142
	v_mul_f32_e32 v143, 0xbfb8aa3b, v81
	v_exp_f32_e32 v143, v143
	s_nop 0
	v_add_f32_e32 v143, 1.0, v143
	s_nop 0
	v_rcp_f32_e32 v143, v143
	v_mul_f32_e32 v144, 0xbfb8aa3b, v82
	v_exp_f32_e32 v144, v144
	v_cvt_pk_bf16_f32 v140, v142, v143
	s_nop 0
	v_add_f32_e32 v144, 1.0, v144
	s_nop 0
	v_rcp_f32_e32 v144, v144
	v_mul_f32_e32 v145, 0xbfb8aa3b, v83
	v_exp_f32_e32 v145, v145
	s_nop 0
	v_add_f32_e32 v145, 1.0, v145
	s_nop 0
	v_rcp_f32_e32 v145, v145
	s_nop 0
	v_cvt_pk_bf16_f32 v141, v144, v145
	global_store_dwordx4 v[136:137], v[138:141], off offset:256 nt
	v_add_u32_e32 v136, 32, v128
	v_ashrrev_i32_e32 v137, 31, v136
	v_mul_f32_e32 v138, 0xbfb8aa3b, v108
	v_exp_f32_e32 v138, v138
	v_lshl_add_u64 v[136:137], v[136:137], 0, s[78:79]
	v_lshlrev_b64 v[136:137], 12, v[136:137]
	v_lshl_add_u64 v[136:137], s[14:15], 0, v[136:137]
	v_add_f32_e32 v138, 1.0, v138
	v_lshl_add_u64 v[136:137], v[136:137], 0, s[10:11]
	v_lshl_add_u64 v[136:137], v[136:137], 0, v[132:133]
	v_rcp_f32_e32 v138, v138
	v_mul_f32_e32 v139, 0xbfb8aa3b, v109
	v_exp_f32_e32 v139, v139
	s_nop 0
	v_add_f32_e32 v139, 1.0, v139
	s_nop 0
	v_rcp_f32_e32 v139, v139
	v_mul_f32_e32 v140, 0xbfb8aa3b, v110
	v_exp_f32_e32 v140, v140
	v_cvt_pk_bf16_f32 v138, v138, v139
	s_nop 0
	v_add_f32_e32 v140, 1.0, v140
	s_nop 0
	v_rcp_f32_e32 v140, v140
	v_mul_f32_e32 v141, 0xbfb8aa3b, v111
	v_exp_f32_e32 v141, v141
	s_nop 0
	v_add_f32_e32 v141, 1.0, v141
	s_nop 0
	v_rcp_f32_e32 v141, v141
	v_mul_f32_e32 v142, 0xbfb8aa3b, v104
	v_exp_f32_e32 v142, v142
	v_cvt_pk_bf16_f32 v139, v140, v141
	s_nop 0
	v_add_f32_e32 v142, 1.0, v142
	s_nop 0
	v_rcp_f32_e32 v142, v142
	v_mul_f32_e32 v143, 0xbfb8aa3b, v105
	v_exp_f32_e32 v143, v143
	s_nop 0
	v_add_f32_e32 v143, 1.0, v143
	s_nop 0
	v_rcp_f32_e32 v143, v143
	v_mul_f32_e32 v144, 0xbfb8aa3b, v106
	v_exp_f32_e32 v144, v144
	v_cvt_pk_bf16_f32 v140, v142, v143
	s_nop 0
	v_add_f32_e32 v144, 1.0, v144
	s_nop 0
	v_rcp_f32_e32 v144, v144
	v_mul_f32_e32 v145, 0xbfb8aa3b, v107
	v_exp_f32_e32 v145, v145
	s_nop 0
	v_add_f32_e32 v145, 1.0, v145
	s_nop 0
	v_rcp_f32_e32 v145, v145
	s_nop 0
	v_cvt_pk_bf16_f32 v141, v144, v145
	global_store_dwordx4 v[136:137], v[138:141], off nt
	s_nop 1
	v_mul_f32_e32 v138, 0xbfb8aa3b, v76
	v_exp_f32_e32 v138, v138
	s_nop 0
	v_add_f32_e32 v138, 1.0, v138
	s_nop 0
	v_rcp_f32_e32 v138, v138
	v_mul_f32_e32 v139, 0xbfb8aa3b, v77
	v_exp_f32_e32 v139, v139
	s_nop 0
	v_add_f32_e32 v139, 1.0, v139
	s_nop 0
	v_rcp_f32_e32 v139, v139
	v_mul_f32_e32 v140, 0xbfb8aa3b, v78
	v_exp_f32_e32 v140, v140
	v_cvt_pk_bf16_f32 v138, v138, v139
	s_nop 0
	v_add_f32_e32 v140, 1.0, v140
	s_nop 0
	v_rcp_f32_e32 v140, v140
	v_mul_f32_e32 v141, 0xbfb8aa3b, v79
	v_exp_f32_e32 v141, v141
	s_nop 0
	v_add_f32_e32 v141, 1.0, v141
	s_nop 0
	v_rcp_f32_e32 v141, v141
	v_mul_f32_e32 v142, 0xbfb8aa3b, v72
	v_exp_f32_e32 v142, v142
	v_cvt_pk_bf16_f32 v139, v140, v141
	s_nop 0
	v_add_f32_e32 v142, 1.0, v142
	s_nop 0
	v_rcp_f32_e32 v142, v142
	v_mul_f32_e32 v143, 0xbfb8aa3b, v73
	v_exp_f32_e32 v143, v143
	s_nop 0
	v_add_f32_e32 v143, 1.0, v143
	s_nop 0
	v_rcp_f32_e32 v143, v143
	v_mul_f32_e32 v144, 0xbfb8aa3b, v74
	v_exp_f32_e32 v144, v144
	v_cvt_pk_bf16_f32 v140, v142, v143
	s_nop 0
	v_add_f32_e32 v144, 1.0, v144
	s_nop 0
	v_rcp_f32_e32 v144, v144
	v_mul_f32_e32 v145, 0xbfb8aa3b, v75
	v_exp_f32_e32 v145, v145
	s_nop 0
	v_add_f32_e32 v145, 1.0, v145
	s_nop 0
	v_rcp_f32_e32 v145, v145
	s_nop 0
	v_cvt_pk_bf16_f32 v141, v144, v145
	global_store_dwordx4 v[136:137], v[138:141], off offset:256 nt
	v_add_u32_e32 v136, 48, v128
	v_ashrrev_i32_e32 v137, 31, v136
	v_mul_f32_e32 v138, 0xbfb8aa3b, v100
	v_exp_f32_e32 v138, v138
	v_lshl_add_u64 v[136:137], v[136:137], 0, s[78:79]
	v_lshlrev_b64 v[136:137], 12, v[136:137]
	v_lshl_add_u64 v[136:137], s[14:15], 0, v[136:137]
	v_add_f32_e32 v138, 1.0, v138
	v_lshl_add_u64 v[136:137], v[136:137], 0, s[10:11]
	v_lshl_add_u64 v[136:137], v[136:137], 0, v[132:133]
	v_rcp_f32_e32 v138, v138
	v_mul_f32_e32 v139, 0xbfb8aa3b, v101
	v_exp_f32_e32 v139, v139
	s_nop 0
	v_add_f32_e32 v139, 1.0, v139
	s_nop 0
	v_rcp_f32_e32 v139, v139
	v_mul_f32_e32 v140, 0xbfb8aa3b, v102
	v_exp_f32_e32 v140, v140
	v_cvt_pk_bf16_f32 v138, v138, v139
	s_nop 0
	v_add_f32_e32 v140, 1.0, v140
	s_nop 0
	v_rcp_f32_e32 v140, v140
	v_mul_f32_e32 v141, 0xbfb8aa3b, v103
	v_exp_f32_e32 v141, v141
	s_nop 0
	v_add_f32_e32 v141, 1.0, v141
	s_nop 0
	v_rcp_f32_e32 v141, v141
	v_mul_f32_e32 v142, 0xbfb8aa3b, v96
	v_exp_f32_e32 v142, v142
	v_cvt_pk_bf16_f32 v139, v140, v141
	s_nop 0
	v_add_f32_e32 v142, 1.0, v142
	s_nop 0
	v_rcp_f32_e32 v142, v142
	v_mul_f32_e32 v143, 0xbfb8aa3b, v97
	v_exp_f32_e32 v143, v143
	s_nop 0
	v_add_f32_e32 v143, 1.0, v143
	s_nop 0
	v_rcp_f32_e32 v143, v143
	v_mul_f32_e32 v144, 0xbfb8aa3b, v98
	v_exp_f32_e32 v144, v144
	v_cvt_pk_bf16_f32 v140, v142, v143
	s_nop 0
	v_add_f32_e32 v144, 1.0, v144
	s_nop 0
	v_rcp_f32_e32 v144, v144
	v_mul_f32_e32 v145, 0xbfb8aa3b, v99
	v_exp_f32_e32 v145, v145
	s_nop 0
	v_add_f32_e32 v145, 1.0, v145
	s_nop 0
	v_rcp_f32_e32 v145, v145
	s_nop 0
	v_cvt_pk_bf16_f32 v141, v144, v145
	global_store_dwordx4 v[136:137], v[138:141], off nt
	s_nop 1
	v_mul_f32_e32 v138, 0xbfb8aa3b, v68
	v_exp_f32_e32 v138, v138
	s_nop 0
	v_add_f32_e32 v138, 1.0, v138
	s_nop 0
	v_rcp_f32_e32 v138, v138
	v_mul_f32_e32 v139, 0xbfb8aa3b, v69
; __device__ __forceinline__ u32x4 pack8(f32x4 a, f32x4 b) { u32x4 w; w.x = pk2(a[0], a[1]); w.y = pk2(a[2], a[3]); w.z = pk2(b[0], b[1]); w.w = pk2(b[2], b[3]); return w; }
; #define NTS(T, ptr, val) __builtin_nontemporal_store((val), (T*)(ptr))
; __device__ __forceinline__ f32x4 sigm4(f32x4 v) { return (f32x4){sigm(v[0]), sigm(v[1]), sigm(v[2]), sigm(v[3])}; }
; #define FOR_ROWS _Pragma("unroll") for (int ai = 0; ai < 2; ++ai) _Pragma("unroll") for (int m = 0; m < 4; ++m)
; __device__ __forceinline__ float sigm(float x) { return 1.f / (1.f + __expf(-x)); }
; __device__ __forceinline__ void epilogue(const int kind, CParams& p, const f32x4 (&acc)[2][2][4][2], const Unit& u, const int wr, const int wc, const int fr_in, const int fq_in) {
;     ...
;             FOR_ROWS { ROWDEF
; #pragma unroll
;                 for (int bj = 0; bj < 2; ++bj) NTS(u32x4, p.gates + row * 2048 + (u.pn - 17) * 256 + bj * 128 + cw, pack8(sigm4(acc[ai][bj][m][0]), sigm4(acc[ai][bj][m][1]))); }
	v_exp_f32_e32 v139, v139
	s_nop 0
	v_add_f32_e32 v139, 1.0, v139
	s_nop 0
	v_rcp_f32_e32 v139, v139
	v_mul_f32_e32 v140, 0xbfb8aa3b, v70
	v_exp_f32_e32 v140, v140
	v_cvt_pk_bf16_f32 v138, v138, v139
	s_nop 0
	v_add_f32_e32 v140, 1.0, v140
	s_nop 0
	v_rcp_f32_e32 v140, v140
	v_mul_f32_e32 v141, 0xbfb8aa3b, v71
	v_exp_f32_e32 v141, v141
	s_nop 0
	v_add_f32_e32 v141, 1.0, v141
	s_nop 0
	v_rcp_f32_e32 v141, v141
	v_mul_f32_e32 v142, 0xbfb8aa3b, v64
	v_exp_f32_e32 v142, v142
	v_cvt_pk_bf16_f32 v139, v140, v141
	s_nop 0
	v_add_f32_e32 v142, 1.0, v142
	s_nop 0
	v_rcp_f32_e32 v142, v142
	v_mul_f32_e32 v143, 0xbfb8aa3b, v65
	v_exp_f32_e32 v143, v143
	s_nop 0
	v_add_f32_e32 v143, 1.0, v143
	s_nop 0
	v_rcp_f32_e32 v143, v143
	v_mul_f32_e32 v144, 0xbfb8aa3b, v66
	v_exp_f32_e32 v144, v144
	v_cvt_pk_bf16_f32 v140, v142, v143
	s_nop 0
	v_add_f32_e32 v144, 1.0, v144
	s_nop 0
	v_rcp_f32_e32 v144, v144
	v_mul_f32_e32 v145, 0xbfb8aa3b, v67
	v_exp_f32_e32 v145, v145
	s_nop 0
	v_add_f32_e32 v145, 1.0, v145
	s_nop 0
	v_rcp_f32_e32 v145, v145
	s_nop 0
	v_cvt_pk_bf16_f32 v141, v144, v145
	global_store_dwordx4 v[136:137], v[138:141], off offset:256 nt
	v_add_u32_e32 v136, 0x80, v128
	v_ashrrev_i32_e32 v137, 31, v136
	v_mul_f32_e32 v138, 0xbfb8aa3b, v60
	v_exp_f32_e32 v138, v138
	v_lshl_add_u64 v[136:137], v[136:137], 0, s[78:79]
	v_lshlrev_b64 v[136:137], 12, v[136:137]
	v_lshl_add_u64 v[136:137], s[14:15], 0, v[136:137]
	v_add_f32_e32 v138, 1.0, v138
	v_lshl_add_u64 v[136:137], v[136:137], 0, s[10:11]
	v_lshl_add_u64 v[136:137], v[136:137], 0, v[132:133]
	v_rcp_f32_e32 v138, v138
	v_mul_f32_e32 v139, 0xbfb8aa3b, v61
	v_exp_f32_e32 v139, v139
	s_nop 0
	v_add_f32_e32 v139, 1.0, v139
	s_nop 0
	v_rcp_f32_e32 v139, v139
	v_mul_f32_e32 v140, 0xbfb8aa3b, v62
	v_exp_f32_e32 v140, v140
	v_cvt_pk_bf16_f32 v138, v138, v139
	s_nop 0
	v_add_f32_e32 v140, 1.0, v140
	s_nop 0
	v_rcp_f32_e32 v140, v140
	v_mul_f32_e32 v141, 0xbfb8aa3b, v63
	v_exp_f32_e32 v141, v141
	s_nop 0
	v_add_f32_e32 v141, 1.0, v141
	s_nop 0
	v_rcp_f32_e32 v141, v141
	v_mul_f32_e32 v142, 0xbfb8aa3b, v56
	v_exp_f32_e32 v142, v142
	v_cvt_pk_bf16_f32 v139, v140, v141
	s_nop 0
	v_add_f32_e32 v142, 1.0, v142
	s_nop 0
	v_rcp_f32_e32 v142, v142
	v_mul_f32_e32 v143, 0xbfb8aa3b, v57
	v_exp_f32_e32 v143, v143
	s_nop 0
	v_add_f32_e32 v143, 1.0, v143
	s_nop 0
	v_rcp_f32_e32 v143, v143
	v_mul_f32_e32 v144, 0xbfb8aa3b, v58
	v_exp_f32_e32 v144, v144
	v_cvt_pk_bf16_f32 v140, v142, v143
	s_nop 0
	v_add_f32_e32 v144, 1.0, v144
	s_nop 0
	v_rcp_f32_e32 v144, v144
	v_mul_f32_e32 v145, 0xbfb8aa3b, v59
	v_exp_f32_e32 v145, v145
	s_nop 0
	v_add_f32_e32 v145, 1.0, v145
	s_nop 0
	v_rcp_f32_e32 v145, v145
	s_nop 0
	v_cvt_pk_bf16_f32 v141, v144, v145
	global_store_dwordx4 v[136:137], v[138:141], off nt
	s_nop 1
	v_mul_f32_e32 v138, 0xbfb8aa3b, v28
	v_exp_f32_e32 v138, v138
	s_nop 0
	v_add_f32_e32 v138, 1.0, v138
	s_nop 0
	v_rcp_f32_e32 v138, v138
	v_mul_f32_e32 v139, 0xbfb8aa3b, v29
	v_exp_f32_e32 v139, v139
	s_nop 0
	v_add_f32_e32 v139, 1.0, v139
	s_nop 0
	v_rcp_f32_e32 v139, v139
	v_mul_f32_e32 v140, 0xbfb8aa3b, v30
	v_exp_f32_e32 v140, v140
	v_cvt_pk_bf16_f32 v138, v138, v139
	s_nop 0
	v_add_f32_e32 v140, 1.0, v140
	s_nop 0
	v_rcp_f32_e32 v140, v140
	v_mul_f32_e32 v141, 0xbfb8aa3b, v31
	v_exp_f32_e32 v141, v141
	s_nop 0
	v_add_f32_e32 v141, 1.0, v141
	s_nop 0
	v_rcp_f32_e32 v141, v141
	v_mul_f32_e32 v142, 0xbfb8aa3b, v24
	v_exp_f32_e32 v142, v142
	v_cvt_pk_bf16_f32 v139, v140, v141
	s_nop 0
	v_add_f32_e32 v142, 1.0, v142
	s_nop 0
	v_rcp_f32_e32 v142, v142
	v_mul_f32_e32 v143, 0xbfb8aa3b, v25
	v_exp_f32_e32 v143, v143
	s_nop 0
	v_add_f32_e32 v143, 1.0, v143
	s_nop 0
	v_rcp_f32_e32 v143, v143
	v_mul_f32_e32 v144, 0xbfb8aa3b, v26
	v_exp_f32_e32 v144, v144
	v_cvt_pk_bf16_f32 v140, v142, v143
	s_nop 0
	v_add_f32_e32 v144, 1.0, v144
	s_nop 0
	v_rcp_f32_e32 v144, v144
	v_mul_f32_e32 v145, 0xbfb8aa3b, v27
	v_exp_f32_e32 v145, v145
	s_nop 0
	v_add_f32_e32 v145, 1.0, v145
	s_nop 0
	v_rcp_f32_e32 v145, v145
	s_nop 0
	v_cvt_pk_bf16_f32 v141, v144, v145
	global_store_dwordx4 v[136:137], v[138:141], off offset:256 nt
	v_add_u32_e32 v136, 0x90, v128
	v_ashrrev_i32_e32 v137, 31, v136
	v_mul_f32_e32 v138, 0xbfb8aa3b, v52
	v_exp_f32_e32 v138, v138
	v_lshl_add_u64 v[136:137], v[136:137], 0, s[78:79]
	v_lshlrev_b64 v[136:137], 12, v[136:137]
	v_lshl_add_u64 v[136:137], s[14:15], 0, v[136:137]
	v_add_f32_e32 v138, 1.0, v138
	v_lshl_add_u64 v[136:137], v[136:137], 0, s[10:11]
	v_lshl_add_u64 v[136:137], v[136:137], 0, v[132:133]
	v_rcp_f32_e32 v138, v138
	v_mul_f32_e32 v139, 0xbfb8aa3b, v53
	v_exp_f32_e32 v139, v139
	s_nop 0
	v_add_f32_e32 v139, 1.0, v139
	s_nop 0
	v_rcp_f32_e32 v139, v139
	v_mul_f32_e32 v140, 0xbfb8aa3b, v54
	v_exp_f32_e32 v140, v140
	v_cvt_pk_bf16_f32 v138, v138, v139
	s_nop 0
	v_add_f32_e32 v140, 1.0, v140
	s_nop 0
	v_rcp_f32_e32 v140, v140
	v_mul_f32_e32 v141, 0xbfb8aa3b, v55
	v_exp_f32_e32 v141, v141
	s_nop 0
	v_add_f32_e32 v141, 1.0, v141
	s_nop 0
	v_rcp_f32_e32 v141, v141
	v_mul_f32_e32 v142, 0xbfb8aa3b, v48
	v_exp_f32_e32 v142, v142
	v_cvt_pk_bf16_f32 v139, v140, v141
	s_nop 0
	v_add_f32_e32 v142, 1.0, v142
	s_nop 0
	v_rcp_f32_e32 v142, v142
	v_mul_f32_e32 v143, 0xbfb8aa3b, v49
	v_exp_f32_e32 v143, v143
	s_nop 0
	v_add_f32_e32 v143, 1.0, v143
	s_nop 0
	v_rcp_f32_e32 v143, v143
	v_mul_f32_e32 v144, 0xbfb8aa3b, v50
	v_exp_f32_e32 v144, v144
	v_cvt_pk_bf16_f32 v140, v142, v143
	s_nop 0
	v_add_f32_e32 v144, 1.0, v144
	s_nop 0
	v_rcp_f32_e32 v144, v144
	v_mul_f32_e32 v145, 0xbfb8aa3b, v51
	v_exp_f32_e32 v145, v145
	s_nop 0
	v_add_f32_e32 v145, 1.0, v145
	s_nop 0
	v_rcp_f32_e32 v145, v145
	s_nop 0
	v_cvt_pk_bf16_f32 v141, v144, v145
; __device__ __forceinline__ u32x4 pack8(f32x4 a, f32x4 b) { u32x4 w; w.x = pk2(a[0], a[1]); w.y = pk2(a[2], a[3]); w.z = pk2(b[0], b[1]); w.w = pk2(b[2], b[3]); return w; }
; #define NTS(T, ptr, val) __builtin_nontemporal_store((val), (T*)(ptr))
; __device__ __forceinline__ f32x4 sigm4(f32x4 v) { return (f32x4){sigm(v[0]), sigm(v[1]), sigm(v[2]), sigm(v[3])}; }
; #define FOR_ROWS _Pragma("unroll") for (int ai = 0; ai < 2; ++ai) _Pragma("unroll") for (int m = 0; m < 4; ++m)
; __device__ __forceinline__ float sigm(float x) { return 1.f / (1.f + __expf(-x)); }
; __device__ __forceinline__ void epilogue(const int kind, CParams& p, const f32x4 (&acc)[2][2][4][2], const Unit& u, const int wr, const int wc, const int fr_in, const int fq_in) {
;     ...
;         } else {
;             FOR_ROWS { ROWDEF
; #pragma unroll
;                 for (int bj = 0; bj < 2; ++bj) NTS(u32x4, p.gates + row * 2048 + (u.pn - 17) * 256 + bj * 128 + cw, pack8(sigm4(acc[ai][bj][m][0]), sigm4(acc[ai][bj][m][1]))); }
;         }
	global_store_dwordx4 v[136:137], v[138:141], off nt
	s_nop 1
	v_mul_f32_e32 v138, 0xbfb8aa3b, v20
	v_exp_f32_e32 v138, v138
	s_nop 0
	v_add_f32_e32 v138, 1.0, v138
	s_nop 0
	v_rcp_f32_e32 v138, v138
	v_mul_f32_e32 v139, 0xbfb8aa3b, v21
	v_exp_f32_e32 v139, v139
	s_nop 0
	v_add_f32_e32 v139, 1.0, v139
	s_nop 0
	v_rcp_f32_e32 v139, v139
	v_mul_f32_e32 v140, 0xbfb8aa3b, v22
	v_exp_f32_e32 v140, v140
	v_cvt_pk_bf16_f32 v138, v138, v139
	s_nop 0
	v_add_f32_e32 v140, 1.0, v140
	s_nop 0
	v_rcp_f32_e32 v140, v140
	v_mul_f32_e32 v141, 0xbfb8aa3b, v23
	v_exp_f32_e32 v141, v141
	s_nop 0
	v_add_f32_e32 v141, 1.0, v141
	s_nop 0
	v_rcp_f32_e32 v141, v141
	v_mul_f32_e32 v142, 0xbfb8aa3b, v16
	v_exp_f32_e32 v142, v142
	v_cvt_pk_bf16_f32 v139, v140, v141
	s_nop 0
	v_add_f32_e32 v142, 1.0, v142
	s_nop 0
	v_rcp_f32_e32 v142, v142
	v_mul_f32_e32 v143, 0xbfb8aa3b, v17
	v_exp_f32_e32 v143, v143
	s_nop 0
	v_add_f32_e32 v143, 1.0, v143
	s_nop 0
	v_rcp_f32_e32 v143, v143
	v_mul_f32_e32 v144, 0xbfb8aa3b, v18
	v_exp_f32_e32 v144, v144
	v_cvt_pk_bf16_f32 v140, v142, v143
	s_nop 0
	v_add_f32_e32 v144, 1.0, v144
	s_nop 0
	v_rcp_f32_e32 v144, v144
	v_mul_f32_e32 v145, 0xbfb8aa3b, v19
	v_exp_f32_e32 v145, v145
	s_nop 0
	v_add_f32_e32 v145, 1.0, v145
	s_nop 0
	v_rcp_f32_e32 v145, v145
	s_nop 0
	v_cvt_pk_bf16_f32 v141, v144, v145
	global_store_dwordx4 v[136:137], v[138:141], off offset:256 nt
	v_add_u32_e32 v136, 0xa0, v128
	v_ashrrev_i32_e32 v137, 31, v136
	v_mul_f32_e32 v138, 0xbfb8aa3b, v44
	v_exp_f32_e32 v138, v138
	v_lshl_add_u64 v[136:137], v[136:137], 0, s[78:79]
	v_lshlrev_b64 v[136:137], 12, v[136:137]
	v_lshl_add_u64 v[136:137], s[14:15], 0, v[136:137]
	v_add_f32_e32 v138, 1.0, v138
	v_lshl_add_u64 v[136:137], v[136:137], 0, s[10:11]
	v_lshl_add_u64 v[136:137], v[136:137], 0, v[132:133]
	v_rcp_f32_e32 v138, v138
	v_mul_f32_e32 v139, 0xbfb8aa3b, v45
	v_exp_f32_e32 v139, v139
	s_nop 0
	v_add_f32_e32 v139, 1.0, v139
	s_nop 0
	v_rcp_f32_e32 v139, v139
	v_mul_f32_e32 v140, 0xbfb8aa3b, v46
	v_exp_f32_e32 v140, v140
	v_cvt_pk_bf16_f32 v138, v138, v139
	s_nop 0
	v_add_f32_e32 v140, 1.0, v140
	s_nop 0
	v_rcp_f32_e32 v140, v140
	v_mul_f32_e32 v141, 0xbfb8aa3b, v47
	v_exp_f32_e32 v141, v141
	s_nop 0
	v_add_f32_e32 v141, 1.0, v141
	s_nop 0
	v_rcp_f32_e32 v141, v141
	v_mul_f32_e32 v142, 0xbfb8aa3b, v40
	v_exp_f32_e32 v142, v142
	v_cvt_pk_bf16_f32 v139, v140, v141
	s_nop 0
	v_add_f32_e32 v142, 1.0, v142
	s_nop 0
	v_rcp_f32_e32 v142, v142
	v_mul_f32_e32 v143, 0xbfb8aa3b, v41
	v_exp_f32_e32 v143, v143
	s_nop 0
	v_add_f32_e32 v143, 1.0, v143
	s_nop 0
	v_rcp_f32_e32 v143, v143
	v_mul_f32_e32 v144, 0xbfb8aa3b, v42
	v_exp_f32_e32 v144, v144
	v_cvt_pk_bf16_f32 v140, v142, v143
	s_nop 0
	v_add_f32_e32 v144, 1.0, v144
	s_nop 0
	v_rcp_f32_e32 v144, v144
	v_mul_f32_e32 v145, 0xbfb8aa3b, v43
	v_exp_f32_e32 v145, v145
	s_nop 0
	v_add_f32_e32 v145, 1.0, v145
	s_nop 0
	v_rcp_f32_e32 v145, v145
	s_nop 0
	v_cvt_pk_bf16_f32 v141, v144, v145
	global_store_dwordx4 v[136:137], v[138:141], off nt
	s_nop 1
	v_mul_f32_e32 v138, 0xbfb8aa3b, v12
	v_exp_f32_e32 v138, v138
	s_nop 0
	v_add_f32_e32 v138, 1.0, v138
	s_nop 0
	v_rcp_f32_e32 v138, v138
	v_mul_f32_e32 v139, 0xbfb8aa3b, v13
	v_exp_f32_e32 v139, v139
	s_nop 0
	v_add_f32_e32 v139, 1.0, v139
	s_nop 0
	v_rcp_f32_e32 v139, v139
	v_mul_f32_e32 v140, 0xbfb8aa3b, v14
	v_exp_f32_e32 v140, v140
	v_cvt_pk_bf16_f32 v138, v138, v139
	s_nop 0
	v_add_f32_e32 v140, 1.0, v140
	s_nop 0
	v_rcp_f32_e32 v140, v140
	v_mul_f32_e32 v141, 0xbfb8aa3b, v15
	v_exp_f32_e32 v141, v141
	s_nop 0
	v_add_f32_e32 v141, 1.0, v141
	s_nop 0
	v_rcp_f32_e32 v141, v141
	v_mul_f32_e32 v142, 0xbfb8aa3b, v8
; __device__ __forceinline__ u32x4 pack8(f32x4 a, f32x4 b) { u32x4 w; w.x = pk2(a[0], a[1]); w.y = pk2(a[2], a[3]); w.z = pk2(b[0], b[1]); w.w = pk2(b[2], b[3]); return w; }
; #define NTS(T, ptr, val) __builtin_nontemporal_store((val), (T*)(ptr))
; __device__ __forceinline__ f32x4 sigm4(f32x4 v) { return (f32x4){sigm(v[0]), sigm(v[1]), sigm(v[2]), sigm(v[3])}; }
; #define FOR_ROWS _Pragma("unroll") for (int ai = 0; ai < 2; ++ai) _Pragma("unroll") for (int m = 0; m < 4; ++m)
; __device__ __forceinline__ float sigm(float x) { return 1.f / (1.f + __expf(-x)); }
; __device__ __forceinline__ void epilogue(const int kind, CParams& p, const f32x4 (&acc)[2][2][4][2], const Unit& u, const int wr, const int wc, const int fr_in, const int fq_in) {
;     ...
;         } else {
;             FOR_ROWS { ROWDEF
; #pragma unroll
;                 for (int bj = 0; bj < 2; ++bj) NTS(u32x4, p.gates + row * 2048 + (u.pn - 17) * 256 + bj * 128 + cw, pack8(sigm4(acc[ai][bj][m][0]), sigm4(acc[ai][bj][m][1]))); }
;         }
	v_exp_f32_e32 v142, v142
	v_cvt_pk_bf16_f32 v139, v140, v141
	s_nop 0
	v_add_f32_e32 v142, 1.0, v142
	s_nop 0
	v_rcp_f32_e32 v142, v142
	v_mul_f32_e32 v143, 0xbfb8aa3b, v9
	v_exp_f32_e32 v143, v143
	s_nop 0
	v_add_f32_e32 v143, 1.0, v143
	s_nop 0
	v_rcp_f32_e32 v143, v143
	v_mul_f32_e32 v144, 0xbfb8aa3b, v10
	v_exp_f32_e32 v144, v144
	v_cvt_pk_bf16_f32 v140, v142, v143
	s_nop 0
	v_add_f32_e32 v144, 1.0, v144
	s_nop 0
	v_rcp_f32_e32 v144, v144
	v_mul_f32_e32 v145, 0xbfb8aa3b, v11
	v_exp_f32_e32 v145, v145
	s_nop 0
	v_add_f32_e32 v145, 1.0, v145
	s_nop 0
	v_rcp_f32_e32 v145, v145
	s_nop 0
	v_cvt_pk_bf16_f32 v141, v144, v145
	global_store_dwordx4 v[136:137], v[138:141], off offset:256 nt
	v_add_u32_e32 v136, 0xb0, v128
	v_ashrrev_i32_e32 v137, 31, v136
	v_mul_f32_e32 v138, 0xbfb8aa3b, v36
	v_exp_f32_e32 v138, v138
	v_lshl_add_u64 v[136:137], v[136:137], 0, s[78:79]
	v_lshlrev_b64 v[136:137], 12, v[136:137]
	v_lshl_add_u64 v[136:137], s[14:15], 0, v[136:137]
	v_add_f32_e32 v138, 1.0, v138
	v_lshl_add_u64 v[136:137], v[136:137], 0, s[10:11]
	v_lshl_add_u64 v[136:137], v[136:137], 0, v[132:133]
	v_rcp_f32_e32 v138, v138
	v_mul_f32_e32 v139, 0xbfb8aa3b, v37
	v_exp_f32_e32 v139, v139
	s_nop 0
	v_add_f32_e32 v139, 1.0, v139
	s_nop 0
	v_rcp_f32_e32 v139, v139
	v_mul_f32_e32 v140, 0xbfb8aa3b, v38
	v_exp_f32_e32 v140, v140
	v_cvt_pk_bf16_f32 v138, v138, v139
	s_nop 0
	v_add_f32_e32 v140, 1.0, v140
	s_nop 0
	v_rcp_f32_e32 v140, v140
	v_mul_f32_e32 v141, 0xbfb8aa3b, v39
	v_exp_f32_e32 v141, v141
	s_nop 0
	v_add_f32_e32 v141, 1.0, v141
	s_nop 0
	v_rcp_f32_e32 v141, v141
	v_mul_f32_e32 v142, 0xbfb8aa3b, v32
	v_exp_f32_e32 v142, v142
	v_cvt_pk_bf16_f32 v139, v140, v141
	s_nop 0
	v_add_f32_e32 v142, 1.0, v142
	s_nop 0
	v_rcp_f32_e32 v142, v142
	v_mul_f32_e32 v143, 0xbfb8aa3b, v33
	v_exp_f32_e32 v143, v143
	s_nop 0
	v_add_f32_e32 v143, 1.0, v143
	s_nop 0
	v_rcp_f32_e32 v143, v143
	v_mul_f32_e32 v144, 0xbfb8aa3b, v34
	v_exp_f32_e32 v144, v144
	v_cvt_pk_bf16_f32 v140, v142, v143
	s_nop 0
	v_add_f32_e32 v144, 1.0, v144
	s_nop 0
	v_rcp_f32_e32 v144, v144
	v_mul_f32_e32 v145, 0xbfb8aa3b, v35
	v_exp_f32_e32 v145, v145
	s_nop 0
	v_add_f32_e32 v145, 1.0, v145
	s_nop 0
	v_rcp_f32_e32 v145, v145
	s_nop 0
	v_cvt_pk_bf16_f32 v141, v144, v145
	global_store_dwordx4 v[136:137], v[138:141], off nt
	s_nop 1
	v_mul_f32_e32 v138, 0xbfb8aa3b, v4
	v_exp_f32_e32 v138, v138
	s_nop 0
	v_add_f32_e32 v138, 1.0, v138
	s_nop 0
	v_rcp_f32_e32 v138, v138
	v_mul_f32_e32 v139, 0xbfb8aa3b, v5
	v_exp_f32_e32 v139, v139
	s_nop 0
	v_add_f32_e32 v139, 1.0, v139
	s_nop 0
	v_rcp_f32_e32 v139, v139
	v_mul_f32_e32 v140, 0xbfb8aa3b, v6
	v_exp_f32_e32 v140, v140
	v_cvt_pk_bf16_f32 v138, v138, v139
	s_nop 0
	v_add_f32_e32 v140, 1.0, v140
	s_nop 0
	v_rcp_f32_e32 v140, v140
	v_mul_f32_e32 v141, 0xbfb8aa3b, v7
	v_exp_f32_e32 v141, v141
	s_nop 0
	v_add_f32_e32 v141, 1.0, v141
	s_nop 0
	v_rcp_f32_e32 v141, v141
	v_mul_f32_e32 v142, 0xbfb8aa3b, v0
	v_exp_f32_e32 v142, v142
	v_cvt_pk_bf16_f32 v139, v140, v141
	s_nop 0
	v_add_f32_e32 v142, 1.0, v142
	s_nop 0
	v_rcp_f32_e32 v142, v142
	v_mul_f32_e32 v143, 0xbfb8aa3b, v1
	v_exp_f32_e32 v143, v143
	s_nop 0
	v_add_f32_e32 v143, 1.0, v143
	s_nop 0
	v_rcp_f32_e32 v143, v143
	v_mul_f32_e32 v144, 0xbfb8aa3b, v2
	v_exp_f32_e32 v144, v144
	v_cvt_pk_bf16_f32 v140, v142, v143
	s_nop 0
	v_add_f32_e32 v144, 1.0, v144
	s_nop 0
	v_rcp_f32_e32 v144, v144
	v_mul_f32_e32 v145, 0xbfb8aa3b, v3
	v_exp_f32_e32 v145, v145
	s_nop 0
	v_add_f32_e32 v145, 1.0, v145
	s_mov_b64 s[10:11], 0
	v_rcp_f32_e32 v145, v145
	s_nop 0
	v_cvt_pk_bf16_f32 v141, v144, v145
	global_store_dwordx4 v[136:137], v[138:141], off offset:256 nt

; __device__ __forceinline__ u32x4 pack8(f32x4 a, f32x4 b) { u32x4 w; w.x = pk2(a[0], a[1]); w.y = pk2(a[2], a[3]); w.z = pk2(b[0], b[1]); w.w = pk2(b[2], b[3]); return w; }
; __device__ __forceinline__ f32x4 sigm4(f32x4 v) { return (f32x4){sigm(v[0]), sigm(v[1]), sigm(v[2]), sigm(v[3])}; }
; #define FOR_ROWS _Pragma("unroll") for (int ai = 0; ai < 2; ++ai) _Pragma("unroll") for (int m = 0; m < 4; ++m)
; __device__ __forceinline__ float sigm(float x) { return 1.f / (1.f + __expf(-x)); }
; __device__ __forceinline__ void epilogue(const int kind, CParams& p, const f32x4 (&acc)[2][2][4][2], const Unit& u, const int wr, const int wc, const int fr_in, const int fq_in) {
;     ...
;         if (u.pn < 4) {
;             FOR_ROWS { ROWDEF
;                 const f32x4 a0 = acc[ai][0][m][0], a1 = acc[ai][0][m][1], b0 = sigm4(acc[ai][1][m][0]), b1 = sigm4(acc[ai][1][m][1]);
;                 *(u32x4*)(p.u + row * DCV + u.pn * 128 + cw) = pack8(a0 * b0, a1 * b1); }
.LBB0_909:
	s_andn2_b64 vcc, exec, s[10:11]
	s_cbranch_vccnz .LBB0_911
	s_ashr_i32 s79, s78, 31
	v_lshl_add_u64 v[132:133], v[128:129], 0, s[78:79]
	v_mul_f32_e32 v129, 0xbfb8aa3b, v92
	v_exp_f32_e32 v134, v129
	v_mul_f32_e32 v129, 0xbfb8aa3b, v93
	v_exp_f32_e32 v135, v129
	v_mul_f32_e32 v129, 0xbfb8aa3b, v94
	v_exp_f32_e32 v136, v129
	v_mul_f32_e32 v129, 0xbfb8aa3b, v95
	v_pk_add_f32 v[134:135], v[134:135], 1.0 op_sel_hi:[1,0]
	v_exp_f32_e32 v137, v129
	s_nop 0
	v_pk_add_f32 v[136:137], v[136:137], 1.0 op_sel_hi:[1,0]
	v_readlane_b32 s16, v244, 36
	v_lshlrev_b64 v[132:133], 10, v[132:133]
	v_rcp_f32_e32 v135, v135
	v_readlane_b32 s17, v244, 37
	v_readlane_b32 s18, v244, 38
	v_readlane_b32 s19, v244, 39
	v_rcp_f32_e32 v134, v134
	s_nop 0
	v_pk_mul_f32 v[134:135], v[124:125], v[134:135]
	v_lshl_add_u64 v[132:133], s[16:17], 0, v[132:133]
	v_cvt_pk_bf16_f32 v134, v134, v135
	v_rcp_f32_e32 v137, v137
	s_nop 0
	v_rcp_f32_e32 v136, v136
	v_mul_f32_e32 v129, 0xbfb8aa3b, v88
	v_exp_f32_e32 v138, v129
	v_mul_f32_e32 v129, 0xbfb8aa3b, v89
	v_exp_f32_e32 v139, v129
	v_mul_f32_e32 v129, 0xbfb8aa3b, v90
	v_exp_f32_e32 v140, v129
	v_mul_f32_e32 v129, 0xbfb8aa3b, v91
	v_pk_add_f32 v[138:139], v[138:139], 1.0 op_sel_hi:[1,0]
	v_exp_f32_e32 v141, v129
	s_nop 0
	v_pk_add_f32 v[140:141], v[140:141], 1.0 op_sel_hi:[1,0]
	v_pk_mul_f32 v[136:137], v[126:127], v[136:137]
	v_rcp_f32_e32 v139, v139
	v_cvt_pk_bf16_f32 v135, v136, v137
	s_nop 0
	v_rcp_f32_e32 v138, v138
	s_nop 0
	v_pk_mul_f32 v[138:139], v[120:121], v[138:139]
	v_rcp_f32_e32 v141, v141
	s_lshl_b32 s10, s92, 7
	s_ashr_i32 s11, s10, 31
	s_lshl_b64 s[10:11], s[10:11], 1
	v_cvt_pk_bf16_f32 v136, v138, v139
	v_lshl_add_u64 v[138:139], v[132:133], 0, s[10:11]
	v_lshlrev_b64 v[132:133], 1, v[172:173]
	v_rcp_f32_e32 v140, v140
	v_lshl_add_u64 v[138:139], v[138:139], 0, v[132:133]
	v_mul_f32_e32 v129, 0xbfb8aa3b, v84
	v_pk_mul_f32 v[140:141], v[122:123], v[140:141]
	v_ashrrev_i32_e32 v131, 31, v130
	v_cvt_pk_bf16_f32 v137, v140, v141
	global_store_dwordx4 v[138:139], v[134:137], off
	v_lshl_add_u64 v[130:131], v[130:131], 0, s[78:79]
	v_lshlrev_b64 v[130:131], 10, v[130:131]
	v_exp_f32_e32 v134, v129
	v_mul_f32_e32 v129, 0xbfb8aa3b, v85
	v_exp_f32_e32 v135, v129
	v_mul_f32_e32 v129, 0xbfb8aa3b, v86
	v_exp_f32_e32 v136, v129
	v_mul_f32_e32 v129, 0xbfb8aa3b, v87
	v_pk_add_f32 v[134:135], v[134:135], 1.0 op_sel_hi:[1,0]
	v_exp_f32_e32 v137, v129
	s_nop 0
	v_pk_add_f32 v[136:137], v[136:137], 1.0 op_sel_hi:[1,0]
	v_lshl_add_u64 v[130:131], s[16:17], 0, v[130:131]
	v_lshl_add_u64 v[130:131], v[130:131], 0, s[10:11]
	v_rcp_f32_e32 v135, v135
	v_lshl_add_u64 v[130:131], v[130:131], 0, v[132:133]
	v_rcp_f32_e32 v134, v134
	s_nop 0
	v_pk_mul_f32 v[134:135], v[116:117], v[134:135]
	v_rcp_f32_e32 v137, v137
	v_cvt_pk_bf16_f32 v134, v134, v135
	s_nop 0
	v_rcp_f32_e32 v136, v136
	v_mul_f32_e32 v129, 0xbfb8aa3b, v80
	v_exp_f32_e32 v138, v129
	v_mul_f32_e32 v129, 0xbfb8aa3b, v81
	v_exp_f32_e32 v139, v129
	v_mul_f32_e32 v129, 0xbfb8aa3b, v82
	v_exp_f32_e32 v140, v129
	v_mul_f32_e32 v129, 0xbfb8aa3b, v83
	v_pk_add_f32 v[138:139], v[138:139], 1.0 op_sel_hi:[1,0]
	v_exp_f32_e32 v141, v129
	s_nop 0
	v_pk_add_f32 v[140:141], v[140:141], 1.0 op_sel_hi:[1,0]
	v_pk_mul_f32 v[136:137], v[118:119], v[136:137]
	v_rcp_f32_e32 v139, v139
	v_cvt_pk_bf16_f32 v135, v136, v137
	s_nop 0
	v_rcp_f32_e32 v138, v138
	s_nop 0
	v_pk_mul_f32 v[138:139], v[112:113], v[138:139]
	v_rcp_f32_e32 v141, v141
	v_cvt_pk_bf16_f32 v136, v138, v139
	s_nop 0
	v_rcp_f32_e32 v140, v140
	v_mul_f32_e32 v129, 0xbfb8aa3b, v76
	v_pk_mul_f32 v[140:141], v[114:115], v[140:141]
	s_nop 0
	v_cvt_pk_bf16_f32 v137, v140, v141
	global_store_dwordx4 v[130:131], v[134:137], off
	v_add_u32_e32 v130, 32, v128
	v_ashrrev_i32_e32 v131, 31, v130
	v_exp_f32_e32 v134, v129
	v_mul_f32_e32 v129, 0xbfb8aa3b, v77
	v_exp_f32_e32 v135, v129
	v_mul_f32_e32 v129, 0xbfb8aa3b, v78
	v_exp_f32_e32 v136, v129
	v_mul_f32_e32 v129, 0xbfb8aa3b, v79
	v_pk_add_f32 v[134:135], v[134:135], 1.0 op_sel_hi:[1,0]
	v_exp_f32_e32 v137, v129
	s_nop 0
	v_pk_add_f32 v[136:137], v[136:137], 1.0 op_sel_hi:[1,0]
	v_lshl_add_u64 v[130:131], v[130:131], 0, s[78:79]
	v_lshlrev_b64 v[130:131], 10, v[130:131]
	v_rcp_f32_e32 v135, v135
	v_lshl_add_u64 v[130:131], s[16:17], 0, v[130:131]
	v_lshl_add_u64 v[130:131], v[130:131], 0, s[10:11]
	v_lshl_add_u64 v[130:131], v[130:131], 0, v[132:133]
	v_rcp_f32_e32 v134, v134
	s_nop 0
	v_pk_mul_f32 v[134:135], v[108:109], v[134:135]
	v_rcp_f32_e32 v137, v137
	v_cvt_pk_bf16_f32 v134, v134, v135
	s_nop 0
	v_rcp_f32_e32 v136, v136
	v_mul_f32_e32 v129, 0xbfb8aa3b, v72
	v_exp_f32_e32 v138, v129
	v_mul_f32_e32 v129, 0xbfb8aa3b, v73
	v_exp_f32_e32 v139, v129
	v_mul_f32_e32 v129, 0xbfb8aa3b, v74
	v_exp_f32_e32 v140, v129
	v_mul_f32_e32 v129, 0xbfb8aa3b, v75
	v_pk_add_f32 v[138:139], v[138:139], 1.0 op_sel_hi:[1,0]
	v_exp_f32_e32 v141, v129
	s_nop 0
	v_pk_add_f32 v[140:141], v[140:141], 1.0 op_sel_hi:[1,0]
	v_pk_mul_f32 v[136:137], v[110:111], v[136:137]
	v_rcp_f32_e32 v139, v139
	v_cvt_pk_bf16_f32 v135, v136, v137
	s_nop 0
	v_rcp_f32_e32 v138, v138
	s_nop 0
	v_pk_mul_f32 v[138:139], v[104:105], v[138:139]
	v_rcp_f32_e32 v141, v141
	v_cvt_pk_bf16_f32 v136, v138, v139
	s_nop 0
	v_rcp_f32_e32 v140, v140
	v_mul_f32_e32 v129, 0xbfb8aa3b, v68
	v_pk_mul_f32 v[140:141], v[106:107], v[140:141]
	s_nop 0
	v_cvt_pk_bf16_f32 v137, v140, v141
	global_store_dwordx4 v[130:131], v[134:137], off
	v_add_u32_e32 v130, 48, v128
	v_ashrrev_i32_e32 v131, 31, v130
	v_exp_f32_e32 v134, v129
	v_mul_f32_e32 v129, 0xbfb8aa3b, v69
	v_exp_f32_e32 v135, v129
	v_mul_f32_e32 v129, 0xbfb8aa3b, v70
	v_exp_f32_e32 v136, v129
; __device__ __forceinline__ u32x4 pack8(f32x4 a, f32x4 b) { u32x4 w; w.x = pk2(a[0], a[1]); w.y = pk2(a[2], a[3]); w.z = pk2(b[0], b[1]); w.w = pk2(b[2], b[3]); return w; }
; __device__ __forceinline__ f32x4 sigm4(f32x4 v) { return (f32x4){sigm(v[0]), sigm(v[1]), sigm(v[2]), sigm(v[3])}; }
; #define FOR_ROWS _Pragma("unroll") for (int ai = 0; ai < 2; ++ai) _Pragma("unroll") for (int m = 0; m < 4; ++m)
; __device__ __forceinline__ float sigm(float x) { return 1.f / (1.f + __expf(-x)); }
; __device__ __forceinline__ void epilogue(const int kind, CParams& p, const f32x4 (&acc)[2][2][4][2], const Unit& u, const int wr, const int wc, const int fr_in, const int fq_in) {
;     ...
;         if (u.pn < 4) {
;             FOR_ROWS { ROWDEF
;                 const f32x4 a0 = acc[ai][0][m][0], a1 = acc[ai][0][m][1], b0 = sigm4(acc[ai][1][m][0]), b1 = sigm4(acc[ai][1][m][1]);
;                 *(u32x4*)(p.u + row * DCV + u.pn * 128 + cw) = pack8(a0 * b0, a1 * b1); }
	v_mul_f32_e32 v129, 0xbfb8aa3b, v71
	v_pk_add_f32 v[134:135], v[134:135], 1.0 op_sel_hi:[1,0]
	v_exp_f32_e32 v137, v129
	s_nop 0
	v_pk_add_f32 v[136:137], v[136:137], 1.0 op_sel_hi:[1,0]
	v_lshl_add_u64 v[130:131], v[130:131], 0, s[78:79]
	v_lshlrev_b64 v[130:131], 10, v[130:131]
	v_rcp_f32_e32 v135, v135
	v_lshl_add_u64 v[130:131], s[16:17], 0, v[130:131]
	v_lshl_add_u64 v[130:131], v[130:131], 0, s[10:11]
	v_lshl_add_u64 v[130:131], v[130:131], 0, v[132:133]
	v_rcp_f32_e32 v134, v134
	s_nop 0
	v_pk_mul_f32 v[134:135], v[100:101], v[134:135]
	v_rcp_f32_e32 v137, v137
	v_cvt_pk_bf16_f32 v134, v134, v135
	s_nop 0
	v_rcp_f32_e32 v136, v136
	v_mul_f32_e32 v129, 0xbfb8aa3b, v64
	v_exp_f32_e32 v138, v129
	v_mul_f32_e32 v129, 0xbfb8aa3b, v65
	v_exp_f32_e32 v139, v129
	v_mul_f32_e32 v129, 0xbfb8aa3b, v66
	v_exp_f32_e32 v140, v129
	v_mul_f32_e32 v129, 0xbfb8aa3b, v67
	v_pk_add_f32 v[138:139], v[138:139], 1.0 op_sel_hi:[1,0]
	v_exp_f32_e32 v141, v129
	s_nop 0
	v_pk_add_f32 v[140:141], v[140:141], 1.0 op_sel_hi:[1,0]
	v_pk_mul_f32 v[136:137], v[102:103], v[136:137]
	v_rcp_f32_e32 v139, v139
	v_cvt_pk_bf16_f32 v135, v136, v137
	s_nop 0
	v_rcp_f32_e32 v138, v138
	s_nop 0
	v_pk_mul_f32 v[138:139], v[96:97], v[138:139]
	v_rcp_f32_e32 v141, v141
	v_cvt_pk_bf16_f32 v136, v138, v139
	s_nop 0
	v_rcp_f32_e32 v140, v140
	v_mul_f32_e32 v129, 0xbfb8aa3b, v28
	v_pk_mul_f32 v[140:141], v[98:99], v[140:141]
	s_nop 0
	v_cvt_pk_bf16_f32 v137, v140, v141
	global_store_dwordx4 v[130:131], v[134:137], off
	v_add_u32_e32 v130, 0x80, v128
	v_ashrrev_i32_e32 v131, 31, v130
	v_exp_f32_e32 v134, v129
	v_mul_f32_e32 v129, 0xbfb8aa3b, v29
	v_exp_f32_e32 v135, v129
	v_mul_f32_e32 v129, 0xbfb8aa3b, v30
	v_exp_f32_e32 v136, v129
	v_mul_f32_e32 v129, 0xbfb8aa3b, v31
	v_pk_add_f32 v[134:135], v[134:135], 1.0 op_sel_hi:[1,0]
	v_exp_f32_e32 v137, v129
	s_nop 0
	v_pk_add_f32 v[136:137], v[136:137], 1.0 op_sel_hi:[1,0]
	v_lshl_add_u64 v[130:131], v[130:131], 0, s[78:79]
	v_lshlrev_b64 v[130:131], 10, v[130:131]
	v_rcp_f32_e32 v135, v135
	v_lshl_add_u64 v[130:131], s[16:17], 0, v[130:131]
	v_lshl_add_u64 v[130:131], v[130:131], 0, s[10:11]
	v_lshl_add_u64 v[130:131], v[130:131], 0, v[132:133]
	v_rcp_f32_e32 v134, v134
	s_nop 0
	v_pk_mul_f32 v[134:135], v[60:61], v[134:135]
	v_rcp_f32_e32 v137, v137
	v_cvt_pk_bf16_f32 v134, v134, v135
	s_nop 0
	v_rcp_f32_e32 v136, v136
	v_mul_f32_e32 v129, 0xbfb8aa3b, v24
	v_exp_f32_e32 v138, v129
	v_mul_f32_e32 v129, 0xbfb8aa3b, v25
	v_exp_f32_e32 v139, v129
	v_mul_f32_e32 v129, 0xbfb8aa3b, v26
	v_exp_f32_e32 v140, v129
	v_mul_f32_e32 v129, 0xbfb8aa3b, v27
	v_pk_add_f32 v[138:139], v[138:139], 1.0 op_sel_hi:[1,0]
	v_exp_f32_e32 v141, v129
	s_nop 0
	v_pk_add_f32 v[140:141], v[140:141], 1.0 op_sel_hi:[1,0]
	v_pk_mul_f32 v[136:137], v[62:63], v[136:137]
	v_rcp_f32_e32 v139, v139
	v_cvt_pk_bf16_f32 v135, v136, v137
	s_nop 0
	v_rcp_f32_e32 v138, v138
	s_nop 0
	v_pk_mul_f32 v[138:139], v[56:57], v[138:139]
	v_rcp_f32_e32 v141, v141
	v_cvt_pk_bf16_f32 v136, v138, v139
	s_nop 0
	v_rcp_f32_e32 v140, v140
	v_mul_f32_e32 v129, 0xbfb8aa3b, v20
	v_pk_mul_f32 v[140:141], v[58:59], v[140:141]
	s_nop 0
	v_cvt_pk_bf16_f32 v137, v140, v141
	global_store_dwordx4 v[130:131], v[134:137], off
	v_add_u32_e32 v130, 0x90, v128
	v_ashrrev_i32_e32 v131, 31, v130
	v_exp_f32_e32 v134, v129
	v_mul_f32_e32 v129, 0xbfb8aa3b, v21
	v_exp_f32_e32 v135, v129
	v_mul_f32_e32 v129, 0xbfb8aa3b, v22
	v_exp_f32_e32 v136, v129
	v_mul_f32_e32 v129, 0xbfb8aa3b, v23
	v_pk_add_f32 v[134:135], v[134:135], 1.0 op_sel_hi:[1,0]
	v_exp_f32_e32 v137, v129
	s_nop 0
	v_pk_add_f32 v[136:137], v[136:137], 1.0 op_sel_hi:[1,0]
	v_lshl_add_u64 v[130:131], v[130:131], 0, s[78:79]
	v_lshlrev_b64 v[130:131], 10, v[130:131]
	v_rcp_f32_e32 v135, v135
	v_lshl_add_u64 v[130:131], s[16:17], 0, v[130:131]
	v_lshl_add_u64 v[130:131], v[130:131], 0, s[10:11]
	v_lshl_add_u64 v[130:131], v[130:131], 0, v[132:133]
	v_rcp_f32_e32 v134, v134
	s_nop 0
	v_pk_mul_f32 v[134:135], v[52:53], v[134:135]
	v_rcp_f32_e32 v137, v137
	v_cvt_pk_bf16_f32 v134, v134, v135
	s_nop 0
	v_rcp_f32_e32 v136, v136
	v_mul_f32_e32 v129, 0xbfb8aa3b, v16
	v_exp_f32_e32 v138, v129
; __device__ __forceinline__ u32x4 pack8(f32x4 a, f32x4 b) { u32x4 w; w.x = pk2(a[0], a[1]); w.y = pk2(a[2], a[3]); w.z = pk2(b[0], b[1]); w.w = pk2(b[2], b[3]); return w; }
; __device__ __forceinline__ f32x4 sigm4(f32x4 v) { return (f32x4){sigm(v[0]), sigm(v[1]), sigm(v[2]), sigm(v[3])}; }
; #define FOR_ROWS _Pragma("unroll") for (int ai = 0; ai < 2; ++ai) _Pragma("unroll") for (int m = 0; m < 4; ++m)
; __device__ __forceinline__ float sigm(float x) { return 1.f / (1.f + __expf(-x)); }
; __device__ __forceinline__ void epilogue(const int kind, CParams& p, const f32x4 (&acc)[2][2][4][2], const Unit& u, const int wr, const int wc, const int fr_in, const int fq_in) {
;     ...
;         if (u.pn < 4) {
;             FOR_ROWS { ROWDEF
;                 const f32x4 a0 = acc[ai][0][m][0], a1 = acc[ai][0][m][1], b0 = sigm4(acc[ai][1][m][0]), b1 = sigm4(acc[ai][1][m][1]);
;                 *(u32x4*)(p.u + row * DCV + u.pn * 128 + cw) = pack8(a0 * b0, a1 * b1); }
	v_mul_f32_e32 v129, 0xbfb8aa3b, v17
	v_exp_f32_e32 v139, v129
	v_mul_f32_e32 v129, 0xbfb8aa3b, v18
	v_exp_f32_e32 v140, v129
	v_mul_f32_e32 v129, 0xbfb8aa3b, v19
	v_pk_add_f32 v[138:139], v[138:139], 1.0 op_sel_hi:[1,0]
	v_exp_f32_e32 v141, v129
	s_nop 0
	v_pk_add_f32 v[140:141], v[140:141], 1.0 op_sel_hi:[1,0]
	v_pk_mul_f32 v[136:137], v[54:55], v[136:137]
	v_rcp_f32_e32 v139, v139
	v_cvt_pk_bf16_f32 v135, v136, v137
	s_nop 0
	v_rcp_f32_e32 v138, v138
	s_nop 0
	v_pk_mul_f32 v[138:139], v[48:49], v[138:139]
	v_rcp_f32_e32 v141, v141
	v_cvt_pk_bf16_f32 v136, v138, v139
	s_nop 0
	v_rcp_f32_e32 v140, v140
	v_mul_f32_e32 v129, 0xbfb8aa3b, v12
	v_pk_mul_f32 v[140:141], v[50:51], v[140:141]
	s_nop 0
	v_cvt_pk_bf16_f32 v137, v140, v141
	global_store_dwordx4 v[130:131], v[134:137], off
	v_add_u32_e32 v130, 0xa0, v128
	v_ashrrev_i32_e32 v131, 31, v130
	v_exp_f32_e32 v134, v129
	v_mul_f32_e32 v129, 0xbfb8aa3b, v13
	v_exp_f32_e32 v135, v129
	v_mul_f32_e32 v129, 0xbfb8aa3b, v14
	v_exp_f32_e32 v136, v129
	v_mul_f32_e32 v129, 0xbfb8aa3b, v15
	v_pk_add_f32 v[134:135], v[134:135], 1.0 op_sel_hi:[1,0]
	v_exp_f32_e32 v137, v129
	s_nop 0
	v_pk_add_f32 v[136:137], v[136:137], 1.0 op_sel_hi:[1,0]
	v_lshl_add_u64 v[130:131], v[130:131], 0, s[78:79]
	v_lshlrev_b64 v[130:131], 10, v[130:131]
	v_rcp_f32_e32 v135, v135
	v_lshl_add_u64 v[130:131], s[16:17], 0, v[130:131]
	v_lshl_add_u64 v[130:131], v[130:131], 0, s[10:11]
	v_lshl_add_u64 v[130:131], v[130:131], 0, v[132:133]
	v_rcp_f32_e32 v134, v134
	s_nop 0
	v_pk_mul_f32 v[134:135], v[44:45], v[134:135]
	v_add_u32_e32 v128, 0xb0, v128
	v_cvt_pk_bf16_f32 v134, v134, v135
	v_rcp_f32_e32 v137, v137
	s_nop 0
	v_rcp_f32_e32 v136, v136
	v_mul_f32_e32 v129, 0xbfb8aa3b, v8
	v_exp_f32_e32 v138, v129
	v_mul_f32_e32 v129, 0xbfb8aa3b, v9
	v_exp_f32_e32 v139, v129
	v_mul_f32_e32 v129, 0xbfb8aa3b, v10
	v_exp_f32_e32 v140, v129
	v_mul_f32_e32 v129, 0xbfb8aa3b, v11
	v_pk_add_f32 v[138:139], v[138:139], 1.0 op_sel_hi:[1,0]
	v_exp_f32_e32 v141, v129
	s_nop 0
	v_pk_add_f32 v[140:141], v[140:141], 1.0 op_sel_hi:[1,0]
	v_pk_mul_f32 v[136:137], v[46:47], v[136:137]
	v_rcp_f32_e32 v139, v139
	v_cvt_pk_bf16_f32 v135, v136, v137
	s_nop 0
	v_rcp_f32_e32 v138, v138
	s_nop 0
	v_pk_mul_f32 v[138:139], v[40:41], v[138:139]
	v_rcp_f32_e32 v141, v141
	v_cvt_pk_bf16_f32 v136, v138, v139
	s_nop 0
	v_rcp_f32_e32 v140, v140
	s_nop 0
	v_pk_mul_f32 v[140:141], v[42:43], v[140:141]
	v_ashrrev_i32_e32 v129, 31, v128
	v_cvt_pk_bf16_f32 v137, v140, v141
	global_store_dwordx4 v[130:131], v[134:137], off
	v_mul_f32_e32 v130, 0xbfb8aa3b, v4
	v_mul_f32_e32 v131, 0xbfb8aa3b, v5
	v_exp_f32_e32 v130, v130
	v_exp_f32_e32 v131, v131
	v_mul_f32_e32 v134, 0xbfb8aa3b, v6
	v_mul_f32_e32 v135, 0xbfb8aa3b, v7
	v_exp_f32_e32 v134, v134
	v_pk_add_f32 v[130:131], v[130:131], 1.0 op_sel_hi:[1,0]
	v_exp_f32_e32 v135, v135
	s_nop 0
	v_pk_add_f32 v[134:135], v[134:135], 1.0 op_sel_hi:[1,0]
	v_lshl_add_u64 v[128:129], v[128:129], 0, s[78:79]
	v_lshlrev_b64 v[128:129], 10, v[128:129]
	v_rcp_f32_e32 v131, v131
	v_lshl_add_u64 v[128:129], s[16:17], 0, v[128:129]
	v_lshl_add_u64 v[128:129], v[128:129], 0, s[10:11]
	v_lshl_add_u64 v[128:129], v[128:129], 0, v[132:133]
	v_rcp_f32_e32 v130, v130
	s_nop 0
	v_pk_mul_f32 v[130:131], v[36:37], v[130:131]
	v_rcp_f32_e32 v135, v135
	s_nop 0
	v_rcp_f32_e32 v134, v134
	v_mul_f32_e32 v136, 0xbfb8aa3b, v0
	v_mul_f32_e32 v137, 0xbfb8aa3b, v1
	v_exp_f32_e32 v136, v136
	v_exp_f32_e32 v137, v137
	v_mul_f32_e32 v138, 0xbfb8aa3b, v2
	v_mul_f32_e32 v139, 0xbfb8aa3b, v3
	v_exp_f32_e32 v138, v138
	v_pk_add_f32 v[136:137], v[136:137], 1.0 op_sel_hi:[1,0]
	v_exp_f32_e32 v139, v139
	s_nop 0
	v_pk_add_f32 v[138:139], v[138:139], 1.0 op_sel_hi:[1,0]
	v_rcp_f32_e32 v137, v137
	s_nop 0
	v_rcp_f32_e32 v136, v136
	s_nop 0
	v_pk_mul_f32 v[136:137], v[32:33], v[136:137]
	v_rcp_f32_e32 v139, v139
	v_cvt_pk_bf16_f32 v136, v136, v137
	s_nop 0
	v_rcp_f32_e32 v138, v138
	v_pk_mul_f32 v[140:141], v[38:39], v[134:135]
	v_pk_mul_f32 v[138:139], v[34:35], v[138:139]
	v_cvt_pk_bf16_f32 v134, v130, v131
	v_cvt_pk_bf16_f32 v135, v140, v141
	s_nop 0
	v_cvt_pk_bf16_f32 v137, v138, v139
	global_store_dwordx4 v[128:129], v[134:137], off

; __device__ __forceinline__ f32x4 sigm4(f32x4 v) { return (f32x4){sigm(v[0]), sigm(v[1]), sigm(v[2]), sigm(v[3])}; }
; __device__ __forceinline__ u32x2 pack4(f32x4 v) { u32x2 w; w.x = pk2(v[0], v[1]); w.y = pk2(v[2], v[3]); return w; }
; __device__ __forceinline__ void narrow_job(CParams& p, LAS unsigned char* lds, const int nk, const bf16_t* A, const int lda, const int K, const bf16_t* B, const int ldb, const int nstrips) {
;     ...
;         __syncthreads();
;         if (kh == 0) {
;             const f32x4 v = acc0 + red[(wq * 64 + lane) * 2]; const int c = c0 + 4 * fq;
;     ...
;             case NK_FFN1: { const float rs = rsqrtf(p.ss2[row] * (1.f / 1024.f) + 1e-6f); const f32x4 g = v * rs, uu = (acc1 + red[(wq * 64 + lane) * 2 + 1]) * rs;
;                 *(u32x2*)(p.hid + row * DFF + c) = pack4(g * sigm4(g) * uu); } break;
.LBB0_936:
	s_andn2_b64 vcc, exec, s[8:9]
	s_waitcnt lgkmcnt(0)
	s_barrier
	s_cbranch_vccnz .LBB0_933
	s_nop 1
	ds_read_b128 v[18:21], v16
	ds_read_b128 v[22:25], v16 offset:16
	s_load_dwordx2 s[10:11], s[62:63], 0x1b0
	s_waitcnt lgkmcnt(0)
	v_pk_add_f32 v[18:19], v[4:5], v[18:19]
	v_lshlrev_b32_e32 v5, 2, v17
	global_load_dword v5, v5, s[10:11]
	s_mov_b32 s10, 0x800000
	v_pk_add_f32 v[6:7], v[6:7], v[20:21]
	v_pk_add_f32 v[2:3], v[2:3], v[24:25]
	v_pk_add_f32 v[0:1], v[0:1], v[22:23]
	v_and_or_b32 v4, s0, -16, v13
	s_waitcnt vmcnt(0)
	v_fmamk_f32 v5, v5, 0x3a800000, v193
	v_cmp_gt_f32_e32 vcc, s10, v5
	v_mul_f32_e32 v20, 0x4b800000, v5
	s_nop 0
	v_cndmask_b32_e32 v5, v5, v20, vcc
	v_rsq_f32_e32 v5, v5
	s_nop 0
	v_mul_f32_e32 v20, 0x45800000, v5
	v_cndmask_b32_e32 v20, v5, v20, vcc
	v_pk_mul_f32 v[18:19], v[18:19], v[20:21] op_sel_hi:[1,0]
	v_pk_mul_f32 v[6:7], v[6:7], v[20:21] op_sel_hi:[1,0]
	v_mul_f32_e32 v5, 0xbfb8aa3b, v18
	v_pk_mul_f32 v[0:1], v[0:1], v[20:21] op_sel_hi:[1,0]
	v_pk_mul_f32 v[2:3], v[2:3], v[20:21] op_sel_hi:[1,0]
	v_exp_f32_e32 v20, v5
	v_mul_f32_e32 v5, 0xbfb8aa3b, v19
	v_exp_f32_e32 v21, v5
	v_mul_f32_e32 v5, 0xbfb8aa3b, v6
	v_exp_f32_e32 v22, v5
	v_mul_f32_e32 v5, 0xbfb8aa3b, v7
	v_exp_f32_e32 v23, v5
	v_pk_add_f32 v[20:21], v[20:21], 1.0 op_sel_hi:[1,0]
	v_pk_add_f32 v[22:23], v[22:23], 1.0 op_sel_hi:[1,0]
	s_nop 0
	s_nop 0
	v_rcp_f32_e32 v23, v23
	s_nop 0
	v_rcp_f32_e32 v22, v22
	s_nop 0
	v_pk_mul_f32 v[6:7], v[6:7], v[22:23]
	v_rcp_f32_e32 v21, v21
	s_load_dwordx2 s[10:11], s[62:63], 0x1f8
	v_pk_mul_f32 v[2:3], v[2:3], v[6:7]
	v_rcp_f32_e32 v20, v20
	s_nop 0
	v_pk_mul_f32 v[18:19], v[18:19], v[20:21]
	v_ashrrev_i32_e32 v5, 31, v4
	v_pk_mul_f32 v[0:1], v[0:1], v[18:19]
	s_nop 0
	v_cvt_pk_bf16_f32 v0, v0, v1
	v_cvt_pk_bf16_f32 v1, v2, v3
	s_waitcnt lgkmcnt(0)
	v_mov_b64_e32 v[2:3], s[10:11]
	s_movk_i32 s10, 0x1600
	v_mad_u64_u32 v[2:3], s[10:11], v17, s10, v[2:3]
	v_lshl_add_u64 v[2:3], v[4:5], 1, v[2:3]
	global_store_dwordx2 v[2:3], v[0:1], off
	s_branch .LBB0_933

; __device__ __forceinline__ f32x4 sigm4(f32x4 v) { return (f32x4){sigm(v[0]), sigm(v[1]), sigm(v[2]), sigm(v[3])}; }
; __device__ __forceinline__ u32x2 pack4(f32x4 v) { u32x2 w; w.x = pk2(v[0], v[1]); w.y = pk2(v[2], v[3]); return w; }
; __device__ __forceinline__ void narrow_job(CParams& p, LAS unsigned char* lds, const int nk, const bf16_t* A, const int lda, const int K, const bf16_t* B, const int ldb, const int nstrips) {
;     ...
;         if (kh == 0) {
;             const f32x4 v = acc0 + red[(wq * 64 + lane) * 2]; const int c = c0 + 4 * fq;
;             switch (nk) {
;             case NK_EA: {
;                 if (c < 1024) { const f32x4 bias = *(const f32x4*)(p.in[I_W0] + c); *(u32x2*)(p.ebuf + row * 1024 + c) = pack4(sigm4(v + bias) * 0.60653066f); }
;                 else { const f32x4 bias = *(const f32x4*)(p.in[I_A0] + (c - 1024)); *(u32x2*)(p.abuf + row * 1024 + (c - 1024)) = pack4(sigm4(v + bias)); }
.LBB0_1011:
	s_andn2_b64 vcc, exec, s[8:9]
	s_waitcnt lgkmcnt(0)
	s_barrier
	s_cbranch_vccnz .LBB0_1008
	ds_read_b128 v[8:11], v20
	s_load_dwordx2 s[10:11], s[62:63], 0x1e0
	s_and_b32 s3, s2, 0x3ffffffc
	s_waitcnt lgkmcnt(0)
	v_pk_add_f32 v[14:15], v[2:3], v[10:11]
	v_or_b32_e32 v2, s3, v17
	v_lshlrev_b32_e32 v12, 2, v2
	s_movk_i32 s3, 0x3ff
	v_pk_add_f32 v[0:1], v[0:1], v[8:9]
	v_cmp_lt_i32_e32 vcc, s3, v12
	v_mov_b64_e32 v[8:9], s[10:11]
	s_and_saveexec_b64 s[10:11], vcc
	s_xor_b64 s[10:11], exec, s[10:11]
	s_cbranch_execz .LBB0_1014
	s_load_dwordx2 s[12:13], s[62:63], 0x90
	v_add_u32_e32 v160, 0xfffffc00, v12
	s_waitcnt lgkmcnt(0)
	v_lshl_add_u64 v[2:3], v[160:161], 2, s[12:13]
	global_load_dwordx4 v[8:11], v[2:3], off
	s_waitcnt vmcnt(0)
	v_pk_add_f32 v[0:1], v[0:1], v[8:9]
	s_nop 0
	v_mul_f32_e32 v0, 0xbfb8aa3b, v0
	v_exp_f32_e32 v0, v0
	v_pk_add_f32 v[2:3], v[14:15], v[10:11]
	v_mul_f32_e32 v1, 0xbfb8aa3b, v1
	v_exp_f32_e32 v1, v1
	v_add_f32_e32 v0, 1.0, v0
	v_add_f32_e32 v1, 1.0, v1
	v_mul_f32_e32 v2, 0xbfb8aa3b, v2
	v_exp_f32_e32 v2, v2
	v_rcp_f32_e32 v0, v0
	v_add_f32_e32 v2, 1.0, v2
	v_mul_f32_e32 v3, 0xbfb8aa3b, v3
	v_exp_f32_e32 v3, v3
	v_rcp_f32_e32 v1, v1
	v_add_f32_e32 v3, 1.0, v3
	v_rcp_f32_e32 v2, v2
	s_load_dwordx2 s[12:13], s[62:63], 0x240
	v_rcp_f32_e32 v3, v3
	v_cvt_pk_bf16_f32 v10, v0, v1
	v_cvt_pk_bf16_f32 v11, v2, v3
	s_waitcnt lgkmcnt(0)
	v_mov_b64_e32 v[8:9], s[12:13]
	v_mov_b64_e32 v[12:13], v[160:161]
.LBB0_1014:
	s_andn2_saveexec_b64 s[10:11], s[10:11]
	s_cbranch_execz .LBB0_1007
	s_load_dwordx2 s[12:13], s[62:63], 0x80
	v_ashrrev_i32_e32 v13, 31, v12
	s_waitcnt lgkmcnt(0)
	v_lshl_add_u64 v[2:3], v[12:13], 2, s[12:13]
	global_load_dwordx4 v[22:25], v[2:3], off
	s_waitcnt vmcnt(0)
	v_pk_add_f32 v[2:3], v[14:15], v[24:25]
	s_nop 0
	v_mul_f32_e32 v2, 0xbfb8aa3b, v2
	v_mul_f32_e32 v3, 0xbfb8aa3b, v3
	v_exp_f32_e32 v2, v2
	v_exp_f32_e32 v3, v3
	v_pk_add_f32 v[0:1], v[0:1], v[22:23]
	v_pk_add_f32 v[2:3], v[2:3], 1.0 op_sel_hi:[1,0]
	s_nop 0
	v_mul_f32_e32 v0, 0xbfb8aa3b, v0
	v_mul_f32_e32 v1, 0xbfb8aa3b, v1
	v_exp_f32_e32 v0, v0
	v_rcp_f32_e32 v3, v3
	v_exp_f32_e32 v1, v1
	s_nop 0
	v_pk_add_f32 v[0:1], v[0:1], 1.0 op_sel_hi:[1,0]
	v_rcp_f32_e32 v2, v2
	s_nop 0
	v_rcp_f32_e32 v1, v1
	s_mov_b32 s12, 0x3f1b4598
	v_pk_mul_f32 v[2:3], v[2:3], s[12:13] op_sel_hi:[1,0]
	v_rcp_f32_e32 v0, v0
	s_nop 0
	v_pk_mul_f32 v[0:1], v[0:1], s[12:13] op_sel_hi:[1,0]
	v_cvt_pk_bf16_f32 v11, v2, v3
	s_nop 0
	v_cvt_pk_bf16_f32 v10, v0, v1
	s_branch .LBB0_1007

; __device__ __forceinline__ u32x2 pack4(f32x4 v) { u32x2 w; w.x = pk2(v[0], v[1]); w.y = pk2(v[2], v[3]); return w; }
; __device__ __forceinline__ void narrow_attn(CParams& p) {
;     ...
;             const bf16_t* ap = p.P + row * 1024 + h * 256 + 8 * fq;
;             bf16x8 av[8], bv[2][8];
; #pragma unroll
;             for (int k = 0; k < 8; ++k) av[k] = *(const bf16x8*)(ap + k * 32);
; #pragma unroll
;             for (int u = 0; u < 2; ++u) { const bf16_t* bp = p.VT + ((size_t)h * 256 + (wid * 2 + u) * 16 + fr) * VTLD + (size_t)(8 + sq) * 256 + 8 * fq;
; #pragma unroll
;                 for (int k = 0; k < 8; ++k) bv[u][k] = *(const bf16x8*)(bp + k * 32); }
;             const float inv = 1.f / __hip_atomic_load(p.psum + row * 4 + h, __ATOMIC_RELAXED, __HIP_MEMORY_SCOPE_AGENT);
; #pragma unroll
;             for (int u = 0; u < 2; ++u) {
;                 f32x4 acc = (f32x4){0.f, 0.f, 0.f, 0.f};
; #pragma unroll
;                 for (int k = 0; k < 8; ++k) acc = __builtin_amdgcn_mfma_f32_16x16x32_bf16(bv[u][k], av[k], acc, 0, 0, 0);
;                 *(u32x2*)(p.ob + row * 1024 + h * 256 + (wid * 2 + u) * 16 + 4 * fq) = pack4(acc * inv);
;             }
.LBB0_1022:
	s_or_b64 exec, exec, s[16:17]
	s_lshl_b32 s1, s1, 8
	v_or_b32_e32 v10, s1, v64
	s_lshl_b64 s[2:3], s[14:15], 9
	v_lshl_add_u64 v[8:9], v[72:73], 0, s[2:3]
	v_add_u32_e32 v4, s4, v10
	s_movk_i32 s14, 0x3000
	v_mad_i64_i32 v[52:53], s[2:3], v4, s14, v[8:9]
	s_waitcnt vmcnt(0)
	s_waitcnt lgkmcnt(0)
	s_barrier
	global_load_dwordx4 v[4:7], v[52:53], off
	v_lshl_add_u64 v[48:49], v[82:83], 0, v[160:161]
	global_load_dwordx4 v[0:3], v[48:49], off
	v_add_u32_e32 v10, s12, v10
	v_mad_i64_i32 v[60:61], s[2:3], v10, s14, v[8:9]
	global_load_dwordx4 v[8:11], v[60:61], off
	global_load_dwordx4 v[12:15], v[52:53], off offset:64
	global_load_dwordx4 v[16:19], v[48:49], off offset:64
	global_load_dwordx4 v[20:23], v[60:61], off offset:64
	global_load_dwordx4 v[24:27], v[52:53], off offset:128
	global_load_dwordx4 v[28:31], v[48:49], off offset:128
	global_load_dwordx4 v[32:35], v[60:61], off offset:128
	s_lshl_b32 s50, s1, 1
	v_mov_b32_e32 v75, v161
	s_add_i32 s0, s0, s26
	s_cmp_lt_i32 s0, 64
	s_waitcnt vmcnt(7)
	v_mfma_f32_16x16x32_bf16 v[4:7], v[4:7], v[0:3], 0
	s_waitcnt vmcnt(6)
	v_mfma_f32_16x16x32_bf16 v[0:3], v[8:11], v[0:3], 0
	global_load_dwordx4 v[8:11], v[52:53], off offset:192
	global_load_dwordx4 v[36:39], v[48:49], off offset:192
	s_waitcnt vmcnt(6)
	v_mfma_f32_16x16x32_bf16 v[4:7], v[12:15], v[16:19], v[4:7]
	global_load_dwordx4 v[12:15], v[60:61], off offset:192
	s_waitcnt vmcnt(6)
	v_mfma_f32_16x16x32_bf16 v[0:3], v[20:23], v[16:19], v[0:3]
	global_load_dwordx4 v[16:19], v[52:53], off offset:256
	global_load_dwordx4 v[20:23], v[48:49], off offset:256
	global_load_dwordx4 v[40:43], v[48:49], off offset:320
	s_waitcnt vmcnt(7)
	v_mfma_f32_16x16x32_bf16 v[4:7], v[24:27], v[28:31], v[4:7]
	global_load_dwordx4 v[24:27], v[60:61], off offset:256
	global_load_dwordx4 v[44:47], v[48:49], off offset:384
	s_nop 0
	global_load_dwordx4 v[48:51], v[48:49], off offset:448
	s_waitcnt vmcnt(9)
	v_mfma_f32_16x16x32_bf16 v[0:3], v[32:35], v[28:31], v[0:3]
	global_load_dwordx4 v[28:31], v[52:53], off offset:320
	global_load_dwordx4 v[32:35], v[52:53], off offset:384
	s_nop 0
	global_load_dwordx4 v[52:55], v[52:53], off offset:448
	s_waitcnt vmcnt(10)
	v_mfma_f32_16x16x32_bf16 v[4:7], v[8:11], v[36:39], v[4:7]
	global_load_dwordx4 v[8:11], v[60:61], off offset:320
	global_load_dwordx4 v[56:59], v[60:61], off offset:384
	s_nop 0
	global_load_dwordx4 v[60:63], v[60:61], off offset:448
	s_waitcnt vmcnt(12)
	v_mfma_f32_16x16x32_bf16 v[0:3], v[12:15], v[36:39], v[0:3]
	global_load_dword v14, v[78:79], off sc1
	v_lshlrev_b64 v[12:13], 10, v[76:77]
	v_lshl_add_u64 v[12:13], v[12:13], 1, s[8:9]
	s_waitcnt vmcnt(11)
	v_mfma_f32_16x16x32_bf16 v[4:7], v[16:19], v[20:23], v[4:7]
	v_lshl_add_u64 v[12:13], v[12:13], 0, s[50:51]
	v_lshl_add_u64 v[12:13], v[12:13], 0, v[74:75]
	v_lshl_add_u64 v[12:13], s[4:5], 1, v[12:13]
	s_waitcnt vmcnt(9)
	v_mfma_f32_16x16x32_bf16 v[0:3], v[24:27], v[20:23], v[0:3]
	s_waitcnt vmcnt(0)
	v_mfma_f32_16x16x32_bf16 v[4:7], v[28:31], v[40:43], v[4:7]
	v_mfma_f32_16x16x32_bf16 v[0:3], v[8:11], v[40:43], v[0:3]
	v_mfma_f32_16x16x32_bf16 v[4:7], v[32:35], v[44:47], v[4:7]
	v_mfma_f32_16x16x32_bf16 v[0:3], v[56:59], v[44:47], v[0:3]
	v_mfma_f32_16x16x32_bf16 v[4:7], v[52:55], v[48:51], v[4:7]
	v_rcp_f32_e32 v8, v14
	v_mfma_f32_16x16x32_bf16 v[0:3], v[60:63], v[48:51], v[0:3]
	s_nop 4
	v_mul_f32_e64 v4, v8, v4
	v_mul_f32_e64 v5, v8, v5
	v_pk_mul_f32 v[6:7], v[8:9], v[6:7] op_sel_hi:[0,1]
	v_pk_mul_f32 v[0:1], v[8:9], v[0:1] op_sel_hi:[0,1]
	v_cvt_pk_bf16_f32 v4, v4, v5
	v_cvt_pk_bf16_f32 v5, v6, v7
	v_pk_mul_f32 v[2:3], v[8:9], v[2:3] op_sel_hi:[0,1]
	v_cvt_pk_bf16_f32 v0, v0, v1
	v_cvt_pk_bf16_f32 v1, v2, v3
	global_store_dwordx2 v[12:13], v[4:5], off
	global_store_dwordx2 v[12:13], v[0:1], off offset:32
	s_cbranch_scc0 .LBB0_1027
